# cross-lane reductions: ds_bpermute round trips replaced by DPP adds (xor 1/2/4) and v_permlane16/32_swap (LayerNorm-epilogue statistics)
# baseline (speedup 1.0000x reference)
; #define LAS __attribute__((address_space(3)))
;     DI void fused(f32x4 (&acc)[2][2][4][2], const Unit& u, int wr, int wc, int fr_, int fq_, LAS unsigned char* lds, int wid, int lane_) const {
;         int lane = lane_; asm volatile("" : "+v"(lane));
;         const int fr = lane & 15, fq = lane >> 4;
;         LAS f32x2* P = (LAS f32x2*)lds;
;         LAS f32x2* S = (LAS f32x2*)(lds + 8192);
;         const int col0 = u.pn * BM + wc * 32 + 4 * fq;
; #pragma unroll
;         for (int ai = 0; ai < 2; ++ai)
; #pragma unroll
;             for (int m = 0; m < 4; ++m) { const int r = u.pm * BM + ai * HALF + wr * 64 + m * 16 + fr; const size_t ro = (size_t)r * ldc + col0;
; #pragma unroll
;                 for (int bj = 0; bj < 2; ++bj)
; #pragma unroll
;                     for (int n = 0; n < 2; ++n) { const f32x4 h = *(const f32x4*)(Hin + ro + bj * HALF + n * 16); acc[ai][bj][m][n] = h * alpha + acc[ai][bj][m][n] * s; }
;                 asm volatile("" : "+v"(acc[ai][0][m][0]), "+v"(acc[ai][0][m][1]), "+v"(acc[ai][1][m][0]), "+v"(acc[ai][1][m][1]));
;                 asm volatile("" ::: "memory"); }
.LBB0_218:
	v_mov_b32_e32 v136, v202
	s_lshl_b32 s0, s24, 5
	s_barrier
	s_lshl_b32 s1, s2, 8
	v_ashrrev_i32_e32 v130, 2, v136
	s_or_b32 s0, s1, s0
	v_and_b32_e32 v130, -4, v130
	s_lshl_b32 s8, s22, 8
	v_and_b32_e32 v1, 15, v136
	v_add_u32_e32 v130, s0, v130
	s_add_i32 s0, s8, s20
	v_or_b32_e32 v134, s0, v1
	v_ashrrev_i32_e32 v135, 31, v134
	v_ashrrev_i32_e32 v131, 31, v130
	v_lshlrev_b64 v[132:133], 12, v[134:135]
	v_lshl_add_u64 v[138:139], s[36:37], 0, v[132:133]
	v_lshlrev_b64 v[132:133], 2, v[130:131]
	v_lshl_add_u64 v[150:151], v[138:139], 0, v[132:133]
	global_load_dwordx4 v[138:141], v[150:151], off
	global_load_dwordx4 v[142:145], v[150:151], off offset:64
	global_load_dwordx4 v[146:149], v[150:151], off offset:512
	global_load_dwordx4 v[154:157], v[150:151], off offset:576
	v_or_b32_e32 v150, 16, v134
	v_pk_mul_f32 v[126:127], v[126:127], 0.5 op_sel_hi:[1,0]
	v_pk_mul_f32 v[128:129], v[128:129], 0.5 op_sel_hi:[1,0]
	s_mov_b32 s0, 0x3fb504f3
	v_pk_mul_f32 v[122:123], v[122:123], 0.5 op_sel_hi:[1,0]
	v_pk_mul_f32 v[124:125], v[124:125], 0.5 op_sel_hi:[1,0]
	v_ashrrev_i32_e32 v151, 31, v150
	v_lshlrev_b64 v[150:151], 12, v[150:151]
	v_lshl_add_u64 v[150:151], s[36:37], 0, v[150:151]
	v_lshl_add_u64 v[150:151], v[150:151], 0, v[132:133]
	v_mbcnt_lo_u32_b32 v135, -1, 0
	v_mbcnt_hi_u32_b32 v135, -1, v135
	v_xor_b32_e32 v137, 16, v135
	s_waitcnt vmcnt(0)
	v_pk_fma_f32 v[128:129], v[140:141], s[0:1], v[128:129] op_sel_hi:[1,0,1]
	v_pk_fma_f32 v[126:127], v[138:139], s[0:1], v[126:127] op_sel_hi:[1,0,1]
	v_pk_fma_f32 v[124:125], v[144:145], s[0:1], v[124:125] op_sel_hi:[1,0,1]
	v_pk_fma_f32 v[122:123], v[142:143], s[0:1], v[122:123] op_sel_hi:[1,0,1]
	v_pk_mul_f32 v[138:139], v[148:149], s[0:1] op_sel_hi:[1,0]
	v_pk_mul_f32 v[140:141], v[146:147], s[0:1] op_sel_hi:[1,0]
	v_pk_mul_f32 v[142:143], v[156:157], s[0:1] op_sel_hi:[1,0]
	v_pk_mul_f32 v[144:145], v[154:155], s[0:1] op_sel_hi:[1,0]
	v_pk_fma_f32 v[120:121], v[120:121], 0.5, v[138:139] op_sel_hi:[1,0,1]
	v_pk_fma_f32 v[118:119], v[118:119], 0.5, v[140:141] op_sel_hi:[1,0,1]
	v_pk_fma_f32 v[108:109], v[108:109], 0.5, v[142:143] op_sel_hi:[1,0,1]
	v_pk_fma_f32 v[106:107], v[106:107], 0.5, v[144:145] op_sel_hi:[1,0,1]
	s_nop 0
	global_load_dwordx4 v[138:141], v[150:151], off
	global_load_dwordx4 v[142:145], v[150:151], off offset:64
	global_load_dwordx4 v[146:149], v[150:151], off offset:512
	global_load_dwordx4 v[154:157], v[150:151], off offset:576
	v_or_b32_e32 v150, 32, v134
	v_ashrrev_i32_e32 v151, 31, v150
	v_lshlrev_b64 v[150:151], 12, v[150:151]
	v_lshl_add_u64 v[150:151], s[36:37], 0, v[150:151]
	v_lshl_add_u64 v[150:151], v[150:151], 0, v[132:133]
	v_mov_b32_e32 v160, v127
	v_mov_b32_e32 v161, v128
	v_mov_b32_e32 v162, v126
	v_mov_b32_e32 v163, v129
	v_mov_b32_e32 v164, v123
	v_mov_b32_e32 v165, v124
	v_pk_add_f32 v[160:161], v[160:161], v[162:163]
	v_add_f32_e32 v167, v120, v121
	v_mov_b32_e32 v166, v107
	v_mov_b32_e32 v168, v109
	s_waitcnt vmcnt(3)
	v_pk_mul_f32 v[140:141], v[140:141], s[0:1] op_sel_hi:[1,0]
	v_pk_mul_f32 v[138:139], v[138:139], s[0:1] op_sel_hi:[1,0]
	s_waitcnt vmcnt(2)
	v_pk_mul_f32 v[144:145], v[144:145], s[0:1] op_sel_hi:[1,0]
	v_pk_mul_f32 v[142:143], v[142:143], s[0:1] op_sel_hi:[1,0]
	s_waitcnt vmcnt(1)
	v_pk_mul_f32 v[148:149], v[148:149], s[0:1] op_sel_hi:[1,0]
	v_pk_mul_f32 v[146:147], v[146:147], s[0:1] op_sel_hi:[1,0]
	s_waitcnt vmcnt(0)
	v_pk_mul_f32 v[156:157], v[156:157], s[0:1] op_sel_hi:[1,0]
	v_pk_mul_f32 v[154:155], v[154:155], s[0:1] op_sel_hi:[1,0]
	v_pk_fma_f32 v[116:117], v[116:117], 0.5, v[140:141] op_sel_hi:[1,0,1]
	v_pk_fma_f32 v[114:115], v[114:115], 0.5, v[138:139] op_sel_hi:[1,0,1]
	v_pk_fma_f32 v[112:113], v[112:113], 0.5, v[144:145] op_sel_hi:[1,0,1]
	v_pk_fma_f32 v[110:111], v[110:111], 0.5, v[142:143] op_sel_hi:[1,0,1]
	v_pk_fma_f32 v[104:105], v[104:105], 0.5, v[148:149] op_sel_hi:[1,0,1]
	v_pk_fma_f32 v[102:103], v[102:103], 0.5, v[146:147] op_sel_hi:[1,0,1]
	v_pk_fma_f32 v[92:93], v[92:93], 0.5, v[156:157] op_sel_hi:[1,0,1]
	v_pk_fma_f32 v[90:91], v[90:91], 0.5, v[154:155] op_sel_hi:[1,0,1]
	s_nop 0
	global_load_dwordx4 v[138:141], v[150:151], off
	global_load_dwordx4 v[142:145], v[150:151], off offset:64
	global_load_dwordx4 v[146:149], v[150:151], off offset:512
	global_load_dwordx4 v[154:157], v[150:151], off offset:576
	v_or_b32_e32 v150, 48, v134
	v_ashrrev_i32_e32 v151, 31, v150
	v_lshlrev_b64 v[150:151], 12, v[150:151]
	v_lshl_add_u64 v[150:151], s[36:37], 0, v[150:151]
	v_lshl_add_u64 v[150:151], v[150:151], 0, v[132:133]
	s_waitcnt vmcnt(3)
	v_pk_mul_f32 v[140:141], v[140:141], s[0:1] op_sel_hi:[1,0]
	v_pk_mul_f32 v[138:139], v[138:139], s[0:1] op_sel_hi:[1,0]
	s_waitcnt vmcnt(2)
	v_pk_mul_f32 v[144:145], v[144:145], s[0:1] op_sel_hi:[1,0]
	v_pk_mul_f32 v[142:143], v[142:143], s[0:1] op_sel_hi:[1,0]
	s_waitcnt vmcnt(1)
	v_pk_mul_f32 v[148:149], v[148:149], s[0:1] op_sel_hi:[1,0]
	v_pk_mul_f32 v[146:147], v[146:147], s[0:1] op_sel_hi:[1,0]
	s_waitcnt vmcnt(0)
	v_pk_mul_f32 v[156:157], v[156:157], s[0:1] op_sel_hi:[1,0]
	v_pk_mul_f32 v[154:155], v[154:155], s[0:1] op_sel_hi:[1,0]
	v_pk_fma_f32 v[100:101], v[100:101], 0.5, v[140:141] op_sel_hi:[1,0,1]
	v_pk_fma_f32 v[98:99], v[98:99], 0.5, v[138:139] op_sel_hi:[1,0,1]
	v_pk_fma_f32 v[96:97], v[96:97], 0.5, v[144:145] op_sel_hi:[1,0,1]
	v_pk_fma_f32 v[94:95], v[94:95], 0.5, v[142:143] op_sel_hi:[1,0,1]
	v_pk_fma_f32 v[88:89], v[88:89], 0.5, v[148:149] op_sel_hi:[1,0,1]
	v_pk_fma_f32 v[86:87], v[86:87], 0.5, v[146:147] op_sel_hi:[1,0,1]
	v_pk_fma_f32 v[76:77], v[76:77], 0.5, v[156:157] op_sel_hi:[1,0,1]
	v_pk_fma_f32 v[74:75], v[74:75], 0.5, v[154:155] op_sel_hi:[1,0,1]
	s_nop 0
	global_load_dwordx4 v[138:141], v[150:151], off
	global_load_dwordx4 v[142:145], v[150:151], off offset:64
	global_load_dwordx4 v[146:149], v[150:151], off offset:512
	global_load_dwordx4 v[154:157], v[150:151], off offset:576
	v_add_u32_e32 v150, 0x80, v134
	v_ashrrev_i32_e32 v151, 31, v150
	v_lshlrev_b64 v[150:151], 12, v[150:151]
	v_lshl_add_u64 v[150:151], s[36:37], 0, v[150:151]
	v_lshl_add_u64 v[150:151], v[150:151], 0, v[132:133]
	s_waitcnt vmcnt(3)
;     DI void fused(f32x4 (&acc)[2][2][4][2], const Unit& u, int wr, int wc, int fr_, int fq_, LAS unsigned char* lds, int wid, int lane_) const {
;     ...
;             for (int m = 0; m < 4; ++m) { const int r = u.pm * BM + ai * HALF + wr * 64 + m * 16 + fr; const size_t ro = (size_t)r * ldc + col0;
; #pragma unroll
;                 for (int bj = 0; bj < 2; ++bj)
; #pragma unroll
;                     for (int n = 0; n < 2; ++n) { const f32x4 h = *(const f32x4*)(Hin + ro + bj * HALF + n * 16); acc[ai][bj][m][n] = h * alpha + acc[ai][bj][m][n] * s; }
;                 asm volatile("" : "+v"(acc[ai][0][m][0]), "+v"(acc[ai][0][m][1]), "+v"(acc[ai][1][m][0]), "+v"(acc[ai][1][m][1]));
;                 asm volatile("" ::: "memory"); }
	v_pk_mul_f32 v[140:141], v[140:141], s[0:1] op_sel_hi:[1,0]
	v_pk_mul_f32 v[138:139], v[138:139], s[0:1] op_sel_hi:[1,0]
	s_waitcnt vmcnt(2)
	v_pk_mul_f32 v[144:145], v[144:145], s[0:1] op_sel_hi:[1,0]
	v_pk_mul_f32 v[142:143], v[142:143], s[0:1] op_sel_hi:[1,0]
	s_waitcnt vmcnt(1)
	v_pk_mul_f32 v[148:149], v[148:149], s[0:1] op_sel_hi:[1,0]
	v_pk_mul_f32 v[146:147], v[146:147], s[0:1] op_sel_hi:[1,0]
	s_waitcnt vmcnt(0)
	v_pk_mul_f32 v[156:157], v[156:157], s[0:1] op_sel_hi:[1,0]
	v_pk_mul_f32 v[154:155], v[154:155], s[0:1] op_sel_hi:[1,0]
	v_pk_fma_f32 v[84:85], v[84:85], 0.5, v[140:141] op_sel_hi:[1,0,1]
	v_pk_fma_f32 v[82:83], v[82:83], 0.5, v[138:139] op_sel_hi:[1,0,1]
	v_pk_fma_f32 v[80:81], v[80:81], 0.5, v[144:145] op_sel_hi:[1,0,1]
	v_pk_fma_f32 v[78:79], v[78:79], 0.5, v[142:143] op_sel_hi:[1,0,1]
	v_pk_fma_f32 v[72:73], v[72:73], 0.5, v[148:149] op_sel_hi:[1,0,1]
	v_pk_fma_f32 v[70:71], v[70:71], 0.5, v[146:147] op_sel_hi:[1,0,1]
	v_pk_fma_f32 v[68:69], v[68:69], 0.5, v[156:157] op_sel_hi:[1,0,1]
	v_pk_fma_f32 v[66:67], v[66:67], 0.5, v[154:155] op_sel_hi:[1,0,1]
	s_nop 0
	global_load_dwordx4 v[138:141], v[150:151], off
	global_load_dwordx4 v[142:145], v[150:151], off offset:64
	global_load_dwordx4 v[146:149], v[150:151], off offset:512
	global_load_dwordx4 v[154:157], v[150:151], off offset:576
	v_add_u32_e32 v150, 0x90, v134
	v_ashrrev_i32_e32 v151, 31, v150
	v_lshlrev_b64 v[150:151], 12, v[150:151]
	v_lshl_add_u64 v[150:151], s[36:37], 0, v[150:151]
	v_lshl_add_u64 v[150:151], v[150:151], 0, v[132:133]
	s_waitcnt vmcnt(3)
	v_pk_mul_f32 v[140:141], v[140:141], s[0:1] op_sel_hi:[1,0]
	v_pk_mul_f32 v[138:139], v[138:139], s[0:1] op_sel_hi:[1,0]
	s_waitcnt vmcnt(2)
	v_pk_mul_f32 v[144:145], v[144:145], s[0:1] op_sel_hi:[1,0]
	v_pk_mul_f32 v[142:143], v[142:143], s[0:1] op_sel_hi:[1,0]
	s_waitcnt vmcnt(1)
	v_pk_mul_f32 v[148:149], v[148:149], s[0:1] op_sel_hi:[1,0]
	v_pk_mul_f32 v[146:147], v[146:147], s[0:1] op_sel_hi:[1,0]
	s_waitcnt vmcnt(0)
	v_pk_mul_f32 v[156:157], v[156:157], s[0:1] op_sel_hi:[1,0]
	v_pk_mul_f32 v[154:155], v[154:155], s[0:1] op_sel_hi:[1,0]
	v_pk_fma_f32 v[64:65], v[64:65], 0.5, v[140:141] op_sel_hi:[1,0,1]
	v_pk_fma_f32 v[62:63], v[62:63], 0.5, v[138:139] op_sel_hi:[1,0,1]
	v_pk_fma_f32 v[60:61], v[60:61], 0.5, v[144:145] op_sel_hi:[1,0,1]
	v_pk_fma_f32 v[58:59], v[58:59], 0.5, v[142:143] op_sel_hi:[1,0,1]
	v_pk_fma_f32 v[56:57], v[56:57], 0.5, v[148:149] op_sel_hi:[1,0,1]
	v_pk_fma_f32 v[54:55], v[54:55], 0.5, v[146:147] op_sel_hi:[1,0,1]
	v_pk_fma_f32 v[52:53], v[52:53], 0.5, v[156:157] op_sel_hi:[1,0,1]
	v_pk_fma_f32 v[50:51], v[50:51], 0.5, v[154:155] op_sel_hi:[1,0,1]
	s_nop 0
	global_load_dwordx4 v[138:141], v[150:151], off
	global_load_dwordx4 v[142:145], v[150:151], off offset:64
	global_load_dwordx4 v[146:149], v[150:151], off offset:512
	global_load_dwordx4 v[154:157], v[150:151], off offset:576
	v_add_u32_e32 v150, 0xa0, v134
	v_ashrrev_i32_e32 v151, 31, v150
	v_lshlrev_b64 v[150:151], 12, v[150:151]
	v_lshl_add_u64 v[150:151], s[36:37], 0, v[150:151]
	v_lshl_add_u64 v[150:151], v[150:151], 0, v[132:133]
	s_waitcnt vmcnt(3)
	v_pk_mul_f32 v[140:141], v[140:141], s[0:1] op_sel_hi:[1,0]
	v_pk_mul_f32 v[138:139], v[138:139], s[0:1] op_sel_hi:[1,0]
	s_waitcnt vmcnt(2)
	v_pk_mul_f32 v[144:145], v[144:145], s[0:1] op_sel_hi:[1,0]
	v_pk_mul_f32 v[142:143], v[142:143], s[0:1] op_sel_hi:[1,0]
	s_waitcnt vmcnt(1)
	v_pk_mul_f32 v[148:149], v[148:149], s[0:1] op_sel_hi:[1,0]
	v_pk_mul_f32 v[146:147], v[146:147], s[0:1] op_sel_hi:[1,0]
	s_waitcnt vmcnt(0)
	v_pk_mul_f32 v[156:157], v[156:157], s[0:1] op_sel_hi:[1,0]
	v_pk_mul_f32 v[154:155], v[154:155], s[0:1] op_sel_hi:[1,0]
	v_pk_fma_f32 v[48:49], v[48:49], 0.5, v[140:141] op_sel_hi:[1,0,1]
	v_pk_fma_f32 v[46:47], v[46:47], 0.5, v[138:139] op_sel_hi:[1,0,1]
	v_pk_fma_f32 v[44:45], v[44:45], 0.5, v[144:145] op_sel_hi:[1,0,1]
	v_pk_fma_f32 v[42:43], v[42:43], 0.5, v[142:143] op_sel_hi:[1,0,1]
	v_pk_fma_f32 v[40:41], v[40:41], 0.5, v[148:149] op_sel_hi:[1,0,1]
	v_pk_fma_f32 v[38:39], v[38:39], 0.5, v[146:147] op_sel_hi:[1,0,1]
	v_pk_fma_f32 v[36:37], v[36:37], 0.5, v[156:157] op_sel_hi:[1,0,1]
	v_pk_fma_f32 v[34:35], v[34:35], 0.5, v[154:155] op_sel_hi:[1,0,1]
	s_nop 0
	global_load_dwordx4 v[138:141], v[150:151], off
	global_load_dwordx4 v[142:145], v[150:151], off offset:64
	global_load_dwordx4 v[146:149], v[150:151], off offset:512
	global_load_dwordx4 v[154:157], v[150:151], off offset:576
	v_and_b32_e32 v150, 64, v135
	v_add_u32_e32 v153, 64, v150
	v_add_u32_e32 v150, 0xb0, v134
	v_ashrrev_i32_e32 v151, 31, v150
	v_lshlrev_b64 v[150:151], 12, v[150:151]
	v_lshl_add_u64 v[150:151], s[36:37], 0, v[150:151]
	v_lshl_add_u64 v[158:159], v[150:151], 0, v[132:133]
	v_cmp_lt_i32_e32 vcc, v137, v153
	s_waitcnt vmcnt(3)
	v_pk_mul_f32 v[140:141], v[140:141], s[0:1] op_sel_hi:[1,0]
	v_pk_mul_f32 v[138:139], v[138:139], s[0:1] op_sel_hi:[1,0]
	s_waitcnt vmcnt(2)
	v_pk_mul_f32 v[144:145], v[144:145], s[0:1] op_sel_hi:[1,0]
	v_pk_mul_f32 v[142:143], v[142:143], s[0:1] op_sel_hi:[1,0]
	s_waitcnt vmcnt(1)
	v_pk_mul_f32 v[148:149], v[148:149], s[0:1] op_sel_hi:[1,0]
	v_pk_mul_f32 v[146:147], v[146:147], s[0:1] op_sel_hi:[1,0]
	s_waitcnt vmcnt(0)
;     DI void fused(f32x4 (&acc)[2][2][4][2], const Unit& u, int wr, int wc, int fr_, int fq_, LAS unsigned char* lds, int wid, int lane_) const {
;     ...
;             for (int m = 0; m < 4; ++m) { const int r = u.pm * BM + ai * HALF + wr * 64 + m * 16 + fr; const size_t ro = (size_t)r * ldc + col0;
; #pragma unroll
;                 for (int bj = 0; bj < 2; ++bj)
; #pragma unroll
;                     for (int n = 0; n < 2; ++n) { const f32x4 h = *(const f32x4*)(Hin + ro + bj * HALF + n * 16); acc[ai][bj][m][n] = h * alpha + acc[ai][bj][m][n] * s; }
;                 asm volatile("" : "+v"(acc[ai][0][m][0]), "+v"(acc[ai][0][m][1]), "+v"(acc[ai][1][m][0]), "+v"(acc[ai][1][m][1]));
;                 asm volatile("" ::: "memory"); }
; #pragma unroll
;         for (int ai = 0; ai < 2; ++ai)
; #pragma unroll
;             for (int m = 0; m < 4; ++m) {
;                 float sm = 0.f;
; #pragma unroll
;                 for (int bj = 0; bj < 2; ++bj)
; #pragma unroll
;                     for (int n = 0; n < 2; ++n) { const f32x4 x = acc[ai][bj][m][n]; sm += (x[0] + x[1]) + (x[2] + x[3]); }
;                 sm += __shfl_xor(sm, 16); sm += __shfl_xor(sm, 32);
;                 const float mw = sm * (1.0f / 64.0f); float q = 0.f;
; #pragma unroll
;                 for (int bj = 0; bj < 2; ++bj)
; #pragma unroll
;                     for (int n = 0; n < 2; ++n) { const f32x4 d = acc[ai][bj][m][n] - mw; q += (d[0] * d[0] + d[1] * d[1]) + (d[2] * d[2] + d[3] * d[3]); }
;                 q += __shfl_xor(q, 16); q += __shfl_xor(q, 32);
;                 if (fq == 0) P[(ai * HALF + wr * 64 + m * 16 + fr) * 4 + wc] = (f32x2){mw, q};
	v_pk_mul_f32 v[150:151], v[156:157], s[0:1] op_sel_hi:[1,0]
	v_pk_mul_f32 v[154:155], v[154:155], s[0:1] op_sel_hi:[1,0]
	v_pk_fma_f32 v[32:33], v[32:33], 0.5, v[140:141] op_sel_hi:[1,0,1]
	v_pk_fma_f32 v[30:31], v[30:31], 0.5, v[138:139] op_sel_hi:[1,0,1]
	v_pk_fma_f32 v[28:29], v[28:29], 0.5, v[144:145] op_sel_hi:[1,0,1]
	v_pk_fma_f32 v[26:27], v[26:27], 0.5, v[142:143] op_sel_hi:[1,0,1]
	v_pk_fma_f32 v[24:25], v[24:25], 0.5, v[148:149] op_sel_hi:[1,0,1]
	v_pk_fma_f32 v[22:23], v[22:23], 0.5, v[146:147] op_sel_hi:[1,0,1]
	v_pk_fma_f32 v[20:21], v[20:21], 0.5, v[150:151] op_sel_hi:[1,0,1]
	v_pk_fma_f32 v[18:19], v[18:19], 0.5, v[154:155] op_sel_hi:[1,0,1]
	v_mov_b32_e32 v138, v122
	global_load_dwordx4 v[140:143], v[158:159], off
	global_load_dwordx4 v[144:147], v[158:159], off offset:64
	global_load_dwordx4 v[148:151], v[158:159], off offset:512
	global_load_dwordx4 v[154:157], v[158:159], off offset:576
	v_mov_b32_e32 v139, v125
	v_pk_add_f32 v[138:139], v[164:165], v[138:139]
	v_cndmask_b32_e32 v134, v135, v137, vcc
	v_add_f32_e32 v137, v160, v161
	v_pk_add_f32 v[138:139], v[138:139], v[138:139] op_sel_hi:[0,1]
	v_add_f32_e32 v159, v118, v119
	v_mov_b32_e32 v158, v106
	v_add_f32_e32 v169, 0, v137
	v_mov_b32_e32 v138, v108
	v_pk_add_f32 v[158:159], v[158:159], v[166:167]
	v_pk_add_f32 v[138:139], v[138:139], v[168:169]
	v_lshlrev_b32_e32 v134, 2, v134
	v_pk_add_f32 v[138:139], v[158:159], v[138:139]
	s_waitcnt vmcnt(3)
	v_pk_mul_f32 v[142:143], v[142:143], s[0:1] op_sel_hi:[1,0]
	v_add_f32_e32 v137, v138, v139
	v_mov_b32_e32 v138, v137
	s_nop 1
	v_permlane16_swap_b32_e32 v137, v138
	v_xor_b32_e32 v139, 32, v135
	v_cmp_lt_i32_e32 vcc, v139, v153
	v_pk_mul_f32 v[140:141], v[140:141], s[0:1] op_sel_hi:[1,0]
	s_waitcnt vmcnt(2)
	v_pk_mul_f32 v[146:147], v[146:147], s[0:1] op_sel_hi:[1,0]
	v_cndmask_b32_e32 v135, v135, v139, vcc
	v_lshlrev_b32_e32 v135, 2, v135
	s_waitcnt lgkmcnt(0)
	v_add_f32_e32 v137, v137, v138
	v_mov_b32_e32 v138, v137
	s_nop 1
	v_permlane32_swap_b32_e32 v137, v138
	v_pk_mul_f32 v[144:145], v[144:145], s[0:1] op_sel_hi:[1,0]
	s_waitcnt vmcnt(1)
	v_pk_mul_f32 v[150:151], v[150:151], s[0:1] op_sel_hi:[1,0]
	v_pk_mul_f32 v[148:149], v[148:149], s[0:1] op_sel_hi:[1,0]
	s_waitcnt vmcnt(0)
	v_pk_mul_f32 v[156:157], v[156:157], s[0:1] op_sel_hi:[1,0]
	s_waitcnt lgkmcnt(0)
	v_add_f32_e32 v137, v137, v138
	v_fmamk_f32 v139, v137, 0xbc800000, v129
	v_fmamk_f32 v158, v137, 0xbc800000, v127
	v_fmamk_f32 v160, v137, 0xbc800000, v125
	v_fmamk_f32 v162, v137, 0xbc800000, v123
	v_fmamk_f32 v138, v137, 0xbc800000, v128
	v_fmamk_f32 v153, v137, 0xbc800000, v126
	v_fmamk_f32 v159, v137, 0xbc800000, v124
	v_fmamk_f32 v161, v137, 0xbc800000, v122
	v_fmamk_f32 v164, v137, 0xbc800000, v121
	v_fmamk_f32 v166, v137, 0xbc800000, v119
	v_mul_f32_e32 v158, v158, v158
	v_mul_f32_e32 v139, v139, v139
	v_mul_f32_e32 v162, v162, v162
	v_mul_f32_e32 v160, v160, v160
	v_fmamk_f32 v163, v137, 0xbc800000, v120
	v_fmamk_f32 v165, v137, 0xbc800000, v118
	v_fmamk_f32 v168, v137, 0xbc800000, v109
	v_fmamk_f32 v170, v137, 0xbc800000, v107
	v_mul_f32_e32 v166, v166, v166
	v_mul_f32_e32 v164, v164, v164
	v_fmac_f32_e32 v158, v153, v153
	v_fmac_f32_e32 v139, v138, v138
	v_fmac_f32_e32 v162, v161, v161
	v_fmac_f32_e32 v160, v159, v159
	v_fmamk_f32 v167, v137, 0xbc800000, v108
	v_fmamk_f32 v169, v137, 0xbc800000, v106
	v_mul_f32_e32 v170, v170, v170
	v_mul_f32_e32 v168, v168, v168
	v_fmac_f32_e32 v166, v165, v165
	v_fmac_f32_e32 v164, v163, v163
	v_add_f32_e32 v138, v158, v139
	v_add_f32_e32 v139, v162, v160
	v_fmac_f32_e32 v170, v169, v169
	v_fmac_f32_e32 v168, v167, v167
	v_add_f32_e32 v153, v166, v164
	v_add_f32_e32 v138, v138, v139
	v_add_f32_e32 v158, v170, v168
	v_add_f32_e32 v138, v153, v138
	v_add_f32_e32 v138, v158, v138
	v_mov_b32_e32 v139, v138
	s_nop 1
	v_permlane16_swap_b32_e32 v138, v139
	v_pk_mul_f32 v[154:155], v[154:155], s[0:1] op_sel_hi:[1,0]
	v_pk_fma_f32 v[16:17], v[16:17], 0.5, v[142:143] op_sel_hi:[1,0,1]
	v_pk_fma_f32 v[14:15], v[14:15], 0.5, v[140:141] op_sel_hi:[1,0,1]
	v_pk_fma_f32 v[12:13], v[12:13], 0.5, v[146:147] op_sel_hi:[1,0,1]
	s_waitcnt lgkmcnt(0)
	v_add_f32_e32 v138, v138, v139
	v_mov_b32_e32 v139, v138
	s_nop 1
	v_permlane32_swap_b32_e32 v138, v139
	v_pk_fma_f32 v[10:11], v[10:11], 0.5, v[144:145] op_sel_hi:[1,0,1]
	v_pk_fma_f32 v[8:9], v[8:9], 0.5, v[150:151] op_sel_hi:[1,0,1]
	v_pk_fma_f32 v[6:7], v[6:7], 0.5, v[148:149] op_sel_hi:[1,0,1]
	v_pk_fma_f32 v[4:5], v[4:5], 0.5, v[156:157] op_sel_hi:[1,0,1]
	v_pk_fma_f32 v[2:3], v[2:3], 0.5, v[154:155] op_sel_hi:[1,0,1]
	s_lshl_b32 s0, s24, 3
	v_cmp_gt_u32_e32 vcc, 16, v136
	s_add_i32 s4, s0, 0x100
	s_and_saveexec_b64 s[0:1], vcc
	v_readlane_b32 s84, v247, 27
	v_readlane_b32 s85, v247, 28
	s_cbranch_execz .LBB0_220
	s_lshl_b32 s5, s23, 11
	s_add_i32 s5, s4, s5
	v_mul_f32_e32 v140, 0x3c800000, v137
	v_lshl_add_u32 v137, v136, 5, s5
	s_waitcnt lgkmcnt(0)
	v_add_f32_e32 v141, v138, v139
	ds_write_b64 v137, v[140:141]
;     DI void fused(f32x4 (&acc)[2][2][4][2], const Unit& u, int wr, int wc, int fr_, int fq_, LAS unsigned char* lds, int wid, int lane_) const {
;     ...
;             for (int m = 0; m < 4; ++m) {
;                 float sm = 0.f;
; #pragma unroll
;                 for (int bj = 0; bj < 2; ++bj)
; #pragma unroll
;                     for (int n = 0; n < 2; ++n) { const f32x4 x = acc[ai][bj][m][n]; sm += (x[0] + x[1]) + (x[2] + x[3]); }
;                 sm += __shfl_xor(sm, 16); sm += __shfl_xor(sm, 32);
;                 const float mw = sm * (1.0f / 64.0f); float q = 0.f;
; #pragma unroll
;                 for (int bj = 0; bj < 2; ++bj)
; #pragma unroll
;                     for (int n = 0; n < 2; ++n) { const f32x4 d = acc[ai][bj][m][n] - mw; q += (d[0] * d[0] + d[1] * d[1]) + (d[2] * d[2] + d[3] * d[3]); }
;                 q += __shfl_xor(q, 16); q += __shfl_xor(q, 32);
;                 if (fq == 0) P[(ai * HALF + wr * 64 + m * 16 + fr) * 4 + wc] = (f32x2){mw, q};
.LBB0_220:
	s_or_b64 exec, exec, s[0:1]
	v_mov_b32_e32 v138, v115
	s_waitcnt lgkmcnt(0)
	v_mov_b32_e32 v139, v116
	v_mov_b32_e32 v140, v114
	v_mov_b32_e32 v141, v117
	v_pk_add_f32 v[138:139], v[138:139], v[140:141]
	v_mov_b32_e32 v140, v111
	v_mov_b32_e32 v141, v112
	v_mov_b32_e32 v142, v110
	v_mov_b32_e32 v143, v113
	v_pk_add_f32 v[140:141], v[140:141], v[142:143]
	v_add_f32_e32 v137, v138, v139
	v_pk_add_f32 v[140:141], v[140:141], v[140:141] op_sel_hi:[0,1]
	v_add_f32_e32 v139, 0, v137
	v_add_f32_e32 v143, v102, v103
	v_add_f32_e32 v145, v104, v105
	v_mov_b32_e32 v142, v90
	v_mov_b32_e32 v144, v91
	v_mov_b32_e32 v140, v92
	v_mov_b32_e32 v138, v93
	v_pk_add_f32 v[142:143], v[142:143], v[144:145]
	v_pk_add_f32 v[138:139], v[140:141], v[138:139]
	s_nop 0
	v_pk_add_f32 v[138:139], v[142:143], v[138:139]
	s_nop 0
	v_add_f32_e32 v137, v138, v139
	v_mov_b32_e32 v138, v137
	s_nop 1
	v_permlane16_swap_b32_e32 v137, v138
	s_waitcnt lgkmcnt(0)
	v_add_f32_e32 v137, v137, v138
	v_mov_b32_e32 v138, v137
	s_nop 1
	v_permlane32_swap_b32_e32 v137, v138
	s_waitcnt lgkmcnt(0)
	v_add_f32_e32 v137, v137, v138
	v_fmamk_f32 v139, v137, 0xbc800000, v117
	v_fmamk_f32 v141, v137, 0xbc800000, v115
	v_fmamk_f32 v138, v137, 0xbc800000, v116
	v_fmamk_f32 v140, v137, 0xbc800000, v114
	v_mul_f32_e32 v141, v141, v141
	v_mul_f32_e32 v139, v139, v139
	v_fmac_f32_e32 v141, v140, v140
	v_fmac_f32_e32 v139, v138, v138
	v_fmamk_f32 v140, v137, 0xbc800000, v113
	v_fmamk_f32 v142, v137, 0xbc800000, v111
	v_add_f32_e32 v138, v141, v139
	v_fmamk_f32 v139, v137, 0xbc800000, v112
	v_fmamk_f32 v141, v137, 0xbc800000, v110
	v_mul_f32_e32 v142, v142, v142
	v_mul_f32_e32 v140, v140, v140
	v_fmac_f32_e32 v142, v141, v141
	v_fmac_f32_e32 v140, v139, v139
	v_add_f32_e32 v139, v142, v140
	v_fmamk_f32 v140, v137, 0xbc800000, v105
	v_fmamk_f32 v142, v137, 0xbc800000, v103
	v_add_f32_e32 v138, v138, v139
	v_fmamk_f32 v139, v137, 0xbc800000, v104
	v_fmamk_f32 v141, v137, 0xbc800000, v102
	v_mul_f32_e32 v142, v142, v142
	v_mul_f32_e32 v140, v140, v140
	v_fmac_f32_e32 v142, v141, v141
	v_fmac_f32_e32 v140, v139, v139
	v_add_f32_e32 v139, v142, v140
	v_fmamk_f32 v140, v137, 0xbc800000, v93
	v_fmamk_f32 v142, v137, 0xbc800000, v91
	v_add_f32_e32 v138, v139, v138
	v_fmamk_f32 v139, v137, 0xbc800000, v92
	v_fmamk_f32 v141, v137, 0xbc800000, v90
	v_mul_f32_e32 v142, v142, v142
	v_mul_f32_e32 v140, v140, v140
	v_fmac_f32_e32 v142, v141, v141
	v_fmac_f32_e32 v140, v139, v139
	v_add_f32_e32 v139, v142, v140
	v_add_f32_e32 v138, v139, v138
	v_mov_b32_e32 v139, v138
	s_nop 1
	v_permlane16_swap_b32_e32 v138, v139
	s_waitcnt lgkmcnt(0)
	v_add_f32_e32 v138, v138, v139
	v_mov_b32_e32 v139, v138
	s_nop 1
	v_permlane32_swap_b32_e32 v138, v139
	s_and_saveexec_b64 s[0:1], vcc
	s_cbranch_execz .LBB0_222
	s_lshl_b32 s5, s23, 11
	s_add_i32 s5, s4, s5
	v_mul_f32_e32 v140, 0x3c800000, v137
	v_lshl_add_u32 v137, v136, 5, s5
	s_waitcnt lgkmcnt(0)
	v_add_f32_e32 v141, v138, v139
	ds_write_b64 v137, v[140:141] offset:512
.LBB0_222:
	s_or_b64 exec, exec, s[0:1]
	v_mov_b32_e32 v138, v99
	s_waitcnt lgkmcnt(0)
	v_mov_b32_e32 v139, v100
	v_mov_b32_e32 v140, v98
	v_mov_b32_e32 v141, v101
	v_pk_add_f32 v[138:139], v[138:139], v[140:141]
	v_mov_b32_e32 v140, v95
	v_mov_b32_e32 v141, v96
	v_mov_b32_e32 v142, v94
	v_mov_b32_e32 v143, v97
	v_pk_add_f32 v[140:141], v[140:141], v[142:143]
	v_add_f32_e32 v137, v138, v139
	v_pk_add_f32 v[140:141], v[140:141], v[140:141] op_sel_hi:[0,1]
	v_add_f32_e32 v139, 0, v137
	v_add_f32_e32 v143, v86, v87
	v_add_f32_e32 v145, v88, v89
	v_mov_b32_e32 v142, v74
	v_mov_b32_e32 v144, v75
	v_mov_b32_e32 v140, v76
	v_mov_b32_e32 v138, v77
	v_pk_add_f32 v[142:143], v[142:143], v[144:145]
	v_pk_add_f32 v[138:139], v[140:141], v[138:139]
	s_nop 0
	v_pk_add_f32 v[138:139], v[142:143], v[138:139]
	s_nop 0
	v_add_f32_e32 v137, v138, v139
	v_mov_b32_e32 v138, v137
	s_nop 1
	v_permlane16_swap_b32_e32 v137, v138
	s_waitcnt lgkmcnt(0)
	v_add_f32_e32 v137, v137, v138
	v_mov_b32_e32 v138, v137
	s_nop 1
	v_permlane32_swap_b32_e32 v137, v138
	s_waitcnt lgkmcnt(0)
	v_add_f32_e32 v137, v137, v138
	v_fmamk_f32 v139, v137, 0xbc800000, v101
	v_fmamk_f32 v141, v137, 0xbc800000, v99
	v_fmamk_f32 v138, v137, 0xbc800000, v100
	v_fmamk_f32 v140, v137, 0xbc800000, v98
	v_mul_f32_e32 v141, v141, v141
	v_mul_f32_e32 v139, v139, v139
	v_fmac_f32_e32 v141, v140, v140
	v_fmac_f32_e32 v139, v138, v138
	v_fmamk_f32 v140, v137, 0xbc800000, v97
	v_fmamk_f32 v142, v137, 0xbc800000, v95
	v_add_f32_e32 v138, v141, v139
	v_fmamk_f32 v139, v137, 0xbc800000, v96
	v_fmamk_f32 v141, v137, 0xbc800000, v94
	v_mul_f32_e32 v142, v142, v142
	v_mul_f32_e32 v140, v140, v140
	v_fmac_f32_e32 v142, v141, v141
	v_fmac_f32_e32 v140, v139, v139
	v_add_f32_e32 v139, v142, v140
	v_fmamk_f32 v140, v137, 0xbc800000, v89
	v_fmamk_f32 v142, v137, 0xbc800000, v87
	v_add_f32_e32 v138, v138, v139
	v_fmamk_f32 v139, v137, 0xbc800000, v88
	v_fmamk_f32 v141, v137, 0xbc800000, v86
	v_mul_f32_e32 v142, v142, v142
	v_mul_f32_e32 v140, v140, v140
	v_fmac_f32_e32 v142, v141, v141
	v_fmac_f32_e32 v140, v139, v139
	v_add_f32_e32 v139, v142, v140
	v_fmamk_f32 v140, v137, 0xbc800000, v77
	v_fmamk_f32 v142, v137, 0xbc800000, v75
	v_add_f32_e32 v138, v139, v138
	v_fmamk_f32 v139, v137, 0xbc800000, v76
	v_fmamk_f32 v141, v137, 0xbc800000, v74
	v_mul_f32_e32 v142, v142, v142
	v_mul_f32_e32 v140, v140, v140
	v_fmac_f32_e32 v142, v141, v141
	v_fmac_f32_e32 v140, v139, v139
	v_add_f32_e32 v139, v142, v140
	v_add_f32_e32 v138, v139, v138
	v_mov_b32_e32 v139, v138
	s_nop 1
	v_permlane16_swap_b32_e32 v138, v139
	s_waitcnt lgkmcnt(0)
	v_add_f32_e32 v138, v138, v139
	v_mov_b32_e32 v139, v138
	s_nop 1
	v_permlane32_swap_b32_e32 v138, v139
	s_and_saveexec_b64 s[0:1], vcc
	s_cbranch_execz .LBB0_224
	s_lshl_b32 s5, s23, 11
	s_add_i32 s5, s4, s5
	v_mul_f32_e32 v140, 0x3c800000, v137
	v_lshl_add_u32 v137, v136, 5, s5
	s_waitcnt lgkmcnt(0)
	v_add_f32_e32 v141, v138, v139
	ds_write_b64 v137, v[140:141] offset:1024
;     DI void fused(f32x4 (&acc)[2][2][4][2], const Unit& u, int wr, int wc, int fr_, int fq_, LAS unsigned char* lds, int wid, int lane_) const {
;     ...
;             for (int m = 0; m < 4; ++m) {
;                 float sm = 0.f;
; #pragma unroll
;                 for (int bj = 0; bj < 2; ++bj)
; #pragma unroll
;                     for (int n = 0; n < 2; ++n) { const f32x4 x = acc[ai][bj][m][n]; sm += (x[0] + x[1]) + (x[2] + x[3]); }
;                 sm += __shfl_xor(sm, 16); sm += __shfl_xor(sm, 32);
;                 const float mw = sm * (1.0f / 64.0f); float q = 0.f;
; #pragma unroll
;                 for (int bj = 0; bj < 2; ++bj)
; #pragma unroll
;                     for (int n = 0; n < 2; ++n) { const f32x4 d = acc[ai][bj][m][n] - mw; q += (d[0] * d[0] + d[1] * d[1]) + (d[2] * d[2] + d[3] * d[3]); }
;                 q += __shfl_xor(q, 16); q += __shfl_xor(q, 32);
;                 if (fq == 0) P[(ai * HALF + wr * 64 + m * 16 + fr) * 4 + wc] = (f32x2){mw, q};
.LBB0_224:
	s_or_b64 exec, exec, s[0:1]
	v_mov_b32_e32 v138, v83
	s_waitcnt lgkmcnt(0)
	v_mov_b32_e32 v139, v84
	v_mov_b32_e32 v140, v82
	v_mov_b32_e32 v141, v85
	v_pk_add_f32 v[138:139], v[138:139], v[140:141]
	v_mov_b32_e32 v140, v79
	v_mov_b32_e32 v141, v80
	v_mov_b32_e32 v142, v78
	v_mov_b32_e32 v143, v81
	v_pk_add_f32 v[140:141], v[140:141], v[142:143]
	v_add_f32_e32 v137, v138, v139
	v_pk_add_f32 v[140:141], v[140:141], v[140:141] op_sel_hi:[0,1]
	v_add_f32_e32 v139, 0, v137
	v_add_f32_e32 v143, v70, v71
	v_add_f32_e32 v145, v72, v73
	v_mov_b32_e32 v142, v66
	v_mov_b32_e32 v144, v67
	v_mov_b32_e32 v140, v68
	v_mov_b32_e32 v138, v69
	v_pk_add_f32 v[142:143], v[142:143], v[144:145]
	v_pk_add_f32 v[138:139], v[140:141], v[138:139]
	s_nop 0
	v_pk_add_f32 v[138:139], v[142:143], v[138:139]
	s_nop 0
	v_add_f32_e32 v137, v138, v139
	v_mov_b32_e32 v138, v137
	s_nop 1
	v_permlane16_swap_b32_e32 v137, v138
	s_waitcnt lgkmcnt(0)
	v_add_f32_e32 v137, v137, v138
	v_mov_b32_e32 v138, v137
	s_nop 1
	v_permlane32_swap_b32_e32 v137, v138
	s_waitcnt lgkmcnt(0)
	v_add_f32_e32 v137, v137, v138
	v_fmamk_f32 v139, v137, 0xbc800000, v85
	v_fmamk_f32 v141, v137, 0xbc800000, v83
	v_fmamk_f32 v138, v137, 0xbc800000, v84
	v_fmamk_f32 v140, v137, 0xbc800000, v82
	v_mul_f32_e32 v141, v141, v141
	v_mul_f32_e32 v139, v139, v139
	v_fmac_f32_e32 v141, v140, v140
	v_fmac_f32_e32 v139, v138, v138
	v_fmamk_f32 v140, v137, 0xbc800000, v81
	v_fmamk_f32 v142, v137, 0xbc800000, v79
	v_add_f32_e32 v138, v141, v139
	v_fmamk_f32 v139, v137, 0xbc800000, v80
	v_fmamk_f32 v141, v137, 0xbc800000, v78
	v_mul_f32_e32 v142, v142, v142
	v_mul_f32_e32 v140, v140, v140
	v_fmac_f32_e32 v142, v141, v141
	v_fmac_f32_e32 v140, v139, v139
	v_add_f32_e32 v139, v142, v140
	v_fmamk_f32 v140, v137, 0xbc800000, v73
	v_fmamk_f32 v142, v137, 0xbc800000, v71
	v_add_f32_e32 v138, v138, v139
	v_fmamk_f32 v139, v137, 0xbc800000, v72
	v_fmamk_f32 v141, v137, 0xbc800000, v70
	v_mul_f32_e32 v142, v142, v142
	v_mul_f32_e32 v140, v140, v140
	v_fmac_f32_e32 v142, v141, v141
	v_fmac_f32_e32 v140, v139, v139
	v_add_f32_e32 v139, v142, v140
	v_fmamk_f32 v140, v137, 0xbc800000, v69
	v_fmamk_f32 v142, v137, 0xbc800000, v67
	v_add_f32_e32 v138, v139, v138
	v_fmamk_f32 v139, v137, 0xbc800000, v68
	v_fmamk_f32 v141, v137, 0xbc800000, v66
	v_mul_f32_e32 v142, v142, v142
	v_mul_f32_e32 v140, v140, v140
	v_fmac_f32_e32 v142, v141, v141
	v_fmac_f32_e32 v140, v139, v139
	v_add_f32_e32 v139, v142, v140
	v_add_f32_e32 v138, v139, v138
	v_mov_b32_e32 v139, v138
	s_nop 1
	v_permlane16_swap_b32_e32 v138, v139
	s_waitcnt lgkmcnt(0)
	v_add_f32_e32 v138, v138, v139
	v_mov_b32_e32 v139, v138
	s_nop 1
	v_permlane32_swap_b32_e32 v138, v139
	s_and_saveexec_b64 s[0:1], vcc
	s_cbranch_execz .LBB0_226
	s_lshl_b32 s5, s23, 11
	s_add_i32 s5, s4, s5
	v_mul_f32_e32 v140, 0x3c800000, v137
	v_lshl_add_u32 v137, v136, 5, s5
	s_waitcnt lgkmcnt(0)
	v_add_f32_e32 v141, v138, v139
	ds_write_b64 v137, v[140:141] offset:1536
.LBB0_226:
	s_or_b64 exec, exec, s[0:1]
	v_mov_b32_e32 v138, v63
	s_waitcnt lgkmcnt(0)
	v_mov_b32_e32 v139, v64
	v_mov_b32_e32 v140, v62
	v_mov_b32_e32 v141, v65
	v_pk_add_f32 v[138:139], v[138:139], v[140:141]
	v_mov_b32_e32 v140, v59
	v_mov_b32_e32 v141, v60
	v_mov_b32_e32 v142, v58
	v_mov_b32_e32 v143, v61
	v_pk_add_f32 v[140:141], v[140:141], v[142:143]
	v_add_f32_e32 v137, v138, v139
	v_pk_add_f32 v[140:141], v[140:141], v[140:141] op_sel_hi:[0,1]
	v_add_f32_e32 v139, 0, v137
	v_add_f32_e32 v143, v54, v55
	v_add_f32_e32 v145, v56, v57
	v_mov_b32_e32 v142, v50
	v_mov_b32_e32 v144, v51
	v_mov_b32_e32 v140, v52
	v_mov_b32_e32 v138, v53
	v_pk_add_f32 v[142:143], v[142:143], v[144:145]
	v_pk_add_f32 v[138:139], v[140:141], v[138:139]
	s_nop 0
	v_pk_add_f32 v[138:139], v[142:143], v[138:139]
	s_nop 0
	v_add_f32_e32 v137, v138, v139
	v_mov_b32_e32 v138, v137
	s_nop 1
	v_permlane16_swap_b32_e32 v137, v138
	s_waitcnt lgkmcnt(0)
	v_add_f32_e32 v137, v137, v138
	v_mov_b32_e32 v138, v137
	s_nop 1
	v_permlane32_swap_b32_e32 v137, v138
	s_waitcnt lgkmcnt(0)
	v_add_f32_e32 v137, v137, v138
	v_fmamk_f32 v139, v137, 0xbc800000, v65
	v_fmamk_f32 v141, v137, 0xbc800000, v63
	v_fmamk_f32 v138, v137, 0xbc800000, v64
	v_fmamk_f32 v140, v137, 0xbc800000, v62
	v_mul_f32_e32 v141, v141, v141
	v_mul_f32_e32 v139, v139, v139
	v_fmac_f32_e32 v141, v140, v140
	v_fmac_f32_e32 v139, v138, v138
	v_fmamk_f32 v140, v137, 0xbc800000, v61
	v_fmamk_f32 v142, v137, 0xbc800000, v59
	v_add_f32_e32 v138, v141, v139
	v_fmamk_f32 v139, v137, 0xbc800000, v60
	v_fmamk_f32 v141, v137, 0xbc800000, v58
	v_mul_f32_e32 v142, v142, v142
	v_mul_f32_e32 v140, v140, v140
	v_fmac_f32_e32 v142, v141, v141
	v_fmac_f32_e32 v140, v139, v139
	v_add_f32_e32 v139, v142, v140
	v_fmamk_f32 v140, v137, 0xbc800000, v57
	v_fmamk_f32 v142, v137, 0xbc800000, v55
	v_add_f32_e32 v138, v138, v139
	v_fmamk_f32 v139, v137, 0xbc800000, v56
	v_fmamk_f32 v141, v137, 0xbc800000, v54
	v_mul_f32_e32 v142, v142, v142
	v_mul_f32_e32 v140, v140, v140
	v_fmac_f32_e32 v142, v141, v141
	v_fmac_f32_e32 v140, v139, v139
	v_add_f32_e32 v139, v142, v140
	v_fmamk_f32 v140, v137, 0xbc800000, v53
	v_fmamk_f32 v142, v137, 0xbc800000, v51
	v_add_f32_e32 v138, v139, v138
	v_fmamk_f32 v139, v137, 0xbc800000, v52
	v_fmamk_f32 v141, v137, 0xbc800000, v50
	v_mul_f32_e32 v142, v142, v142
	v_mul_f32_e32 v140, v140, v140
	v_fmac_f32_e32 v142, v141, v141
	v_fmac_f32_e32 v140, v139, v139
	v_add_f32_e32 v139, v142, v140
	v_add_f32_e32 v138, v139, v138
	v_mov_b32_e32 v139, v138
	s_nop 1
	v_permlane16_swap_b32_e32 v138, v139
	s_waitcnt lgkmcnt(0)
	v_add_f32_e32 v138, v138, v139
	v_mov_b32_e32 v139, v138
	s_nop 1
	v_permlane32_swap_b32_e32 v138, v139
	s_and_saveexec_b64 s[0:1], vcc
	s_cbranch_execz .LBB0_228
	s_lshl_b32 s5, s23, 11
	s_add_i32 s5, s4, s5
	v_mul_f32_e32 v140, 0x3c800000, v137
	v_lshl_add_u32 v137, v136, 5, s5
	s_waitcnt lgkmcnt(0)
	v_add_f32_e32 v141, v138, v139
	ds_write_b64 v137, v[140:141] offset:4096
;     DI void fused(f32x4 (&acc)[2][2][4][2], const Unit& u, int wr, int wc, int fr_, int fq_, LAS unsigned char* lds, int wid, int lane_) const {
;     ...
;             for (int m = 0; m < 4; ++m) {
;                 float sm = 0.f;
; #pragma unroll
;                 for (int bj = 0; bj < 2; ++bj)
; #pragma unroll
;                     for (int n = 0; n < 2; ++n) { const f32x4 x = acc[ai][bj][m][n]; sm += (x[0] + x[1]) + (x[2] + x[3]); }
;                 sm += __shfl_xor(sm, 16); sm += __shfl_xor(sm, 32);
;                 const float mw = sm * (1.0f / 64.0f); float q = 0.f;
; #pragma unroll
;                 for (int bj = 0; bj < 2; ++bj)
; #pragma unroll
;                     for (int n = 0; n < 2; ++n) { const f32x4 d = acc[ai][bj][m][n] - mw; q += (d[0] * d[0] + d[1] * d[1]) + (d[2] * d[2] + d[3] * d[3]); }
;                 q += __shfl_xor(q, 16); q += __shfl_xor(q, 32);
;                 if (fq == 0) P[(ai * HALF + wr * 64 + m * 16 + fr) * 4 + wc] = (f32x2){mw, q};
.LBB0_228:
	s_or_b64 exec, exec, s[0:1]
	v_mov_b32_e32 v138, v47
	s_waitcnt lgkmcnt(0)
	v_mov_b32_e32 v139, v48
	v_mov_b32_e32 v140, v46
	v_mov_b32_e32 v141, v49
	v_pk_add_f32 v[138:139], v[138:139], v[140:141]
	v_mov_b32_e32 v140, v43
	v_mov_b32_e32 v141, v44
	v_mov_b32_e32 v142, v42
	v_mov_b32_e32 v143, v45
	v_pk_add_f32 v[140:141], v[140:141], v[142:143]
	v_add_f32_e32 v137, v138, v139
	v_pk_add_f32 v[140:141], v[140:141], v[140:141] op_sel_hi:[0,1]
	v_add_f32_e32 v139, 0, v137
	v_add_f32_e32 v143, v38, v39
	v_add_f32_e32 v145, v40, v41
	v_mov_b32_e32 v142, v34
	v_mov_b32_e32 v144, v35
	v_mov_b32_e32 v140, v36
	v_mov_b32_e32 v138, v37
	v_pk_add_f32 v[142:143], v[142:143], v[144:145]
	v_pk_add_f32 v[138:139], v[140:141], v[138:139]
	s_nop 0
	v_pk_add_f32 v[138:139], v[142:143], v[138:139]
	s_nop 0
	v_add_f32_e32 v137, v138, v139
	v_mov_b32_e32 v138, v137
	s_nop 1
	v_permlane16_swap_b32_e32 v137, v138
	s_waitcnt lgkmcnt(0)
	v_add_f32_e32 v137, v137, v138
	v_mov_b32_e32 v138, v137
	s_nop 1
	v_permlane32_swap_b32_e32 v137, v138
	s_waitcnt lgkmcnt(0)
	v_add_f32_e32 v137, v137, v138
	v_fmamk_f32 v139, v137, 0xbc800000, v49
	v_fmamk_f32 v141, v137, 0xbc800000, v47
	v_fmamk_f32 v138, v137, 0xbc800000, v48
	v_fmamk_f32 v140, v137, 0xbc800000, v46
	v_mul_f32_e32 v141, v141, v141
	v_mul_f32_e32 v139, v139, v139
	v_fmac_f32_e32 v141, v140, v140
	v_fmac_f32_e32 v139, v138, v138
	v_fmamk_f32 v140, v137, 0xbc800000, v45
	v_fmamk_f32 v142, v137, 0xbc800000, v43
	v_add_f32_e32 v138, v141, v139
	v_fmamk_f32 v139, v137, 0xbc800000, v44
	v_fmamk_f32 v141, v137, 0xbc800000, v42
	v_mul_f32_e32 v142, v142, v142
	v_mul_f32_e32 v140, v140, v140
	v_fmac_f32_e32 v142, v141, v141
	v_fmac_f32_e32 v140, v139, v139
	v_add_f32_e32 v139, v142, v140
	v_fmamk_f32 v140, v137, 0xbc800000, v41
	v_fmamk_f32 v142, v137, 0xbc800000, v39
	v_add_f32_e32 v138, v138, v139
	v_fmamk_f32 v139, v137, 0xbc800000, v40
	v_fmamk_f32 v141, v137, 0xbc800000, v38
	v_mul_f32_e32 v142, v142, v142
	v_mul_f32_e32 v140, v140, v140
	v_fmac_f32_e32 v142, v141, v141
	v_fmac_f32_e32 v140, v139, v139
	v_add_f32_e32 v139, v142, v140
	v_fmamk_f32 v140, v137, 0xbc800000, v37
	v_fmamk_f32 v142, v137, 0xbc800000, v35
	v_add_f32_e32 v138, v139, v138
	v_fmamk_f32 v139, v137, 0xbc800000, v36
	v_fmamk_f32 v141, v137, 0xbc800000, v34
	v_mul_f32_e32 v142, v142, v142
	v_mul_f32_e32 v140, v140, v140
	v_fmac_f32_e32 v142, v141, v141
	v_fmac_f32_e32 v140, v139, v139
	v_add_f32_e32 v139, v142, v140
	v_add_f32_e32 v138, v139, v138
	v_mov_b32_e32 v139, v138
	s_nop 1
	v_permlane16_swap_b32_e32 v138, v139
	s_waitcnt lgkmcnt(0)
	v_add_f32_e32 v138, v138, v139
	v_mov_b32_e32 v139, v138
	s_nop 1
	v_permlane32_swap_b32_e32 v138, v139
	s_and_saveexec_b64 s[0:1], vcc
	s_cbranch_execz .LBB0_230
	s_lshl_b32 s5, s23, 11
	s_add_i32 s5, s4, s5
	v_mul_f32_e32 v140, 0x3c800000, v137
	v_lshl_add_u32 v137, v136, 5, s5
	s_waitcnt lgkmcnt(0)
	v_add_f32_e32 v141, v138, v139
	ds_write_b64 v137, v[140:141] offset:4608
;     DI void fused(f32x4 (&acc)[2][2][4][2], const Unit& u, int wr, int wc, int fr_, int fq_, LAS unsigned char* lds, int wid, int lane_) const {
;     ...
;             for (int m = 0; m < 4; ++m) {
;                 float sm = 0.f;
; #pragma unroll
;                 for (int bj = 0; bj < 2; ++bj)
; #pragma unroll
;                     for (int n = 0; n < 2; ++n) { const f32x4 x = acc[ai][bj][m][n]; sm += (x[0] + x[1]) + (x[2] + x[3]); }
;                 sm += __shfl_xor(sm, 16); sm += __shfl_xor(sm, 32);
;                 const float mw = sm * (1.0f / 64.0f); float q = 0.f;
; #pragma unroll
;                 for (int bj = 0; bj < 2; ++bj)
; #pragma unroll
;                     for (int n = 0; n < 2; ++n) { const f32x4 d = acc[ai][bj][m][n] - mw; q += (d[0] * d[0] + d[1] * d[1]) + (d[2] * d[2] + d[3] * d[3]); }
;                 q += __shfl_xor(q, 16); q += __shfl_xor(q, 32);
;                 if (fq == 0) P[(ai * HALF + wr * 64 + m * 16 + fr) * 4 + wc] = (f32x2){mw, q};
;                 __builtin_amdgcn_sched_barrier(0);
;             }
.LBB0_230:
	s_or_b64 exec, exec, s[0:1]
	v_mov_b32_e32 v138, v31
	s_waitcnt lgkmcnt(0)
	v_mov_b32_e32 v139, v32
	v_mov_b32_e32 v140, v30
	v_mov_b32_e32 v141, v33
	v_pk_add_f32 v[138:139], v[138:139], v[140:141]
	v_mov_b32_e32 v140, v27
	v_mov_b32_e32 v141, v28
	v_mov_b32_e32 v142, v26
	v_mov_b32_e32 v143, v29
	v_pk_add_f32 v[140:141], v[140:141], v[142:143]
	v_add_f32_e32 v137, v138, v139
	v_pk_add_f32 v[140:141], v[140:141], v[140:141] op_sel_hi:[0,1]
	v_add_f32_e32 v139, 0, v137
	v_add_f32_e32 v143, v22, v23
	v_add_f32_e32 v145, v24, v25
	v_mov_b32_e32 v142, v18
	v_mov_b32_e32 v144, v19
	v_mov_b32_e32 v140, v20
	v_mov_b32_e32 v138, v21
	v_pk_add_f32 v[142:143], v[142:143], v[144:145]
	v_pk_add_f32 v[138:139], v[140:141], v[138:139]
	s_nop 0
	v_pk_add_f32 v[138:139], v[142:143], v[138:139]
	s_nop 0
	v_add_f32_e32 v137, v138, v139
	v_mov_b32_e32 v138, v137
	s_nop 1
	v_permlane16_swap_b32_e32 v137, v138
	s_waitcnt lgkmcnt(0)
	v_add_f32_e32 v137, v137, v138
	v_mov_b32_e32 v138, v137
	s_nop 1
	v_permlane32_swap_b32_e32 v137, v138
	s_waitcnt lgkmcnt(0)
	v_add_f32_e32 v137, v137, v138
	v_fmamk_f32 v139, v137, 0xbc800000, v33
	v_fmamk_f32 v141, v137, 0xbc800000, v31
	v_fmamk_f32 v138, v137, 0xbc800000, v32
	v_fmamk_f32 v140, v137, 0xbc800000, v30
	v_mul_f32_e32 v141, v141, v141
	v_mul_f32_e32 v139, v139, v139
	v_fmac_f32_e32 v141, v140, v140
	v_fmac_f32_e32 v139, v138, v138
	v_fmamk_f32 v140, v137, 0xbc800000, v29
	v_fmamk_f32 v142, v137, 0xbc800000, v27
	v_add_f32_e32 v138, v141, v139
	v_fmamk_f32 v139, v137, 0xbc800000, v28
	v_fmamk_f32 v141, v137, 0xbc800000, v26
	v_mul_f32_e32 v142, v142, v142
	v_mul_f32_e32 v140, v140, v140
	v_fmac_f32_e32 v142, v141, v141
	v_fmac_f32_e32 v140, v139, v139
	v_add_f32_e32 v139, v142, v140
	v_fmamk_f32 v140, v137, 0xbc800000, v25
	v_fmamk_f32 v142, v137, 0xbc800000, v23
	v_add_f32_e32 v138, v138, v139
	v_fmamk_f32 v139, v137, 0xbc800000, v24
	v_fmamk_f32 v141, v137, 0xbc800000, v22
	v_mul_f32_e32 v142, v142, v142
	v_mul_f32_e32 v140, v140, v140
	v_fmac_f32_e32 v142, v141, v141
	v_fmac_f32_e32 v140, v139, v139
	v_add_f32_e32 v139, v142, v140
	v_fmamk_f32 v140, v137, 0xbc800000, v21
	v_fmamk_f32 v142, v137, 0xbc800000, v19
	v_add_f32_e32 v138, v139, v138
	v_fmamk_f32 v139, v137, 0xbc800000, v20
	v_fmamk_f32 v141, v137, 0xbc800000, v18
	v_mul_f32_e32 v142, v142, v142
	v_mul_f32_e32 v140, v140, v140
	v_fmac_f32_e32 v142, v141, v141
	v_fmac_f32_e32 v140, v139, v139
	v_add_f32_e32 v139, v142, v140
	v_add_f32_e32 v138, v139, v138
	v_mov_b32_e32 v139, v138
	s_nop 1
	v_permlane16_swap_b32_e32 v138, v139
	s_waitcnt lgkmcnt(0)
	v_add_f32_e32 v138, v138, v139
	v_mov_b32_e32 v139, v138
	s_nop 1
	v_permlane32_swap_b32_e32 v138, v139
	s_and_saveexec_b64 s[0:1], vcc
	s_cbranch_execz .LBB0_232
	s_lshl_b32 s5, s23, 11
	s_add_i32 s5, s4, s5
	v_mul_f32_e32 v140, 0x3c800000, v137
	v_lshl_add_u32 v137, v136, 5, s5
	s_waitcnt lgkmcnt(0)
	v_add_f32_e32 v141, v138, v139
	ds_write_b64 v137, v[140:141] offset:5120
.LBB0_232:
	s_or_b64 exec, exec, s[0:1]
	v_mov_b32_e32 v138, v15
	s_waitcnt lgkmcnt(0)
	v_mov_b32_e32 v139, v16
	v_mov_b32_e32 v140, v14
	v_mov_b32_e32 v141, v17
	v_pk_add_f32 v[138:139], v[138:139], v[140:141]
	v_mov_b32_e32 v140, v11
	v_mov_b32_e32 v141, v12
	v_mov_b32_e32 v142, v10
	v_mov_b32_e32 v143, v13
	v_pk_add_f32 v[140:141], v[140:141], v[142:143]
	v_add_f32_e32 v137, v138, v139
	v_pk_add_f32 v[140:141], v[140:141], v[140:141] op_sel_hi:[0,1]
	v_add_f32_e32 v139, 0, v137
	v_add_f32_e32 v143, v6, v7
	v_add_f32_e32 v145, v8, v9
	v_mov_b32_e32 v142, v2
	v_mov_b32_e32 v144, v3
	v_mov_b32_e32 v140, v4
	v_mov_b32_e32 v138, v5
	v_pk_add_f32 v[142:143], v[142:143], v[144:145]
	v_pk_add_f32 v[138:139], v[140:141], v[138:139]
	s_nop 0
	v_pk_add_f32 v[138:139], v[142:143], v[138:139]
	s_nop 0
	v_add_f32_e32 v137, v138, v139
	v_mov_b32_e32 v138, v137
	s_nop 1
	v_permlane16_swap_b32_e32 v137, v138
	s_waitcnt lgkmcnt(0)
	v_add_f32_e32 v137, v137, v138
	v_mov_b32_e32 v138, v137
	s_nop 1
	v_permlane32_swap_b32_e32 v137, v138
	s_waitcnt lgkmcnt(0)
	v_add_f32_e32 v137, v137, v138
	v_fmamk_f32 v139, v137, 0xbc800000, v17
	v_fmamk_f32 v141, v137, 0xbc800000, v15
	v_fmamk_f32 v138, v137, 0xbc800000, v16
	v_fmamk_f32 v140, v137, 0xbc800000, v14
	v_mul_f32_e32 v141, v141, v141
	v_mul_f32_e32 v139, v139, v139
	v_fmac_f32_e32 v141, v140, v140
	v_fmac_f32_e32 v139, v138, v138
	v_fmamk_f32 v140, v137, 0xbc800000, v13
	v_fmamk_f32 v142, v137, 0xbc800000, v11
	v_add_f32_e32 v138, v141, v139
	v_fmamk_f32 v139, v137, 0xbc800000, v12
	v_fmamk_f32 v141, v137, 0xbc800000, v10
	v_mul_f32_e32 v142, v142, v142
	v_mul_f32_e32 v140, v140, v140
	v_fmac_f32_e32 v142, v141, v141
	v_fmac_f32_e32 v140, v139, v139
	v_add_f32_e32 v139, v142, v140
	v_fmamk_f32 v140, v137, 0xbc800000, v9
	v_fmamk_f32 v142, v137, 0xbc800000, v7
	v_add_f32_e32 v138, v138, v139
	v_fmamk_f32 v139, v137, 0xbc800000, v8
	v_fmamk_f32 v141, v137, 0xbc800000, v6
	v_mul_f32_e32 v142, v142, v142
	v_mul_f32_e32 v140, v140, v140
	v_fmac_f32_e32 v142, v141, v141
	v_fmac_f32_e32 v140, v139, v139
	v_add_f32_e32 v139, v142, v140
	v_fmamk_f32 v140, v137, 0xbc800000, v5
	v_fmamk_f32 v142, v137, 0xbc800000, v3
	v_add_f32_e32 v138, v139, v138
	v_fmamk_f32 v139, v137, 0xbc800000, v4
	v_fmamk_f32 v141, v137, 0xbc800000, v2
	v_mul_f32_e32 v142, v142, v142
	v_mul_f32_e32 v140, v140, v140
	v_fmac_f32_e32 v142, v141, v141
	v_fmac_f32_e32 v140, v139, v139
	v_add_f32_e32 v139, v142, v140
	v_add_f32_e32 v138, v139, v138
	v_mov_b32_e32 v134, v138
	s_nop 1
	v_permlane16_swap_b32_e32 v138, v134
	s_waitcnt lgkmcnt(0)
	v_add_f32_e32 v134, v138, v134
	v_mov_b32_e32 v135, v134
	s_nop 1
	v_permlane32_swap_b32_e32 v134, v135
	s_and_saveexec_b64 s[0:1], vcc
	s_cbranch_execz .LBB0_234
	s_lshl_b32 s5, s23, 11
	s_add_i32 s4, s4, s5
	v_mul_f32_e32 v138, 0x3c800000, v137
	v_lshl_add_u32 v137, v136, 5, s4
	s_waitcnt lgkmcnt(0)
	v_add_f32_e32 v139, v134, v135
	ds_write_b64 v137, v[138:139] offset:5632

; DI float bflo(unsigned w) { return __uint_as_float(w << 16); }
; DI float bfhi(unsigned w) { return __uint_as_float(w & 0xffff0000u); }
; DI float silu_f(float g) { return g * frcp(1.f + fexp2(-1.4426950408889634f * g)); }
;     ...
;     for (int which = 0; which < 3; ++which) {
;         const int t = tid >> 3, cg8 = tid & 7; const int col = which * 512 + h * 64 + cg8 * 8;
;         float acc[8];
; #pragma unroll
;         for (int e = 0; e < 8; ++e) acc[e] = 0.f;
; #pragma unroll
;         for (int j = 0; j < 4; ++j) { const int sp = n * 64 + t - 3 + j; const float ok = sp >= 0 ? 1.f : 0.f;
;             const u32x4 xv = xin[which * 4 + j];
;             const f32x4 w0 = *(const f32x4*)(conv_w + j * 1536 + col) * ok, w1 = *(const f32x4*)(conv_w + j * 1536 + col + 4) * ok;
;             acc[0] += w0[0] * bflo(xv.x); acc[1] += w0[1] * bfhi(xv.x); acc[2] += w0[2] * bflo(xv.y); acc[3] += w0[3] * bfhi(xv.y);
;             acc[4] += w1[0] * bflo(xv.z); acc[5] += w1[1] * bfhi(xv.z); acc[6] += w1[2] * bflo(xv.w); acc[7] += w1[3] * bfhi(xv.w); }
; #pragma unroll
;         for (int e = 0; e < 8; ++e) acc[e] = silu_f(acc[e]);
.LBB0_434:
	s_lshl_b32 s19, s2, 6
	s_and_b32 s19, s19, 0xfc0
	v_add_u32_e32 v2, s19, v110
	v_cmp_lt_u32_e32 vcc, 2, v2
	s_bfe_u32 s3, s2, 0x30006
	s_bfe_u32 s100, s70, 0x30006
	s_xor_b32 s100, s100, s3
	s_mul_i32 s100, s100, 0x300
	v_lshlrev_b32_e32 v255, 2, v111
	v_add_u32_e32 v255, s100, v255
	v_add_u32_e32 v255, 0x24100, v255
	s_movk_i32 s19, 0x1000
	v_cndmask_b32_e64 v26, 0, 1.0, vcc
	v_cmp_lt_u32_e32 vcc, 1, v2
	s_mov_b64 s[42:43], 0x1800
	s_waitcnt vmcnt(0)
	s_lshl_b32 s101, s3, 2
	v_mov_b32_e32 v254, s101
	v_readlane_b32 s100, v247, 9
	v_readlane_b32 s101, v247, 10
	global_load_dword v252, v254, s[50:51]
	s_nop 4
	global_load_dword v253, v254, s[100:101]
	v_lshlrev_b32_e32 v208, 16, v54
	v_cndmask_b32_e64 v24, 0, 1.0, vcc
	v_cmp_eq_u32_e32 vcc, 0, v2
	v_lshlrev_b32_e32 v2, 2, v111
	v_lshl_or_b32 v82, s3, 8, v2
	ds_read_b128 v[18:21], v255 offset:0
	ds_read_b128 v[2:5], v255 offset:16
	v_lshl_add_u64 v[14:15], s[48:49], 0, v[82:83]
	v_cndmask_b32_e64 v22, 1.0, 0, vcc
	v_and_b32_e32 v209, 0xffff0000, v54
	s_waitcnt lgkmcnt(0)
	v_pk_mul_f32 v[18:19], v[26:27], v[18:19] op_sel_hi:[0,1]
	s_waitcnt lgkmcnt(0)
	v_pk_mul_f32 v[10:11], v[2:3], v[26:27] op_sel_hi:[1,0]
	v_add_co_u32_e32 v2, vcc, s19, v14
	v_pk_mul_f32 v[8:9], v[4:5], v[26:27] op_sel_hi:[1,0]
	v_lshl_add_u64 v[4:5], v[14:15], 0, s[42:43]
	v_addc_co_u32_e32 v3, vcc, 0, v15, vcc
	ds_read_b128 v[28:31], v255 offset:768
	s_nop 0
	ds_read_b128 v[4:7], v255 offset:784
	s_movk_i32 s19, 0x3000
	s_mov_b64 s[42:43], 0x3000
	v_lshl_add_u64 v[32:33], v[14:15], 0, s[42:43]
	s_mov_b64 s[42:43], 0x4800
	v_lshl_add_u64 v[200:201], v[14:15], 0, s[42:43]
	v_pk_mul_f32 v[20:21], v[26:27], v[20:21] op_sel_hi:[0,1]
	s_mov_b64 s[42:43], 0x2000
	s_waitcnt lgkmcnt(0)
	v_pk_mul_f32 v[28:29], v[24:25], v[28:29] op_sel_hi:[0,1]
	s_waitcnt lgkmcnt(0)
	v_pk_mul_f32 v[12:13], v[6:7], v[24:25] op_sel_hi:[1,0]
	v_add_co_u32_e32 v6, vcc, s19, v14
	s_movk_i32 s19, 0x4000
	s_nop 0
	v_addc_co_u32_e32 v7, vcc, 0, v15, vcc
	v_pk_mul_f32 v[16:17], v[4:5], v[24:25] op_sel_hi:[1,0]
	v_add_co_u32_e32 v4, vcc, s19, v14
	v_pk_mul_f32 v[30:31], v[24:25], v[30:31] op_sel_hi:[0,1]
	s_nop 0
	v_addc_co_u32_e32 v5, vcc, 0, v15, vcc
	ds_read_b128 v[94:97], v255 offset:1536
	ds_read_b128 v[196:199], v255 offset:1552
	s_movk_i32 s19, 0x2000
	s_waitcnt lgkmcnt(0)
	v_pk_mul_f32 v[94:95], v[22:23], v[94:95] op_sel_hi:[0,1]
	s_waitcnt lgkmcnt(0)
	v_pk_mul_f32 v[32:33], v[198:199], v[22:23] op_sel_hi:[1,0]
	v_pk_mul_f32 v[98:99], v[196:197], v[22:23] op_sel_hi:[1,0]
	ds_read_b128 v[196:199], v255 offset:2304
	ds_read_b128 v[204:207], v255 offset:2320
	v_lshlrev_b32_e32 v200, 16, v70
	v_and_b32_e32 v201, 0xffff0000, v70
	v_pk_fma_f32 v[18:19], v[18:19], v[200:201], 0 op_sel_hi:[1,1,0]
	v_lshlrev_b32_e32 v200, 16, v74
	v_and_b32_e32 v201, 0xffff0000, v74
	v_pk_fma_f32 v[18:19], v[28:29], v[200:201], v[18:19]
	v_lshlrev_b32_e32 v28, 16, v58
	v_and_b32_e32 v29, 0xffff0000, v58
	v_pk_fma_f32 v[18:19], v[94:95], v[28:29], v[18:19]
	v_lshlrev_b32_e32 v28, 16, v78
	v_and_b32_e32 v29, 0xffff0000, v78
	v_pk_mul_f32 v[96:97], v[22:23], v[96:97] op_sel_hi:[0,1]
	s_waitcnt lgkmcnt(0)
	v_pk_fma_f32 v[18:19], v[196:197], v[28:29], v[18:19]
	s_nop 0
	v_mul_f32_e32 v23, 0xbfb8aa3b, v18
	v_exp_f32_e32 v23, v23
	s_nop 0
	v_add_f32_e32 v23, 1.0, v23
	v_rcp_f32_e32 v28, v23
	v_mul_f32_e32 v23, 0xbfb8aa3b, v19
	v_exp_f32_e32 v23, v23
	s_nop 0
	v_add_f32_e32 v23, 1.0, v23
	v_rcp_f32_e32 v29, v23
	s_nop 0
	v_pk_mul_f32 v[28:29], v[18:19], v[28:29]
	v_lshlrev_b32_e32 v18, 16, v71
	v_and_b32_e32 v19, 0xffff0000, v71
	v_pk_fma_f32 v[18:19], v[20:21], v[18:19], 0 op_sel_hi:[1,1,0]
	v_lshlrev_b32_e32 v20, 16, v75
	v_and_b32_e32 v21, 0xffff0000, v75
	v_pk_fma_f32 v[18:19], v[30:31], v[20:21], v[18:19]
	v_lshlrev_b32_e32 v20, 16, v59
	v_and_b32_e32 v21, 0xffff0000, v59
	v_pk_fma_f32 v[18:19], v[96:97], v[20:21], v[18:19]
	v_lshlrev_b32_e32 v20, 16, v79
	v_and_b32_e32 v21, 0xffff0000, v79
	v_pk_fma_f32 v[18:19], v[198:199], v[20:21], v[18:19]
	s_nop 0
	v_mul_f32_e32 v20, 0xbfb8aa3b, v18
	v_mul_f32_e32 v21, 0xbfb8aa3b, v19
	v_exp_f32_e32 v20, v20
	v_exp_f32_e32 v21, v21
	v_add_f32_e32 v20, 1.0, v20
	v_add_f32_e32 v21, 1.0, v21
	v_rcp_f32_e32 v20, v20
	v_rcp_f32_e32 v21, v21
	s_nop 0
	v_pk_mul_f32 v[20:21], v[18:19], v[20:21]
	v_lshlrev_b32_e32 v18, 16, v72
	v_and_b32_e32 v19, 0xffff0000, v72
	v_pk_fma_f32 v[10:11], v[10:11], v[18:19], 0 op_sel_hi:[1,1,0]
	v_lshlrev_b32_e32 v18, 16, v76
	v_and_b32_e32 v19, 0xffff0000, v76
	v_pk_fma_f32 v[10:11], v[16:17], v[18:19], v[10:11]
	v_lshlrev_b32_e32 v16, 16, v60
	v_and_b32_e32 v17, 0xffff0000, v60
	v_pk_fma_f32 v[10:11], v[98:99], v[16:17], v[10:11]
	v_lshlrev_b32_e32 v16, 16, v80
	v_and_b32_e32 v17, 0xffff0000, v80
	s_waitcnt lgkmcnt(0)
; #define LAS __attribute__((address_space(3)))
; DI unsigned pk2(float lo, float hi) { typedef __bf16 b2 __attribute__((ext_vector_type(2))); f32x2 v = {lo, hi}; b2 b = __builtin_convertvector(v, b2); return __builtin_bit_cast(unsigned, b); }
; DI float bflo(unsigned w) { return __uint_as_float(w << 16); }
; DI float bfhi(unsigned w) { return __uint_as_float(w & 0xffff0000u); }
; DI float silu_f(float g) { return g * frcp(1.f + fexp2(-1.4426950408889634f * g)); }
;     ...
;             acc[4] += w1[0] * bflo(xv.z); acc[5] += w1[1] * bfhi(xv.z); acc[6] += w1[2] * bflo(xv.w); acc[7] += w1[3] * bfhi(xv.w); }
; #pragma unroll
;         for (int e = 0; e < 8; ++e) acc[e] = silu_f(acc[e]);
;         if (which == 2) { LAS float* dst = vc + t * 68 + cg8 * 8; *(LAS f32x4*)dst = (f32x4){acc[0], acc[1], acc[2], acc[3]}; *(LAS f32x4*)(dst + 4) = (f32x4){acc[4], acc[5], acc[6], acc[7]}; }
;         else {
;             float ss = (acc[0] * acc[0] + acc[1] * acc[1]) + (acc[2] * acc[2] + acc[3] * acc[3]) + (acc[4] * acc[4] + acc[5] * acc[5]) + (acc[6] * acc[6] + acc[7] * acc[7]);
;             ss += __shfl_xor(ss, 1); ss += __shfl_xor(ss, 2); ss += __shfl_xor(ss, 4);
;             const float sc = (which ? 1.0f : 0.125f) * __builtin_amdgcn_rsqf(ss + 1e-6f);
;             const f32x4 y0 = (f32x4){acc[0], acc[1], acc[2], acc[3]} * sc, y1 = (f32x4){acc[4], acc[5], acc[6], acc[7]} * sc;
;             LAS float* dst = (which ? kc : qc) + t * 68 + cg8 * 8; *(LAS f32x4*)dst = y0; *(LAS f32x4*)(dst + 4) = y1;
;             u32x4 hh; hh.x = pk2(y0[0], y0[1]); hh.y = pk2(y0[2], y0[3]); hh.z = pk2(y1[0], y1[1]); hh.w = pk2(y1[2], y1[3]);
;             u32x4 lo; lo.x = pk2(y0[0] - bflo(hh.x), y0[1] - bfhi(hh.x)); lo.y = pk2(y0[2] - bflo(hh.y), y0[3] - bfhi(hh.y)); lo.z = pk2(y1[0] - bflo(hh.z), y1[1] - bfhi(hh.z)); lo.w = pk2(y1[2] - bflo(hh.w), y1[3] - bfhi(hh.w));
;             *(LAS u32x4*)((which ? KH : QH) + t * 72 + cg8 * 8) = hh; *(LAS u32x4*)((which ? KL : QL) + t * 72 + cg8 * 8) = lo; }
	v_pk_fma_f32 v[10:11], v[204:205], v[16:17], v[10:11]
	v_add_co_u32_e32 v98, vcc, s19, v14
	v_mul_f32_e32 v16, 0xbfb8aa3b, v10
	v_mul_f32_e32 v17, 0xbfb8aa3b, v11
	v_exp_f32_e32 v16, v16
	v_exp_f32_e32 v17, v17
	v_addc_co_u32_e32 v99, vcc, 0, v15, vcc
	v_add_f32_e32 v16, 1.0, v16
	v_add_f32_e32 v17, 1.0, v17
	v_rcp_f32_e32 v16, v16
	v_rcp_f32_e32 v17, v17
	s_movk_i32 s19, 0x5000
	v_pk_mul_f32 v[30:31], v[10:11], v[16:17]
	v_lshlrev_b32_e32 v10, 16, v73
	v_and_b32_e32 v11, 0xffff0000, v73
	v_pk_fma_f32 v[8:9], v[8:9], v[10:11], 0 op_sel_hi:[1,1,0]
	v_lshlrev_b32_e32 v10, 16, v77
	v_and_b32_e32 v11, 0xffff0000, v77
	v_pk_fma_f32 v[8:9], v[12:13], v[10:11], v[8:9]
	v_lshlrev_b32_e32 v10, 16, v61
	v_and_b32_e32 v11, 0xffff0000, v61
	v_pk_fma_f32 v[8:9], v[32:33], v[10:11], v[8:9]
	v_lshlrev_b32_e32 v10, 16, v81
	v_and_b32_e32 v11, 0xffff0000, v81
	v_pk_fma_f32 v[8:9], v[206:207], v[10:11], v[8:9]
	v_mov_b32_e32 v17, v31
	v_mul_f32_e32 v10, 0xbfb8aa3b, v9
	v_exp_f32_e32 v10, v10
	s_nop 0
	v_add_f32_e32 v10, 1.0, v10
	v_rcp_f32_e32 v11, v10
	v_mul_f32_e32 v10, 0xbfb8aa3b, v8
	v_exp_f32_e32 v10, v10
	s_nop 0
	v_add_f32_e32 v10, 1.0, v10
	v_rcp_f32_e32 v10, v10
	s_nop 0
	v_pk_mul_f32 v[12:13], v[8:9], v[10:11]
	v_mov_b32_e32 v10, v29
	v_mov_b32_e32 v11, v21
	v_mov_b32_e32 v8, v28
	v_mov_b32_e32 v9, v20
	v_pk_mul_f32 v[10:11], v[10:11], v[10:11]
	v_mov_b32_e32 v16, v13
	v_pk_fma_f32 v[8:9], v[8:9], v[8:9], v[10:11]
	v_mov_b32_e32 v10, v12
	v_mov_b32_e32 v11, v30
	v_pk_mul_f32 v[16:17], v[16:17], v[16:17]
	v_add_f32_e32 v8, v8, v9
	v_pk_fma_f32 v[10:11], v[10:11], v[10:11], v[16:17]
	s_nop 0
	v_add_f32_e32 v8, v11, v8
	v_add_f32_e32 v8, v10, v8
	s_nop 1
	v_add_f32_dpp v8, v8, v8 quad_perm:[1,0,3,2] row_mask:0xf bank_mask:0xf
	s_nop 1
	v_add_f32_dpp v8, v8, v8 quad_perm:[2,3,0,1] row_mask:0xf bank_mask:0xf
	s_nop 1
	v_add_f32_dpp v8, v8, v8 row_half_mirror row_mask:0xf bank_mask:0xf
	v_add_f32_e32 v8, 0x358637bd, v8
	v_rsq_f32_e32 v8, v8
	s_nop 0
	v_mul_f32_e32 v32, 0x3e000000, v8
	v_pk_mul_f32 v[10:11], v[20:21], v[32:33] op_sel_hi:[1,0]
	v_pk_mul_f32 v[8:9], v[28:29], v[32:33] op_sel_hi:[1,0]
	v_pk_mul_f32 v[18:19], v[12:13], v[32:33] op_sel_hi:[1,0]
	v_pk_mul_f32 v[16:17], v[30:31], v[32:33] op_sel_hi:[1,0]
	ds_write_b128 v112, v[8:11]
	ds_write_b128 v112, v[16:19] offset:16
	v_cvt_pk_bf16_f32 v8, v8, v9
	v_cvt_pk_bf16_f32 v9, v10, v11
	v_cvt_pk_bf16_f32 v10, v16, v17
	v_cvt_pk_bf16_f32 v11, v18, v19
	v_lshlrev_b32_e32 v16, 16, v8
	v_and_b32_e32 v17, 0xffff0000, v8
	v_lshlrev_b32_e32 v18, 16, v9
	v_and_b32_e32 v19, 0xffff0000, v9
	v_pk_fma_f32 v[16:17], v[28:29], v[32:33], v[16:17] op_sel_hi:[1,0,1] neg_lo:[0,0,1] neg_hi:[0,0,1]
	v_pk_fma_f32 v[18:19], v[20:21], v[32:33], v[18:19] op_sel_hi:[1,0,1] neg_lo:[0,0,1] neg_hi:[0,0,1]
	v_cvt_pk_bf16_f32 v16, v16, v17
	v_cvt_pk_bf16_f32 v17, v18, v19
	v_lshlrev_b32_e32 v18, 16, v10
	v_and_b32_e32 v19, 0xffff0000, v10
	v_lshlrev_b32_e32 v20, 16, v11
	v_and_b32_e32 v21, 0xffff0000, v11
	v_pk_fma_f32 v[18:19], v[30:31], v[32:33], v[18:19] op_sel_hi:[1,0,1] neg_lo:[0,0,1] neg_hi:[0,0,1]
	v_pk_fma_f32 v[12:13], v[12:13], v[32:33], v[20:21] op_sel_hi:[1,0,1] neg_lo:[0,0,1] neg_hi:[0,0,1]
	v_cvt_pk_bf16_f32 v18, v18, v19
	v_cvt_pk_bf16_f32 v19, v12, v13
	ds_write_b128 v113, v[8:11]
	ds_write_b128 v114, v[16:19]
	ds_read_b128 v[8:11], v255 offset:256
	ds_read_b128 v[16:19], v255 offset:272
	s_waitcnt lgkmcnt(0)
	v_pk_mul_f32 v[8:9], v[26:27], v[8:9] op_sel_hi:[0,1]
	s_waitcnt lgkmcnt(0)
	v_pk_mul_f32 v[12:13], v[26:27], v[18:19] op_sel_hi:[0,1]
	v_pk_mul_f32 v[32:33], v[26:27], v[16:17] op_sel_hi:[0,1]
	v_lshl_add_u64 v[16:17], v[14:15], 0, s[42:43]
	ds_read_b128 v[18:21], v255 offset:1024
	ds_read_b128 v[28:31], v255 offset:1040
	s_mov_b64 s[42:43], 0x3800
	v_lshl_add_u64 v[16:17], v[14:15], 0, s[42:43]
	s_mov_b64 s[42:43], 0x5000
	v_lshl_add_u64 v[196:197], v[14:15], 0, s[42:43]
	v_pk_fma_f32 v[8:9], v[8:9], v[208:209], 0 op_sel_hi:[1,1,0]
	v_lshlrev_b32_e32 v208, 16, v62
	v_and_b32_e32 v209, 0xffff0000, v62
	v_pk_mul_f32 v[10:11], v[26:27], v[10:11] op_sel_hi:[0,1]
	s_mov_b64 s[42:43], 0x1000
	s_waitcnt lgkmcnt(0)
	v_pk_mul_f32 v[18:19], v[24:25], v[18:19] op_sel_hi:[0,1]
	s_waitcnt lgkmcnt(0)
	v_pk_mul_f32 v[200:201], v[24:25], v[30:31] op_sel_hi:[0,1]
	v_pk_mul_f32 v[204:205], v[24:25], v[28:29] op_sel_hi:[0,1]
	ds_read_b128 v[28:31], v255 offset:1792
	ds_read_b128 v[94:97], v255 offset:1808
	v_add_co_u32_e32 v16, vcc, s19, v14
	v_pk_fma_f32 v[8:9], v[18:19], v[208:209], v[8:9]
	s_nop 0
	v_addc_co_u32_e32 v17, vcc, 0, v15, vcc
	v_lshlrev_b32_e32 v18, 16, v50
	v_and_b32_e32 v19, 0xffff0000, v50
	v_pk_mul_f32 v[20:21], v[24:25], v[20:21] op_sel_hi:[0,1]
	s_andn2_b64 vcc, exec, s[20:21]
	s_waitcnt lgkmcnt(0)
	v_pk_mul_f32 v[28:29], v[22:23], v[28:29] op_sel_hi:[0,1]
	s_waitcnt lgkmcnt(0)
	v_pk_mul_f32 v[6:7], v[22:23], v[96:97] op_sel_hi:[0,1]
	v_pk_mul_f32 v[206:207], v[22:23], v[94:95] op_sel_hi:[0,1]
	ds_read_b128 v[94:97], v255 offset:2560
	s_nop 0
	ds_read_b128 v[196:199], v255 offset:2576
	v_pk_fma_f32 v[8:9], v[28:29], v[18:19], v[8:9]
	v_lshlrev_b32_e32 v18, 16, v66
	v_and_b32_e32 v19, 0xffff0000, v66
	v_pk_mul_f32 v[30:31], v[22:23], v[30:31] op_sel_hi:[0,1]
	s_waitcnt lgkmcnt(0)
; #define LAS __attribute__((address_space(3)))
; DI unsigned pk2(float lo, float hi) { typedef __bf16 b2 __attribute__((ext_vector_type(2))); f32x2 v = {lo, hi}; b2 b = __builtin_convertvector(v, b2); return __builtin_bit_cast(unsigned, b); }
; DI float bflo(unsigned w) { return __uint_as_float(w << 16); }
; DI float bfhi(unsigned w) { return __uint_as_float(w & 0xffff0000u); }
; DI float silu_f(float g) { return g * frcp(1.f + fexp2(-1.4426950408889634f * g)); }
;     ...
;             acc[4] += w1[0] * bflo(xv.z); acc[5] += w1[1] * bfhi(xv.z); acc[6] += w1[2] * bflo(xv.w); acc[7] += w1[3] * bfhi(xv.w); }
; #pragma unroll
;         for (int e = 0; e < 8; ++e) acc[e] = silu_f(acc[e]);
;         if (which == 2) { LAS float* dst = vc + t * 68 + cg8 * 8; *(LAS f32x4*)dst = (f32x4){acc[0], acc[1], acc[2], acc[3]}; *(LAS f32x4*)(dst + 4) = (f32x4){acc[4], acc[5], acc[6], acc[7]}; }
;         else {
;             float ss = (acc[0] * acc[0] + acc[1] * acc[1]) + (acc[2] * acc[2] + acc[3] * acc[3]) + (acc[4] * acc[4] + acc[5] * acc[5]) + (acc[6] * acc[6] + acc[7] * acc[7]);
;             ss += __shfl_xor(ss, 1); ss += __shfl_xor(ss, 2); ss += __shfl_xor(ss, 4);
;             const float sc = (which ? 1.0f : 0.125f) * __builtin_amdgcn_rsqf(ss + 1e-6f);
;             const f32x4 y0 = (f32x4){acc[0], acc[1], acc[2], acc[3]} * sc, y1 = (f32x4){acc[4], acc[5], acc[6], acc[7]} * sc;
;             LAS float* dst = (which ? kc : qc) + t * 68 + cg8 * 8; *(LAS f32x4*)dst = y0; *(LAS f32x4*)(dst + 4) = y1;
;             u32x4 hh; hh.x = pk2(y0[0], y0[1]); hh.y = pk2(y0[2], y0[3]); hh.z = pk2(y1[0], y1[1]); hh.w = pk2(y1[2], y1[3]);
;             u32x4 lo; lo.x = pk2(y0[0] - bflo(hh.x), y0[1] - bfhi(hh.x)); lo.y = pk2(y0[2] - bflo(hh.y), y0[3] - bfhi(hh.y)); lo.z = pk2(y1[0] - bflo(hh.z), y1[1] - bfhi(hh.z)); lo.w = pk2(y1[2] - bflo(hh.w), y1[3] - bfhi(hh.w));
;             *(LAS u32x4*)((which ? KH : QH) + t * 72 + cg8 * 8) = hh; *(LAS u32x4*)((which ? KL : QL) + t * 72 + cg8 * 8) = lo; }
	v_pk_fma_f32 v[8:9], v[94:95], v[18:19], v[8:9]
	s_nop 0
	v_mul_f32_e32 v18, 0xbfb8aa3b, v8
	v_mul_f32_e32 v19, 0xbfb8aa3b, v9
	v_exp_f32_e32 v18, v18
	v_exp_f32_e32 v19, v19
	v_add_f32_e32 v18, 1.0, v18
	v_add_f32_e32 v19, 1.0, v19
	v_rcp_f32_e32 v18, v18
	v_rcp_f32_e32 v19, v19
	s_nop 0
	v_pk_mul_f32 v[18:19], v[8:9], v[18:19]
	v_lshlrev_b32_e32 v8, 16, v55
	v_and_b32_e32 v9, 0xffff0000, v55
	v_pk_fma_f32 v[8:9], v[10:11], v[8:9], 0 op_sel_hi:[1,1,0]
	v_lshlrev_b32_e32 v10, 16, v63
	v_and_b32_e32 v11, 0xffff0000, v63
	v_pk_fma_f32 v[8:9], v[20:21], v[10:11], v[8:9]
	v_lshlrev_b32_e32 v10, 16, v51
	v_and_b32_e32 v11, 0xffff0000, v51
	v_pk_fma_f32 v[8:9], v[30:31], v[10:11], v[8:9]
	v_lshlrev_b32_e32 v10, 16, v67
	v_and_b32_e32 v11, 0xffff0000, v67
	v_pk_fma_f32 v[8:9], v[96:97], v[10:11], v[8:9]
	s_nop 0
	v_mul_f32_e32 v10, 0xbfb8aa3b, v8
	v_mul_f32_e32 v11, 0xbfb8aa3b, v9
	v_exp_f32_e32 v10, v10
	v_exp_f32_e32 v11, v11
	v_add_f32_e32 v10, 1.0, v10
	v_add_f32_e32 v11, 1.0, v11
	v_rcp_f32_e32 v10, v10
	v_rcp_f32_e32 v11, v11
	s_nop 0
	v_pk_mul_f32 v[20:21], v[8:9], v[10:11]
	v_lshlrev_b32_e32 v8, 16, v56
	v_and_b32_e32 v9, 0xffff0000, v56
	v_pk_fma_f32 v[8:9], v[32:33], v[8:9], 0 op_sel_hi:[1,1,0]
	v_lshlrev_b32_e32 v10, 16, v64
	v_and_b32_e32 v11, 0xffff0000, v64
	v_pk_fma_f32 v[8:9], v[204:205], v[10:11], v[8:9]
	v_lshlrev_b32_e32 v10, 16, v52
	v_and_b32_e32 v11, 0xffff0000, v52
	v_pk_fma_f32 v[8:9], v[206:207], v[10:11], v[8:9]
	v_lshlrev_b32_e32 v10, 16, v68
	v_and_b32_e32 v11, 0xffff0000, v68
	s_waitcnt lgkmcnt(0)
	v_pk_fma_f32 v[8:9], v[196:197], v[10:11], v[8:9]
	s_nop 0
	v_mul_f32_e32 v10, 0xbfb8aa3b, v8
	v_mul_f32_e32 v11, 0xbfb8aa3b, v9
	v_exp_f32_e32 v10, v10
	v_exp_f32_e32 v11, v11
	v_add_f32_e32 v10, 1.0, v10
	v_add_f32_e32 v11, 1.0, v11
	v_rcp_f32_e32 v10, v10
	v_rcp_f32_e32 v11, v11
	s_nop 0
	v_pk_mul_f32 v[28:29], v[8:9], v[10:11]
	v_lshlrev_b32_e32 v8, 16, v57
	v_and_b32_e32 v9, 0xffff0000, v57
	v_pk_fma_f32 v[8:9], v[12:13], v[8:9], 0 op_sel_hi:[1,1,0]
	v_lshlrev_b32_e32 v10, 16, v65
	v_and_b32_e32 v11, 0xffff0000, v65
	v_pk_fma_f32 v[8:9], v[200:201], v[10:11], v[8:9]
	v_lshlrev_b32_e32 v10, 16, v53
	v_and_b32_e32 v11, 0xffff0000, v53
	v_pk_fma_f32 v[6:7], v[6:7], v[10:11], v[8:9]
	v_lshlrev_b32_e32 v8, 16, v69
	v_and_b32_e32 v9, 0xffff0000, v69
	v_pk_fma_f32 v[6:7], v[198:199], v[8:9], v[6:7]
	v_mov_b32_e32 v11, v29
	v_mul_f32_e32 v8, 0xbfb8aa3b, v7
	v_exp_f32_e32 v8, v8
	s_nop 0
	v_add_f32_e32 v8, 1.0, v8
	v_rcp_f32_e32 v9, v8
	v_mul_f32_e32 v8, 0xbfb8aa3b, v6
	v_exp_f32_e32 v8, v8
	s_nop 0
	v_add_f32_e32 v8, 1.0, v8
	v_rcp_f32_e32 v8, v8
	s_nop 0
	v_pk_mul_f32 v[30:31], v[6:7], v[8:9]
	v_mov_b32_e32 v8, v19
	v_mov_b32_e32 v9, v21
	v_mov_b32_e32 v6, v18
	v_mov_b32_e32 v7, v20
	v_pk_mul_f32 v[8:9], v[8:9], v[8:9]
	v_mov_b32_e32 v10, v31
	v_pk_fma_f32 v[6:7], v[6:7], v[6:7], v[8:9]
	v_mov_b32_e32 v8, v30
	v_mov_b32_e32 v9, v28
	v_pk_mul_f32 v[10:11], v[10:11], v[10:11]
	v_add_f32_e32 v6, v6, v7
	v_pk_fma_f32 v[8:9], v[8:9], v[8:9], v[10:11]
	s_nop 0
	v_add_f32_e32 v6, v9, v6
	v_add_f32_e32 v6, v8, v6
	s_nop 1
	v_add_f32_dpp v6, v6, v6 quad_perm:[1,0,3,2] row_mask:0xf bank_mask:0xf
	s_nop 1
	v_add_f32_dpp v6, v6, v6 quad_perm:[2,3,0,1] row_mask:0xf bank_mask:0xf
	s_nop 1
	v_add_f32_dpp v6, v6, v6 row_half_mirror row_mask:0xf bank_mask:0xf
	v_add_f32_e32 v6, 0x358637bd, v6
	v_rsq_f32_e32 v32, v6
	s_nop 0
	v_pk_mul_f32 v[8:9], v[20:21], v[32:33] op_sel_hi:[1,0]
	v_pk_mul_f32 v[6:7], v[18:19], v[32:33] op_sel_hi:[1,0]
	v_pk_mul_f32 v[12:13], v[30:31], v[32:33] op_sel_hi:[1,0]
	v_pk_mul_f32 v[10:11], v[28:29], v[32:33] op_sel_hi:[1,0]
	ds_write_b128 v112, v[6:9] offset:17408
	ds_write_b128 v112, v[10:13] offset:17424
	v_cvt_pk_bf16_f32 v6, v6, v7
	v_cvt_pk_bf16_f32 v7, v8, v9
	v_cvt_pk_bf16_f32 v8, v10, v11
	v_cvt_pk_bf16_f32 v9, v12, v13
	v_lshlrev_b32_e32 v10, 16, v6
	v_and_b32_e32 v11, 0xffff0000, v6
	v_lshlrev_b32_e32 v12, 16, v7
	v_and_b32_e32 v13, 0xffff0000, v7
	v_pk_fma_f32 v[10:11], v[18:19], v[32:33], v[10:11] op_sel_hi:[1,0,1] neg_lo:[0,0,1] neg_hi:[0,0,1]
	v_pk_fma_f32 v[12:13], v[20:21], v[32:33], v[12:13] op_sel_hi:[1,0,1] neg_lo:[0,0,1] neg_hi:[0,0,1]
	v_cvt_pk_bf16_f32 v10, v10, v11
	v_cvt_pk_bf16_f32 v11, v12, v13
	v_lshlrev_b32_e32 v12, 16, v8
	v_and_b32_e32 v13, 0xffff0000, v8
	v_lshlrev_b32_e32 v18, 16, v9
	v_and_b32_e32 v19, 0xffff0000, v9
	v_pk_fma_f32 v[12:13], v[28:29], v[32:33], v[12:13] op_sel_hi:[1,0,1] neg_lo:[0,0,1] neg_hi:[0,0,1]
	v_pk_fma_f32 v[18:19], v[30:31], v[32:33], v[18:19] op_sel_hi:[1,0,1] neg_lo:[0,0,1] neg_hi:[0,0,1]
	v_cvt_pk_bf16_f32 v12, v12, v13
	v_cvt_pk_bf16_f32 v13, v18, v19
	ds_write_b128 v115, v[6:9]
	ds_write_b128 v116, v[10:13]
	v_lshl_add_u64 v[10:11], v[14:15], 0, s[42:43]
	ds_read_b128 v[6:9], v255 offset:512
	s_nop 0
	ds_read_b128 v[10:13], v255 offset:528
	s_mov_b64 s[42:43], 0x2800
	v_lshl_add_u64 v[2:3], v[14:15], 0, s[42:43]
	s_mov_b64 s[42:43], 0x5800
	s_waitcnt lgkmcnt(0)
	v_pk_mul_f32 v[6:7], v[26:27], v[6:7] op_sel_hi:[0,1]
	s_waitcnt lgkmcnt(0)
	v_pk_mul_f32 v[28:29], v[26:27], v[12:13] op_sel_hi:[0,1]
	v_pk_mul_f32 v[94:95], v[26:27], v[10:11] op_sel_hi:[0,1]
	ds_read_b128 v[10:13], v255 offset:1280
	ds_read_b128 v[18:21], v255 offset:1296
	v_pk_mul_f32 v[8:9], v[26:27], v[8:9] op_sel_hi:[0,1]
	s_waitcnt lgkmcnt(0)
	v_pk_mul_f32 v[10:11], v[24:25], v[10:11] op_sel_hi:[0,1]
	s_waitcnt lgkmcnt(0)
	v_pk_mul_f32 v[96:97], v[24:25], v[18:19] op_sel_hi:[0,1]
	v_lshl_add_u64 v[18:19], v[14:15], 0, s[28:29]
	v_pk_mul_f32 v[30:31], v[24:25], v[20:21] op_sel_hi:[0,1]
	ds_read_b128 v[2:5], v255 offset:2048
	s_nop 0
	ds_read_b128 v[18:21], v255 offset:2064
	v_pk_mul_f32 v[12:13], v[24:25], v[12:13] op_sel_hi:[0,1]
	s_waitcnt lgkmcnt(0)
; #define LAS __attribute__((address_space(3)))
; DI float bflo(unsigned w) { return __uint_as_float(w << 16); }
; DI float bfhi(unsigned w) { return __uint_as_float(w & 0xffff0000u); }
; DI float silu_f(float g) { return g * frcp(1.f + fexp2(-1.4426950408889634f * g)); }
;     ...
;         for (int j = 0; j < 4; ++j) { const int sp = n * 64 + t - 3 + j; const float ok = sp >= 0 ? 1.f : 0.f;
;             const u32x4 xv = xin[which * 4 + j];
;             const f32x4 w0 = *(const f32x4*)(conv_w + j * 1536 + col) * ok, w1 = *(const f32x4*)(conv_w + j * 1536 + col + 4) * ok;
;             acc[0] += w0[0] * bflo(xv.x); acc[1] += w0[1] * bfhi(xv.x); acc[2] += w0[2] * bflo(xv.y); acc[3] += w0[3] * bfhi(xv.y);
;             acc[4] += w1[0] * bflo(xv.z); acc[5] += w1[1] * bfhi(xv.z); acc[6] += w1[2] * bflo(xv.w); acc[7] += w1[3] * bfhi(xv.w); }
; #pragma unroll
;         for (int e = 0; e < 8; ++e) acc[e] = silu_f(acc[e]);
;         if (which == 2) { LAS float* dst = vc + t * 68 + cg8 * 8; *(LAS f32x4*)dst = (f32x4){acc[0], acc[1], acc[2], acc[3]}; *(LAS f32x4*)(dst + 4) = (f32x4){acc[4], acc[5], acc[6], acc[7]}; }
	v_pk_mul_f32 v[4:5], v[22:23], v[4:5] op_sel_hi:[0,1]
	s_waitcnt lgkmcnt(0)
	v_pk_mul_f32 v[98:99], v[22:23], v[18:19] op_sel_hi:[0,1]
	v_lshl_add_u64 v[18:19], v[14:15], 0, s[42:43]
	v_pk_mul_f32 v[32:33], v[22:23], v[20:21] op_sel_hi:[0,1]
	ds_read_b128 v[14:17], v255 offset:2816
	s_nop 0
	ds_read_b128 v[18:21], v255 offset:2832
	v_pk_mul_f32 v[2:3], v[22:23], v[2:3] op_sel_hi:[0,1]
	v_lshlrev_b32_e32 v22, 16, v34
	v_and_b32_e32 v23, 0xffff0000, v34
	v_pk_fma_f32 v[6:7], v[6:7], v[22:23], 0 op_sel_hi:[1,1,0]
	v_lshlrev_b32_e32 v22, 16, v38
	v_and_b32_e32 v23, 0xffff0000, v38
	v_pk_fma_f32 v[6:7], v[10:11], v[22:23], v[6:7]
	v_lshlrev_b32_e32 v10, 16, v42
	v_and_b32_e32 v11, 0xffff0000, v42
	v_pk_fma_f32 v[2:3], v[2:3], v[10:11], v[6:7]
	v_lshlrev_b32_e32 v10, 16, v35
	v_and_b32_e32 v11, 0xffff0000, v35
	v_pk_fma_f32 v[8:9], v[8:9], v[10:11], 0 op_sel_hi:[1,1,0]
	v_lshlrev_b32_e32 v10, 16, v39
	v_and_b32_e32 v11, 0xffff0000, v39
	v_lshlrev_b32_e32 v6, 16, v46
	v_and_b32_e32 v7, 0xffff0000, v46
	v_pk_fma_f32 v[8:9], v[12:13], v[10:11], v[8:9]
	v_lshlrev_b32_e32 v10, 16, v43
	v_and_b32_e32 v11, 0xffff0000, v43
	v_pk_fma_f32 v[4:5], v[4:5], v[10:11], v[8:9]
	v_lshlrev_b32_e32 v8, 16, v47
	v_and_b32_e32 v9, 0xffff0000, v47
	v_lshlrev_b32_e32 v10, 16, v37
	v_and_b32_e32 v11, 0xffff0000, v37
	v_pk_fma_f32 v[10:11], v[28:29], v[10:11], 0 op_sel_hi:[1,1,0]
	v_lshlrev_b32_e32 v12, 16, v41
	v_and_b32_e32 v13, 0xffff0000, v41
	v_pk_fma_f32 v[10:11], v[30:31], v[12:13], v[10:11]
	v_lshlrev_b32_e32 v12, 16, v45
	v_and_b32_e32 v13, 0xffff0000, v45
	v_pk_fma_f32 v[10:11], v[32:33], v[12:13], v[10:11]
	v_lshlrev_b32_e32 v12, 16, v49
	v_and_b32_e32 v13, 0xffff0000, v49
	s_waitcnt lgkmcnt(0)
	v_pk_fma_f32 v[2:3], v[14:15], v[6:7], v[2:3]
	s_nop 0
	v_mul_f32_e32 v6, 0xbfb8aa3b, v2
	v_mul_f32_e32 v7, 0xbfb8aa3b, v3
	v_pk_fma_f32 v[4:5], v[16:17], v[8:9], v[4:5]
	v_exp_f32_e32 v6, v6
	v_exp_f32_e32 v7, v7
	v_mul_f32_e32 v8, 0xbfb8aa3b, v4
	v_mul_f32_e32 v9, 0xbfb8aa3b, v5
	v_exp_f32_e32 v8, v8
	v_exp_f32_e32 v9, v9
	v_add_f32_e32 v6, 1.0, v6
	v_add_f32_e32 v7, 1.0, v7
	v_rcp_f32_e32 v6, v6
	v_rcp_f32_e32 v7, v7
	v_add_f32_e32 v8, 1.0, v8
	v_add_f32_e32 v9, 1.0, v9
	v_rcp_f32_e32 v8, v8
	v_rcp_f32_e32 v9, v9
	s_waitcnt lgkmcnt(0)
	v_pk_fma_f32 v[10:11], v[20:21], v[12:13], v[10:11]
	v_pk_mul_f32 v[2:3], v[2:3], v[6:7]
	v_mul_f32_e32 v12, 0xbfb8aa3b, v11
	v_lshlrev_b32_e32 v6, 16, v36
	v_and_b32_e32 v7, 0xffff0000, v36
	v_exp_f32_e32 v12, v12
	v_pk_mul_f32 v[4:5], v[4:5], v[8:9]
	v_pk_fma_f32 v[6:7], v[94:95], v[6:7], 0 op_sel_hi:[1,1,0]
	v_lshlrev_b32_e32 v8, 16, v40
	v_and_b32_e32 v9, 0xffff0000, v40
	v_pk_fma_f32 v[6:7], v[96:97], v[8:9], v[6:7]
	v_lshlrev_b32_e32 v8, 16, v44
	v_and_b32_e32 v9, 0xffff0000, v44
	v_pk_fma_f32 v[6:7], v[98:99], v[8:9], v[6:7]
	v_lshlrev_b32_e32 v8, 16, v48
	v_and_b32_e32 v9, 0xffff0000, v48
	v_pk_fma_f32 v[6:7], v[18:19], v[8:9], v[6:7]
	v_add_f32_e32 v12, 1.0, v12
	v_mul_f32_e32 v8, 0xbfb8aa3b, v6
	v_mul_f32_e32 v9, 0xbfb8aa3b, v7
	v_rcp_f32_e32 v13, v12
	v_mul_f32_e32 v12, 0xbfb8aa3b, v10
	v_exp_f32_e32 v8, v8
	v_exp_f32_e32 v9, v9
	v_exp_f32_e32 v12, v12
	v_add_f32_e32 v8, 1.0, v8
	v_add_f32_e32 v9, 1.0, v9
	v_add_f32_e32 v12, 1.0, v12
	v_rcp_f32_e32 v8, v8
	v_rcp_f32_e32 v9, v9
	v_rcp_f32_e32 v12, v12
	v_pk_mul_f32 v[6:7], v[6:7], v[8:9]
	v_pk_mul_f32 v[8:9], v[10:11], v[12:13]
	ds_write_b128 v176, v[2:5] offset:34816
	ds_write_b128 v176, v[6:9] offset:34832
	s_cbranch_vccnz .LBB0_436
; DI float bf2f(bf16_t u) { return __uint_as_float(((unsigned)u) << 16); }
;     ...
;     { const float ga = bf2f(gain), gb = bf2f(gbin);
;         const float x = ga + dt_bias[h]; const float sp = fmaxf(x, 0.f) + log1pf(expf(-fabsf(x)));
;         float gv = -expf(a_log[h]) * sp; const float bv = 1.f / (1.f + expf(-gb));
;         if (wid == 0) {
; #pragma unroll
;             for (int o = 1; o < 64; o <<= 1) { const float tt = __shfl_up(gv, o); if (lane >= o) gv += tt; }
;             gcs[lane] = gv; bet[lane] = bv; } }
	s_lshl_b32 s3, s3, 2
	v_mov_b32_e32 v2, s3
	v_readlane_b32 s52, v247, 9
	s_waitcnt vmcnt(0)
	v_mov_b32_e32 v3, v252
	v_readlane_b32 s53, v247, 10
	v_lshlrev_b32_e32 v5, 16, v1
	s_mov_b32 s3, 0xb2a5705f
	v_readlane_b32 s54, v247, 11
	v_readlane_b32 s55, v247, 12
	v_readlane_b32 s56, v247, 13
	v_mov_b32_e32 v4, v253
	v_lshlrev_b32_e32 v2, 16, v100
	v_mul_f32_e32 v6, 0xbfb8aa3b, v2
	v_rndne_f32_e32 v7, v6
	v_fma_f32 v8, v2, s78, -v6
	v_sub_f32_e32 v6, v6, v7
	v_fmac_f32_e32 v8, 0xb2a5705f, v2
	v_add_f32_e32 v6, v6, v8
	v_cvt_i32_f32_e32 v7, v7
	v_exp_f32_e32 v6, v6
	v_readlane_b32 s57, v247, 14
	v_readlane_b32 s58, v247, 15
	v_readlane_b32 s59, v247, 16
	v_ldexp_f32 v6, v6, v7
	v_readlane_b32 s60, v247, 17
	v_readlane_b32 s61, v247, 18
	v_readlane_b32 s62, v247, 19
	v_readlane_b32 s63, v247, 20
	v_readlane_b32 s64, v247, 21
	v_readlane_b32 s65, v247, 22
	v_readlane_b32 s66, v247, 23
	v_readlane_b32 s67, v247, 24
	s_waitcnt vmcnt(1)
	v_mul_f32_e32 v8, 0x3fb8aa3b, v3
	v_rndne_f32_e32 v9, v8
	v_cmp_ngt_f32_e32 vcc, s95, v3
	s_waitcnt vmcnt(0)
	v_add_f32_e32 v4, v4, v5
	v_fma_f32 v5, v3, s27, -v8
	v_mul_f32_e64 v10, |v4|, s78
	v_fmac_f32_e32 v5, 0x32a5705f, v3
	v_sub_f32_e32 v8, v8, v9
	v_fma_f32 v12, |v4|, s78, -v10
	v_rndne_f32_e32 v13, v10
	v_add_f32_e32 v5, v8, v5
	v_cvt_i32_f32_e32 v9, v9
	v_fma_f32 v8, |v4|, s3, v12
	v_sub_f32_e32 v10, v10, v13
	v_exp_f32_e32 v5, v5
	v_add_f32_e32 v8, v10, v8
	v_cvt_i32_f32_e32 v12, v13
	v_exp_f32_e32 v8, v8
	v_ldexp_f32 v5, v5, v9
	v_cndmask_b32_e32 v5, 0, v5, vcc
	v_cmp_nlt_f32_e32 vcc, s16, v3
	v_ldexp_f32 v8, v8, v12
	v_max_f32_e32 v11, 0, v4
	v_cndmask_b32_e32 v3, v193, v5, vcc
	v_cmp_ngt_f32_e64 vcc, |v4|, s79
	s_mov_b32 s3, 0x3f2aaaab
	s_nop 0
	v_cndmask_b32_e32 v5, 0, v8, vcc
	v_cmp_nlt_f32_e64 vcc, |v4|, s26
	s_nop 1
	v_cndmask_b32_e32 v8, v193, v5, vcc
	v_add_f32_e32 v9, 1.0, v8
	v_cvt_f64_f32_e32 v[4:5], v9
	v_frexp_mant_f32_e32 v10, v9
	v_add_f32_e32 v12, -1.0, v9
	v_frexp_exp_i32_f64_e32 v4, v[4:5]
	v_cmp_gt_f32_e32 vcc, s3, v10
	v_sub_f32_e32 v5, v8, v12
	v_sub_f32_e32 v12, v12, v9
	v_subbrev_co_u32_e32 v4, vcc, 0, v4, vcc
	v_add_f32_e32 v10, 1.0, v12
	v_cvt_f32_i32_e32 v12, v4
	v_sub_u32_e32 v4, 0, v4
	v_add_f32_e32 v5, v5, v10
	v_ldexp_f32 v9, v9, v4
	v_ldexp_f32 v4, v5, v4
	v_add_f32_e32 v5, -1.0, v9
	v_add_f32_e32 v10, 1.0, v9
	v_add_f32_e32 v13, 1.0, v5
	v_add_f32_e32 v14, -1.0, v10
	v_mul_f32_e32 v15, 0x3f317218, v12
	v_sub_f32_e32 v13, v9, v13
	v_sub_f32_e32 v9, v9, v14
	s_mov_b32 s3, 0x3f317218
	v_fma_f32 v14, v12, s3, -v15
	v_add_f32_e32 v13, v4, v13
	v_add_f32_e32 v4, v4, v9
	v_fmac_f32_e32 v14, 0xb102e308, v12
	v_add_f32_e32 v12, v10, v4
	v_rcp_f32_e32 v17, v12
	v_add_f32_e32 v9, v5, v13
	v_add_f32_e32 v16, v15, v14
	v_sub_f32_e32 v10, v10, v12
	v_sub_f32_e32 v5, v5, v9
	v_add_f32_e32 v4, v4, v10
	v_add_f32_e32 v5, v13, v5
	v_sub_f32_e32 v10, v16, v15
	v_mul_f32_e32 v13, v9, v17
	v_sub_f32_e32 v10, v14, v10
	v_mul_f32_e32 v14, v12, v13
	v_fma_f32 v15, v13, v12, -v14
	v_fmac_f32_e32 v15, v13, v4
	v_add_f32_e32 v18, v14, v15
	v_sub_f32_e32 v19, v9, v18
	v_sub_f32_e32 v9, v9, v19
	v_sub_f32_e32 v14, v18, v14
	v_sub_f32_e32 v9, v9, v18
	v_sub_f32_e32 v14, v14, v15
	v_add_f32_e32 v5, v5, v9
	v_add_f32_e32 v5, v14, v5
	v_add_f32_e32 v9, v19, v5
	v_mul_f32_e32 v14, v17, v9
	v_sub_f32_e32 v15, v19, v9
	v_mul_f32_e32 v19, v12, v14
	v_fma_f32 v12, v14, v12, -v19
	v_add_f32_e32 v18, v13, v14
	v_fmac_f32_e32 v12, v14, v4
	v_sub_f32_e32 v13, v18, v13
	v_add_f32_e32 v4, v19, v12
	v_sub_f32_e32 v13, v14, v13
	v_sub_f32_e32 v14, v9, v4
	v_sub_f32_e32 v9, v9, v14
	v_add_f32_e32 v5, v5, v15
	v_sub_f32_e32 v15, v4, v19
	v_sub_f32_e32 v4, v9, v4
	v_sub_f32_e32 v12, v15, v12
	v_add_f32_e32 v4, v5, v4
	v_add_f32_e32 v4, v12, v4
	v_add_f32_e32 v4, v14, v4
	v_mul_f32_e32 v4, v17, v4
	v_add_f32_e32 v4, v13, v4
	v_add_f32_e32 v5, v18, v4
	v_mul_f32_e32 v12, v5, v5
	v_fmamk_f32 v14, v12, 0x3e9b6dac, v177
	v_ldexp_f32 v9, v5, 1
	v_sub_f32_e32 v13, v5, v18
	v_mul_f32_e32 v5, v5, v12
	v_fmaak_f32 v12, v12, v14, 0x3f2aaada
	v_mul_f32_e32 v5, v5, v12
	v_add_f32_e32 v12, v9, v5
	v_sub_f32_e32 v4, v4, v13
	v_sub_f32_e32 v9, v12, v9
	v_ldexp_f32 v4, v4, 1
	v_sub_f32_e32 v5, v5, v9
	v_add_f32_e32 v4, v4, v5
	v_add_f32_e32 v5, v12, v4
	v_add_f32_e32 v9, v16, v5
	v_sub_f32_e32 v12, v5, v12
	v_sub_f32_e32 v4, v4, v12
	v_sub_f32_e32 v12, v9, v16
	v_sub_f32_e32 v5, v5, v12
	v_sub_f32_e32 v12, v9, v12
	v_add_f32_e32 v13, v10, v4
	v_sub_f32_e32 v12, v16, v12
	v_sub_f32_e32 v14, v13, v10
	v_add_f32_e32 v5, v5, v12
	v_sub_f32_e32 v12, v13, v14
	v_add_f32_e32 v5, v13, v5
	v_sub_f32_e32 v10, v10, v12
	v_add_f32_e32 v12, v9, v5
	v_sub_f32_e32 v4, v4, v14
	v_sub_f32_e32 v9, v12, v9
	v_add_f32_e32 v4, v4, v10
	v_sub_f32_e32 v5, v5, v9
	v_add_f32_e32 v4, v4, v5
	s_mov_b32 s3, 0x7f800000
	v_add_f32_e32 v4, v12, v4
	v_cmp_neq_f32_e32 vcc, s3, v8
	s_mov_b32 s3, 0x33800000
	s_nop 0
	v_cndmask_b32_e32 v4, v193, v4, vcc
	v_cmp_lt_f32_e64 vcc, |v8|, s3
	s_nop 1
	v_cndmask_b32_e32 v4, v4, v8, vcc
	v_add_f32_e32 v4, v11, v4
	v_mul_f32_e64 v5, v4, -v3
	ds_bpermute_b32 v8, v104, v5
	v_cmp_nlt_f32_e32 vcc, s79, v2
	s_waitcnt lgkmcnt(0)
	v_fma_f32 v3, v4, -v3, v8
	v_cndmask_b32_e64 v3, v3, v5, s[4:5]
	ds_bpermute_b32 v4, v105, v3
	v_cndmask_b32_e32 v5, 0, v6, vcc
	v_cmp_ngt_f32_e32 vcc, s26, v2
	s_waitcnt lgkmcnt(0)
	v_add_f32_e32 v4, v3, v4
	v_cndmask_b32_e64 v3, v4, v3, s[6:7]
	ds_bpermute_b32 v4, v106, v3
	v_cndmask_b32_e32 v2, v193, v5, vcc
	v_add_f32_e32 v2, 1.0, v2
	v_div_scale_f32 v5, s[42:43], v2, v2, 1.0
	s_waitcnt lgkmcnt(0)
	v_add_f32_e32 v4, v3, v4
	v_cndmask_b32_e64 v3, v4, v3, s[8:9]
	ds_bpermute_b32 v4, v107, v3
	v_rcp_f32_e32 v6, v5
	v_div_scale_f32 v7, vcc, 1.0, v2, 1.0
	s_waitcnt lgkmcnt(0)
	v_add_f32_e32 v4, v3, v4
	v_cndmask_b32_e64 v3, v4, v3, s[10:11]
	ds_bpermute_b32 v4, v108, v3
	v_fma_f32 v8, -v5, v6, 1.0
	v_fmac_f32_e32 v6, v8, v6
	v_mul_f32_e32 v8, v7, v6
	v_fma_f32 v9, -v5, v8, v7
	s_waitcnt lgkmcnt(0)
	v_add_f32_e32 v4, v3, v4
	v_cndmask_b32_e64 v3, v4, v3, s[12:13]
	ds_bpermute_b32 v4, v109, v3
	v_fmac_f32_e32 v8, v9, v6
	v_fma_f32 v5, -v5, v8, v7
	v_div_fmas_f32 v5, v5, v6, v8
	v_div_fixup_f32 v2, v5, v2, 1.0
	s_waitcnt lgkmcnt(0)
	v_add_f32_e32 v4, v3, v4
	v_cndmask_b32_e64 v3, v4, v3, s[14:15]
	ds_write_b32 v117, v3
	ds_write_b32 v118, v2

;     DI void fused(f32x4 (&acc)[2][2][4][2], const Unit& u, int wr, int wc, int fr_, int fq_, LAS unsigned char* lds, int wid, int lane_) const {
;     ...
;             for (int m = 0; m < 4; ++m) { const int r = u.pm * BM + ai * HALF + wr * 64 + m * 16 + fr; const size_t ro = (size_t)r * ldc + col0;
; #pragma unroll
;                 for (int bj = 0; bj < 2; ++bj)
; #pragma unroll
;                     for (int n = 0; n < 2; ++n) { const f32x4 h = *(const f32x4*)(Hin + ro + bj * HALF + n * 16); acc[ai][bj][m][n] = h * alpha + acc[ai][bj][m][n] * s; }
;                 asm volatile("" : "+v"(acc[ai][0][m][0]), "+v"(acc[ai][0][m][1]), "+v"(acc[ai][1][m][0]), "+v"(acc[ai][1][m][1]));
;                 asm volatile("" ::: "memory"); }
; #pragma unroll
;         for (int ai = 0; ai < 2; ++ai)
; #pragma unroll
;             for (int m = 0; m < 4; ++m) {
;                 float sm = 0.f;
; #pragma unroll
;                 for (int bj = 0; bj < 2; ++bj)
; #pragma unroll
;                     for (int n = 0; n < 2; ++n) { const f32x4 x = acc[ai][bj][m][n]; sm += (x[0] + x[1]) + (x[2] + x[3]); }
;                 sm += __shfl_xor(sm, 16); sm += __shfl_xor(sm, 32);
.LBB0_1011:
	v_mov_b32_e32 v153, v202
	s_lshl_b32 s0, s28, 5
	s_barrier
	s_lshl_b32 s1, s8, 8
	v_ashrrev_i32_e32 v130, 2, v153
	s_or_b32 s0, s1, s0
	v_and_b32_e32 v130, -4, v130
	s_lshl_b32 s10, s26, 8
	v_and_b32_e32 v1, 15, v153
	v_add_u32_e32 v130, s0, v130
	s_add_i32 s0, s10, s24
	v_or_b32_e32 v134, s0, v1
	v_ashrrev_i32_e32 v135, 31, v134
	v_ashrrev_i32_e32 v131, 31, v130
	v_lshlrev_b64 v[132:133], 12, v[134:135]
	v_lshl_add_u64 v[132:133], s[90:91], 0, v[132:133]
	v_lshlrev_b64 v[148:149], 2, v[130:131]
	v_lshl_add_u64 v[146:147], v[132:133], 0, v[148:149]
	global_load_dwordx4 v[136:139], v[146:147], off
	global_load_dwordx4 v[140:143], v[146:147], off offset:64
	global_load_dwordx4 v[154:157], v[146:147], off offset:512
	global_load_dwordx4 v[158:161], v[146:147], off offset:576
	v_or_b32_e32 v132, 16, v134
	v_ashrrev_i32_e32 v133, 31, v132
	s_mov_b32 s0, 0x3fb504f3
	v_lshlrev_b64 v[132:133], 12, v[132:133]
	v_lshl_add_u64 v[132:133], s[90:91], 0, v[132:133]
	v_lshl_add_u64 v[144:145], v[132:133], 0, v[148:149]
	v_or_b32_e32 v132, 32, v134
	v_ashrrev_i32_e32 v133, 31, v132
	v_lshlrev_b64 v[132:133], 12, v[132:133]
	v_lshl_add_u64 v[132:133], s[90:91], 0, v[132:133]
	v_mbcnt_lo_u32_b32 v135, -1, 0
	v_mbcnt_hi_u32_b32 v151, -1, v135
	v_and_b32_e32 v150, 64, v151
	v_xor_b32_e32 v135, 16, v151
	v_add_u32_e32 v184, 64, v150
	v_cmp_lt_i32_e32 vcc, v135, v184
	s_waitcnt vmcnt(0)
	v_pk_fma_f32 v[128:129], v[138:139], s[0:1], v[128:129] op_sel_hi:[1,0,1]
	v_pk_fma_f32 v[126:127], v[136:137], s[0:1], v[126:127] op_sel_hi:[1,0,1]
	v_pk_fma_f32 v[124:125], v[142:143], s[0:1], v[124:125] op_sel_hi:[1,0,1]
	v_pk_fma_f32 v[122:123], v[140:141], s[0:1], v[122:123] op_sel_hi:[1,0,1]
	v_pk_fma_f32 v[120:121], v[156:157], s[0:1], v[120:121] op_sel_hi:[1,0,1]
	v_pk_fma_f32 v[118:119], v[154:155], s[0:1], v[118:119] op_sel_hi:[1,0,1]
	v_pk_fma_f32 v[112:113], v[160:161], s[0:1], v[112:113] op_sel_hi:[1,0,1]
	v_pk_fma_f32 v[110:111], v[158:159], s[0:1], v[110:111] op_sel_hi:[1,0,1]
	v_lshl_add_u64 v[142:143], v[132:133], 0, v[148:149]
	global_load_dwordx4 v[136:139], v[144:145], off
	global_load_dwordx4 v[154:157], v[144:145], off offset:64
	global_load_dwordx4 v[158:161], v[144:145], off offset:512
	global_load_dwordx4 v[162:165], v[144:145], off offset:576
	v_or_b32_e32 v132, 48, v134
	v_ashrrev_i32_e32 v133, 31, v132
	v_lshlrev_b64 v[132:133], 12, v[132:133]
	v_lshl_add_u64 v[132:133], s[90:91], 0, v[132:133]
	v_lshl_add_u64 v[140:141], v[132:133], 0, v[148:149]
	v_add_u32_e32 v132, 0x80, v134
	v_ashrrev_i32_e32 v133, 31, v132
	v_lshlrev_b64 v[132:133], 12, v[132:133]
	v_lshl_add_u64 v[132:133], s[90:91], 0, v[132:133]
	v_cndmask_b32_e32 v150, v151, v135, vcc
	v_mov_b32_e32 v174, v127
	v_mov_b32_e32 v175, v128
	v_mov_b32_e32 v176, v126
	v_mov_b32_e32 v177, v129
	v_mov_b32_e32 v178, v123
	v_mov_b32_e32 v179, v124
	v_pk_add_f32 v[174:175], v[174:175], v[176:177]
	v_add_f32_e32 v181, v120, v121
	v_add_f32_e32 v174, v174, v175
	v_mov_b32_e32 v180, v111
	v_mov_b32_e32 v182, v113
	v_add_f32_e32 v183, 0, v174
	v_lshlrev_b32_e32 v150, 2, v150
	s_waitcnt vmcnt(3)
	v_pk_fma_f32 v[116:117], v[138:139], s[0:1], v[116:117] op_sel_hi:[1,0,1]
	v_pk_fma_f32 v[114:115], v[136:137], s[0:1], v[114:115] op_sel_hi:[1,0,1]
	s_waitcnt vmcnt(2)
	v_pk_fma_f32 v[108:109], v[156:157], s[0:1], v[108:109] op_sel_hi:[1,0,1]
	v_pk_fma_f32 v[106:107], v[154:155], s[0:1], v[106:107] op_sel_hi:[1,0,1]
	s_waitcnt vmcnt(1)
	v_pk_fma_f32 v[104:105], v[160:161], s[0:1], v[104:105] op_sel_hi:[1,0,1]
	v_pk_fma_f32 v[102:103], v[158:159], s[0:1], v[102:103] op_sel_hi:[1,0,1]
	s_waitcnt vmcnt(0)
	v_pk_fma_f32 v[96:97], v[164:165], s[0:1], v[96:97] op_sel_hi:[1,0,1]
	v_pk_fma_f32 v[94:95], v[162:163], s[0:1], v[94:95] op_sel_hi:[1,0,1]
	s_nop 0
	global_load_dwordx4 v[136:139], v[142:143], off
	global_load_dwordx4 v[154:157], v[142:143], off offset:64
	global_load_dwordx4 v[158:161], v[142:143], off offset:512
	global_load_dwordx4 v[162:165], v[142:143], off offset:576
	s_waitcnt vmcnt(3)
	v_pk_fma_f32 v[100:101], v[138:139], s[0:1], v[100:101] op_sel_hi:[1,0,1]
	v_pk_fma_f32 v[98:99], v[136:137], s[0:1], v[98:99] op_sel_hi:[1,0,1]
	s_waitcnt vmcnt(2)
	v_pk_fma_f32 v[92:93], v[156:157], s[0:1], v[92:93] op_sel_hi:[1,0,1]
	v_pk_fma_f32 v[90:91], v[154:155], s[0:1], v[90:91] op_sel_hi:[1,0,1]
	s_waitcnt vmcnt(1)
	v_pk_fma_f32 v[88:89], v[160:161], s[0:1], v[88:89] op_sel_hi:[1,0,1]
	v_pk_fma_f32 v[86:87], v[158:159], s[0:1], v[86:87] op_sel_hi:[1,0,1]
	s_waitcnt vmcnt(0)
	v_pk_fma_f32 v[80:81], v[164:165], s[0:1], v[80:81] op_sel_hi:[1,0,1]
	v_pk_fma_f32 v[78:79], v[162:163], s[0:1], v[78:79] op_sel_hi:[1,0,1]
	v_lshl_add_u64 v[138:139], v[132:133], 0, v[148:149]
	global_load_dwordx4 v[154:157], v[140:141], off
	global_load_dwordx4 v[158:161], v[140:141], off offset:64
	global_load_dwordx4 v[162:165], v[140:141], off offset:512
	global_load_dwordx4 v[166:169], v[140:141], off offset:576
	v_add_u32_e32 v132, 0x90, v134
	v_ashrrev_i32_e32 v133, 31, v132
	v_lshlrev_b64 v[132:133], 12, v[132:133]
	v_lshl_add_u64 v[132:133], s[90:91], 0, v[132:133]
	v_lshl_add_u64 v[136:137], v[132:133], 0, v[148:149]
	v_add_u32_e32 v132, 0xa0, v134
	v_ashrrev_i32_e32 v133, 31, v132
	v_lshlrev_b64 v[132:133], 12, v[132:133]
	v_lshl_add_u64 v[132:133], s[90:91], 0, v[132:133]
	v_lshl_add_u64 v[132:133], v[132:133], 0, v[148:149]
	v_add_u32_e32 v134, 0xb0, v134
	v_ashrrev_i32_e32 v135, 31, v134
	v_lshlrev_b64 v[134:135], 12, v[134:135]
	v_lshl_add_u64 v[134:135], s[90:91], 0, v[134:135]
	v_lshl_add_u64 v[134:135], v[134:135], 0, v[148:149]
	s_waitcnt vmcnt(3)
;     DI void fused(f32x4 (&acc)[2][2][4][2], const Unit& u, int wr, int wc, int fr_, int fq_, LAS unsigned char* lds, int wid, int lane_) const {
;     ...
;             for (int m = 0; m < 4; ++m) { const int r = u.pm * BM + ai * HALF + wr * 64 + m * 16 + fr; const size_t ro = (size_t)r * ldc + col0;
; #pragma unroll
;                 for (int bj = 0; bj < 2; ++bj)
; #pragma unroll
;                     for (int n = 0; n < 2; ++n) { const f32x4 h = *(const f32x4*)(Hin + ro + bj * HALF + n * 16); acc[ai][bj][m][n] = h * alpha + acc[ai][bj][m][n] * s; }
;                 asm volatile("" : "+v"(acc[ai][0][m][0]), "+v"(acc[ai][0][m][1]), "+v"(acc[ai][1][m][0]), "+v"(acc[ai][1][m][1]));
;                 asm volatile("" ::: "memory"); }
; #pragma unroll
;         for (int ai = 0; ai < 2; ++ai)
; #pragma unroll
;             for (int m = 0; m < 4; ++m) {
;                 float sm = 0.f;
; #pragma unroll
;                 for (int bj = 0; bj < 2; ++bj)
; #pragma unroll
;                     for (int n = 0; n < 2; ++n) { const f32x4 x = acc[ai][bj][m][n]; sm += (x[0] + x[1]) + (x[2] + x[3]); }
;                 sm += __shfl_xor(sm, 16); sm += __shfl_xor(sm, 32);
;                 const float mw = sm * (1.0f / 64.0f); float q = 0.f;
; #pragma unroll
;                 for (int bj = 0; bj < 2; ++bj)
; #pragma unroll
;                     for (int n = 0; n < 2; ++n) { const f32x4 d = acc[ai][bj][m][n] - mw; q += (d[0] * d[0] + d[1] * d[1]) + (d[2] * d[2] + d[3] * d[3]); }
;                 q += __shfl_xor(q, 16); q += __shfl_xor(q, 32);
;                 if (fq == 0) P[(ai * HALF + wr * 64 + m * 16 + fr) * 4 + wc] = (f32x2){mw, q};
;                 __builtin_amdgcn_sched_barrier(0);
;             }
	v_pk_fma_f32 v[84:85], v[156:157], s[0:1], v[84:85] op_sel_hi:[1,0,1]
	v_pk_fma_f32 v[82:83], v[154:155], s[0:1], v[82:83] op_sel_hi:[1,0,1]
	s_waitcnt vmcnt(2)
	v_pk_fma_f32 v[76:77], v[160:161], s[0:1], v[76:77] op_sel_hi:[1,0,1]
	v_pk_fma_f32 v[74:75], v[158:159], s[0:1], v[74:75] op_sel_hi:[1,0,1]
	s_waitcnt vmcnt(1)
	v_pk_fma_f32 v[72:73], v[164:165], s[0:1], v[72:73] op_sel_hi:[1,0,1]
	v_pk_fma_f32 v[70:71], v[162:163], s[0:1], v[70:71] op_sel_hi:[1,0,1]
	s_waitcnt vmcnt(0)
	v_pk_fma_f32 v[68:69], v[168:169], s[0:1], v[68:69] op_sel_hi:[1,0,1]
	v_pk_fma_f32 v[66:67], v[166:167], s[0:1], v[66:67] op_sel_hi:[1,0,1]
	s_nop 0
	global_load_dwordx4 v[154:157], v[138:139], off
	global_load_dwordx4 v[158:161], v[138:139], off offset:64
	global_load_dwordx4 v[162:165], v[138:139], off offset:512
	global_load_dwordx4 v[166:169], v[138:139], off offset:576
	s_waitcnt vmcnt(3)
	v_pk_fma_f32 v[64:65], v[156:157], s[0:1], v[64:65] op_sel_hi:[1,0,1]
	v_pk_fma_f32 v[62:63], v[154:155], s[0:1], v[62:63] op_sel_hi:[1,0,1]
	s_waitcnt vmcnt(2)
	v_pk_fma_f32 v[60:61], v[160:161], s[0:1], v[60:61] op_sel_hi:[1,0,1]
	v_pk_fma_f32 v[58:59], v[158:159], s[0:1], v[58:59] op_sel_hi:[1,0,1]
	s_waitcnt vmcnt(1)
	v_pk_fma_f32 v[56:57], v[164:165], s[0:1], v[56:57] op_sel_hi:[1,0,1]
	v_pk_fma_f32 v[54:55], v[162:163], s[0:1], v[54:55] op_sel_hi:[1,0,1]
	s_waitcnt vmcnt(0)
	v_pk_fma_f32 v[52:53], v[168:169], s[0:1], v[52:53] op_sel_hi:[1,0,1]
	v_pk_fma_f32 v[50:51], v[166:167], s[0:1], v[50:51] op_sel_hi:[1,0,1]
	s_nop 0
	global_load_dwordx4 v[154:157], v[136:137], off
	global_load_dwordx4 v[158:161], v[136:137], off offset:64
	global_load_dwordx4 v[162:165], v[136:137], off offset:512
	global_load_dwordx4 v[166:169], v[136:137], off offset:576
	s_waitcnt vmcnt(3)
	v_pk_fma_f32 v[48:49], v[156:157], s[0:1], v[48:49] op_sel_hi:[1,0,1]
	v_pk_fma_f32 v[46:47], v[154:155], s[0:1], v[46:47] op_sel_hi:[1,0,1]
	s_waitcnt vmcnt(2)
	v_pk_fma_f32 v[44:45], v[160:161], s[0:1], v[44:45] op_sel_hi:[1,0,1]
	v_pk_fma_f32 v[42:43], v[158:159], s[0:1], v[42:43] op_sel_hi:[1,0,1]
	s_waitcnt vmcnt(1)
	v_pk_fma_f32 v[40:41], v[164:165], s[0:1], v[40:41] op_sel_hi:[1,0,1]
	v_pk_fma_f32 v[38:39], v[162:163], s[0:1], v[38:39] op_sel_hi:[1,0,1]
	s_waitcnt vmcnt(0)
	v_pk_fma_f32 v[36:37], v[168:169], s[0:1], v[36:37] op_sel_hi:[1,0,1]
	v_pk_fma_f32 v[34:35], v[166:167], s[0:1], v[34:35] op_sel_hi:[1,0,1]
	s_nop 0
	global_load_dwordx4 v[154:157], v[132:133], off
	global_load_dwordx4 v[158:161], v[132:133], off offset:64
	global_load_dwordx4 v[162:165], v[132:133], off offset:512
	global_load_dwordx4 v[166:169], v[132:133], off offset:576
	s_waitcnt vmcnt(3)
	v_pk_fma_f32 v[32:33], v[156:157], s[0:1], v[32:33] op_sel_hi:[1,0,1]
	v_pk_fma_f32 v[30:31], v[154:155], s[0:1], v[30:31] op_sel_hi:[1,0,1]
	s_waitcnt vmcnt(2)
	v_pk_fma_f32 v[28:29], v[160:161], s[0:1], v[28:29] op_sel_hi:[1,0,1]
	v_pk_fma_f32 v[26:27], v[158:159], s[0:1], v[26:27] op_sel_hi:[1,0,1]
	s_waitcnt vmcnt(1)
	v_pk_fma_f32 v[24:25], v[164:165], s[0:1], v[24:25] op_sel_hi:[1,0,1]
	v_pk_fma_f32 v[22:23], v[162:163], s[0:1], v[22:23] op_sel_hi:[1,0,1]
	s_waitcnt vmcnt(0)
	v_pk_fma_f32 v[20:21], v[168:169], s[0:1], v[20:21] op_sel_hi:[1,0,1]
	v_pk_fma_f32 v[18:19], v[166:167], s[0:1], v[18:19] op_sel_hi:[1,0,1]
	v_mov_b32_e32 v154, v122
	global_load_dwordx4 v[158:161], v[134:135], off
	global_load_dwordx4 v[162:165], v[134:135], off offset:64
	global_load_dwordx4 v[166:169], v[134:135], off offset:512
	global_load_dwordx4 v[170:173], v[134:135], off offset:576
	v_mov_b32_e32 v155, v125
	v_pk_add_f32 v[154:155], v[178:179], v[154:155]
	v_add_f32_e32 v157, v118, v119
	v_pk_add_f32 v[154:155], v[154:155], v[154:155] op_sel_hi:[0,1]
	v_mov_b32_e32 v156, v110
	v_mov_b32_e32 v154, v112
	v_pk_add_f32 v[156:157], v[156:157], v[180:181]
	v_pk_add_f32 v[154:155], v[154:155], v[182:183]
	s_waitcnt vmcnt(3)
	v_pk_fma_f32 v[16:17], v[160:161], s[0:1], v[16:17] op_sel_hi:[1,0,1]
	v_pk_add_f32 v[154:155], v[156:157], v[154:155]
	v_xor_b32_e32 v156, 32, v151
	v_add_f32_e32 v154, v154, v155
	v_mov_b32_e32 v155, v154
	s_nop 1
	v_permlane16_swap_b32_e32 v154, v155
	v_cmp_lt_i32_e32 vcc, v156, v184
	v_pk_fma_f32 v[14:15], v[158:159], s[0:1], v[14:15] op_sel_hi:[1,0,1]
	s_waitcnt vmcnt(2)
	v_pk_fma_f32 v[12:13], v[164:165], s[0:1], v[12:13] op_sel_hi:[1,0,1]
	v_cndmask_b32_e32 v151, v151, v156, vcc
	v_lshlrev_b32_e32 v151, 2, v151
	s_waitcnt lgkmcnt(0)
	v_add_f32_e32 v154, v154, v155
	v_mov_b32_e32 v155, v154
	s_nop 1
	v_permlane32_swap_b32_e32 v154, v155
	v_pk_fma_f32 v[10:11], v[162:163], s[0:1], v[10:11] op_sel_hi:[1,0,1]
	s_waitcnt vmcnt(1)
	v_pk_fma_f32 v[8:9], v[168:169], s[0:1], v[8:9] op_sel_hi:[1,0,1]
	v_pk_fma_f32 v[6:7], v[166:167], s[0:1], v[6:7] op_sel_hi:[1,0,1]
	s_waitcnt vmcnt(0)
	v_pk_fma_f32 v[4:5], v[172:173], s[0:1], v[4:5] op_sel_hi:[1,0,1]
	s_waitcnt lgkmcnt(0)
	v_add_f32_e32 v154, v154, v155
	v_fmamk_f32 v156, v154, 0xbc800000, v129
	v_fmamk_f32 v174, v154, 0xbc800000, v127
	v_fmamk_f32 v176, v154, 0xbc800000, v125
	v_fmamk_f32 v178, v154, 0xbc800000, v123
	v_fmamk_f32 v155, v154, 0xbc800000, v128
	v_fmamk_f32 v157, v154, 0xbc800000, v126
	v_fmamk_f32 v175, v154, 0xbc800000, v124
	v_fmamk_f32 v177, v154, 0xbc800000, v122
	v_fmamk_f32 v180, v154, 0xbc800000, v121
	v_fmamk_f32 v182, v154, 0xbc800000, v119
	v_mul_f32_e32 v174, v174, v174
	v_mul_f32_e32 v156, v156, v156
	v_mul_f32_e32 v178, v178, v178
	v_mul_f32_e32 v176, v176, v176
	v_fmamk_f32 v179, v154, 0xbc800000, v120
	v_fmamk_f32 v181, v154, 0xbc800000, v118
	v_fmamk_f32 v184, v154, 0xbc800000, v113
	v_fmamk_f32 v186, v154, 0xbc800000, v111
	v_mul_f32_e32 v182, v182, v182
	v_mul_f32_e32 v180, v180, v180
	v_fmac_f32_e32 v174, v157, v157
	v_fmac_f32_e32 v156, v155, v155
	v_fmac_f32_e32 v178, v177, v177
	v_fmac_f32_e32 v176, v175, v175
	v_fmamk_f32 v183, v154, 0xbc800000, v112
	v_fmamk_f32 v185, v154, 0xbc800000, v110
	v_mul_f32_e32 v186, v186, v186
	v_mul_f32_e32 v184, v184, v184
	v_fmac_f32_e32 v182, v181, v181
	v_fmac_f32_e32 v180, v179, v179
	v_add_f32_e32 v155, v174, v156
	v_add_f32_e32 v156, v178, v176
	v_fmac_f32_e32 v186, v185, v185
	v_fmac_f32_e32 v184, v183, v183
	v_add_f32_e32 v157, v182, v180
	v_add_f32_e32 v155, v155, v156
	v_add_f32_e32 v174, v186, v184
	v_add_f32_e32 v155, v157, v155
	v_add_f32_e32 v155, v174, v155
	v_mov_b32_e32 v156, v155
	s_nop 1
	v_permlane16_swap_b32_e32 v155, v156
	v_pk_fma_f32 v[2:3], v[170:171], s[0:1], v[2:3] op_sel_hi:[1,0,1]
	s_lshl_b32 s0, s28, 3
	s_waitcnt lgkmcnt(0)
	v_add_f32_e32 v155, v155, v156
	v_mov_b32_e32 v156, v155
	s_nop 1
	v_permlane32_swap_b32_e32 v155, v156
	v_cmp_gt_u32_e32 vcc, 16, v153
	s_add_i32 s4, s0, 0x100
	s_and_saveexec_b64 s[0:1], vcc
	s_cbranch_execz .LBB0_1013
	s_lshl_b32 s5, s27, 11
	s_add_i32 s5, s4, s5
	v_mul_f32_e32 v154, 0x3c800000, v154
	v_lshl_add_u32 v157, v153, 5, s5
	s_waitcnt lgkmcnt(0)
	v_add_f32_e32 v155, v155, v156
	ds_write_b64 v157, v[154:155]
;     DI void fused(f32x4 (&acc)[2][2][4][2], const Unit& u, int wr, int wc, int fr_, int fq_, LAS unsigned char* lds, int wid, int lane_) const {
;     ...
;             for (int m = 0; m < 4; ++m) {
;                 float sm = 0.f;
; #pragma unroll
;                 for (int bj = 0; bj < 2; ++bj)
; #pragma unroll
;                     for (int n = 0; n < 2; ++n) { const f32x4 x = acc[ai][bj][m][n]; sm += (x[0] + x[1]) + (x[2] + x[3]); }
;                 sm += __shfl_xor(sm, 16); sm += __shfl_xor(sm, 32);
;                 const float mw = sm * (1.0f / 64.0f); float q = 0.f;
; #pragma unroll
;                 for (int bj = 0; bj < 2; ++bj)
; #pragma unroll
;                     for (int n = 0; n < 2; ++n) { const f32x4 d = acc[ai][bj][m][n] - mw; q += (d[0] * d[0] + d[1] * d[1]) + (d[2] * d[2] + d[3] * d[3]); }
;                 q += __shfl_xor(q, 16); q += __shfl_xor(q, 32);
;                 if (fq == 0) P[(ai * HALF + wr * 64 + m * 16 + fr) * 4 + wc] = (f32x2){mw, q};
;                 __builtin_amdgcn_sched_barrier(0);
;             }
.LBB0_1013:
	s_or_b64 exec, exec, s[0:1]
	v_mov_b32_e32 v154, v115
	v_mov_b32_e32 v155, v116
	s_waitcnt lgkmcnt(0)
	v_mov_b32_e32 v156, v114
	v_mov_b32_e32 v157, v117
	v_pk_add_f32 v[154:155], v[154:155], v[156:157]
	v_mov_b32_e32 v156, v107
	v_mov_b32_e32 v157, v108
	v_mov_b32_e32 v158, v106
	v_mov_b32_e32 v159, v109
	v_pk_add_f32 v[156:157], v[156:157], v[158:159]
	v_add_f32_e32 v154, v154, v155
	v_pk_add_f32 v[156:157], v[156:157], v[156:157] op_sel_hi:[0,1]
	v_add_f32_e32 v155, 0, v154
	v_add_f32_e32 v159, v102, v103
	v_add_f32_e32 v161, v104, v105
	v_mov_b32_e32 v158, v94
	v_mov_b32_e32 v160, v95
	v_mov_b32_e32 v156, v96
	v_mov_b32_e32 v154, v97
	v_pk_add_f32 v[158:159], v[158:159], v[160:161]
	v_pk_add_f32 v[154:155], v[156:157], v[154:155]
	s_nop 0
	v_pk_add_f32 v[154:155], v[158:159], v[154:155]
	s_nop 0
	v_add_f32_e32 v154, v154, v155
	v_mov_b32_e32 v155, v154
	s_nop 1
	v_permlane16_swap_b32_e32 v154, v155
	s_waitcnt lgkmcnt(0)
	v_add_f32_e32 v154, v154, v155
	v_mov_b32_e32 v155, v154
	s_nop 1
	v_permlane32_swap_b32_e32 v154, v155
	s_waitcnt lgkmcnt(0)
	v_add_f32_e32 v154, v154, v155
	v_fmamk_f32 v156, v154, 0xbc800000, v117
	v_fmamk_f32 v158, v154, 0xbc800000, v115
	v_fmamk_f32 v155, v154, 0xbc800000, v116
	v_fmamk_f32 v157, v154, 0xbc800000, v114
	v_mul_f32_e32 v158, v158, v158
	v_mul_f32_e32 v156, v156, v156
	v_fmac_f32_e32 v158, v157, v157
	v_fmac_f32_e32 v156, v155, v155
	v_fmamk_f32 v157, v154, 0xbc800000, v109
	v_fmamk_f32 v159, v154, 0xbc800000, v107
	v_add_f32_e32 v155, v158, v156
	v_fmamk_f32 v156, v154, 0xbc800000, v108
	v_fmamk_f32 v158, v154, 0xbc800000, v106
	v_mul_f32_e32 v159, v159, v159
	v_mul_f32_e32 v157, v157, v157
	v_fmac_f32_e32 v159, v158, v158
	v_fmac_f32_e32 v157, v156, v156
	v_add_f32_e32 v156, v159, v157
	v_fmamk_f32 v157, v154, 0xbc800000, v105
	v_fmamk_f32 v159, v154, 0xbc800000, v103
	v_add_f32_e32 v155, v155, v156
	v_fmamk_f32 v156, v154, 0xbc800000, v104
	v_fmamk_f32 v158, v154, 0xbc800000, v102
	v_mul_f32_e32 v159, v159, v159
	v_mul_f32_e32 v157, v157, v157
	v_fmac_f32_e32 v159, v158, v158
	v_fmac_f32_e32 v157, v156, v156
	v_add_f32_e32 v156, v159, v157
	v_fmamk_f32 v157, v154, 0xbc800000, v97
	v_fmamk_f32 v159, v154, 0xbc800000, v95
	v_add_f32_e32 v155, v156, v155
	v_fmamk_f32 v156, v154, 0xbc800000, v96
	v_fmamk_f32 v158, v154, 0xbc800000, v94
	v_mul_f32_e32 v159, v159, v159
	v_mul_f32_e32 v157, v157, v157
	v_fmac_f32_e32 v159, v158, v158
	v_fmac_f32_e32 v157, v156, v156
	v_add_f32_e32 v156, v159, v157
	v_add_f32_e32 v155, v156, v155
	v_mov_b32_e32 v156, v155
	s_nop 1
	v_permlane16_swap_b32_e32 v155, v156
	s_waitcnt lgkmcnt(0)
	v_add_f32_e32 v155, v155, v156
	v_mov_b32_e32 v156, v155
	s_nop 1
	v_permlane32_swap_b32_e32 v155, v156
	s_and_saveexec_b64 s[0:1], vcc
	s_cbranch_execz .LBB0_1015
	s_lshl_b32 s5, s27, 11
	s_add_i32 s5, s4, s5
	v_mul_f32_e32 v154, 0x3c800000, v154
	v_lshl_add_u32 v157, v153, 5, s5
	s_waitcnt lgkmcnt(0)
	v_add_f32_e32 v155, v155, v156
	ds_write_b64 v157, v[154:155] offset:512
.LBB0_1015:
	s_or_b64 exec, exec, s[0:1]
	v_mov_b32_e32 v154, v99
	v_mov_b32_e32 v155, v100
	s_waitcnt lgkmcnt(0)
	v_mov_b32_e32 v156, v98
	v_mov_b32_e32 v157, v101
	v_pk_add_f32 v[154:155], v[154:155], v[156:157]
	v_mov_b32_e32 v156, v91
	v_mov_b32_e32 v157, v92
	v_mov_b32_e32 v158, v90
	v_mov_b32_e32 v159, v93
	v_pk_add_f32 v[156:157], v[156:157], v[158:159]
	v_add_f32_e32 v154, v154, v155
	v_pk_add_f32 v[156:157], v[156:157], v[156:157] op_sel_hi:[0,1]
	v_add_f32_e32 v155, 0, v154
	v_add_f32_e32 v159, v86, v87
	v_add_f32_e32 v161, v88, v89
	v_mov_b32_e32 v158, v78
	v_mov_b32_e32 v160, v79
	v_mov_b32_e32 v156, v80
	v_mov_b32_e32 v154, v81
	v_pk_add_f32 v[158:159], v[158:159], v[160:161]
	v_pk_add_f32 v[154:155], v[156:157], v[154:155]
	s_nop 0
	v_pk_add_f32 v[154:155], v[158:159], v[154:155]
	s_nop 0
	v_add_f32_e32 v154, v154, v155
	v_mov_b32_e32 v155, v154
	s_nop 1
	v_permlane16_swap_b32_e32 v154, v155
	s_waitcnt lgkmcnt(0)
	v_add_f32_e32 v154, v154, v155
	v_mov_b32_e32 v155, v154
	s_nop 1
	v_permlane32_swap_b32_e32 v154, v155
	s_waitcnt lgkmcnt(0)
	v_add_f32_e32 v154, v154, v155
	v_fmamk_f32 v156, v154, 0xbc800000, v101
	v_fmamk_f32 v158, v154, 0xbc800000, v99
	v_fmamk_f32 v155, v154, 0xbc800000, v100
	v_fmamk_f32 v157, v154, 0xbc800000, v98
	v_mul_f32_e32 v158, v158, v158
	v_mul_f32_e32 v156, v156, v156
	v_fmac_f32_e32 v158, v157, v157
	v_fmac_f32_e32 v156, v155, v155
	v_fmamk_f32 v157, v154, 0xbc800000, v93
	v_fmamk_f32 v159, v154, 0xbc800000, v91
	v_add_f32_e32 v155, v158, v156
	v_fmamk_f32 v156, v154, 0xbc800000, v92
	v_fmamk_f32 v158, v154, 0xbc800000, v90
	v_mul_f32_e32 v159, v159, v159
	v_mul_f32_e32 v157, v157, v157
	v_fmac_f32_e32 v159, v158, v158
	v_fmac_f32_e32 v157, v156, v156
	v_add_f32_e32 v156, v159, v157
	v_fmamk_f32 v157, v154, 0xbc800000, v89
	v_fmamk_f32 v159, v154, 0xbc800000, v87
	v_add_f32_e32 v155, v155, v156
	v_fmamk_f32 v156, v154, 0xbc800000, v88
	v_fmamk_f32 v158, v154, 0xbc800000, v86
	v_mul_f32_e32 v159, v159, v159
	v_mul_f32_e32 v157, v157, v157
	v_fmac_f32_e32 v159, v158, v158
	v_fmac_f32_e32 v157, v156, v156
	v_add_f32_e32 v156, v159, v157
	v_fmamk_f32 v157, v154, 0xbc800000, v81
	v_fmamk_f32 v159, v154, 0xbc800000, v79
	v_add_f32_e32 v155, v156, v155
	v_fmamk_f32 v156, v154, 0xbc800000, v80
	v_fmamk_f32 v158, v154, 0xbc800000, v78
	v_mul_f32_e32 v159, v159, v159
	v_mul_f32_e32 v157, v157, v157
	v_fmac_f32_e32 v159, v158, v158
	v_fmac_f32_e32 v157, v156, v156
	v_add_f32_e32 v156, v159, v157
	v_add_f32_e32 v155, v156, v155
	v_mov_b32_e32 v156, v155
	s_nop 1
	v_permlane16_swap_b32_e32 v155, v156
	s_waitcnt lgkmcnt(0)
	v_add_f32_e32 v155, v155, v156
	v_mov_b32_e32 v156, v155
	s_nop 1
	v_permlane32_swap_b32_e32 v155, v156
	s_and_saveexec_b64 s[0:1], vcc
	s_cbranch_execz .LBB0_1017
	s_lshl_b32 s5, s27, 11
	s_add_i32 s5, s4, s5
	v_mul_f32_e32 v154, 0x3c800000, v154
	v_lshl_add_u32 v157, v153, 5, s5
	s_waitcnt lgkmcnt(0)
	v_add_f32_e32 v155, v155, v156
	ds_write_b64 v157, v[154:155] offset:1024
;     DI void fused(f32x4 (&acc)[2][2][4][2], const Unit& u, int wr, int wc, int fr_, int fq_, LAS unsigned char* lds, int wid, int lane_) const {
;     ...
;             for (int m = 0; m < 4; ++m) {
;                 float sm = 0.f;
; #pragma unroll
;                 for (int bj = 0; bj < 2; ++bj)
; #pragma unroll
;                     for (int n = 0; n < 2; ++n) { const f32x4 x = acc[ai][bj][m][n]; sm += (x[0] + x[1]) + (x[2] + x[3]); }
;                 sm += __shfl_xor(sm, 16); sm += __shfl_xor(sm, 32);
;                 const float mw = sm * (1.0f / 64.0f); float q = 0.f;
; #pragma unroll
;                 for (int bj = 0; bj < 2; ++bj)
; #pragma unroll
;                     for (int n = 0; n < 2; ++n) { const f32x4 d = acc[ai][bj][m][n] - mw; q += (d[0] * d[0] + d[1] * d[1]) + (d[2] * d[2] + d[3] * d[3]); }
;                 q += __shfl_xor(q, 16); q += __shfl_xor(q, 32);
;                 if (fq == 0) P[(ai * HALF + wr * 64 + m * 16 + fr) * 4 + wc] = (f32x2){mw, q};
;                 __builtin_amdgcn_sched_barrier(0);
;             }
.LBB0_1017:
	s_or_b64 exec, exec, s[0:1]
	v_mov_b32_e32 v154, v83
	v_mov_b32_e32 v155, v84
	s_waitcnt lgkmcnt(0)
	v_mov_b32_e32 v156, v82
	v_mov_b32_e32 v157, v85
	v_pk_add_f32 v[154:155], v[154:155], v[156:157]
	v_mov_b32_e32 v156, v75
	v_mov_b32_e32 v157, v76
	v_mov_b32_e32 v158, v74
	v_mov_b32_e32 v159, v77
	v_pk_add_f32 v[156:157], v[156:157], v[158:159]
	v_add_f32_e32 v154, v154, v155
	v_pk_add_f32 v[156:157], v[156:157], v[156:157] op_sel_hi:[0,1]
	v_add_f32_e32 v155, 0, v154
	v_add_f32_e32 v159, v70, v71
	v_add_f32_e32 v161, v72, v73
	v_mov_b32_e32 v158, v66
	v_mov_b32_e32 v160, v67
	v_mov_b32_e32 v156, v68
	v_mov_b32_e32 v154, v69
	v_pk_add_f32 v[158:159], v[158:159], v[160:161]
	v_pk_add_f32 v[154:155], v[156:157], v[154:155]
	s_nop 0
	v_pk_add_f32 v[154:155], v[158:159], v[154:155]
	s_nop 0
	v_add_f32_e32 v154, v154, v155
	v_mov_b32_e32 v155, v154
	s_nop 1
	v_permlane16_swap_b32_e32 v154, v155
	s_waitcnt lgkmcnt(0)
	v_add_f32_e32 v154, v154, v155
	v_mov_b32_e32 v155, v154
	s_nop 1
	v_permlane32_swap_b32_e32 v154, v155
	s_waitcnt lgkmcnt(0)
	v_add_f32_e32 v154, v154, v155
	v_fmamk_f32 v156, v154, 0xbc800000, v85
	v_fmamk_f32 v158, v154, 0xbc800000, v83
	v_fmamk_f32 v155, v154, 0xbc800000, v84
	v_fmamk_f32 v157, v154, 0xbc800000, v82
	v_mul_f32_e32 v158, v158, v158
	v_mul_f32_e32 v156, v156, v156
	v_fmac_f32_e32 v158, v157, v157
	v_fmac_f32_e32 v156, v155, v155
	v_fmamk_f32 v157, v154, 0xbc800000, v77
	v_fmamk_f32 v159, v154, 0xbc800000, v75
	v_add_f32_e32 v155, v158, v156
	v_fmamk_f32 v156, v154, 0xbc800000, v76
	v_fmamk_f32 v158, v154, 0xbc800000, v74
	v_mul_f32_e32 v159, v159, v159
	v_mul_f32_e32 v157, v157, v157
	v_fmac_f32_e32 v159, v158, v158
	v_fmac_f32_e32 v157, v156, v156
	v_add_f32_e32 v156, v159, v157
	v_fmamk_f32 v157, v154, 0xbc800000, v73
	v_fmamk_f32 v159, v154, 0xbc800000, v71
	v_add_f32_e32 v155, v155, v156
	v_fmamk_f32 v156, v154, 0xbc800000, v72
	v_fmamk_f32 v158, v154, 0xbc800000, v70
	v_mul_f32_e32 v159, v159, v159
	v_mul_f32_e32 v157, v157, v157
	v_fmac_f32_e32 v159, v158, v158
	v_fmac_f32_e32 v157, v156, v156
	v_add_f32_e32 v156, v159, v157
	v_fmamk_f32 v157, v154, 0xbc800000, v69
	v_fmamk_f32 v159, v154, 0xbc800000, v67
	v_add_f32_e32 v155, v156, v155
	v_fmamk_f32 v156, v154, 0xbc800000, v68
	v_fmamk_f32 v158, v154, 0xbc800000, v66
	v_mul_f32_e32 v159, v159, v159
	v_mul_f32_e32 v157, v157, v157
	v_fmac_f32_e32 v159, v158, v158
	v_fmac_f32_e32 v157, v156, v156
	v_add_f32_e32 v156, v159, v157
	v_add_f32_e32 v155, v156, v155
	v_mov_b32_e32 v156, v155
	s_nop 1
	v_permlane16_swap_b32_e32 v155, v156
	s_waitcnt lgkmcnt(0)
	v_add_f32_e32 v155, v155, v156
	v_mov_b32_e32 v156, v155
	s_nop 1
	v_permlane32_swap_b32_e32 v155, v156
	s_and_saveexec_b64 s[0:1], vcc
	s_cbranch_execz .LBB0_1019
	s_lshl_b32 s5, s27, 11
	s_add_i32 s5, s4, s5
	v_mul_f32_e32 v154, 0x3c800000, v154
	v_lshl_add_u32 v157, v153, 5, s5
	s_waitcnt lgkmcnt(0)
	v_add_f32_e32 v155, v155, v156
	ds_write_b64 v157, v[154:155] offset:1536
.LBB0_1019:
	s_or_b64 exec, exec, s[0:1]
	v_mov_b32_e32 v154, v63
	v_mov_b32_e32 v155, v64
	s_waitcnt lgkmcnt(0)
	v_mov_b32_e32 v156, v62
	v_mov_b32_e32 v157, v65
	v_pk_add_f32 v[154:155], v[154:155], v[156:157]
	v_mov_b32_e32 v156, v59
	v_mov_b32_e32 v157, v60
	v_mov_b32_e32 v158, v58
	v_mov_b32_e32 v159, v61
	v_pk_add_f32 v[156:157], v[156:157], v[158:159]
	v_add_f32_e32 v154, v154, v155
	v_pk_add_f32 v[156:157], v[156:157], v[156:157] op_sel_hi:[0,1]
	v_add_f32_e32 v155, 0, v154
	v_add_f32_e32 v159, v54, v55
	v_add_f32_e32 v161, v56, v57
	v_mov_b32_e32 v158, v50
	v_mov_b32_e32 v160, v51
	v_mov_b32_e32 v156, v52
	v_mov_b32_e32 v154, v53
	v_pk_add_f32 v[158:159], v[158:159], v[160:161]
	v_pk_add_f32 v[154:155], v[156:157], v[154:155]
	s_nop 0
	v_pk_add_f32 v[154:155], v[158:159], v[154:155]
	s_nop 0
	v_add_f32_e32 v154, v154, v155
	v_mov_b32_e32 v155, v154
	s_nop 1
	v_permlane16_swap_b32_e32 v154, v155
	s_waitcnt lgkmcnt(0)
	v_add_f32_e32 v154, v154, v155
	v_mov_b32_e32 v155, v154
	s_nop 1
	v_permlane32_swap_b32_e32 v154, v155
	s_waitcnt lgkmcnt(0)
	v_add_f32_e32 v154, v154, v155
	v_fmamk_f32 v156, v154, 0xbc800000, v65
	v_fmamk_f32 v158, v154, 0xbc800000, v63
	v_fmamk_f32 v155, v154, 0xbc800000, v64
	v_fmamk_f32 v157, v154, 0xbc800000, v62
	v_mul_f32_e32 v158, v158, v158
	v_mul_f32_e32 v156, v156, v156
	v_fmac_f32_e32 v158, v157, v157
	v_fmac_f32_e32 v156, v155, v155
	v_fmamk_f32 v157, v154, 0xbc800000, v61
	v_fmamk_f32 v159, v154, 0xbc800000, v59
	v_add_f32_e32 v155, v158, v156
	v_fmamk_f32 v156, v154, 0xbc800000, v60
	v_fmamk_f32 v158, v154, 0xbc800000, v58
	v_mul_f32_e32 v159, v159, v159
	v_mul_f32_e32 v157, v157, v157
	v_fmac_f32_e32 v159, v158, v158
	v_fmac_f32_e32 v157, v156, v156
	v_add_f32_e32 v156, v159, v157
	v_fmamk_f32 v157, v154, 0xbc800000, v57
	v_fmamk_f32 v159, v154, 0xbc800000, v55
	v_add_f32_e32 v155, v155, v156
	v_fmamk_f32 v156, v154, 0xbc800000, v56
	v_fmamk_f32 v158, v154, 0xbc800000, v54
	v_mul_f32_e32 v159, v159, v159
	v_mul_f32_e32 v157, v157, v157
	v_fmac_f32_e32 v159, v158, v158
	v_fmac_f32_e32 v157, v156, v156
	v_add_f32_e32 v156, v159, v157
	v_fmamk_f32 v157, v154, 0xbc800000, v53
	v_fmamk_f32 v159, v154, 0xbc800000, v51
	v_add_f32_e32 v155, v156, v155
	v_fmamk_f32 v156, v154, 0xbc800000, v52
	v_fmamk_f32 v158, v154, 0xbc800000, v50
	v_mul_f32_e32 v159, v159, v159
	v_mul_f32_e32 v157, v157, v157
	v_fmac_f32_e32 v159, v158, v158
	v_fmac_f32_e32 v157, v156, v156
	v_add_f32_e32 v156, v159, v157
	v_add_f32_e32 v155, v156, v155
	v_mov_b32_e32 v156, v155
	s_nop 1
	v_permlane16_swap_b32_e32 v155, v156
	s_waitcnt lgkmcnt(0)
	v_add_f32_e32 v155, v155, v156
	v_mov_b32_e32 v156, v155
	s_nop 1
	v_permlane32_swap_b32_e32 v155, v156
	s_and_saveexec_b64 s[0:1], vcc
	s_cbranch_execz .LBB0_1021
	s_lshl_b32 s5, s27, 11
	s_add_i32 s5, s4, s5
	v_mul_f32_e32 v154, 0x3c800000, v154
	v_lshl_add_u32 v157, v153, 5, s5
	s_waitcnt lgkmcnt(0)
	v_add_f32_e32 v155, v155, v156
	ds_write_b64 v157, v[154:155] offset:4096
;     DI void fused(f32x4 (&acc)[2][2][4][2], const Unit& u, int wr, int wc, int fr_, int fq_, LAS unsigned char* lds, int wid, int lane_) const {
;     ...
;             for (int m = 0; m < 4; ++m) {
;                 float sm = 0.f;
; #pragma unroll
;                 for (int bj = 0; bj < 2; ++bj)
; #pragma unroll
;                     for (int n = 0; n < 2; ++n) { const f32x4 x = acc[ai][bj][m][n]; sm += (x[0] + x[1]) + (x[2] + x[3]); }
;                 sm += __shfl_xor(sm, 16); sm += __shfl_xor(sm, 32);
;                 const float mw = sm * (1.0f / 64.0f); float q = 0.f;
; #pragma unroll
;                 for (int bj = 0; bj < 2; ++bj)
; #pragma unroll
;                     for (int n = 0; n < 2; ++n) { const f32x4 d = acc[ai][bj][m][n] - mw; q += (d[0] * d[0] + d[1] * d[1]) + (d[2] * d[2] + d[3] * d[3]); }
;                 q += __shfl_xor(q, 16); q += __shfl_xor(q, 32);
;                 if (fq == 0) P[(ai * HALF + wr * 64 + m * 16 + fr) * 4 + wc] = (f32x2){mw, q};
;                 __builtin_amdgcn_sched_barrier(0);
;             }
.LBB0_1021:
	s_or_b64 exec, exec, s[0:1]
	v_mov_b32_e32 v154, v47
	v_mov_b32_e32 v155, v48
	s_waitcnt lgkmcnt(0)
	v_mov_b32_e32 v156, v46
	v_mov_b32_e32 v157, v49
	v_pk_add_f32 v[154:155], v[154:155], v[156:157]
	v_mov_b32_e32 v156, v43
	v_mov_b32_e32 v157, v44
	v_mov_b32_e32 v158, v42
	v_mov_b32_e32 v159, v45
	v_pk_add_f32 v[156:157], v[156:157], v[158:159]
	v_add_f32_e32 v154, v154, v155
	v_pk_add_f32 v[156:157], v[156:157], v[156:157] op_sel_hi:[0,1]
	v_add_f32_e32 v155, 0, v154
	v_add_f32_e32 v159, v38, v39
	v_add_f32_e32 v161, v40, v41
	v_mov_b32_e32 v158, v34
	v_mov_b32_e32 v160, v35
	v_mov_b32_e32 v156, v36
	v_mov_b32_e32 v154, v37
	v_pk_add_f32 v[158:159], v[158:159], v[160:161]
	v_pk_add_f32 v[154:155], v[156:157], v[154:155]
	s_nop 0
	v_pk_add_f32 v[154:155], v[158:159], v[154:155]
	s_nop 0
	v_add_f32_e32 v154, v154, v155
	v_mov_b32_e32 v155, v154
	s_nop 1
	v_permlane16_swap_b32_e32 v154, v155
	s_waitcnt lgkmcnt(0)
	v_add_f32_e32 v154, v154, v155
	v_mov_b32_e32 v155, v154
	s_nop 1
	v_permlane32_swap_b32_e32 v154, v155
	s_waitcnt lgkmcnt(0)
	v_add_f32_e32 v154, v154, v155
	v_fmamk_f32 v156, v154, 0xbc800000, v49
	v_fmamk_f32 v158, v154, 0xbc800000, v47
	v_fmamk_f32 v155, v154, 0xbc800000, v48
	v_fmamk_f32 v157, v154, 0xbc800000, v46
	v_mul_f32_e32 v158, v158, v158
	v_mul_f32_e32 v156, v156, v156
	v_fmac_f32_e32 v158, v157, v157
	v_fmac_f32_e32 v156, v155, v155
	v_fmamk_f32 v157, v154, 0xbc800000, v45
	v_fmamk_f32 v159, v154, 0xbc800000, v43
	v_add_f32_e32 v155, v158, v156
	v_fmamk_f32 v156, v154, 0xbc800000, v44
	v_fmamk_f32 v158, v154, 0xbc800000, v42
	v_mul_f32_e32 v159, v159, v159
	v_mul_f32_e32 v157, v157, v157
	v_fmac_f32_e32 v159, v158, v158
	v_fmac_f32_e32 v157, v156, v156
	v_add_f32_e32 v156, v159, v157
	v_fmamk_f32 v157, v154, 0xbc800000, v41
	v_fmamk_f32 v159, v154, 0xbc800000, v39
	v_add_f32_e32 v155, v155, v156
	v_fmamk_f32 v156, v154, 0xbc800000, v40
	v_fmamk_f32 v158, v154, 0xbc800000, v38
	v_mul_f32_e32 v159, v159, v159
	v_mul_f32_e32 v157, v157, v157
	v_fmac_f32_e32 v159, v158, v158
	v_fmac_f32_e32 v157, v156, v156
	v_add_f32_e32 v156, v159, v157
	v_fmamk_f32 v157, v154, 0xbc800000, v37
	v_fmamk_f32 v159, v154, 0xbc800000, v35
	v_add_f32_e32 v155, v156, v155
	v_fmamk_f32 v156, v154, 0xbc800000, v36
	v_fmamk_f32 v158, v154, 0xbc800000, v34
	v_mul_f32_e32 v159, v159, v159
	v_mul_f32_e32 v157, v157, v157
	v_fmac_f32_e32 v159, v158, v158
	v_fmac_f32_e32 v157, v156, v156
	v_add_f32_e32 v156, v159, v157
	v_add_f32_e32 v155, v156, v155
	v_mov_b32_e32 v156, v155
	s_nop 1
	v_permlane16_swap_b32_e32 v155, v156
	s_waitcnt lgkmcnt(0)
	v_add_f32_e32 v155, v155, v156
	v_mov_b32_e32 v156, v155
	s_nop 1
	v_permlane32_swap_b32_e32 v155, v156
	s_and_saveexec_b64 s[0:1], vcc
	s_cbranch_execz .LBB0_1023
	s_lshl_b32 s5, s27, 11
	s_add_i32 s5, s4, s5
	v_mul_f32_e32 v154, 0x3c800000, v154
	v_lshl_add_u32 v157, v153, 5, s5
	s_waitcnt lgkmcnt(0)
	v_add_f32_e32 v155, v155, v156
	ds_write_b64 v157, v[154:155] offset:4608
;     DI void fused(f32x4 (&acc)[2][2][4][2], const Unit& u, int wr, int wc, int fr_, int fq_, LAS unsigned char* lds, int wid, int lane_) const {
;     ...
;             for (int m = 0; m < 4; ++m) {
;                 float sm = 0.f;
; #pragma unroll
;                 for (int bj = 0; bj < 2; ++bj)
; #pragma unroll
;                     for (int n = 0; n < 2; ++n) { const f32x4 x = acc[ai][bj][m][n]; sm += (x[0] + x[1]) + (x[2] + x[3]); }
;                 sm += __shfl_xor(sm, 16); sm += __shfl_xor(sm, 32);
;                 const float mw = sm * (1.0f / 64.0f); float q = 0.f;
; #pragma unroll
;                 for (int bj = 0; bj < 2; ++bj)
; #pragma unroll
;                     for (int n = 0; n < 2; ++n) { const f32x4 d = acc[ai][bj][m][n] - mw; q += (d[0] * d[0] + d[1] * d[1]) + (d[2] * d[2] + d[3] * d[3]); }
;                 q += __shfl_xor(q, 16); q += __shfl_xor(q, 32);
;                 if (fq == 0) P[(ai * HALF + wr * 64 + m * 16 + fr) * 4 + wc] = (f32x2){mw, q};
;                 __builtin_amdgcn_sched_barrier(0);
;             }
.LBB0_1023:
	s_or_b64 exec, exec, s[0:1]
	v_mov_b32_e32 v154, v31
	v_mov_b32_e32 v155, v32
	s_waitcnt lgkmcnt(0)
	v_mov_b32_e32 v156, v30
	v_mov_b32_e32 v157, v33
	v_pk_add_f32 v[154:155], v[154:155], v[156:157]
	v_mov_b32_e32 v156, v27
	v_mov_b32_e32 v157, v28
	v_mov_b32_e32 v158, v26
	v_mov_b32_e32 v159, v29
	v_pk_add_f32 v[156:157], v[156:157], v[158:159]
	v_add_f32_e32 v154, v154, v155
	v_pk_add_f32 v[156:157], v[156:157], v[156:157] op_sel_hi:[0,1]
	v_add_f32_e32 v155, 0, v154
	v_add_f32_e32 v159, v22, v23
	v_add_f32_e32 v161, v24, v25
	v_mov_b32_e32 v158, v18
	v_mov_b32_e32 v160, v19
	v_mov_b32_e32 v156, v20
	v_mov_b32_e32 v154, v21
	v_pk_add_f32 v[158:159], v[158:159], v[160:161]
	v_pk_add_f32 v[154:155], v[156:157], v[154:155]
	s_nop 0
	v_pk_add_f32 v[154:155], v[158:159], v[154:155]
	s_nop 0
	v_add_f32_e32 v154, v154, v155
	v_mov_b32_e32 v155, v154
	s_nop 1
	v_permlane16_swap_b32_e32 v154, v155
	s_waitcnt lgkmcnt(0)
	v_add_f32_e32 v154, v154, v155
	v_mov_b32_e32 v155, v154
	s_nop 1
	v_permlane32_swap_b32_e32 v154, v155
	s_waitcnt lgkmcnt(0)
	v_add_f32_e32 v154, v154, v155
	v_fmamk_f32 v156, v154, 0xbc800000, v33
	v_fmamk_f32 v158, v154, 0xbc800000, v31
	v_fmamk_f32 v155, v154, 0xbc800000, v32
	v_fmamk_f32 v157, v154, 0xbc800000, v30
	v_mul_f32_e32 v158, v158, v158
	v_mul_f32_e32 v156, v156, v156
	v_fmac_f32_e32 v158, v157, v157
	v_fmac_f32_e32 v156, v155, v155
	v_fmamk_f32 v157, v154, 0xbc800000, v29
	v_fmamk_f32 v159, v154, 0xbc800000, v27
	v_add_f32_e32 v155, v158, v156
	v_fmamk_f32 v156, v154, 0xbc800000, v28
	v_fmamk_f32 v158, v154, 0xbc800000, v26
	v_mul_f32_e32 v159, v159, v159
	v_mul_f32_e32 v157, v157, v157
	v_fmac_f32_e32 v159, v158, v158
	v_fmac_f32_e32 v157, v156, v156
	v_add_f32_e32 v156, v159, v157
	v_fmamk_f32 v157, v154, 0xbc800000, v25
	v_fmamk_f32 v159, v154, 0xbc800000, v23
	v_add_f32_e32 v155, v155, v156
	v_fmamk_f32 v156, v154, 0xbc800000, v24
	v_fmamk_f32 v158, v154, 0xbc800000, v22
	v_mul_f32_e32 v159, v159, v159
	v_mul_f32_e32 v157, v157, v157
	v_fmac_f32_e32 v159, v158, v158
	v_fmac_f32_e32 v157, v156, v156
	v_add_f32_e32 v156, v159, v157
	v_fmamk_f32 v157, v154, 0xbc800000, v21
	v_fmamk_f32 v159, v154, 0xbc800000, v19
	v_add_f32_e32 v155, v156, v155
	v_fmamk_f32 v156, v154, 0xbc800000, v20
	v_fmamk_f32 v158, v154, 0xbc800000, v18
	v_mul_f32_e32 v159, v159, v159
	v_mul_f32_e32 v157, v157, v157
	v_fmac_f32_e32 v159, v158, v158
	v_fmac_f32_e32 v157, v156, v156
	v_add_f32_e32 v156, v159, v157
	v_add_f32_e32 v155, v156, v155
	v_mov_b32_e32 v156, v155
	s_nop 1
	v_permlane16_swap_b32_e32 v155, v156
	s_waitcnt lgkmcnt(0)
	v_add_f32_e32 v155, v155, v156
	v_mov_b32_e32 v156, v155
	s_nop 1
	v_permlane32_swap_b32_e32 v155, v156
	s_and_saveexec_b64 s[0:1], vcc
	s_cbranch_execz .LBB0_1025
	s_lshl_b32 s5, s27, 11
	s_add_i32 s5, s4, s5
	v_mul_f32_e32 v154, 0x3c800000, v154
	v_lshl_add_u32 v157, v153, 5, s5
	s_waitcnt lgkmcnt(0)
	v_add_f32_e32 v155, v155, v156
	ds_write_b64 v157, v[154:155] offset:5120
.LBB0_1025:
	s_or_b64 exec, exec, s[0:1]
	v_mov_b32_e32 v154, v15
	v_mov_b32_e32 v155, v16
	s_waitcnt lgkmcnt(0)
	v_mov_b32_e32 v156, v14
	v_mov_b32_e32 v157, v17
	v_pk_add_f32 v[154:155], v[154:155], v[156:157]
	v_mov_b32_e32 v156, v11
	v_mov_b32_e32 v157, v12
	v_mov_b32_e32 v158, v10
	v_mov_b32_e32 v159, v13
	v_pk_add_f32 v[156:157], v[156:157], v[158:159]
	v_add_f32_e32 v154, v154, v155
	v_pk_add_f32 v[156:157], v[156:157], v[156:157] op_sel_hi:[0,1]
	v_add_f32_e32 v155, 0, v154
	v_add_f32_e32 v159, v6, v7
	v_add_f32_e32 v161, v8, v9
	v_mov_b32_e32 v158, v2
	v_mov_b32_e32 v160, v3
	v_mov_b32_e32 v156, v4
	v_mov_b32_e32 v154, v5
	v_pk_add_f32 v[158:159], v[158:159], v[160:161]
	v_pk_add_f32 v[154:155], v[156:157], v[154:155]
	s_nop 0
	v_pk_add_f32 v[154:155], v[158:159], v[154:155]
	s_nop 0
	v_add_f32_e32 v154, v154, v155
	v_mov_b32_e32 v155, v154
	s_nop 1
	v_permlane16_swap_b32_e32 v154, v155
	s_waitcnt lgkmcnt(0)
	v_add_f32_e32 v154, v154, v155
	v_mov_b32_e32 v155, v154
	s_nop 1
	v_permlane32_swap_b32_e32 v154, v155
	s_waitcnt lgkmcnt(0)
	v_add_f32_e32 v154, v154, v155
	v_fmamk_f32 v156, v154, 0xbc800000, v17
	v_fmamk_f32 v158, v154, 0xbc800000, v15
	v_fmamk_f32 v155, v154, 0xbc800000, v16
	v_fmamk_f32 v157, v154, 0xbc800000, v14
	v_mul_f32_e32 v158, v158, v158
	v_mul_f32_e32 v156, v156, v156
	v_fmac_f32_e32 v158, v157, v157
	v_fmac_f32_e32 v156, v155, v155
	v_fmamk_f32 v157, v154, 0xbc800000, v13
	v_fmamk_f32 v159, v154, 0xbc800000, v11
	v_add_f32_e32 v155, v158, v156
	v_fmamk_f32 v156, v154, 0xbc800000, v12
	v_fmamk_f32 v158, v154, 0xbc800000, v10
	v_mul_f32_e32 v159, v159, v159
	v_mul_f32_e32 v157, v157, v157
	v_fmac_f32_e32 v159, v158, v158
	v_fmac_f32_e32 v157, v156, v156
	v_add_f32_e32 v156, v159, v157
	v_fmamk_f32 v157, v154, 0xbc800000, v9
	v_fmamk_f32 v159, v154, 0xbc800000, v7
	v_add_f32_e32 v155, v155, v156
	v_fmamk_f32 v156, v154, 0xbc800000, v8
	v_fmamk_f32 v158, v154, 0xbc800000, v6
	v_mul_f32_e32 v159, v159, v159
	v_mul_f32_e32 v157, v157, v157
	v_fmac_f32_e32 v159, v158, v158
	v_fmac_f32_e32 v157, v156, v156
	v_add_f32_e32 v156, v159, v157
	v_fmamk_f32 v157, v154, 0xbc800000, v5
	v_fmamk_f32 v159, v154, 0xbc800000, v3
	v_add_f32_e32 v155, v156, v155
	v_fmamk_f32 v156, v154, 0xbc800000, v4
	v_fmamk_f32 v158, v154, 0xbc800000, v2
	v_mul_f32_e32 v159, v159, v159
	v_mul_f32_e32 v157, v157, v157
	v_fmac_f32_e32 v159, v158, v158
	v_fmac_f32_e32 v157, v156, v156
	v_add_f32_e32 v156, v159, v157
	v_add_f32_e32 v155, v156, v155
	v_mov_b32_e32 v150, v155
	s_nop 1
	v_permlane16_swap_b32_e32 v155, v150
	s_waitcnt lgkmcnt(0)
	v_add_f32_e32 v150, v155, v150
	v_mov_b32_e32 v151, v150
	s_nop 1
	v_permlane32_swap_b32_e32 v150, v151
	s_and_saveexec_b64 s[0:1], vcc
	s_cbranch_execz .LBB0_1027
	s_lshl_b32 s5, s27, 11
	s_add_i32 s4, s4, s5
	v_mul_f32_e32 v154, 0x3c800000, v154
	v_lshl_add_u32 v156, v153, 5, s4
	s_waitcnt lgkmcnt(0)
	v_add_f32_e32 v155, v150, v151
	ds_write_b64 v156, v[154:155] offset:5632

;     DI void fused(f32x4 (&acc)[2][2][4][2], const Unit& u, int wr, int wc, int fr_, int fq_, LAS unsigned char* lds, int wid, int lane_) const {
;     ...
;             for (int m = 0; m < 4; ++m) { const int r = u.pm * BM + ai * HALF + wr * 64 + m * 16 + fr; const size_t ro = (size_t)r * ldc + col0;
; #pragma unroll
;                 for (int bj = 0; bj < 2; ++bj)
; #pragma unroll
;                     for (int n = 0; n < 2; ++n) { const f32x4 h = *(const f32x4*)(Hin + ro + bj * HALF + n * 16); acc[ai][bj][m][n] = h * alpha + acc[ai][bj][m][n] * s; }
;                 asm volatile("" : "+v"(acc[ai][0][m][0]), "+v"(acc[ai][0][m][1]), "+v"(acc[ai][1][m][0]), "+v"(acc[ai][1][m][1]));
;                 asm volatile("" ::: "memory"); }
.LBB0_1244:
	v_mov_b32_e32 v153, v202
	s_lshl_b32 s0, s24, 5
	s_barrier
	s_lshl_b32 s1, s2, 8
	v_ashrrev_i32_e32 v130, 2, v153
	s_or_b32 s0, s1, s0
	v_and_b32_e32 v130, -4, v130
	s_lshl_b32 s8, s22, 8
	v_and_b32_e32 v1, 15, v153
	v_add_u32_e32 v130, s0, v130
	s_add_i32 s0, s8, s20
	v_or_b32_e32 v134, s0, v1
	v_ashrrev_i32_e32 v135, 31, v134
	v_ashrrev_i32_e32 v131, 31, v130
	v_lshlrev_b64 v[132:133], 12, v[134:135]
	v_lshl_add_u64 v[132:133], s[90:91], 0, v[132:133]
	v_lshlrev_b64 v[148:149], 2, v[130:131]
	v_lshl_add_u64 v[146:147], v[132:133], 0, v[148:149]
	global_load_dwordx4 v[136:139], v[146:147], off
	global_load_dwordx4 v[140:143], v[146:147], off offset:64
	global_load_dwordx4 v[154:157], v[146:147], off offset:512
	global_load_dwordx4 v[158:161], v[146:147], off offset:576
	v_or_b32_e32 v132, 16, v134
	v_ashrrev_i32_e32 v133, 31, v132
	v_lshlrev_b64 v[132:133], 12, v[132:133]
	v_pk_mul_f32 v[126:127], v[126:127], 0.5 op_sel_hi:[1,0]
	v_pk_mul_f32 v[128:129], v[128:129], 0.5 op_sel_hi:[1,0]
	s_mov_b32 s0, 0x3fb504f3
	v_pk_mul_f32 v[122:123], v[122:123], 0.5 op_sel_hi:[1,0]
	v_lshl_add_u64 v[132:133], s[90:91], 0, v[132:133]
	v_pk_mul_f32 v[124:125], v[124:125], 0.5 op_sel_hi:[1,0]
	v_lshl_add_u64 v[144:145], v[132:133], 0, v[148:149]
	v_mbcnt_lo_u32_b32 v135, -1, 0
	s_waitcnt vmcnt(0)
	v_pk_fma_f32 v[128:129], v[138:139], s[0:1], v[128:129] op_sel_hi:[1,0,1]
	v_pk_fma_f32 v[126:127], v[136:137], s[0:1], v[126:127] op_sel_hi:[1,0,1]
	v_pk_fma_f32 v[122:123], v[140:141], s[0:1], v[122:123] op_sel_hi:[1,0,1]
	v_pk_mul_f32 v[132:133], v[156:157], s[0:1] op_sel_hi:[1,0]
	v_pk_mul_f32 v[136:137], v[154:155], s[0:1] op_sel_hi:[1,0]
	v_pk_mul_f32 v[138:139], v[160:161], s[0:1] op_sel_hi:[1,0]
	v_pk_mul_f32 v[140:141], v[158:159], s[0:1] op_sel_hi:[1,0]
	v_pk_fma_f32 v[124:125], v[142:143], s[0:1], v[124:125] op_sel_hi:[1,0,1]
	v_pk_fma_f32 v[120:121], v[120:121], 0.5, v[132:133] op_sel_hi:[1,0,1]
	v_pk_fma_f32 v[118:119], v[118:119], 0.5, v[136:137] op_sel_hi:[1,0,1]
	v_pk_fma_f32 v[108:109], v[108:109], 0.5, v[138:139] op_sel_hi:[1,0,1]
	v_pk_fma_f32 v[106:107], v[106:107], 0.5, v[140:141] op_sel_hi:[1,0,1]
	v_or_b32_e32 v132, 32, v134
	global_load_dwordx4 v[136:139], v[144:145], off
	global_load_dwordx4 v[154:157], v[144:145], off offset:64
	global_load_dwordx4 v[158:161], v[144:145], off offset:512
	global_load_dwordx4 v[162:165], v[144:145], off offset:576
	v_ashrrev_i32_e32 v133, 31, v132
	v_lshlrev_b64 v[132:133], 12, v[132:133]
	v_lshl_add_u64 v[132:133], s[90:91], 0, v[132:133]
	v_lshl_add_u64 v[142:143], v[132:133], 0, v[148:149]
	v_mov_b32_e32 v174, v127
	v_mov_b32_e32 v175, v128
	v_mov_b32_e32 v176, v126
	v_mov_b32_e32 v177, v129
	v_mov_b32_e32 v178, v123
	v_mov_b32_e32 v179, v124
	v_pk_add_f32 v[174:175], v[174:175], v[176:177]
	v_add_f32_e32 v181, v120, v121
	v_add_f32_e32 v174, v174, v175
	v_mov_b32_e32 v180, v107
	v_mov_b32_e32 v182, v109
	v_add_f32_e32 v183, 0, v174
	s_waitcnt vmcnt(3)
	v_pk_mul_f32 v[132:133], v[138:139], s[0:1] op_sel_hi:[1,0]
	v_pk_mul_f32 v[136:137], v[136:137], s[0:1] op_sel_hi:[1,0]
	s_waitcnt vmcnt(2)
	v_pk_mul_f32 v[138:139], v[156:157], s[0:1] op_sel_hi:[1,0]
	v_pk_mul_f32 v[140:141], v[154:155], s[0:1] op_sel_hi:[1,0]
	s_waitcnt vmcnt(1)
	v_pk_mul_f32 v[150:151], v[160:161], s[0:1] op_sel_hi:[1,0]
	v_pk_mul_f32 v[154:155], v[158:159], s[0:1] op_sel_hi:[1,0]
	s_waitcnt vmcnt(0)
	v_pk_mul_f32 v[156:157], v[164:165], s[0:1] op_sel_hi:[1,0]
	v_pk_mul_f32 v[158:159], v[162:163], s[0:1] op_sel_hi:[1,0]
	v_pk_fma_f32 v[116:117], v[116:117], 0.5, v[132:133] op_sel_hi:[1,0,1]
	v_pk_fma_f32 v[114:115], v[114:115], 0.5, v[136:137] op_sel_hi:[1,0,1]
	v_pk_fma_f32 v[112:113], v[112:113], 0.5, v[138:139] op_sel_hi:[1,0,1]
	v_pk_fma_f32 v[110:111], v[110:111], 0.5, v[140:141] op_sel_hi:[1,0,1]
	v_pk_fma_f32 v[104:105], v[104:105], 0.5, v[150:151] op_sel_hi:[1,0,1]
	v_pk_fma_f32 v[102:103], v[102:103], 0.5, v[154:155] op_sel_hi:[1,0,1]
	v_pk_fma_f32 v[92:93], v[92:93], 0.5, v[156:157] op_sel_hi:[1,0,1]
	v_pk_fma_f32 v[90:91], v[90:91], 0.5, v[158:159] op_sel_hi:[1,0,1]
	v_or_b32_e32 v132, 48, v134
	global_load_dwordx4 v[136:139], v[142:143], off
	global_load_dwordx4 v[154:157], v[142:143], off offset:64
	global_load_dwordx4 v[158:161], v[142:143], off offset:512
	global_load_dwordx4 v[162:165], v[142:143], off offset:576
	v_ashrrev_i32_e32 v133, 31, v132
	v_lshlrev_b64 v[132:133], 12, v[132:133]
	v_lshl_add_u64 v[132:133], s[90:91], 0, v[132:133]
	v_lshl_add_u64 v[140:141], v[132:133], 0, v[148:149]
	s_waitcnt vmcnt(3)
	v_pk_mul_f32 v[132:133], v[138:139], s[0:1] op_sel_hi:[1,0]
	v_pk_mul_f32 v[136:137], v[136:137], s[0:1] op_sel_hi:[1,0]
	s_waitcnt vmcnt(2)
	v_pk_mul_f32 v[138:139], v[156:157], s[0:1] op_sel_hi:[1,0]
	v_pk_mul_f32 v[150:151], v[154:155], s[0:1] op_sel_hi:[1,0]
	s_waitcnt vmcnt(1)
	v_pk_mul_f32 v[154:155], v[160:161], s[0:1] op_sel_hi:[1,0]
	v_pk_mul_f32 v[156:157], v[158:159], s[0:1] op_sel_hi:[1,0]
	s_waitcnt vmcnt(0)
	v_pk_mul_f32 v[158:159], v[164:165], s[0:1] op_sel_hi:[1,0]
	v_pk_mul_f32 v[160:161], v[162:163], s[0:1] op_sel_hi:[1,0]
	v_pk_fma_f32 v[100:101], v[100:101], 0.5, v[132:133] op_sel_hi:[1,0,1]
	v_pk_fma_f32 v[98:99], v[98:99], 0.5, v[136:137] op_sel_hi:[1,0,1]
	v_pk_fma_f32 v[96:97], v[96:97], 0.5, v[138:139] op_sel_hi:[1,0,1]
	v_pk_fma_f32 v[94:95], v[94:95], 0.5, v[150:151] op_sel_hi:[1,0,1]
	v_pk_fma_f32 v[88:89], v[88:89], 0.5, v[154:155] op_sel_hi:[1,0,1]
	v_pk_fma_f32 v[86:87], v[86:87], 0.5, v[156:157] op_sel_hi:[1,0,1]
	v_pk_fma_f32 v[76:77], v[76:77], 0.5, v[158:159] op_sel_hi:[1,0,1]
	v_pk_fma_f32 v[74:75], v[74:75], 0.5, v[160:161] op_sel_hi:[1,0,1]
	v_add_u32_e32 v132, 0x80, v134
	global_load_dwordx4 v[154:157], v[140:141], off
	global_load_dwordx4 v[158:161], v[140:141], off offset:64
	global_load_dwordx4 v[162:165], v[140:141], off offset:512
	global_load_dwordx4 v[166:169], v[140:141], off offset:576
	v_ashrrev_i32_e32 v133, 31, v132
	v_lshlrev_b64 v[132:133], 12, v[132:133]
	v_lshl_add_u64 v[132:133], s[90:91], 0, v[132:133]
	v_lshl_add_u64 v[138:139], v[132:133], 0, v[148:149]
	s_waitcnt vmcnt(3)
;     DI void fused(f32x4 (&acc)[2][2][4][2], const Unit& u, int wr, int wc, int fr_, int fq_, LAS unsigned char* lds, int wid, int lane_) const {
;     ...
;             for (int m = 0; m < 4; ++m) { const int r = u.pm * BM + ai * HALF + wr * 64 + m * 16 + fr; const size_t ro = (size_t)r * ldc + col0;
; #pragma unroll
;                 for (int bj = 0; bj < 2; ++bj)
; #pragma unroll
;                     for (int n = 0; n < 2; ++n) { const f32x4 h = *(const f32x4*)(Hin + ro + bj * HALF + n * 16); acc[ai][bj][m][n] = h * alpha + acc[ai][bj][m][n] * s; }
;                 asm volatile("" : "+v"(acc[ai][0][m][0]), "+v"(acc[ai][0][m][1]), "+v"(acc[ai][1][m][0]), "+v"(acc[ai][1][m][1]));
;                 asm volatile("" ::: "memory"); }
	v_pk_mul_f32 v[132:133], v[156:157], s[0:1] op_sel_hi:[1,0]
	v_pk_mul_f32 v[136:137], v[154:155], s[0:1] op_sel_hi:[1,0]
	s_waitcnt vmcnt(2)
	v_pk_mul_f32 v[150:151], v[160:161], s[0:1] op_sel_hi:[1,0]
	v_pk_mul_f32 v[154:155], v[158:159], s[0:1] op_sel_hi:[1,0]
	s_waitcnt vmcnt(1)
	v_pk_mul_f32 v[156:157], v[164:165], s[0:1] op_sel_hi:[1,0]
	v_pk_mul_f32 v[158:159], v[162:163], s[0:1] op_sel_hi:[1,0]
	s_waitcnt vmcnt(0)
	v_pk_mul_f32 v[160:161], v[168:169], s[0:1] op_sel_hi:[1,0]
	v_pk_mul_f32 v[162:163], v[166:167], s[0:1] op_sel_hi:[1,0]
	v_pk_fma_f32 v[84:85], v[84:85], 0.5, v[132:133] op_sel_hi:[1,0,1]
	v_pk_fma_f32 v[82:83], v[82:83], 0.5, v[136:137] op_sel_hi:[1,0,1]
	v_pk_fma_f32 v[80:81], v[80:81], 0.5, v[150:151] op_sel_hi:[1,0,1]
	v_pk_fma_f32 v[78:79], v[78:79], 0.5, v[154:155] op_sel_hi:[1,0,1]
	v_pk_fma_f32 v[72:73], v[72:73], 0.5, v[156:157] op_sel_hi:[1,0,1]
	v_pk_fma_f32 v[70:71], v[70:71], 0.5, v[158:159] op_sel_hi:[1,0,1]
	v_pk_fma_f32 v[68:69], v[68:69], 0.5, v[160:161] op_sel_hi:[1,0,1]
	v_pk_fma_f32 v[66:67], v[66:67], 0.5, v[162:163] op_sel_hi:[1,0,1]
	v_add_u32_e32 v132, 0x90, v134
	global_load_dwordx4 v[154:157], v[138:139], off
	global_load_dwordx4 v[158:161], v[138:139], off offset:64
	global_load_dwordx4 v[162:165], v[138:139], off offset:512
	global_load_dwordx4 v[166:169], v[138:139], off offset:576
	v_ashrrev_i32_e32 v133, 31, v132
	v_lshlrev_b64 v[132:133], 12, v[132:133]
	v_lshl_add_u64 v[132:133], s[90:91], 0, v[132:133]
	v_lshl_add_u64 v[136:137], v[132:133], 0, v[148:149]
	s_waitcnt vmcnt(3)
	v_pk_mul_f32 v[132:133], v[156:157], s[0:1] op_sel_hi:[1,0]
	v_pk_mul_f32 v[150:151], v[154:155], s[0:1] op_sel_hi:[1,0]
	s_waitcnt vmcnt(2)
	v_pk_mul_f32 v[154:155], v[160:161], s[0:1] op_sel_hi:[1,0]
	v_pk_mul_f32 v[156:157], v[158:159], s[0:1] op_sel_hi:[1,0]
	s_waitcnt vmcnt(1)
	v_pk_mul_f32 v[158:159], v[164:165], s[0:1] op_sel_hi:[1,0]
	v_pk_mul_f32 v[160:161], v[162:163], s[0:1] op_sel_hi:[1,0]
	s_waitcnt vmcnt(0)
	v_pk_mul_f32 v[162:163], v[168:169], s[0:1] op_sel_hi:[1,0]
	v_pk_mul_f32 v[164:165], v[166:167], s[0:1] op_sel_hi:[1,0]
	v_pk_fma_f32 v[64:65], v[64:65], 0.5, v[132:133] op_sel_hi:[1,0,1]
	v_pk_fma_f32 v[62:63], v[62:63], 0.5, v[150:151] op_sel_hi:[1,0,1]
	v_pk_fma_f32 v[60:61], v[60:61], 0.5, v[154:155] op_sel_hi:[1,0,1]
	v_pk_fma_f32 v[58:59], v[58:59], 0.5, v[156:157] op_sel_hi:[1,0,1]
	v_pk_fma_f32 v[56:57], v[56:57], 0.5, v[158:159] op_sel_hi:[1,0,1]
	v_pk_fma_f32 v[54:55], v[54:55], 0.5, v[160:161] op_sel_hi:[1,0,1]
	v_pk_fma_f32 v[52:53], v[52:53], 0.5, v[162:163] op_sel_hi:[1,0,1]
	v_pk_fma_f32 v[50:51], v[50:51], 0.5, v[164:165] op_sel_hi:[1,0,1]
	v_add_u32_e32 v132, 0xa0, v134
	global_load_dwordx4 v[154:157], v[136:137], off
	global_load_dwordx4 v[158:161], v[136:137], off offset:64
	global_load_dwordx4 v[162:165], v[136:137], off offset:512
	global_load_dwordx4 v[166:169], v[136:137], off offset:576
	v_ashrrev_i32_e32 v133, 31, v132
	v_lshlrev_b64 v[132:133], 12, v[132:133]
	v_lshl_add_u64 v[132:133], s[90:91], 0, v[132:133]
	v_lshl_add_u64 v[132:133], v[132:133], 0, v[148:149]
	v_add_u32_e32 v134, 0xb0, v134
	s_waitcnt vmcnt(3)
	v_pk_mul_f32 v[150:151], v[156:157], s[0:1] op_sel_hi:[1,0]
	v_pk_mul_f32 v[154:155], v[154:155], s[0:1] op_sel_hi:[1,0]
	s_waitcnt vmcnt(2)
	v_pk_mul_f32 v[156:157], v[160:161], s[0:1] op_sel_hi:[1,0]
	v_pk_mul_f32 v[158:159], v[158:159], s[0:1] op_sel_hi:[1,0]
	s_waitcnt vmcnt(1)
	v_pk_mul_f32 v[160:161], v[164:165], s[0:1] op_sel_hi:[1,0]
	v_pk_mul_f32 v[162:163], v[162:163], s[0:1] op_sel_hi:[1,0]
	s_waitcnt vmcnt(0)
	v_pk_mul_f32 v[164:165], v[168:169], s[0:1] op_sel_hi:[1,0]
	v_pk_mul_f32 v[166:167], v[166:167], s[0:1] op_sel_hi:[1,0]
	v_pk_fma_f32 v[48:49], v[48:49], 0.5, v[150:151] op_sel_hi:[1,0,1]
	v_pk_fma_f32 v[46:47], v[46:47], 0.5, v[154:155] op_sel_hi:[1,0,1]
	v_pk_fma_f32 v[44:45], v[44:45], 0.5, v[156:157] op_sel_hi:[1,0,1]
	v_pk_fma_f32 v[42:43], v[42:43], 0.5, v[158:159] op_sel_hi:[1,0,1]
	v_pk_fma_f32 v[40:41], v[40:41], 0.5, v[160:161] op_sel_hi:[1,0,1]
	v_pk_fma_f32 v[38:39], v[38:39], 0.5, v[162:163] op_sel_hi:[1,0,1]
	v_pk_fma_f32 v[36:37], v[36:37], 0.5, v[164:165] op_sel_hi:[1,0,1]
	v_pk_fma_f32 v[34:35], v[34:35], 0.5, v[166:167] op_sel_hi:[1,0,1]
	v_mbcnt_hi_u32_b32 v151, -1, v135
	global_load_dwordx4 v[154:157], v[132:133], off
	global_load_dwordx4 v[158:161], v[132:133], off offset:64
	global_load_dwordx4 v[162:165], v[132:133], off offset:512
	global_load_dwordx4 v[166:169], v[132:133], off offset:576
	v_and_b32_e32 v150, 64, v151
	v_xor_b32_e32 v135, 16, v151
	v_add_u32_e32 v184, 64, v150
	v_cmp_lt_i32_e32 vcc, v135, v184
	s_waitcnt vmcnt(3)
	v_pk_mul_f32 v[156:157], v[156:157], s[0:1] op_sel_hi:[1,0]
	v_cndmask_b32_e32 v150, v151, v135, vcc
	v_ashrrev_i32_e32 v135, 31, v134
	v_lshlrev_b64 v[134:135], 12, v[134:135]
	v_pk_mul_f32 v[154:155], v[154:155], s[0:1] op_sel_hi:[1,0]
	s_waitcnt vmcnt(2)
	v_pk_mul_f32 v[160:161], v[160:161], s[0:1] op_sel_hi:[1,0]
	v_pk_mul_f32 v[158:159], v[158:159], s[0:1] op_sel_hi:[1,0]
	s_waitcnt vmcnt(1)
	v_pk_mul_f32 v[164:165], v[164:165], s[0:1] op_sel_hi:[1,0]
	v_pk_mul_f32 v[162:163], v[162:163], s[0:1] op_sel_hi:[1,0]
	s_waitcnt vmcnt(0)
;     DI void fused(f32x4 (&acc)[2][2][4][2], const Unit& u, int wr, int wc, int fr_, int fq_, LAS unsigned char* lds, int wid, int lane_) const {
;     ...
;             for (int m = 0; m < 4; ++m) { const int r = u.pm * BM + ai * HALF + wr * 64 + m * 16 + fr; const size_t ro = (size_t)r * ldc + col0;
; #pragma unroll
;                 for (int bj = 0; bj < 2; ++bj)
; #pragma unroll
;                     for (int n = 0; n < 2; ++n) { const f32x4 h = *(const f32x4*)(Hin + ro + bj * HALF + n * 16); acc[ai][bj][m][n] = h * alpha + acc[ai][bj][m][n] * s; }
;                 asm volatile("" : "+v"(acc[ai][0][m][0]), "+v"(acc[ai][0][m][1]), "+v"(acc[ai][1][m][0]), "+v"(acc[ai][1][m][1]));
;                 asm volatile("" ::: "memory"); }
; #pragma unroll
;         for (int ai = 0; ai < 2; ++ai)
; #pragma unroll
;             for (int m = 0; m < 4; ++m) {
;                 float sm = 0.f;
; #pragma unroll
;                 for (int bj = 0; bj < 2; ++bj)
; #pragma unroll
;                     for (int n = 0; n < 2; ++n) { const f32x4 x = acc[ai][bj][m][n]; sm += (x[0] + x[1]) + (x[2] + x[3]); }
;                 sm += __shfl_xor(sm, 16); sm += __shfl_xor(sm, 32);
;                 const float mw = sm * (1.0f / 64.0f); float q = 0.f;
; #pragma unroll
;                 for (int bj = 0; bj < 2; ++bj)
; #pragma unroll
;                     for (int n = 0; n < 2; ++n) { const f32x4 d = acc[ai][bj][m][n] - mw; q += (d[0] * d[0] + d[1] * d[1]) + (d[2] * d[2] + d[3] * d[3]); }
;                 q += __shfl_xor(q, 16); q += __shfl_xor(q, 32);
;                 if (fq == 0) P[(ai * HALF + wr * 64 + m * 16 + fr) * 4 + wc] = (f32x2){mw, q};
;                 __builtin_amdgcn_sched_barrier(0);
;             }
	v_pk_mul_f32 v[168:169], v[168:169], s[0:1] op_sel_hi:[1,0]
	v_pk_mul_f32 v[166:167], v[166:167], s[0:1] op_sel_hi:[1,0]
	v_lshl_add_u64 v[134:135], s[90:91], 0, v[134:135]
	v_pk_fma_f32 v[32:33], v[32:33], 0.5, v[156:157] op_sel_hi:[1,0,1]
	v_pk_fma_f32 v[30:31], v[30:31], 0.5, v[154:155] op_sel_hi:[1,0,1]
	v_pk_fma_f32 v[28:29], v[28:29], 0.5, v[160:161] op_sel_hi:[1,0,1]
	v_pk_fma_f32 v[26:27], v[26:27], 0.5, v[158:159] op_sel_hi:[1,0,1]
	v_pk_fma_f32 v[24:25], v[24:25], 0.5, v[164:165] op_sel_hi:[1,0,1]
	v_pk_fma_f32 v[22:23], v[22:23], 0.5, v[162:163] op_sel_hi:[1,0,1]
	v_pk_fma_f32 v[20:21], v[20:21], 0.5, v[168:169] op_sel_hi:[1,0,1]
	v_pk_fma_f32 v[18:19], v[18:19], 0.5, v[166:167] op_sel_hi:[1,0,1]
	v_lshl_add_u64 v[134:135], v[134:135], 0, v[148:149]
	global_load_dwordx4 v[158:161], v[134:135], off
	global_load_dwordx4 v[162:165], v[134:135], off offset:64
	global_load_dwordx4 v[166:169], v[134:135], off offset:512
	global_load_dwordx4 v[170:173], v[134:135], off offset:576
	v_mov_b32_e32 v154, v122
	v_mov_b32_e32 v155, v125
	v_pk_add_f32 v[154:155], v[178:179], v[154:155]
	v_add_f32_e32 v157, v118, v119
	v_pk_add_f32 v[154:155], v[154:155], v[154:155] op_sel_hi:[0,1]
	v_mov_b32_e32 v156, v106
	v_mov_b32_e32 v154, v108
	v_pk_add_f32 v[156:157], v[156:157], v[180:181]
	v_pk_add_f32 v[154:155], v[154:155], v[182:183]
	v_lshlrev_b32_e32 v150, 2, v150
	v_pk_add_f32 v[154:155], v[156:157], v[154:155]
	v_xor_b32_e32 v156, 32, v151
	v_add_f32_e32 v154, v154, v155
	v_mov_b32_e32 v155, v154
	s_nop 1
	v_permlane16_swap_b32_e32 v154, v155
	v_cmp_lt_i32_e32 vcc, v156, v184
	s_waitcnt lgkmcnt(0)
	v_add_f32_e32 v154, v154, v155
	v_cndmask_b32_e32 v151, v151, v156, vcc
	v_lshlrev_b32_e32 v151, 2, v151
	v_mov_b32_e32 v155, v154
	s_nop 1
	v_permlane32_swap_b32_e32 v154, v155
	v_cmp_gt_u32_e32 vcc, 16, v153
	s_waitcnt lgkmcnt(0)
	v_add_f32_e32 v154, v154, v155
	v_fmamk_f32 v156, v154, 0xbc800000, v129
	v_fmamk_f32 v174, v154, 0xbc800000, v127
	v_fmamk_f32 v176, v154, 0xbc800000, v125
	v_fmamk_f32 v178, v154, 0xbc800000, v123
	v_fmamk_f32 v155, v154, 0xbc800000, v128
	v_fmamk_f32 v157, v154, 0xbc800000, v126
	v_fmamk_f32 v175, v154, 0xbc800000, v124
	v_fmamk_f32 v177, v154, 0xbc800000, v122
	v_fmamk_f32 v180, v154, 0xbc800000, v121
	v_fmamk_f32 v182, v154, 0xbc800000, v119
	v_mul_f32_e32 v174, v174, v174
	v_mul_f32_e32 v156, v156, v156
	v_mul_f32_e32 v178, v178, v178
	v_mul_f32_e32 v176, v176, v176
	v_fmamk_f32 v179, v154, 0xbc800000, v120
	v_fmamk_f32 v181, v154, 0xbc800000, v118
	v_fmamk_f32 v184, v154, 0xbc800000, v109
	v_fmamk_f32 v186, v154, 0xbc800000, v107
	v_mul_f32_e32 v182, v182, v182
	v_mul_f32_e32 v180, v180, v180
	v_fmac_f32_e32 v174, v157, v157
	v_fmac_f32_e32 v156, v155, v155
	v_fmac_f32_e32 v178, v177, v177
	v_fmac_f32_e32 v176, v175, v175
	v_fmamk_f32 v183, v154, 0xbc800000, v108
	v_fmamk_f32 v185, v154, 0xbc800000, v106
	v_mul_f32_e32 v186, v186, v186
	v_mul_f32_e32 v184, v184, v184
	v_fmac_f32_e32 v182, v181, v181
	v_fmac_f32_e32 v180, v179, v179
	v_add_f32_e32 v155, v174, v156
	v_add_f32_e32 v156, v178, v176
	v_fmac_f32_e32 v186, v185, v185
	v_fmac_f32_e32 v184, v183, v183
	v_add_f32_e32 v157, v182, v180
	v_add_f32_e32 v155, v155, v156
	v_add_f32_e32 v174, v186, v184
	v_add_f32_e32 v155, v157, v155
	v_add_f32_e32 v155, v174, v155
	v_mov_b32_e32 v156, v155
	s_nop 1
	v_permlane16_swap_b32_e32 v155, v156
	s_waitcnt lgkmcnt(0)
	v_add_f32_e32 v155, v155, v156
	v_mov_b32_e32 v156, v155
	s_nop 1
	v_permlane32_swap_b32_e32 v155, v156
	s_waitcnt vmcnt(3)
	v_pk_mul_f32 v[160:161], v[160:161], s[0:1] op_sel_hi:[1,0]
	v_pk_mul_f32 v[158:159], v[158:159], s[0:1] op_sel_hi:[1,0]
	s_waitcnt vmcnt(2)
	v_pk_mul_f32 v[164:165], v[164:165], s[0:1] op_sel_hi:[1,0]
	v_pk_mul_f32 v[162:163], v[162:163], s[0:1] op_sel_hi:[1,0]
	s_waitcnt vmcnt(1)
	v_pk_mul_f32 v[168:169], v[168:169], s[0:1] op_sel_hi:[1,0]
	v_pk_mul_f32 v[166:167], v[166:167], s[0:1] op_sel_hi:[1,0]
	s_waitcnt vmcnt(0)
	v_pk_mul_f32 v[172:173], v[172:173], s[0:1] op_sel_hi:[1,0]
	v_pk_mul_f32 v[170:171], v[170:171], s[0:1] op_sel_hi:[1,0]
	v_pk_fma_f32 v[16:17], v[16:17], 0.5, v[160:161] op_sel_hi:[1,0,1]
	v_pk_fma_f32 v[14:15], v[14:15], 0.5, v[158:159] op_sel_hi:[1,0,1]
	v_pk_fma_f32 v[12:13], v[12:13], 0.5, v[164:165] op_sel_hi:[1,0,1]
	v_pk_fma_f32 v[10:11], v[10:11], 0.5, v[162:163] op_sel_hi:[1,0,1]
	v_pk_fma_f32 v[8:9], v[8:9], 0.5, v[168:169] op_sel_hi:[1,0,1]
	v_pk_fma_f32 v[6:7], v[6:7], 0.5, v[166:167] op_sel_hi:[1,0,1]
	v_pk_fma_f32 v[4:5], v[4:5], 0.5, v[172:173] op_sel_hi:[1,0,1]
	v_pk_fma_f32 v[2:3], v[2:3], 0.5, v[170:171] op_sel_hi:[1,0,1]
	s_lshl_b32 s0, s24, 3
	s_add_i32 s4, s0, 0x100
	s_and_saveexec_b64 s[0:1], vcc
	s_cbranch_execz .LBB0_1246
	s_lshl_b32 s5, s23, 11
	s_add_i32 s5, s4, s5
	v_mul_f32_e32 v154, 0x3c800000, v154
	v_lshl_add_u32 v157, v153, 5, s5
	s_waitcnt lgkmcnt(0)
	v_add_f32_e32 v155, v155, v156
	ds_write_b64 v157, v[154:155]
;     DI void fused(f32x4 (&acc)[2][2][4][2], const Unit& u, int wr, int wc, int fr_, int fq_, LAS unsigned char* lds, int wid, int lane_) const {
;     ...
;             for (int m = 0; m < 4; ++m) {
;                 float sm = 0.f;
; #pragma unroll
;                 for (int bj = 0; bj < 2; ++bj)
; #pragma unroll
;                     for (int n = 0; n < 2; ++n) { const f32x4 x = acc[ai][bj][m][n]; sm += (x[0] + x[1]) + (x[2] + x[3]); }
;                 sm += __shfl_xor(sm, 16); sm += __shfl_xor(sm, 32);
;                 const float mw = sm * (1.0f / 64.0f); float q = 0.f;
; #pragma unroll
;                 for (int bj = 0; bj < 2; ++bj)
; #pragma unroll
;                     for (int n = 0; n < 2; ++n) { const f32x4 d = acc[ai][bj][m][n] - mw; q += (d[0] * d[0] + d[1] * d[1]) + (d[2] * d[2] + d[3] * d[3]); }
;                 q += __shfl_xor(q, 16); q += __shfl_xor(q, 32);
;                 if (fq == 0) P[(ai * HALF + wr * 64 + m * 16 + fr) * 4 + wc] = (f32x2){mw, q};
;                 __builtin_amdgcn_sched_barrier(0);
;             }
.LBB0_1246:
	s_or_b64 exec, exec, s[0:1]
	v_mov_b32_e32 v154, v115
	v_mov_b32_e32 v155, v116
	s_waitcnt lgkmcnt(0)
	v_mov_b32_e32 v156, v114
	v_mov_b32_e32 v157, v117
	v_pk_add_f32 v[154:155], v[154:155], v[156:157]
	v_mov_b32_e32 v156, v111
	v_mov_b32_e32 v157, v112
	v_mov_b32_e32 v158, v110
	v_mov_b32_e32 v159, v113
	v_pk_add_f32 v[156:157], v[156:157], v[158:159]
	v_add_f32_e32 v154, v154, v155
	v_pk_add_f32 v[156:157], v[156:157], v[156:157] op_sel_hi:[0,1]
	v_add_f32_e32 v155, 0, v154
	v_add_f32_e32 v159, v102, v103
	v_add_f32_e32 v161, v104, v105
	v_mov_b32_e32 v158, v90
	v_mov_b32_e32 v160, v91
	v_mov_b32_e32 v156, v92
	v_mov_b32_e32 v154, v93
	v_pk_add_f32 v[158:159], v[158:159], v[160:161]
	v_pk_add_f32 v[154:155], v[156:157], v[154:155]
	s_nop 0
	v_pk_add_f32 v[154:155], v[158:159], v[154:155]
	s_nop 0
	v_add_f32_e32 v154, v154, v155
	v_mov_b32_e32 v155, v154
	s_nop 1
	v_permlane16_swap_b32_e32 v154, v155
	s_waitcnt lgkmcnt(0)
	v_add_f32_e32 v154, v154, v155
	v_mov_b32_e32 v155, v154
	s_nop 1
	v_permlane32_swap_b32_e32 v154, v155
	s_waitcnt lgkmcnt(0)
	v_add_f32_e32 v154, v154, v155
	v_fmamk_f32 v156, v154, 0xbc800000, v117
	v_fmamk_f32 v158, v154, 0xbc800000, v115
	v_fmamk_f32 v155, v154, 0xbc800000, v116
	v_fmamk_f32 v157, v154, 0xbc800000, v114
	v_mul_f32_e32 v158, v158, v158
	v_mul_f32_e32 v156, v156, v156
	v_fmac_f32_e32 v158, v157, v157
	v_fmac_f32_e32 v156, v155, v155
	v_fmamk_f32 v157, v154, 0xbc800000, v113
	v_fmamk_f32 v159, v154, 0xbc800000, v111
	v_add_f32_e32 v155, v158, v156
	v_fmamk_f32 v156, v154, 0xbc800000, v112
	v_fmamk_f32 v158, v154, 0xbc800000, v110
	v_mul_f32_e32 v159, v159, v159
	v_mul_f32_e32 v157, v157, v157
	v_fmac_f32_e32 v159, v158, v158
	v_fmac_f32_e32 v157, v156, v156
	v_add_f32_e32 v156, v159, v157
	v_fmamk_f32 v157, v154, 0xbc800000, v105
	v_fmamk_f32 v159, v154, 0xbc800000, v103
	v_add_f32_e32 v155, v155, v156
	v_fmamk_f32 v156, v154, 0xbc800000, v104
	v_fmamk_f32 v158, v154, 0xbc800000, v102
	v_mul_f32_e32 v159, v159, v159
	v_mul_f32_e32 v157, v157, v157
	v_fmac_f32_e32 v159, v158, v158
	v_fmac_f32_e32 v157, v156, v156
	v_add_f32_e32 v156, v159, v157
	v_fmamk_f32 v157, v154, 0xbc800000, v93
	v_fmamk_f32 v159, v154, 0xbc800000, v91
	v_add_f32_e32 v155, v156, v155
	v_fmamk_f32 v156, v154, 0xbc800000, v92
	v_fmamk_f32 v158, v154, 0xbc800000, v90
	v_mul_f32_e32 v159, v159, v159
	v_mul_f32_e32 v157, v157, v157
	v_fmac_f32_e32 v159, v158, v158
	v_fmac_f32_e32 v157, v156, v156
	v_add_f32_e32 v156, v159, v157
	v_add_f32_e32 v155, v156, v155
	v_mov_b32_e32 v156, v155
	s_nop 1
	v_permlane16_swap_b32_e32 v155, v156
	s_waitcnt lgkmcnt(0)
	v_add_f32_e32 v155, v155, v156
	v_mov_b32_e32 v156, v155
	s_nop 1
	v_permlane32_swap_b32_e32 v155, v156
	s_and_saveexec_b64 s[0:1], vcc
	s_cbranch_execz .LBB0_1248
	s_lshl_b32 s5, s23, 11
	s_add_i32 s5, s4, s5
	v_mul_f32_e32 v154, 0x3c800000, v154
	v_lshl_add_u32 v157, v153, 5, s5
	s_waitcnt lgkmcnt(0)
	v_add_f32_e32 v155, v155, v156
	ds_write_b64 v157, v[154:155] offset:512
.LBB0_1248:
	s_or_b64 exec, exec, s[0:1]
	v_mov_b32_e32 v154, v99
	v_mov_b32_e32 v155, v100
	s_waitcnt lgkmcnt(0)
	v_mov_b32_e32 v156, v98
	v_mov_b32_e32 v157, v101
	v_pk_add_f32 v[154:155], v[154:155], v[156:157]
	v_mov_b32_e32 v156, v95
	v_mov_b32_e32 v157, v96
	v_mov_b32_e32 v158, v94
	v_mov_b32_e32 v159, v97
	v_pk_add_f32 v[156:157], v[156:157], v[158:159]
	v_add_f32_e32 v154, v154, v155
	v_pk_add_f32 v[156:157], v[156:157], v[156:157] op_sel_hi:[0,1]
	v_add_f32_e32 v155, 0, v154
	v_add_f32_e32 v159, v86, v87
	v_add_f32_e32 v161, v88, v89
	v_mov_b32_e32 v158, v74
	v_mov_b32_e32 v160, v75
	v_mov_b32_e32 v156, v76
	v_mov_b32_e32 v154, v77
	v_pk_add_f32 v[158:159], v[158:159], v[160:161]
	v_pk_add_f32 v[154:155], v[156:157], v[154:155]
	s_nop 0
	v_pk_add_f32 v[154:155], v[158:159], v[154:155]
	s_nop 0
	v_add_f32_e32 v154, v154, v155
	v_mov_b32_e32 v155, v154
	s_nop 1
	v_permlane16_swap_b32_e32 v154, v155
	s_waitcnt lgkmcnt(0)
	v_add_f32_e32 v154, v154, v155
	v_mov_b32_e32 v155, v154
	s_nop 1
	v_permlane32_swap_b32_e32 v154, v155
	s_waitcnt lgkmcnt(0)
	v_add_f32_e32 v154, v154, v155
	v_fmamk_f32 v156, v154, 0xbc800000, v101
	v_fmamk_f32 v158, v154, 0xbc800000, v99
	v_fmamk_f32 v155, v154, 0xbc800000, v100
	v_fmamk_f32 v157, v154, 0xbc800000, v98
	v_mul_f32_e32 v158, v158, v158
	v_mul_f32_e32 v156, v156, v156
	v_fmac_f32_e32 v158, v157, v157
	v_fmac_f32_e32 v156, v155, v155
	v_fmamk_f32 v157, v154, 0xbc800000, v97
	v_fmamk_f32 v159, v154, 0xbc800000, v95
	v_add_f32_e32 v155, v158, v156
	v_fmamk_f32 v156, v154, 0xbc800000, v96
	v_fmamk_f32 v158, v154, 0xbc800000, v94
	v_mul_f32_e32 v159, v159, v159
	v_mul_f32_e32 v157, v157, v157
	v_fmac_f32_e32 v159, v158, v158
	v_fmac_f32_e32 v157, v156, v156
	v_add_f32_e32 v156, v159, v157
	v_fmamk_f32 v157, v154, 0xbc800000, v89
	v_fmamk_f32 v159, v154, 0xbc800000, v87
	v_add_f32_e32 v155, v155, v156
	v_fmamk_f32 v156, v154, 0xbc800000, v88
	v_fmamk_f32 v158, v154, 0xbc800000, v86
	v_mul_f32_e32 v159, v159, v159
	v_mul_f32_e32 v157, v157, v157
	v_fmac_f32_e32 v159, v158, v158
	v_fmac_f32_e32 v157, v156, v156
	v_add_f32_e32 v156, v159, v157
	v_fmamk_f32 v157, v154, 0xbc800000, v77
	v_fmamk_f32 v159, v154, 0xbc800000, v75
	v_add_f32_e32 v155, v156, v155
	v_fmamk_f32 v156, v154, 0xbc800000, v76
	v_fmamk_f32 v158, v154, 0xbc800000, v74
	v_mul_f32_e32 v159, v159, v159
	v_mul_f32_e32 v157, v157, v157
	v_fmac_f32_e32 v159, v158, v158
	v_fmac_f32_e32 v157, v156, v156
	v_add_f32_e32 v156, v159, v157
	v_add_f32_e32 v155, v156, v155
	v_mov_b32_e32 v156, v155
	s_nop 1
	v_permlane16_swap_b32_e32 v155, v156
	s_waitcnt lgkmcnt(0)
	v_add_f32_e32 v155, v155, v156
	v_mov_b32_e32 v156, v155
	s_nop 1
	v_permlane32_swap_b32_e32 v155, v156
	s_and_saveexec_b64 s[0:1], vcc
	s_cbranch_execz .LBB0_1250
	s_lshl_b32 s5, s23, 11
	s_add_i32 s5, s4, s5
	v_mul_f32_e32 v154, 0x3c800000, v154
	v_lshl_add_u32 v157, v153, 5, s5
	s_waitcnt lgkmcnt(0)
	v_add_f32_e32 v155, v155, v156
	ds_write_b64 v157, v[154:155] offset:1024
;     DI void fused(f32x4 (&acc)[2][2][4][2], const Unit& u, int wr, int wc, int fr_, int fq_, LAS unsigned char* lds, int wid, int lane_) const {
;     ...
;             for (int m = 0; m < 4; ++m) {
;                 float sm = 0.f;
; #pragma unroll
;                 for (int bj = 0; bj < 2; ++bj)
; #pragma unroll
;                     for (int n = 0; n < 2; ++n) { const f32x4 x = acc[ai][bj][m][n]; sm += (x[0] + x[1]) + (x[2] + x[3]); }
;                 sm += __shfl_xor(sm, 16); sm += __shfl_xor(sm, 32);
;                 const float mw = sm * (1.0f / 64.0f); float q = 0.f;
; #pragma unroll
;                 for (int bj = 0; bj < 2; ++bj)
; #pragma unroll
;                     for (int n = 0; n < 2; ++n) { const f32x4 d = acc[ai][bj][m][n] - mw; q += (d[0] * d[0] + d[1] * d[1]) + (d[2] * d[2] + d[3] * d[3]); }
;                 q += __shfl_xor(q, 16); q += __shfl_xor(q, 32);
;                 if (fq == 0) P[(ai * HALF + wr * 64 + m * 16 + fr) * 4 + wc] = (f32x2){mw, q};
;                 __builtin_amdgcn_sched_barrier(0);
;             }
.LBB0_1250:
	s_or_b64 exec, exec, s[0:1]
	v_mov_b32_e32 v154, v83
	v_mov_b32_e32 v155, v84
	s_waitcnt lgkmcnt(0)
	v_mov_b32_e32 v156, v82
	v_mov_b32_e32 v157, v85
	v_pk_add_f32 v[154:155], v[154:155], v[156:157]
	v_mov_b32_e32 v156, v79
	v_mov_b32_e32 v157, v80
	v_mov_b32_e32 v158, v78
	v_mov_b32_e32 v159, v81
	v_pk_add_f32 v[156:157], v[156:157], v[158:159]
	v_add_f32_e32 v154, v154, v155
	v_pk_add_f32 v[156:157], v[156:157], v[156:157] op_sel_hi:[0,1]
	v_add_f32_e32 v155, 0, v154
	v_add_f32_e32 v159, v70, v71
	v_add_f32_e32 v161, v72, v73
	v_mov_b32_e32 v158, v66
	v_mov_b32_e32 v160, v67
	v_mov_b32_e32 v156, v68
	v_mov_b32_e32 v154, v69
	v_pk_add_f32 v[158:159], v[158:159], v[160:161]
	v_pk_add_f32 v[154:155], v[156:157], v[154:155]
	s_nop 0
	v_pk_add_f32 v[154:155], v[158:159], v[154:155]
	s_nop 0
	v_add_f32_e32 v154, v154, v155
	v_mov_b32_e32 v155, v154
	s_nop 1
	v_permlane16_swap_b32_e32 v154, v155
	s_waitcnt lgkmcnt(0)
	v_add_f32_e32 v154, v154, v155
	v_mov_b32_e32 v155, v154
	s_nop 1
	v_permlane32_swap_b32_e32 v154, v155
	s_waitcnt lgkmcnt(0)
	v_add_f32_e32 v154, v154, v155
	v_fmamk_f32 v156, v154, 0xbc800000, v85
	v_fmamk_f32 v158, v154, 0xbc800000, v83
	v_fmamk_f32 v155, v154, 0xbc800000, v84
	v_fmamk_f32 v157, v154, 0xbc800000, v82
	v_mul_f32_e32 v158, v158, v158
	v_mul_f32_e32 v156, v156, v156
	v_fmac_f32_e32 v158, v157, v157
	v_fmac_f32_e32 v156, v155, v155
	v_fmamk_f32 v157, v154, 0xbc800000, v81
	v_fmamk_f32 v159, v154, 0xbc800000, v79
	v_add_f32_e32 v155, v158, v156
	v_fmamk_f32 v156, v154, 0xbc800000, v80
	v_fmamk_f32 v158, v154, 0xbc800000, v78
	v_mul_f32_e32 v159, v159, v159
	v_mul_f32_e32 v157, v157, v157
	v_fmac_f32_e32 v159, v158, v158
	v_fmac_f32_e32 v157, v156, v156
	v_add_f32_e32 v156, v159, v157
	v_fmamk_f32 v157, v154, 0xbc800000, v73
	v_fmamk_f32 v159, v154, 0xbc800000, v71
	v_add_f32_e32 v155, v155, v156
	v_fmamk_f32 v156, v154, 0xbc800000, v72
	v_fmamk_f32 v158, v154, 0xbc800000, v70
	v_mul_f32_e32 v159, v159, v159
	v_mul_f32_e32 v157, v157, v157
	v_fmac_f32_e32 v159, v158, v158
	v_fmac_f32_e32 v157, v156, v156
	v_add_f32_e32 v156, v159, v157
	v_fmamk_f32 v157, v154, 0xbc800000, v69
	v_fmamk_f32 v159, v154, 0xbc800000, v67
	v_add_f32_e32 v155, v156, v155
	v_fmamk_f32 v156, v154, 0xbc800000, v68
	v_fmamk_f32 v158, v154, 0xbc800000, v66
	v_mul_f32_e32 v159, v159, v159
	v_mul_f32_e32 v157, v157, v157
	v_fmac_f32_e32 v159, v158, v158
	v_fmac_f32_e32 v157, v156, v156
	v_add_f32_e32 v156, v159, v157
	v_add_f32_e32 v155, v156, v155
	v_mov_b32_e32 v156, v155
	s_nop 1
	v_permlane16_swap_b32_e32 v155, v156
	s_waitcnt lgkmcnt(0)
	v_add_f32_e32 v155, v155, v156
	v_mov_b32_e32 v156, v155
	s_nop 1
	v_permlane32_swap_b32_e32 v155, v156
	s_and_saveexec_b64 s[0:1], vcc
	s_cbranch_execz .LBB0_1252
	s_lshl_b32 s5, s23, 11
	s_add_i32 s5, s4, s5
	v_mul_f32_e32 v154, 0x3c800000, v154
	v_lshl_add_u32 v157, v153, 5, s5
	s_waitcnt lgkmcnt(0)
	v_add_f32_e32 v155, v155, v156
	ds_write_b64 v157, v[154:155] offset:1536
.LBB0_1252:
	s_or_b64 exec, exec, s[0:1]
	v_mov_b32_e32 v154, v63
	v_mov_b32_e32 v155, v64
	s_waitcnt lgkmcnt(0)
	v_mov_b32_e32 v156, v62
	v_mov_b32_e32 v157, v65
	v_pk_add_f32 v[154:155], v[154:155], v[156:157]
	v_mov_b32_e32 v156, v59
	v_mov_b32_e32 v157, v60
	v_mov_b32_e32 v158, v58
	v_mov_b32_e32 v159, v61
	v_pk_add_f32 v[156:157], v[156:157], v[158:159]
	v_add_f32_e32 v154, v154, v155
	v_pk_add_f32 v[156:157], v[156:157], v[156:157] op_sel_hi:[0,1]
	v_add_f32_e32 v155, 0, v154
	v_add_f32_e32 v159, v54, v55
	v_add_f32_e32 v161, v56, v57
	v_mov_b32_e32 v158, v50
	v_mov_b32_e32 v160, v51
	v_mov_b32_e32 v156, v52
	v_mov_b32_e32 v154, v53
	v_pk_add_f32 v[158:159], v[158:159], v[160:161]
	v_pk_add_f32 v[154:155], v[156:157], v[154:155]
	s_nop 0
	v_pk_add_f32 v[154:155], v[158:159], v[154:155]
	s_nop 0
	v_add_f32_e32 v154, v154, v155
	v_mov_b32_e32 v155, v154
	s_nop 1
	v_permlane16_swap_b32_e32 v154, v155
	s_waitcnt lgkmcnt(0)
	v_add_f32_e32 v154, v154, v155
	v_mov_b32_e32 v155, v154
	s_nop 1
	v_permlane32_swap_b32_e32 v154, v155
	s_waitcnt lgkmcnt(0)
	v_add_f32_e32 v154, v154, v155
	v_fmamk_f32 v156, v154, 0xbc800000, v65
	v_fmamk_f32 v158, v154, 0xbc800000, v63
	v_fmamk_f32 v155, v154, 0xbc800000, v64
	v_fmamk_f32 v157, v154, 0xbc800000, v62
	v_mul_f32_e32 v158, v158, v158
	v_mul_f32_e32 v156, v156, v156
	v_fmac_f32_e32 v158, v157, v157
	v_fmac_f32_e32 v156, v155, v155
	v_fmamk_f32 v157, v154, 0xbc800000, v61
	v_fmamk_f32 v159, v154, 0xbc800000, v59
	v_add_f32_e32 v155, v158, v156
	v_fmamk_f32 v156, v154, 0xbc800000, v60
	v_fmamk_f32 v158, v154, 0xbc800000, v58
	v_mul_f32_e32 v159, v159, v159
	v_mul_f32_e32 v157, v157, v157
	v_fmac_f32_e32 v159, v158, v158
	v_fmac_f32_e32 v157, v156, v156
	v_add_f32_e32 v156, v159, v157
	v_fmamk_f32 v157, v154, 0xbc800000, v57
	v_fmamk_f32 v159, v154, 0xbc800000, v55
	v_add_f32_e32 v155, v155, v156
	v_fmamk_f32 v156, v154, 0xbc800000, v56
	v_fmamk_f32 v158, v154, 0xbc800000, v54
	v_mul_f32_e32 v159, v159, v159
	v_mul_f32_e32 v157, v157, v157
	v_fmac_f32_e32 v159, v158, v158
	v_fmac_f32_e32 v157, v156, v156
	v_add_f32_e32 v156, v159, v157
	v_fmamk_f32 v157, v154, 0xbc800000, v53
	v_fmamk_f32 v159, v154, 0xbc800000, v51
	v_add_f32_e32 v155, v156, v155
	v_fmamk_f32 v156, v154, 0xbc800000, v52
	v_fmamk_f32 v158, v154, 0xbc800000, v50
	v_mul_f32_e32 v159, v159, v159
	v_mul_f32_e32 v157, v157, v157
	v_fmac_f32_e32 v159, v158, v158
	v_fmac_f32_e32 v157, v156, v156
	v_add_f32_e32 v156, v159, v157
	v_add_f32_e32 v155, v156, v155
	v_mov_b32_e32 v156, v155
	s_nop 1
	v_permlane16_swap_b32_e32 v155, v156
	s_waitcnt lgkmcnt(0)
	v_add_f32_e32 v155, v155, v156
	v_mov_b32_e32 v156, v155
	s_nop 1
	v_permlane32_swap_b32_e32 v155, v156
	s_and_saveexec_b64 s[0:1], vcc
	s_cbranch_execz .LBB0_1254
	s_lshl_b32 s5, s23, 11
	s_add_i32 s5, s4, s5
	v_mul_f32_e32 v154, 0x3c800000, v154
	v_lshl_add_u32 v157, v153, 5, s5
	s_waitcnt lgkmcnt(0)
	v_add_f32_e32 v155, v155, v156
	ds_write_b64 v157, v[154:155] offset:4096
;     DI void fused(f32x4 (&acc)[2][2][4][2], const Unit& u, int wr, int wc, int fr_, int fq_, LAS unsigned char* lds, int wid, int lane_) const {
;     ...
;             for (int m = 0; m < 4; ++m) {
;                 float sm = 0.f;
; #pragma unroll
;                 for (int bj = 0; bj < 2; ++bj)
; #pragma unroll
;                     for (int n = 0; n < 2; ++n) { const f32x4 x = acc[ai][bj][m][n]; sm += (x[0] + x[1]) + (x[2] + x[3]); }
;                 sm += __shfl_xor(sm, 16); sm += __shfl_xor(sm, 32);
;                 const float mw = sm * (1.0f / 64.0f); float q = 0.f;
; #pragma unroll
;                 for (int bj = 0; bj < 2; ++bj)
; #pragma unroll
;                     for (int n = 0; n < 2; ++n) { const f32x4 d = acc[ai][bj][m][n] - mw; q += (d[0] * d[0] + d[1] * d[1]) + (d[2] * d[2] + d[3] * d[3]); }
;                 q += __shfl_xor(q, 16); q += __shfl_xor(q, 32);
;                 if (fq == 0) P[(ai * HALF + wr * 64 + m * 16 + fr) * 4 + wc] = (f32x2){mw, q};
;                 __builtin_amdgcn_sched_barrier(0);
;             }
.LBB0_1254:
	s_or_b64 exec, exec, s[0:1]
	v_mov_b32_e32 v154, v47
	v_mov_b32_e32 v155, v48
	s_waitcnt lgkmcnt(0)
	v_mov_b32_e32 v156, v46
	v_mov_b32_e32 v157, v49
	v_pk_add_f32 v[154:155], v[154:155], v[156:157]
	v_mov_b32_e32 v156, v43
	v_mov_b32_e32 v157, v44
	v_mov_b32_e32 v158, v42
	v_mov_b32_e32 v159, v45
	v_pk_add_f32 v[156:157], v[156:157], v[158:159]
	v_add_f32_e32 v154, v154, v155
	v_pk_add_f32 v[156:157], v[156:157], v[156:157] op_sel_hi:[0,1]
	v_add_f32_e32 v155, 0, v154
	v_add_f32_e32 v159, v38, v39
	v_add_f32_e32 v161, v40, v41
	v_mov_b32_e32 v158, v34
	v_mov_b32_e32 v160, v35
	v_mov_b32_e32 v156, v36
	v_mov_b32_e32 v154, v37
	v_pk_add_f32 v[158:159], v[158:159], v[160:161]
	v_pk_add_f32 v[154:155], v[156:157], v[154:155]
	s_nop 0
	v_pk_add_f32 v[154:155], v[158:159], v[154:155]
	s_nop 0
	v_add_f32_e32 v154, v154, v155
	v_mov_b32_e32 v155, v154
	s_nop 1
	v_permlane16_swap_b32_e32 v154, v155
	s_waitcnt lgkmcnt(0)
	v_add_f32_e32 v154, v154, v155
	v_mov_b32_e32 v155, v154
	s_nop 1
	v_permlane32_swap_b32_e32 v154, v155
	s_waitcnt lgkmcnt(0)
	v_add_f32_e32 v154, v154, v155
	v_fmamk_f32 v156, v154, 0xbc800000, v49
	v_fmamk_f32 v158, v154, 0xbc800000, v47
	v_fmamk_f32 v155, v154, 0xbc800000, v48
	v_fmamk_f32 v157, v154, 0xbc800000, v46
	v_mul_f32_e32 v158, v158, v158
	v_mul_f32_e32 v156, v156, v156
	v_fmac_f32_e32 v158, v157, v157
	v_fmac_f32_e32 v156, v155, v155
	v_fmamk_f32 v157, v154, 0xbc800000, v45
	v_fmamk_f32 v159, v154, 0xbc800000, v43
	v_add_f32_e32 v155, v158, v156
	v_fmamk_f32 v156, v154, 0xbc800000, v44
	v_fmamk_f32 v158, v154, 0xbc800000, v42
	v_mul_f32_e32 v159, v159, v159
	v_mul_f32_e32 v157, v157, v157
	v_fmac_f32_e32 v159, v158, v158
	v_fmac_f32_e32 v157, v156, v156
	v_add_f32_e32 v156, v159, v157
	v_fmamk_f32 v157, v154, 0xbc800000, v41
	v_fmamk_f32 v159, v154, 0xbc800000, v39
	v_add_f32_e32 v155, v155, v156
	v_fmamk_f32 v156, v154, 0xbc800000, v40
	v_fmamk_f32 v158, v154, 0xbc800000, v38
	v_mul_f32_e32 v159, v159, v159
	v_mul_f32_e32 v157, v157, v157
	v_fmac_f32_e32 v159, v158, v158
	v_fmac_f32_e32 v157, v156, v156
	v_add_f32_e32 v156, v159, v157
	v_fmamk_f32 v157, v154, 0xbc800000, v37
	v_fmamk_f32 v159, v154, 0xbc800000, v35
	v_add_f32_e32 v155, v156, v155
	v_fmamk_f32 v156, v154, 0xbc800000, v36
	v_fmamk_f32 v158, v154, 0xbc800000, v34
	v_mul_f32_e32 v159, v159, v159
	v_mul_f32_e32 v157, v157, v157
	v_fmac_f32_e32 v159, v158, v158
	v_fmac_f32_e32 v157, v156, v156
	v_add_f32_e32 v156, v159, v157
	v_add_f32_e32 v155, v156, v155
	v_mov_b32_e32 v156, v155
	s_nop 1
	v_permlane16_swap_b32_e32 v155, v156
	s_waitcnt lgkmcnt(0)
	v_add_f32_e32 v155, v155, v156
	v_mov_b32_e32 v156, v155
	s_nop 1
	v_permlane32_swap_b32_e32 v155, v156
	s_and_saveexec_b64 s[0:1], vcc
	s_cbranch_execz .LBB0_1256
	s_lshl_b32 s5, s23, 11
	s_add_i32 s5, s4, s5
	v_mul_f32_e32 v154, 0x3c800000, v154
	v_lshl_add_u32 v157, v153, 5, s5
	s_waitcnt lgkmcnt(0)
	v_add_f32_e32 v155, v155, v156
	ds_write_b64 v157, v[154:155] offset:4608
;     DI void fused(f32x4 (&acc)[2][2][4][2], const Unit& u, int wr, int wc, int fr_, int fq_, LAS unsigned char* lds, int wid, int lane_) const {
;     ...
;             for (int m = 0; m < 4; ++m) {
;                 float sm = 0.f;
; #pragma unroll
;                 for (int bj = 0; bj < 2; ++bj)
; #pragma unroll
;                     for (int n = 0; n < 2; ++n) { const f32x4 x = acc[ai][bj][m][n]; sm += (x[0] + x[1]) + (x[2] + x[3]); }
;                 sm += __shfl_xor(sm, 16); sm += __shfl_xor(sm, 32);
;                 const float mw = sm * (1.0f / 64.0f); float q = 0.f;
; #pragma unroll
;                 for (int bj = 0; bj < 2; ++bj)
; #pragma unroll
;                     for (int n = 0; n < 2; ++n) { const f32x4 d = acc[ai][bj][m][n] - mw; q += (d[0] * d[0] + d[1] * d[1]) + (d[2] * d[2] + d[3] * d[3]); }
;                 q += __shfl_xor(q, 16); q += __shfl_xor(q, 32);
;                 if (fq == 0) P[(ai * HALF + wr * 64 + m * 16 + fr) * 4 + wc] = (f32x2){mw, q};
;                 __builtin_amdgcn_sched_barrier(0);
;             }
.LBB0_1256:
	s_or_b64 exec, exec, s[0:1]
	v_mov_b32_e32 v154, v31
	v_mov_b32_e32 v155, v32
	s_waitcnt lgkmcnt(0)
	v_mov_b32_e32 v156, v30
	v_mov_b32_e32 v157, v33
	v_pk_add_f32 v[154:155], v[154:155], v[156:157]
	v_mov_b32_e32 v156, v27
	v_mov_b32_e32 v157, v28
	v_mov_b32_e32 v158, v26
	v_mov_b32_e32 v159, v29
	v_pk_add_f32 v[156:157], v[156:157], v[158:159]
	v_add_f32_e32 v154, v154, v155
	v_pk_add_f32 v[156:157], v[156:157], v[156:157] op_sel_hi:[0,1]
	v_add_f32_e32 v155, 0, v154
	v_add_f32_e32 v159, v22, v23
	v_add_f32_e32 v161, v24, v25
	v_mov_b32_e32 v158, v18
	v_mov_b32_e32 v160, v19
	v_mov_b32_e32 v156, v20
	v_mov_b32_e32 v154, v21
	v_pk_add_f32 v[158:159], v[158:159], v[160:161]
	v_pk_add_f32 v[154:155], v[156:157], v[154:155]
	s_nop 0
	v_pk_add_f32 v[154:155], v[158:159], v[154:155]
	s_nop 0
	v_add_f32_e32 v154, v154, v155
	v_mov_b32_e32 v155, v154
	s_nop 1
	v_permlane16_swap_b32_e32 v154, v155
	s_waitcnt lgkmcnt(0)
	v_add_f32_e32 v154, v154, v155
	v_mov_b32_e32 v155, v154
	s_nop 1
	v_permlane32_swap_b32_e32 v154, v155
	s_waitcnt lgkmcnt(0)
	v_add_f32_e32 v154, v154, v155
	v_fmamk_f32 v156, v154, 0xbc800000, v33
	v_fmamk_f32 v158, v154, 0xbc800000, v31
	v_fmamk_f32 v155, v154, 0xbc800000, v32
	v_fmamk_f32 v157, v154, 0xbc800000, v30
	v_mul_f32_e32 v158, v158, v158
	v_mul_f32_e32 v156, v156, v156
	v_fmac_f32_e32 v158, v157, v157
	v_fmac_f32_e32 v156, v155, v155
	v_fmamk_f32 v157, v154, 0xbc800000, v29
	v_fmamk_f32 v159, v154, 0xbc800000, v27
	v_add_f32_e32 v155, v158, v156
	v_fmamk_f32 v156, v154, 0xbc800000, v28
	v_fmamk_f32 v158, v154, 0xbc800000, v26
	v_mul_f32_e32 v159, v159, v159
	v_mul_f32_e32 v157, v157, v157
	v_fmac_f32_e32 v159, v158, v158
	v_fmac_f32_e32 v157, v156, v156
	v_add_f32_e32 v156, v159, v157
	v_fmamk_f32 v157, v154, 0xbc800000, v25
	v_fmamk_f32 v159, v154, 0xbc800000, v23
	v_add_f32_e32 v155, v155, v156
	v_fmamk_f32 v156, v154, 0xbc800000, v24
	v_fmamk_f32 v158, v154, 0xbc800000, v22
	v_mul_f32_e32 v159, v159, v159
	v_mul_f32_e32 v157, v157, v157
	v_fmac_f32_e32 v159, v158, v158
	v_fmac_f32_e32 v157, v156, v156
	v_add_f32_e32 v156, v159, v157
	v_fmamk_f32 v157, v154, 0xbc800000, v21
	v_fmamk_f32 v159, v154, 0xbc800000, v19
	v_add_f32_e32 v155, v156, v155
	v_fmamk_f32 v156, v154, 0xbc800000, v20
	v_fmamk_f32 v158, v154, 0xbc800000, v18
	v_mul_f32_e32 v159, v159, v159
	v_mul_f32_e32 v157, v157, v157
	v_fmac_f32_e32 v159, v158, v158
	v_fmac_f32_e32 v157, v156, v156
	v_add_f32_e32 v156, v159, v157
	v_add_f32_e32 v155, v156, v155
	v_mov_b32_e32 v156, v155
	s_nop 1
	v_permlane16_swap_b32_e32 v155, v156
	s_waitcnt lgkmcnt(0)
	v_add_f32_e32 v155, v155, v156
	v_mov_b32_e32 v156, v155
	s_nop 1
	v_permlane32_swap_b32_e32 v155, v156
	s_and_saveexec_b64 s[0:1], vcc
	s_cbranch_execz .LBB0_1258
	s_lshl_b32 s5, s23, 11
	s_add_i32 s5, s4, s5
	v_mul_f32_e32 v154, 0x3c800000, v154
	v_lshl_add_u32 v157, v153, 5, s5
	s_waitcnt lgkmcnt(0)
	v_add_f32_e32 v155, v155, v156
	ds_write_b64 v157, v[154:155] offset:5120
.LBB0_1258:
	s_or_b64 exec, exec, s[0:1]
	v_mov_b32_e32 v154, v15
	v_mov_b32_e32 v155, v16
	s_waitcnt lgkmcnt(0)
	v_mov_b32_e32 v156, v14
	v_mov_b32_e32 v157, v17
	v_pk_add_f32 v[154:155], v[154:155], v[156:157]
	v_mov_b32_e32 v156, v11
	v_mov_b32_e32 v157, v12
	v_mov_b32_e32 v158, v10
	v_mov_b32_e32 v159, v13
	v_pk_add_f32 v[156:157], v[156:157], v[158:159]
	v_add_f32_e32 v154, v154, v155
	v_pk_add_f32 v[156:157], v[156:157], v[156:157] op_sel_hi:[0,1]
	v_add_f32_e32 v155, 0, v154
	v_add_f32_e32 v159, v6, v7
	v_add_f32_e32 v161, v8, v9
	v_mov_b32_e32 v158, v2
	v_mov_b32_e32 v160, v3
	v_mov_b32_e32 v156, v4
	v_mov_b32_e32 v154, v5
	v_pk_add_f32 v[158:159], v[158:159], v[160:161]
	v_pk_add_f32 v[154:155], v[156:157], v[154:155]
	s_nop 0
	v_pk_add_f32 v[154:155], v[158:159], v[154:155]
	s_nop 0
	v_add_f32_e32 v154, v154, v155
	v_mov_b32_e32 v155, v154
	s_nop 1
	v_permlane16_swap_b32_e32 v154, v155
	s_waitcnt lgkmcnt(0)
	v_add_f32_e32 v154, v154, v155
	v_mov_b32_e32 v155, v154
	s_nop 1
	v_permlane32_swap_b32_e32 v154, v155
	s_waitcnt lgkmcnt(0)
	v_add_f32_e32 v154, v154, v155
	v_fmamk_f32 v156, v154, 0xbc800000, v17
	v_fmamk_f32 v158, v154, 0xbc800000, v15
	v_fmamk_f32 v155, v154, 0xbc800000, v16
	v_fmamk_f32 v157, v154, 0xbc800000, v14
	v_mul_f32_e32 v158, v158, v158
	v_mul_f32_e32 v156, v156, v156
	v_fmac_f32_e32 v158, v157, v157
	v_fmac_f32_e32 v156, v155, v155
	v_fmamk_f32 v157, v154, 0xbc800000, v13
	v_fmamk_f32 v159, v154, 0xbc800000, v11
	v_add_f32_e32 v155, v158, v156
	v_fmamk_f32 v156, v154, 0xbc800000, v12
	v_fmamk_f32 v158, v154, 0xbc800000, v10
	v_mul_f32_e32 v159, v159, v159
	v_mul_f32_e32 v157, v157, v157
	v_fmac_f32_e32 v159, v158, v158
	v_fmac_f32_e32 v157, v156, v156
	v_add_f32_e32 v156, v159, v157
	v_fmamk_f32 v157, v154, 0xbc800000, v9
	v_fmamk_f32 v159, v154, 0xbc800000, v7
	v_add_f32_e32 v155, v155, v156
	v_fmamk_f32 v156, v154, 0xbc800000, v8
	v_fmamk_f32 v158, v154, 0xbc800000, v6
	v_mul_f32_e32 v159, v159, v159
	v_mul_f32_e32 v157, v157, v157
	v_fmac_f32_e32 v159, v158, v158
	v_fmac_f32_e32 v157, v156, v156
	v_add_f32_e32 v156, v159, v157
	v_fmamk_f32 v157, v154, 0xbc800000, v5
	v_fmamk_f32 v159, v154, 0xbc800000, v3
	v_add_f32_e32 v155, v156, v155
	v_fmamk_f32 v156, v154, 0xbc800000, v4
	v_fmamk_f32 v158, v154, 0xbc800000, v2
	v_mul_f32_e32 v159, v159, v159
	v_mul_f32_e32 v157, v157, v157
	v_fmac_f32_e32 v159, v158, v158
	v_fmac_f32_e32 v157, v156, v156
	v_add_f32_e32 v156, v159, v157
	v_add_f32_e32 v155, v156, v155
	v_mov_b32_e32 v150, v155
	s_nop 1
	v_permlane16_swap_b32_e32 v155, v150
	s_waitcnt lgkmcnt(0)
	v_add_f32_e32 v150, v155, v150
	v_mov_b32_e32 v151, v150
	s_nop 1
	v_permlane32_swap_b32_e32 v150, v151
	s_and_saveexec_b64 s[0:1], vcc
	s_cbranch_execz .LBB0_1260
	s_lshl_b32 s5, s23, 11
	s_add_i32 s4, s4, s5
	v_mul_f32_e32 v154, 0x3c800000, v154
	v_lshl_add_u32 v156, v153, 5, s4
	s_waitcnt lgkmcnt(0)
	v_add_f32_e32 v155, v150, v151
	ds_write_b64 v156, v[154:155] offset:5632

; DI float bflo(unsigned w) { return __uint_as_float(w << 16); }
; DI float bfhi(unsigned w) { return __uint_as_float(w & 0xffff0000u); }
; DI float silu_f(float g) { return g * frcp(1.f + fexp2(-1.4426950408889634f * g)); }
;     ...
;     for (int which = 0; which < 3; ++which) {
;         const int t = tid >> 3, cg8 = tid & 7; const int col = which * 512 + h * 64 + cg8 * 8;
;         float acc[8];
; #pragma unroll
;         for (int e = 0; e < 8; ++e) acc[e] = 0.f;
; #pragma unroll
;         for (int j = 0; j < 4; ++j) { const int sp = n * 64 + t - 3 + j; const float ok = sp >= 0 ? 1.f : 0.f;
;             const u32x4 xv = xin[which * 4 + j];
;             const f32x4 w0 = *(const f32x4*)(conv_w + j * 1536 + col) * ok, w1 = *(const f32x4*)(conv_w + j * 1536 + col + 4) * ok;
;             acc[0] += w0[0] * bflo(xv.x); acc[1] += w0[1] * bfhi(xv.x); acc[2] += w0[2] * bflo(xv.y); acc[3] += w0[3] * bfhi(xv.y);
;             acc[4] += w1[0] * bflo(xv.z); acc[5] += w1[1] * bfhi(xv.z); acc[6] += w1[2] * bflo(xv.w); acc[7] += w1[3] * bfhi(xv.w); }
; #pragma unroll
;         for (int e = 0; e < 8; ++e) acc[e] = silu_f(acc[e]);
.LBB0_1745:
	s_lshl_b32 s16, s68, 6
	s_and_b32 s16, s16, 0xfc0
	v_add_u32_e32 v2, s16, v110
	v_cmp_lt_u32_e32 vcc, 2, v2
	s_bfe_u32 s24, s68, 0x30006
	s_bfe_u32 s100, s70, 0x30006
	s_xor_b32 s100, s100, s24
	s_mul_i32 s100, s100, 0x300
	v_lshlrev_b32_e32 v255, 2, v111
	v_add_u32_e32 v255, s100, v255
	v_add_u32_e32 v255, 0x24100, v255
	s_mov_b64 s[16:17], 0x1800
	v_cndmask_b32_e64 v26, 0, 1.0, vcc
	v_cmp_lt_u32_e32 vcc, 1, v2
	s_waitcnt vmcnt(0)
	s_lshl_b32 s101, s24, 2
	v_mov_b32_e32 v254, s101
	v_readlane_b32 s100, v247, 9
	v_readlane_b32 s101, v247, 10
	global_load_dword v252, v254, s[50:51] offset:32
	s_nop 4
	global_load_dword v253, v254, s[100:101] offset:32
	v_lshlrev_b32_e32 v208, 16, v54
	v_and_b32_e32 v209, 0xffff0000, v54
	v_cndmask_b32_e64 v24, 0, 1.0, vcc
	v_cmp_eq_u32_e32 vcc, 0, v2
	v_lshlrev_b32_e32 v2, 2, v111
	v_lshl_or_b32 v82, s24, 8, v2
	ds_read_b128 v[18:21], v255 offset:0
	ds_read_b128 v[2:5], v255 offset:16
	v_lshl_add_u64 v[14:15], s[44:45], 0, v[82:83]
	v_cndmask_b32_e64 v22, 1.0, 0, vcc
	s_waitcnt lgkmcnt(0)
	v_pk_mul_f32 v[18:19], v[26:27], v[18:19] op_sel_hi:[0,1]
	v_pk_mul_f32 v[8:9], v[4:5], v[26:27] op_sel_hi:[1,0]
	v_lshl_add_u64 v[4:5], v[14:15], 0, s[16:17]
	s_movk_i32 s16, 0x1000
	v_pk_mul_f32 v[10:11], v[2:3], v[26:27] op_sel_hi:[1,0]
	v_add_co_u32_e32 v2, vcc, s16, v14
	s_mov_b64 s[16:17], 0x3000
	s_nop 0
	v_addc_co_u32_e32 v3, vcc, 0, v15, vcc
	ds_read_b128 v[28:31], v255 offset:768
	s_nop 0
	ds_read_b128 v[4:7], v255 offset:784
	v_lshl_add_u64 v[32:33], v[14:15], 0, s[16:17]
	s_movk_i32 s16, 0x3000
	v_pk_mul_f32 v[20:21], v[26:27], v[20:21] op_sel_hi:[0,1]
	s_waitcnt lgkmcnt(0)
	v_pk_mul_f32 v[28:29], v[24:25], v[28:29] op_sel_hi:[0,1]
	v_pk_mul_f32 v[12:13], v[6:7], v[24:25] op_sel_hi:[1,0]
	v_add_co_u32_e32 v6, vcc, s16, v14
	s_movk_i32 s16, 0x4000
	s_nop 0
	v_addc_co_u32_e32 v7, vcc, 0, v15, vcc
	v_pk_mul_f32 v[16:17], v[4:5], v[24:25] op_sel_hi:[1,0]
	v_add_co_u32_e32 v4, vcc, s16, v14
	s_mov_b64 s[16:17], 0x4800
	s_nop 0
	v_addc_co_u32_e32 v5, vcc, 0, v15, vcc
	ds_read_b128 v[94:97], v255 offset:1536
	ds_read_b128 v[196:199], v255 offset:1552
	v_lshl_add_u64 v[200:201], v[14:15], 0, s[16:17]
	v_pk_mul_f32 v[30:31], v[24:25], v[30:31] op_sel_hi:[0,1]
	s_mov_b64 s[16:17], 0x2000
	s_waitcnt lgkmcnt(0)
	v_pk_mul_f32 v[94:95], v[22:23], v[94:95] op_sel_hi:[0,1]
	v_pk_mul_f32 v[32:33], v[198:199], v[22:23] op_sel_hi:[1,0]
	v_pk_mul_f32 v[98:99], v[196:197], v[22:23] op_sel_hi:[1,0]
	ds_read_b128 v[196:199], v255 offset:2304
	ds_read_b128 v[204:207], v255 offset:2320
	v_lshlrev_b32_e32 v200, 16, v70
	v_and_b32_e32 v201, 0xffff0000, v70
	v_pk_fma_f32 v[18:19], v[18:19], v[200:201], 0 op_sel_hi:[1,1,0]
	v_lshlrev_b32_e32 v200, 16, v74
	v_and_b32_e32 v201, 0xffff0000, v74
	v_pk_fma_f32 v[18:19], v[28:29], v[200:201], v[18:19]
	v_lshlrev_b32_e32 v28, 16, v58
	v_and_b32_e32 v29, 0xffff0000, v58
	v_pk_fma_f32 v[18:19], v[94:95], v[28:29], v[18:19]
	v_lshlrev_b32_e32 v28, 16, v78
	v_and_b32_e32 v29, 0xffff0000, v78
	v_pk_mul_f32 v[96:97], v[22:23], v[96:97] op_sel_hi:[0,1]
	s_waitcnt lgkmcnt(0)
	v_pk_fma_f32 v[18:19], v[196:197], v[28:29], v[18:19]
	s_nop 0
	v_mul_f32_e32 v23, 0xbfb8aa3b, v18
	v_exp_f32_e32 v23, v23
	s_nop 0
	v_add_f32_e32 v23, 1.0, v23
	v_rcp_f32_e32 v28, v23
	v_mul_f32_e32 v23, 0xbfb8aa3b, v19
	v_exp_f32_e32 v23, v23
	s_nop 0
	v_add_f32_e32 v23, 1.0, v23
	v_rcp_f32_e32 v29, v23
	s_nop 0
	v_pk_mul_f32 v[28:29], v[18:19], v[28:29]
	v_lshlrev_b32_e32 v18, 16, v71
	v_and_b32_e32 v19, 0xffff0000, v71
	v_pk_fma_f32 v[18:19], v[20:21], v[18:19], 0 op_sel_hi:[1,1,0]
	v_lshlrev_b32_e32 v20, 16, v75
	v_and_b32_e32 v21, 0xffff0000, v75
	v_pk_fma_f32 v[18:19], v[30:31], v[20:21], v[18:19]
	v_lshlrev_b32_e32 v20, 16, v59
	v_and_b32_e32 v21, 0xffff0000, v59
	v_pk_fma_f32 v[18:19], v[96:97], v[20:21], v[18:19]
	v_lshlrev_b32_e32 v20, 16, v79
	v_and_b32_e32 v21, 0xffff0000, v79
	v_pk_fma_f32 v[18:19], v[198:199], v[20:21], v[18:19]
	s_nop 0
	v_mul_f32_e32 v20, 0xbfb8aa3b, v18
	v_mul_f32_e32 v21, 0xbfb8aa3b, v19
	v_exp_f32_e32 v20, v20
	v_exp_f32_e32 v21, v21
	v_add_f32_e32 v20, 1.0, v20
	v_add_f32_e32 v21, 1.0, v21
	v_rcp_f32_e32 v20, v20
	v_rcp_f32_e32 v21, v21
	s_nop 0
	v_pk_mul_f32 v[20:21], v[18:19], v[20:21]
	v_lshlrev_b32_e32 v18, 16, v72
	v_and_b32_e32 v19, 0xffff0000, v72
	v_pk_fma_f32 v[10:11], v[10:11], v[18:19], 0 op_sel_hi:[1,1,0]
	v_lshlrev_b32_e32 v18, 16, v76
	v_and_b32_e32 v19, 0xffff0000, v76
	v_pk_fma_f32 v[10:11], v[16:17], v[18:19], v[10:11]
	v_lshlrev_b32_e32 v16, 16, v60
	v_and_b32_e32 v17, 0xffff0000, v60
	v_pk_fma_f32 v[10:11], v[98:99], v[16:17], v[10:11]
	v_lshlrev_b32_e32 v16, 16, v80
	v_and_b32_e32 v17, 0xffff0000, v80
	v_pk_fma_f32 v[10:11], v[204:205], v[16:17], v[10:11]
	s_nop 0
	v_mul_f32_e32 v16, 0xbfb8aa3b, v10
	v_mul_f32_e32 v17, 0xbfb8aa3b, v11
	v_exp_f32_e32 v16, v16
	v_exp_f32_e32 v17, v17
	v_add_f32_e32 v16, 1.0, v16
	v_add_f32_e32 v17, 1.0, v17
	v_rcp_f32_e32 v16, v16
	v_rcp_f32_e32 v17, v17
	s_nop 0
	v_pk_mul_f32 v[30:31], v[10:11], v[16:17]
	v_lshlrev_b32_e32 v10, 16, v73
	v_and_b32_e32 v11, 0xffff0000, v73
	v_pk_fma_f32 v[8:9], v[8:9], v[10:11], 0 op_sel_hi:[1,1,0]
	v_lshlrev_b32_e32 v10, 16, v77
	v_and_b32_e32 v11, 0xffff0000, v77
	v_pk_fma_f32 v[8:9], v[12:13], v[10:11], v[8:9]
	v_lshlrev_b32_e32 v10, 16, v61
	v_and_b32_e32 v11, 0xffff0000, v61
	v_pk_fma_f32 v[8:9], v[32:33], v[10:11], v[8:9]
	v_lshlrev_b32_e32 v10, 16, v81
	v_and_b32_e32 v11, 0xffff0000, v81
	v_pk_fma_f32 v[8:9], v[206:207], v[10:11], v[8:9]
	v_mov_b32_e32 v17, v31
	v_mul_f32_e32 v10, 0xbfb8aa3b, v9
	v_exp_f32_e32 v10, v10
	s_nop 0
	v_add_f32_e32 v10, 1.0, v10
	v_rcp_f32_e32 v11, v10
; #define LAS __attribute__((address_space(3)))
; DI unsigned pk2(float lo, float hi) { typedef __bf16 b2 __attribute__((ext_vector_type(2))); f32x2 v = {lo, hi}; b2 b = __builtin_convertvector(v, b2); return __builtin_bit_cast(unsigned, b); }
; DI float bflo(unsigned w) { return __uint_as_float(w << 16); }
; DI float bfhi(unsigned w) { return __uint_as_float(w & 0xffff0000u); }
; DI float silu_f(float g) { return g * frcp(1.f + fexp2(-1.4426950408889634f * g)); }
;     ...
;             acc[4] += w1[0] * bflo(xv.z); acc[5] += w1[1] * bfhi(xv.z); acc[6] += w1[2] * bflo(xv.w); acc[7] += w1[3] * bfhi(xv.w); }
; #pragma unroll
;         for (int e = 0; e < 8; ++e) acc[e] = silu_f(acc[e]);
;         if (which == 2) { LAS float* dst = vc + t * 68 + cg8 * 8; *(LAS f32x4*)dst = (f32x4){acc[0], acc[1], acc[2], acc[3]}; *(LAS f32x4*)(dst + 4) = (f32x4){acc[4], acc[5], acc[6], acc[7]}; }
;         else {
;             float ss = (acc[0] * acc[0] + acc[1] * acc[1]) + (acc[2] * acc[2] + acc[3] * acc[3]) + (acc[4] * acc[4] + acc[5] * acc[5]) + (acc[6] * acc[6] + acc[7] * acc[7]);
;             ss += __shfl_xor(ss, 1); ss += __shfl_xor(ss, 2); ss += __shfl_xor(ss, 4);
;             const float sc = (which ? 1.0f : 0.125f) * __builtin_amdgcn_rsqf(ss + 1e-6f);
;             const f32x4 y0 = (f32x4){acc[0], acc[1], acc[2], acc[3]} * sc, y1 = (f32x4){acc[4], acc[5], acc[6], acc[7]} * sc;
;             LAS float* dst = (which ? kc : qc) + t * 68 + cg8 * 8; *(LAS f32x4*)dst = y0; *(LAS f32x4*)(dst + 4) = y1;
;             u32x4 hh; hh.x = pk2(y0[0], y0[1]); hh.y = pk2(y0[2], y0[3]); hh.z = pk2(y1[0], y1[1]); hh.w = pk2(y1[2], y1[3]);
;             u32x4 lo; lo.x = pk2(y0[0] - bflo(hh.x), y0[1] - bfhi(hh.x)); lo.y = pk2(y0[2] - bflo(hh.y), y0[3] - bfhi(hh.y)); lo.z = pk2(y1[0] - bflo(hh.z), y1[1] - bfhi(hh.z)); lo.w = pk2(y1[2] - bflo(hh.w), y1[3] - bfhi(hh.w));
;             *(LAS u32x4*)((which ? KH : QH) + t * 72 + cg8 * 8) = hh; *(LAS u32x4*)((which ? KL : QL) + t * 72 + cg8 * 8) = lo; }
	v_mul_f32_e32 v10, 0xbfb8aa3b, v8
	v_exp_f32_e32 v10, v10
	s_nop 0
	v_add_f32_e32 v10, 1.0, v10
	v_rcp_f32_e32 v10, v10
	s_nop 0
	v_pk_mul_f32 v[12:13], v[8:9], v[10:11]
	v_mov_b32_e32 v10, v29
	v_mov_b32_e32 v11, v21
	v_mov_b32_e32 v8, v28
	v_mov_b32_e32 v9, v20
	v_pk_mul_f32 v[10:11], v[10:11], v[10:11]
	v_mov_b32_e32 v16, v13
	v_pk_fma_f32 v[8:9], v[8:9], v[8:9], v[10:11]
	v_mov_b32_e32 v10, v12
	v_mov_b32_e32 v11, v30
	v_pk_mul_f32 v[16:17], v[16:17], v[16:17]
	v_add_f32_e32 v8, v8, v9
	v_pk_fma_f32 v[10:11], v[10:11], v[10:11], v[16:17]
	s_nop 0
	v_add_f32_e32 v8, v11, v8
	v_add_f32_e32 v8, v10, v8
	s_nop 1
	v_add_f32_dpp v8, v8, v8 quad_perm:[1,0,3,2] row_mask:0xf bank_mask:0xf
	s_nop 1
	v_add_f32_dpp v8, v8, v8 quad_perm:[2,3,0,1] row_mask:0xf bank_mask:0xf
	s_nop 1
	v_add_f32_dpp v8, v8, v8 row_half_mirror row_mask:0xf bank_mask:0xf
	v_add_f32_e32 v8, 0x358637bd, v8
	v_rsq_f32_e32 v8, v8
	s_nop 0
	v_mul_f32_e32 v32, 0x3e000000, v8
	v_pk_mul_f32 v[10:11], v[20:21], v[32:33] op_sel_hi:[1,0]
	v_pk_mul_f32 v[8:9], v[28:29], v[32:33] op_sel_hi:[1,0]
	v_pk_mul_f32 v[18:19], v[12:13], v[32:33] op_sel_hi:[1,0]
	v_pk_mul_f32 v[16:17], v[30:31], v[32:33] op_sel_hi:[1,0]
	ds_write_b128 v112, v[8:11]
	ds_write_b128 v112, v[16:19] offset:16
	v_cvt_pk_bf16_f32 v8, v8, v9
	v_cvt_pk_bf16_f32 v9, v10, v11
	v_cvt_pk_bf16_f32 v10, v16, v17
	v_cvt_pk_bf16_f32 v11, v18, v19
	v_lshlrev_b32_e32 v16, 16, v8
	v_and_b32_e32 v17, 0xffff0000, v8
	v_lshlrev_b32_e32 v18, 16, v9
	v_and_b32_e32 v19, 0xffff0000, v9
	v_pk_fma_f32 v[16:17], v[28:29], v[32:33], v[16:17] op_sel_hi:[1,0,1] neg_lo:[0,0,1] neg_hi:[0,0,1]
	v_pk_fma_f32 v[18:19], v[20:21], v[32:33], v[18:19] op_sel_hi:[1,0,1] neg_lo:[0,0,1] neg_hi:[0,0,1]
	v_cvt_pk_bf16_f32 v16, v16, v17
	v_cvt_pk_bf16_f32 v17, v18, v19
	v_lshlrev_b32_e32 v18, 16, v10
	v_and_b32_e32 v19, 0xffff0000, v10
	v_lshlrev_b32_e32 v20, 16, v11
	v_and_b32_e32 v21, 0xffff0000, v11
	v_pk_fma_f32 v[18:19], v[30:31], v[32:33], v[18:19] op_sel_hi:[1,0,1] neg_lo:[0,0,1] neg_hi:[0,0,1]
	v_pk_fma_f32 v[12:13], v[12:13], v[32:33], v[20:21] op_sel_hi:[1,0,1] neg_lo:[0,0,1] neg_hi:[0,0,1]
	v_cvt_pk_bf16_f32 v18, v18, v19
	v_cvt_pk_bf16_f32 v19, v12, v13
	ds_write_b128 v113, v[8:11]
	ds_write_b128 v114, v[16:19]
	ds_read_b128 v[8:11], v255 offset:256
	ds_read_b128 v[16:19], v255 offset:272
	s_waitcnt lgkmcnt(0)
	v_pk_mul_f32 v[8:9], v[26:27], v[8:9] op_sel_hi:[0,1]
	s_waitcnt lgkmcnt(0)
	v_pk_mul_f32 v[32:33], v[26:27], v[16:17] op_sel_hi:[0,1]
	v_lshl_add_u64 v[16:17], v[14:15], 0, s[16:17]
	s_movk_i32 s16, 0x2000
	v_add_co_u32_e32 v98, vcc, s16, v14
	v_pk_mul_f32 v[12:13], v[26:27], v[18:19] op_sel_hi:[0,1]
	s_nop 0
	v_addc_co_u32_e32 v99, vcc, 0, v15, vcc
	ds_read_b128 v[18:21], v255 offset:1024
	ds_read_b128 v[28:31], v255 offset:1040
	s_mov_b64 s[16:17], 0x3800
	v_lshl_add_u64 v[16:17], v[14:15], 0, s[16:17]
	s_mov_b64 s[16:17], 0x5000
	v_lshl_add_u64 v[196:197], v[14:15], 0, s[16:17]
	s_movk_i32 s16, 0x5000
	v_pk_fma_f32 v[8:9], v[8:9], v[208:209], 0 op_sel_hi:[1,1,0]
	v_lshlrev_b32_e32 v208, 16, v62
	v_and_b32_e32 v209, 0xffff0000, v62
	v_pk_mul_f32 v[10:11], v[26:27], v[10:11] op_sel_hi:[0,1]
	s_waitcnt lgkmcnt(0)
	v_pk_mul_f32 v[18:19], v[24:25], v[18:19] op_sel_hi:[0,1]
	s_waitcnt lgkmcnt(0)
	v_pk_mul_f32 v[200:201], v[24:25], v[30:31] op_sel_hi:[0,1]
	v_pk_mul_f32 v[204:205], v[24:25], v[28:29] op_sel_hi:[0,1]
	ds_read_b128 v[28:31], v255 offset:1792
	ds_read_b128 v[94:97], v255 offset:1808
	v_add_co_u32_e32 v16, vcc, s16, v14
	v_pk_fma_f32 v[8:9], v[18:19], v[208:209], v[8:9]
	s_nop 0
	v_addc_co_u32_e32 v17, vcc, 0, v15, vcc
	v_lshlrev_b32_e32 v18, 16, v50
	v_and_b32_e32 v19, 0xffff0000, v50
	v_pk_mul_f32 v[20:21], v[24:25], v[20:21] op_sel_hi:[0,1]
	s_mov_b64 s[16:17], 0x1000
	s_andn2_b64 vcc, exec, s[46:47]
	s_waitcnt lgkmcnt(0)
	v_pk_mul_f32 v[28:29], v[22:23], v[28:29] op_sel_hi:[0,1]
	s_waitcnt lgkmcnt(0)
	v_pk_mul_f32 v[6:7], v[22:23], v[96:97] op_sel_hi:[0,1]
	v_pk_mul_f32 v[206:207], v[22:23], v[94:95] op_sel_hi:[0,1]
	ds_read_b128 v[94:97], v255 offset:2560
	s_nop 0
	ds_read_b128 v[196:199], v255 offset:2576
	v_pk_fma_f32 v[8:9], v[28:29], v[18:19], v[8:9]
	v_lshlrev_b32_e32 v18, 16, v66
	v_and_b32_e32 v19, 0xffff0000, v66
	v_pk_mul_f32 v[30:31], v[22:23], v[30:31] op_sel_hi:[0,1]
	s_waitcnt lgkmcnt(0)
	v_pk_fma_f32 v[8:9], v[94:95], v[18:19], v[8:9]
	s_nop 0
	v_mul_f32_e32 v18, 0xbfb8aa3b, v8
	v_mul_f32_e32 v19, 0xbfb8aa3b, v9
	v_exp_f32_e32 v18, v18
	v_exp_f32_e32 v19, v19
	v_add_f32_e32 v18, 1.0, v18
	v_add_f32_e32 v19, 1.0, v19
	v_rcp_f32_e32 v18, v18
	v_rcp_f32_e32 v19, v19
	s_nop 0
	v_pk_mul_f32 v[18:19], v[8:9], v[18:19]
	v_lshlrev_b32_e32 v8, 16, v55
	v_and_b32_e32 v9, 0xffff0000, v55
	v_pk_fma_f32 v[8:9], v[10:11], v[8:9], 0 op_sel_hi:[1,1,0]
	v_lshlrev_b32_e32 v10, 16, v63
	v_and_b32_e32 v11, 0xffff0000, v63
	v_pk_fma_f32 v[8:9], v[20:21], v[10:11], v[8:9]
	v_lshlrev_b32_e32 v10, 16, v51
	v_and_b32_e32 v11, 0xffff0000, v51
	v_pk_fma_f32 v[8:9], v[30:31], v[10:11], v[8:9]
	v_lshlrev_b32_e32 v10, 16, v67
	v_and_b32_e32 v11, 0xffff0000, v67
	v_pk_fma_f32 v[8:9], v[96:97], v[10:11], v[8:9]
	s_nop 0
	v_mul_f32_e32 v10, 0xbfb8aa3b, v8
	v_mul_f32_e32 v11, 0xbfb8aa3b, v9
	v_exp_f32_e32 v10, v10
	v_exp_f32_e32 v11, v11
	v_add_f32_e32 v10, 1.0, v10
	v_add_f32_e32 v11, 1.0, v11
	v_rcp_f32_e32 v10, v10
	v_rcp_f32_e32 v11, v11
	s_nop 0
	v_pk_mul_f32 v[20:21], v[8:9], v[10:11]
	v_lshlrev_b32_e32 v8, 16, v56
	v_and_b32_e32 v9, 0xffff0000, v56
	v_pk_fma_f32 v[8:9], v[32:33], v[8:9], 0 op_sel_hi:[1,1,0]
	v_lshlrev_b32_e32 v10, 16, v64
	v_and_b32_e32 v11, 0xffff0000, v64
	v_pk_fma_f32 v[8:9], v[204:205], v[10:11], v[8:9]
	v_lshlrev_b32_e32 v10, 16, v52
	v_and_b32_e32 v11, 0xffff0000, v52
	v_pk_fma_f32 v[8:9], v[206:207], v[10:11], v[8:9]
	v_lshlrev_b32_e32 v10, 16, v68
	v_and_b32_e32 v11, 0xffff0000, v68
	s_waitcnt lgkmcnt(0)
; #define LAS __attribute__((address_space(3)))
; DI unsigned pk2(float lo, float hi) { typedef __bf16 b2 __attribute__((ext_vector_type(2))); f32x2 v = {lo, hi}; b2 b = __builtin_convertvector(v, b2); return __builtin_bit_cast(unsigned, b); }
; DI float bflo(unsigned w) { return __uint_as_float(w << 16); }
; DI float bfhi(unsigned w) { return __uint_as_float(w & 0xffff0000u); }
; DI float silu_f(float g) { return g * frcp(1.f + fexp2(-1.4426950408889634f * g)); }
;     ...
;             acc[4] += w1[0] * bflo(xv.z); acc[5] += w1[1] * bfhi(xv.z); acc[6] += w1[2] * bflo(xv.w); acc[7] += w1[3] * bfhi(xv.w); }
; #pragma unroll
;         for (int e = 0; e < 8; ++e) acc[e] = silu_f(acc[e]);
;         if (which == 2) { LAS float* dst = vc + t * 68 + cg8 * 8; *(LAS f32x4*)dst = (f32x4){acc[0], acc[1], acc[2], acc[3]}; *(LAS f32x4*)(dst + 4) = (f32x4){acc[4], acc[5], acc[6], acc[7]}; }
;         else {
;             float ss = (acc[0] * acc[0] + acc[1] * acc[1]) + (acc[2] * acc[2] + acc[3] * acc[3]) + (acc[4] * acc[4] + acc[5] * acc[5]) + (acc[6] * acc[6] + acc[7] * acc[7]);
;             ss += __shfl_xor(ss, 1); ss += __shfl_xor(ss, 2); ss += __shfl_xor(ss, 4);
;             const float sc = (which ? 1.0f : 0.125f) * __builtin_amdgcn_rsqf(ss + 1e-6f);
;             const f32x4 y0 = (f32x4){acc[0], acc[1], acc[2], acc[3]} * sc, y1 = (f32x4){acc[4], acc[5], acc[6], acc[7]} * sc;
;             LAS float* dst = (which ? kc : qc) + t * 68 + cg8 * 8; *(LAS f32x4*)dst = y0; *(LAS f32x4*)(dst + 4) = y1;
;             u32x4 hh; hh.x = pk2(y0[0], y0[1]); hh.y = pk2(y0[2], y0[3]); hh.z = pk2(y1[0], y1[1]); hh.w = pk2(y1[2], y1[3]);
;             u32x4 lo; lo.x = pk2(y0[0] - bflo(hh.x), y0[1] - bfhi(hh.x)); lo.y = pk2(y0[2] - bflo(hh.y), y0[3] - bfhi(hh.y)); lo.z = pk2(y1[0] - bflo(hh.z), y1[1] - bfhi(hh.z)); lo.w = pk2(y1[2] - bflo(hh.w), y1[3] - bfhi(hh.w));
;             *(LAS u32x4*)((which ? KH : QH) + t * 72 + cg8 * 8) = hh; *(LAS u32x4*)((which ? KL : QL) + t * 72 + cg8 * 8) = lo; }
	v_pk_fma_f32 v[8:9], v[196:197], v[10:11], v[8:9]
	s_nop 0
	v_mul_f32_e32 v10, 0xbfb8aa3b, v8
	v_mul_f32_e32 v11, 0xbfb8aa3b, v9
	v_exp_f32_e32 v10, v10
	v_exp_f32_e32 v11, v11
	v_add_f32_e32 v10, 1.0, v10
	v_add_f32_e32 v11, 1.0, v11
	v_rcp_f32_e32 v10, v10
	v_rcp_f32_e32 v11, v11
	s_nop 0
	v_pk_mul_f32 v[28:29], v[8:9], v[10:11]
	v_lshlrev_b32_e32 v8, 16, v57
	v_and_b32_e32 v9, 0xffff0000, v57
	v_pk_fma_f32 v[8:9], v[12:13], v[8:9], 0 op_sel_hi:[1,1,0]
	v_lshlrev_b32_e32 v10, 16, v65
	v_and_b32_e32 v11, 0xffff0000, v65
	v_pk_fma_f32 v[8:9], v[200:201], v[10:11], v[8:9]
	v_lshlrev_b32_e32 v10, 16, v53
	v_and_b32_e32 v11, 0xffff0000, v53
	v_pk_fma_f32 v[6:7], v[6:7], v[10:11], v[8:9]
	v_lshlrev_b32_e32 v8, 16, v69
	v_and_b32_e32 v9, 0xffff0000, v69
	v_pk_fma_f32 v[6:7], v[198:199], v[8:9], v[6:7]
	v_mov_b32_e32 v11, v29
	v_mul_f32_e32 v8, 0xbfb8aa3b, v7
	v_exp_f32_e32 v8, v8
	s_nop 0
	v_add_f32_e32 v8, 1.0, v8
	v_rcp_f32_e32 v9, v8
	v_mul_f32_e32 v8, 0xbfb8aa3b, v6
	v_exp_f32_e32 v8, v8
	s_nop 0
	v_add_f32_e32 v8, 1.0, v8
	v_rcp_f32_e32 v8, v8
	s_nop 0
	v_pk_mul_f32 v[30:31], v[6:7], v[8:9]
	v_mov_b32_e32 v8, v19
	v_mov_b32_e32 v9, v21
	v_mov_b32_e32 v6, v18
	v_mov_b32_e32 v7, v20
	v_pk_mul_f32 v[8:9], v[8:9], v[8:9]
	v_mov_b32_e32 v10, v31
	v_pk_fma_f32 v[6:7], v[6:7], v[6:7], v[8:9]
	v_mov_b32_e32 v8, v30
	v_mov_b32_e32 v9, v28
	v_pk_mul_f32 v[10:11], v[10:11], v[10:11]
	v_add_f32_e32 v6, v6, v7
	v_pk_fma_f32 v[8:9], v[8:9], v[8:9], v[10:11]
	s_nop 0
	v_add_f32_e32 v6, v9, v6
	v_add_f32_e32 v6, v8, v6
	s_nop 1
	v_add_f32_dpp v6, v6, v6 quad_perm:[1,0,3,2] row_mask:0xf bank_mask:0xf
	s_nop 1
	v_add_f32_dpp v6, v6, v6 quad_perm:[2,3,0,1] row_mask:0xf bank_mask:0xf
	s_nop 1
	v_add_f32_dpp v6, v6, v6 row_half_mirror row_mask:0xf bank_mask:0xf
	v_add_f32_e32 v6, 0x358637bd, v6
	v_rsq_f32_e32 v32, v6
	s_nop 0
	v_pk_mul_f32 v[8:9], v[20:21], v[32:33] op_sel_hi:[1,0]
	v_pk_mul_f32 v[6:7], v[18:19], v[32:33] op_sel_hi:[1,0]
	v_pk_mul_f32 v[12:13], v[30:31], v[32:33] op_sel_hi:[1,0]
	v_pk_mul_f32 v[10:11], v[28:29], v[32:33] op_sel_hi:[1,0]
	ds_write_b128 v112, v[6:9] offset:17408
	ds_write_b128 v112, v[10:13] offset:17424
	v_cvt_pk_bf16_f32 v6, v6, v7
	v_cvt_pk_bf16_f32 v7, v8, v9
	v_cvt_pk_bf16_f32 v8, v10, v11
	v_cvt_pk_bf16_f32 v9, v12, v13
	v_lshlrev_b32_e32 v10, 16, v6
	v_and_b32_e32 v11, 0xffff0000, v6
	v_lshlrev_b32_e32 v12, 16, v7
	v_and_b32_e32 v13, 0xffff0000, v7
	v_pk_fma_f32 v[10:11], v[18:19], v[32:33], v[10:11] op_sel_hi:[1,0,1] neg_lo:[0,0,1] neg_hi:[0,0,1]
	v_pk_fma_f32 v[12:13], v[20:21], v[32:33], v[12:13] op_sel_hi:[1,0,1] neg_lo:[0,0,1] neg_hi:[0,0,1]
	v_cvt_pk_bf16_f32 v10, v10, v11
	v_cvt_pk_bf16_f32 v11, v12, v13
	v_lshlrev_b32_e32 v12, 16, v8
	v_and_b32_e32 v13, 0xffff0000, v8
	v_lshlrev_b32_e32 v18, 16, v9
	v_and_b32_e32 v19, 0xffff0000, v9
	v_pk_fma_f32 v[12:13], v[28:29], v[32:33], v[12:13] op_sel_hi:[1,0,1] neg_lo:[0,0,1] neg_hi:[0,0,1]
	v_pk_fma_f32 v[18:19], v[30:31], v[32:33], v[18:19] op_sel_hi:[1,0,1] neg_lo:[0,0,1] neg_hi:[0,0,1]
	v_cvt_pk_bf16_f32 v12, v12, v13
	v_cvt_pk_bf16_f32 v13, v18, v19
	ds_write_b128 v115, v[6:9]
	ds_write_b128 v116, v[10:13]
	v_lshl_add_u64 v[10:11], v[14:15], 0, s[16:17]
	ds_read_b128 v[6:9], v255 offset:512
	s_nop 0
	ds_read_b128 v[10:13], v255 offset:528
	s_mov_b64 s[16:17], 0x2800
	v_lshl_add_u64 v[2:3], v[14:15], 0, s[16:17]
	s_mov_b64 s[16:17], 0x5800
	s_waitcnt lgkmcnt(0)
	v_pk_mul_f32 v[6:7], v[26:27], v[6:7] op_sel_hi:[0,1]
	s_waitcnt lgkmcnt(0)
	v_pk_mul_f32 v[28:29], v[26:27], v[12:13] op_sel_hi:[0,1]
	v_pk_mul_f32 v[94:95], v[26:27], v[10:11] op_sel_hi:[0,1]
	ds_read_b128 v[10:13], v255 offset:1280
	ds_read_b128 v[18:21], v255 offset:1296
	v_pk_mul_f32 v[8:9], v[26:27], v[8:9] op_sel_hi:[0,1]
	s_waitcnt lgkmcnt(0)
	v_pk_mul_f32 v[10:11], v[24:25], v[10:11] op_sel_hi:[0,1]
	s_waitcnt lgkmcnt(0)
	v_pk_mul_f32 v[96:97], v[24:25], v[18:19] op_sel_hi:[0,1]
	v_lshl_add_u64 v[18:19], v[14:15], 0, s[62:63]
	v_pk_mul_f32 v[30:31], v[24:25], v[20:21] op_sel_hi:[0,1]
	ds_read_b128 v[2:5], v255 offset:2048
	s_nop 0
	ds_read_b128 v[18:21], v255 offset:2064
	v_pk_mul_f32 v[12:13], v[24:25], v[12:13] op_sel_hi:[0,1]
	s_waitcnt lgkmcnt(0)
	v_pk_mul_f32 v[4:5], v[22:23], v[4:5] op_sel_hi:[0,1]
	s_waitcnt lgkmcnt(0)
	v_pk_mul_f32 v[98:99], v[22:23], v[18:19] op_sel_hi:[0,1]
	v_lshl_add_u64 v[18:19], v[14:15], 0, s[16:17]
	v_pk_mul_f32 v[32:33], v[22:23], v[20:21] op_sel_hi:[0,1]
	ds_read_b128 v[14:17], v255 offset:2816
	s_nop 0
	ds_read_b128 v[18:21], v255 offset:2832
	v_pk_mul_f32 v[2:3], v[22:23], v[2:3] op_sel_hi:[0,1]
	v_lshlrev_b32_e32 v22, 16, v34
	v_and_b32_e32 v23, 0xffff0000, v34
	v_pk_fma_f32 v[6:7], v[6:7], v[22:23], 0 op_sel_hi:[1,1,0]
	v_lshlrev_b32_e32 v22, 16, v38
	v_and_b32_e32 v23, 0xffff0000, v38
	v_pk_fma_f32 v[6:7], v[10:11], v[22:23], v[6:7]
	v_lshlrev_b32_e32 v10, 16, v42
	v_and_b32_e32 v11, 0xffff0000, v42
	v_pk_fma_f32 v[2:3], v[2:3], v[10:11], v[6:7]
	v_lshlrev_b32_e32 v10, 16, v35
	v_and_b32_e32 v11, 0xffff0000, v35
	v_pk_fma_f32 v[8:9], v[8:9], v[10:11], 0 op_sel_hi:[1,1,0]
	v_lshlrev_b32_e32 v10, 16, v39
	v_and_b32_e32 v11, 0xffff0000, v39
	v_lshlrev_b32_e32 v6, 16, v46
	v_and_b32_e32 v7, 0xffff0000, v46
	v_pk_fma_f32 v[8:9], v[12:13], v[10:11], v[8:9]
	v_lshlrev_b32_e32 v10, 16, v43
	v_and_b32_e32 v11, 0xffff0000, v43
	v_pk_fma_f32 v[4:5], v[4:5], v[10:11], v[8:9]
	v_lshlrev_b32_e32 v8, 16, v47
	v_and_b32_e32 v9, 0xffff0000, v47
	v_lshlrev_b32_e32 v10, 16, v37
	v_and_b32_e32 v11, 0xffff0000, v37
	v_pk_fma_f32 v[10:11], v[28:29], v[10:11], 0 op_sel_hi:[1,1,0]
	v_lshlrev_b32_e32 v12, 16, v41
	v_and_b32_e32 v13, 0xffff0000, v41
	v_pk_fma_f32 v[10:11], v[30:31], v[12:13], v[10:11]
	v_lshlrev_b32_e32 v12, 16, v45
	v_and_b32_e32 v13, 0xffff0000, v45
	v_pk_fma_f32 v[10:11], v[32:33], v[12:13], v[10:11]
	v_lshlrev_b32_e32 v12, 16, v49
	v_and_b32_e32 v13, 0xffff0000, v49
	s_waitcnt lgkmcnt(0)
; #define LAS __attribute__((address_space(3)))
; DI float bflo(unsigned w) { return __uint_as_float(w << 16); }
; DI float bfhi(unsigned w) { return __uint_as_float(w & 0xffff0000u); }
; DI float silu_f(float g) { return g * frcp(1.f + fexp2(-1.4426950408889634f * g)); }
;     ...
;         for (int j = 0; j < 4; ++j) { const int sp = n * 64 + t - 3 + j; const float ok = sp >= 0 ? 1.f : 0.f;
;             const u32x4 xv = xin[which * 4 + j];
;             const f32x4 w0 = *(const f32x4*)(conv_w + j * 1536 + col) * ok, w1 = *(const f32x4*)(conv_w + j * 1536 + col + 4) * ok;
;             acc[0] += w0[0] * bflo(xv.x); acc[1] += w0[1] * bfhi(xv.x); acc[2] += w0[2] * bflo(xv.y); acc[3] += w0[3] * bfhi(xv.y);
;             acc[4] += w1[0] * bflo(xv.z); acc[5] += w1[1] * bfhi(xv.z); acc[6] += w1[2] * bflo(xv.w); acc[7] += w1[3] * bfhi(xv.w); }
; #pragma unroll
;         for (int e = 0; e < 8; ++e) acc[e] = silu_f(acc[e]);
;         if (which == 2) { LAS float* dst = vc + t * 68 + cg8 * 8; *(LAS f32x4*)dst = (f32x4){acc[0], acc[1], acc[2], acc[3]}; *(LAS f32x4*)(dst + 4) = (f32x4){acc[4], acc[5], acc[6], acc[7]}; }
	v_pk_fma_f32 v[2:3], v[14:15], v[6:7], v[2:3]
	s_nop 0
	v_mul_f32_e32 v6, 0xbfb8aa3b, v2
	v_mul_f32_e32 v7, 0xbfb8aa3b, v3
	v_pk_fma_f32 v[4:5], v[16:17], v[8:9], v[4:5]
	v_exp_f32_e32 v6, v6
	v_exp_f32_e32 v7, v7
	v_mul_f32_e32 v8, 0xbfb8aa3b, v4
	v_mul_f32_e32 v9, 0xbfb8aa3b, v5
	v_exp_f32_e32 v8, v8
	v_exp_f32_e32 v9, v9
	v_add_f32_e32 v6, 1.0, v6
	v_add_f32_e32 v7, 1.0, v7
	v_rcp_f32_e32 v6, v6
	v_rcp_f32_e32 v7, v7
	v_add_f32_e32 v8, 1.0, v8
	v_add_f32_e32 v9, 1.0, v9
	v_rcp_f32_e32 v8, v8
	v_rcp_f32_e32 v9, v9
	s_waitcnt lgkmcnt(0)
	v_pk_fma_f32 v[10:11], v[20:21], v[12:13], v[10:11]
	v_pk_mul_f32 v[2:3], v[2:3], v[6:7]
	v_mul_f32_e32 v12, 0xbfb8aa3b, v11
	v_lshlrev_b32_e32 v6, 16, v36
	v_and_b32_e32 v7, 0xffff0000, v36
	v_exp_f32_e32 v12, v12
	v_pk_mul_f32 v[4:5], v[4:5], v[8:9]
	v_pk_fma_f32 v[6:7], v[94:95], v[6:7], 0 op_sel_hi:[1,1,0]
	v_lshlrev_b32_e32 v8, 16, v40
	v_and_b32_e32 v9, 0xffff0000, v40
	v_pk_fma_f32 v[6:7], v[96:97], v[8:9], v[6:7]
	v_lshlrev_b32_e32 v8, 16, v44
	v_and_b32_e32 v9, 0xffff0000, v44
	v_pk_fma_f32 v[6:7], v[98:99], v[8:9], v[6:7]
	v_lshlrev_b32_e32 v8, 16, v48
	v_and_b32_e32 v9, 0xffff0000, v48
	v_pk_fma_f32 v[6:7], v[18:19], v[8:9], v[6:7]
	v_add_f32_e32 v12, 1.0, v12
	v_mul_f32_e32 v8, 0xbfb8aa3b, v6
	v_mul_f32_e32 v9, 0xbfb8aa3b, v7
	v_rcp_f32_e32 v13, v12
	v_mul_f32_e32 v12, 0xbfb8aa3b, v10
	v_exp_f32_e32 v8, v8
	v_exp_f32_e32 v9, v9
	v_exp_f32_e32 v12, v12
	v_add_f32_e32 v8, 1.0, v8
	v_add_f32_e32 v9, 1.0, v9
	v_add_f32_e32 v12, 1.0, v12
	v_rcp_f32_e32 v8, v8
	v_rcp_f32_e32 v9, v9
	v_rcp_f32_e32 v12, v12
	v_pk_mul_f32 v[6:7], v[6:7], v[8:9]
	v_pk_mul_f32 v[8:9], v[10:11], v[12:13]
	ds_write_b128 v176, v[2:5] offset:34816
	ds_write_b128 v176, v[6:9] offset:34832
	s_cbranch_vccnz .LBB0_1747
; DI float bf2f(bf16_t u) { return __uint_as_float(((unsigned)u) << 16); }
;     ...
;     { const float ga = bf2f(gain), gb = bf2f(gbin);
;         const float x = ga + dt_bias[h]; const float sp = fmaxf(x, 0.f) + log1pf(expf(-fabsf(x)));
;         float gv = -expf(a_log[h]) * sp; const float bv = 1.f / (1.f + expf(-gb));
;         if (wid == 0) {
; #pragma unroll
;             for (int o = 1; o < 64; o <<= 1) { const float tt = __shfl_up(gv, o); if (lane >= o) gv += tt; }
;             gcs[lane] = gv; bet[lane] = bv; } }
	s_lshl_b32 s16, s24, 2
	v_mov_b32_e32 v2, s16
	v_readlane_b32 s4, v247, 9
	s_waitcnt vmcnt(0)
	v_mov_b32_e32 v3, v252
	v_readlane_b32 s5, v247, 10
	v_lshlrev_b32_e32 v5, 16, v1
	v_readlane_b32 s16, v247, 21
	s_mov_b32 s16, 0xb2a5705f
	v_readlane_b32 s17, v247, 22
	v_readlane_b32 s6, v247, 11
	v_mov_b32_e32 v4, v253
	v_lshlrev_b32_e32 v2, 16, v100
	v_mul_f32_e32 v6, 0xbfb8aa3b, v2
	v_rndne_f32_e32 v7, v6
	v_fma_f32 v8, v2, s23, -v6
	v_sub_f32_e32 v6, v6, v7
	v_fmac_f32_e32 v8, 0xb2a5705f, v2
	v_add_f32_e32 v6, v6, v8
	v_cvt_i32_f32_e32 v7, v7
	v_exp_f32_e32 v6, v6
	v_readlane_b32 s7, v247, 12
	v_readlane_b32 s8, v247, 13
	v_readlane_b32 s9, v247, 14
	v_ldexp_f32 v6, v6, v7
	v_readlane_b32 s10, v247, 15
	v_readlane_b32 s11, v247, 16
	v_readlane_b32 s12, v247, 17
	v_readlane_b32 s13, v247, 18
	v_readlane_b32 s14, v247, 19
	v_readlane_b32 s15, v247, 20
	v_readlane_b32 s18, v247, 23
	v_readlane_b32 s19, v247, 24
	s_waitcnt vmcnt(1)
	v_mul_f32_e32 v8, 0x3fb8aa3b, v3
	v_rndne_f32_e32 v9, v8
	v_cmp_ngt_f32_e32 vcc, s3, v3
	s_waitcnt vmcnt(0)
	v_add_f32_e32 v4, v4, v5
	v_fma_f32 v5, v3, s2, -v8
	v_mul_f32_e64 v10, |v4|, s23
	v_fmac_f32_e32 v5, 0x32a5705f, v3
	v_sub_f32_e32 v8, v8, v9
	v_fma_f32 v12, |v4|, s23, -v10
	v_rndne_f32_e32 v13, v10
	v_add_f32_e32 v5, v8, v5
	v_cvt_i32_f32_e32 v9, v9
	v_fma_f32 v8, |v4|, s16, v12
	v_sub_f32_e32 v10, v10, v13
	v_exp_f32_e32 v5, v5
	v_add_f32_e32 v8, v10, v8
	v_cvt_i32_f32_e32 v12, v13
	v_exp_f32_e32 v8, v8
	v_ldexp_f32 v5, v5, v9
	v_cndmask_b32_e32 v5, 0, v5, vcc
	v_cmp_nlt_f32_e32 vcc, s64, v3
	v_ldexp_f32 v8, v8, v12
	v_max_f32_e32 v11, 0, v4
	v_cndmask_b32_e32 v3, v193, v5, vcc
	v_cmp_ngt_f32_e64 vcc, |v4|, s96
	s_mov_b32 s16, 0x3f2aaaab
	s_nop 0
	v_cndmask_b32_e32 v5, 0, v8, vcc
	v_cmp_nlt_f32_e64 vcc, |v4|, s97
	s_nop 1
	v_cndmask_b32_e32 v8, v193, v5, vcc
	v_add_f32_e32 v9, 1.0, v8
	v_cvt_f64_f32_e32 v[4:5], v9
	v_frexp_mant_f32_e32 v10, v9
	v_add_f32_e32 v12, -1.0, v9
	v_frexp_exp_i32_f64_e32 v4, v[4:5]
	v_cmp_gt_f32_e32 vcc, s16, v10
	v_sub_f32_e32 v5, v8, v12
	v_sub_f32_e32 v12, v12, v9
	v_subbrev_co_u32_e32 v4, vcc, 0, v4, vcc
	v_add_f32_e32 v10, 1.0, v12
	v_cvt_f32_i32_e32 v12, v4
	v_sub_u32_e32 v4, 0, v4
	v_add_f32_e32 v5, v5, v10
	v_ldexp_f32 v9, v9, v4
	v_ldexp_f32 v4, v5, v4
	v_add_f32_e32 v5, -1.0, v9
	v_add_f32_e32 v10, 1.0, v9
	v_add_f32_e32 v13, 1.0, v5
	v_add_f32_e32 v14, -1.0, v10
	v_mul_f32_e32 v15, 0x3f317218, v12
	v_sub_f32_e32 v13, v9, v13
	v_sub_f32_e32 v9, v9, v14
	s_mov_b32 s16, 0x3f317218
	v_fma_f32 v14, v12, s16, -v15
	v_add_f32_e32 v13, v4, v13
	v_add_f32_e32 v4, v4, v9
	v_fmac_f32_e32 v14, 0xb102e308, v12
	v_add_f32_e32 v12, v10, v4
	v_rcp_f32_e32 v17, v12
	v_add_f32_e32 v9, v5, v13
	v_add_f32_e32 v16, v15, v14
	v_sub_f32_e32 v10, v10, v12
	v_sub_f32_e32 v5, v5, v9
	v_add_f32_e32 v4, v4, v10
	v_add_f32_e32 v5, v13, v5
	v_sub_f32_e32 v10, v16, v15
	v_mul_f32_e32 v13, v9, v17
	v_sub_f32_e32 v10, v14, v10
	v_mul_f32_e32 v14, v12, v13
	v_fma_f32 v15, v13, v12, -v14
	v_fmac_f32_e32 v15, v13, v4
	v_add_f32_e32 v18, v14, v15
	v_sub_f32_e32 v19, v9, v18
	v_sub_f32_e32 v9, v9, v19
	v_sub_f32_e32 v14, v18, v14
	v_sub_f32_e32 v9, v9, v18
	v_sub_f32_e32 v14, v14, v15
	v_add_f32_e32 v5, v5, v9
	v_add_f32_e32 v5, v14, v5
	v_add_f32_e32 v9, v19, v5
	v_mul_f32_e32 v14, v17, v9
	v_sub_f32_e32 v15, v19, v9
	v_mul_f32_e32 v19, v12, v14
	v_fma_f32 v12, v14, v12, -v19
	v_add_f32_e32 v18, v13, v14
	v_fmac_f32_e32 v12, v14, v4
	v_sub_f32_e32 v13, v18, v13
	v_add_f32_e32 v4, v19, v12
	v_sub_f32_e32 v13, v14, v13
	v_sub_f32_e32 v14, v9, v4
	v_sub_f32_e32 v9, v9, v14
	v_add_f32_e32 v5, v5, v15
	v_sub_f32_e32 v15, v4, v19
	v_sub_f32_e32 v4, v9, v4
	v_sub_f32_e32 v12, v15, v12
	v_add_f32_e32 v4, v5, v4
	v_add_f32_e32 v4, v12, v4
	v_add_f32_e32 v4, v14, v4
	v_mul_f32_e32 v4, v17, v4
	v_add_f32_e32 v4, v13, v4
	v_add_f32_e32 v5, v18, v4
	v_mul_f32_e32 v12, v5, v5
	v_fmamk_f32 v14, v12, 0x3e9b6dac, v177
	v_ldexp_f32 v9, v5, 1
	v_sub_f32_e32 v13, v5, v18
	v_mul_f32_e32 v5, v5, v12
	v_fmaak_f32 v12, v12, v14, 0x3f2aaada
	v_mul_f32_e32 v5, v5, v12
	v_add_f32_e32 v12, v9, v5
	v_sub_f32_e32 v4, v4, v13
	v_sub_f32_e32 v9, v12, v9
	v_ldexp_f32 v4, v4, 1
	v_sub_f32_e32 v5, v5, v9
	v_add_f32_e32 v4, v4, v5
	v_add_f32_e32 v5, v12, v4
	v_add_f32_e32 v9, v16, v5
	v_sub_f32_e32 v12, v5, v12
	v_sub_f32_e32 v4, v4, v12
	v_sub_f32_e32 v12, v9, v16
	v_sub_f32_e32 v5, v5, v12
	v_sub_f32_e32 v12, v9, v12
	v_add_f32_e32 v13, v10, v4
	v_sub_f32_e32 v12, v16, v12
	v_sub_f32_e32 v14, v13, v10
	v_add_f32_e32 v5, v5, v12
	v_sub_f32_e32 v12, v13, v14
	v_add_f32_e32 v5, v13, v5
	v_sub_f32_e32 v10, v10, v12
	v_add_f32_e32 v12, v9, v5
	v_sub_f32_e32 v4, v4, v14
	v_sub_f32_e32 v9, v12, v9
	v_add_f32_e32 v4, v4, v10
	v_sub_f32_e32 v5, v5, v9
	v_add_f32_e32 v4, v4, v5
	s_mov_b32 s16, 0x7f800000
	v_add_f32_e32 v4, v12, v4
	v_cmp_neq_f32_e32 vcc, s16, v8
	s_mov_b32 s16, 0x33800000
	s_nop 0
	v_cndmask_b32_e32 v4, v193, v4, vcc
	v_cmp_lt_f32_e64 vcc, |v8|, s16
	s_nop 1
	v_cndmask_b32_e32 v4, v4, v8, vcc
	v_add_f32_e32 v4, v11, v4
	v_mul_f32_e64 v5, v4, -v3
	ds_bpermute_b32 v8, v104, v5
	v_cmp_nlt_f32_e32 vcc, s96, v2
	s_waitcnt lgkmcnt(0)
	v_fma_f32 v3, v4, -v3, v8
	v_cndmask_b32_e64 v3, v3, v5, s[58:59]
	ds_bpermute_b32 v4, v105, v3
	v_cndmask_b32_e32 v5, 0, v6, vcc
	v_cmp_ngt_f32_e32 vcc, s97, v2
	s_waitcnt lgkmcnt(0)
	v_add_f32_e32 v4, v3, v4
	v_cndmask_b32_e64 v3, v4, v3, s[56:57]
	ds_bpermute_b32 v4, v106, v3
	v_cndmask_b32_e32 v2, v193, v5, vcc
	v_add_f32_e32 v2, 1.0, v2
	v_div_scale_f32 v5, s[16:17], v2, v2, 1.0
	s_waitcnt lgkmcnt(0)
	v_add_f32_e32 v4, v3, v4
	v_cndmask_b32_e64 v3, v4, v3, s[74:75]
	ds_bpermute_b32 v4, v107, v3
	v_rcp_f32_e32 v6, v5
	v_div_scale_f32 v7, vcc, 1.0, v2, 1.0
	s_waitcnt lgkmcnt(0)
	v_add_f32_e32 v4, v3, v4
	v_cndmask_b32_e64 v3, v4, v3, s[76:77]
	ds_bpermute_b32 v4, v108, v3
	v_fma_f32 v8, -v5, v6, 1.0
	v_fmac_f32_e32 v6, v8, v6
	v_mul_f32_e32 v8, v7, v6
	v_fma_f32 v9, -v5, v8, v7
	s_waitcnt lgkmcnt(0)
	v_add_f32_e32 v4, v3, v4
	v_cndmask_b32_e64 v3, v4, v3, s[78:79]
	ds_bpermute_b32 v4, v109, v3
	v_fmac_f32_e32 v8, v9, v6
	v_fma_f32 v5, -v5, v8, v7
	v_div_fmas_f32 v5, v5, v6, v8
	v_div_fixup_f32 v2, v5, v2, 1.0
	s_waitcnt lgkmcnt(0)
	v_add_f32_e32 v4, v3, v4
	v_cndmask_b32_e64 v3, v4, v3, s[60:61]
	ds_write_b32 v117, v3
	ds_write_b32 v118, v2

;     DI void fused(f32x4 (&acc)[2][2][4][2], const Unit& u, int wr, int wc, int fr_, int fq_, LAS unsigned char* lds, int wid, int lane_) const {
;     ...
;         const int col0 = u.pn * BM + wc * 32 + 4 * fq;
; #pragma unroll
;         for (int ai = 0; ai < 2; ++ai)
; #pragma unroll
;             for (int m = 0; m < 4; ++m) { const int r = u.pm * BM + ai * HALF + wr * 64 + m * 16 + fr; const size_t ro = (size_t)r * ldc + col0;
; #pragma unroll
;                 for (int bj = 0; bj < 2; ++bj)
; #pragma unroll
;                     for (int n = 0; n < 2; ++n) { const f32x4 h = *(const f32x4*)(Hin + ro + bj * HALF + n * 16); acc[ai][bj][m][n] = h * alpha + acc[ai][bj][m][n] * s; }
;                 asm volatile("" : "+v"(acc[ai][0][m][0]), "+v"(acc[ai][0][m][1]), "+v"(acc[ai][1][m][0]), "+v"(acc[ai][1][m][1]));
;                 asm volatile("" ::: "memory"); }
.LBB0_2322:
	v_mov_b32_e32 v150, v202
	s_lshl_b32 s0, s28, 5
	s_barrier
	s_lshl_b32 s1, s8, 8
	v_ashrrev_i32_e32 v128, 2, v150
	s_or_b32 s0, s1, s0
	v_and_b32_e32 v128, -4, v128
	s_lshl_b32 s10, s26, 8
	v_and_b32_e32 v153, 15, v150
	v_add_u32_e32 v128, s0, v128
	s_add_i32 s0, s10, s24
	v_or_b32_e32 v132, s0, v153
	v_ashrrev_i32_e32 v133, 31, v132
	v_ashrrev_i32_e32 v129, 31, v128
	v_lshlrev_b64 v[130:131], 12, v[132:133]
	v_lshl_add_u64 v[130:131], s[90:91], 0, v[130:131]
	v_lshlrev_b64 v[146:147], 2, v[128:129]
	v_lshl_add_u64 v[144:145], v[130:131], 0, v[146:147]
	global_load_dwordx4 v[134:137], v[144:145], off
	global_load_dwordx4 v[138:141], v[144:145], off offset:64
	global_load_dwordx4 v[154:157], v[144:145], off offset:512
	global_load_dwordx4 v[158:161], v[144:145], off offset:576
	v_or_b32_e32 v130, 16, v132
	v_ashrrev_i32_e32 v131, 31, v130
	s_mov_b32 s0, 0x3fb504f3
	v_lshlrev_b64 v[130:131], 12, v[130:131]
	v_lshl_add_u64 v[130:131], s[90:91], 0, v[130:131]
	v_lshl_add_u64 v[142:143], v[130:131], 0, v[146:147]
	v_or_b32_e32 v130, 32, v132
	v_ashrrev_i32_e32 v131, 31, v130
	v_lshlrev_b64 v[130:131], 12, v[130:131]
	v_lshl_add_u64 v[130:131], s[90:91], 0, v[130:131]
	v_mbcnt_lo_u32_b32 v133, -1, 0
	v_mbcnt_hi_u32_b32 v149, -1, v133
	v_and_b32_e32 v148, 64, v149
	v_xor_b32_e32 v133, 16, v149
	v_add_u32_e32 v151, 64, v148
	v_cmp_lt_i32_e32 vcc, v133, v151
	s_waitcnt vmcnt(0)
	v_pk_fma_f32 v[126:127], v[136:137], s[0:1], v[126:127] op_sel_hi:[1,0,1]
	v_pk_fma_f32 v[124:125], v[134:135], s[0:1], v[124:125] op_sel_hi:[1,0,1]
	v_pk_fma_f32 v[122:123], v[140:141], s[0:1], v[122:123] op_sel_hi:[1,0,1]
	v_pk_fma_f32 v[120:121], v[138:139], s[0:1], v[120:121] op_sel_hi:[1,0,1]
	v_pk_fma_f32 v[118:119], v[156:157], s[0:1], v[118:119] op_sel_hi:[1,0,1]
	v_pk_fma_f32 v[116:117], v[154:155], s[0:1], v[116:117] op_sel_hi:[1,0,1]
	v_pk_fma_f32 v[110:111], v[160:161], s[0:1], v[110:111] op_sel_hi:[1,0,1]
	v_pk_fma_f32 v[108:109], v[158:159], s[0:1], v[108:109] op_sel_hi:[1,0,1]
	v_lshl_add_u64 v[140:141], v[130:131], 0, v[146:147]
	global_load_dwordx4 v[134:137], v[142:143], off
	global_load_dwordx4 v[154:157], v[142:143], off offset:64
	global_load_dwordx4 v[158:161], v[142:143], off offset:512
	global_load_dwordx4 v[162:165], v[142:143], off offset:576
	v_or_b32_e32 v130, 48, v132
	v_ashrrev_i32_e32 v131, 31, v130
	v_lshlrev_b64 v[130:131], 12, v[130:131]
	v_lshl_add_u64 v[130:131], s[90:91], 0, v[130:131]
	v_lshl_add_u64 v[138:139], v[130:131], 0, v[146:147]
	v_add_u32_e32 v130, 0x80, v132
	v_ashrrev_i32_e32 v131, 31, v130
	v_lshlrev_b64 v[130:131], 12, v[130:131]
	v_lshl_add_u64 v[130:131], s[90:91], 0, v[130:131]
	v_cndmask_b32_e32 v148, v149, v133, vcc
	v_mov_b32_e32 v172, v125
	v_mov_b32_e32 v173, v126
	v_mov_b32_e32 v174, v124
	v_mov_b32_e32 v175, v127
	v_mov_b32_e32 v176, v121
	v_mov_b32_e32 v177, v122
	v_pk_add_f32 v[172:173], v[172:173], v[174:175]
	v_add_f32_e32 v179, v116, v117
	v_add_f32_e32 v172, v172, v173
	v_add_f32_e32 v181, v118, v119
	v_mov_b32_e32 v178, v108
	v_mov_b32_e32 v180, v109
	v_mov_b32_e32 v182, v111
	v_add_f32_e32 v183, 0, v172
	v_pk_add_f32 v[174:175], v[178:179], v[180:181]
	v_lshlrev_b32_e32 v148, 2, v148
	v_xor_b32_e32 v172, 32, v149
	v_cmp_lt_i32_e32 vcc, v172, v151
	s_waitcnt vmcnt(3)
	v_pk_fma_f32 v[114:115], v[136:137], s[0:1], v[114:115] op_sel_hi:[1,0,1]
	v_pk_fma_f32 v[112:113], v[134:135], s[0:1], v[112:113] op_sel_hi:[1,0,1]
	s_waitcnt vmcnt(2)
	v_pk_fma_f32 v[106:107], v[156:157], s[0:1], v[106:107] op_sel_hi:[1,0,1]
	v_pk_fma_f32 v[104:105], v[154:155], s[0:1], v[104:105] op_sel_hi:[1,0,1]
	s_waitcnt vmcnt(1)
	v_pk_fma_f32 v[102:103], v[160:161], s[0:1], v[102:103] op_sel_hi:[1,0,1]
	v_pk_fma_f32 v[100:101], v[158:159], s[0:1], v[100:101] op_sel_hi:[1,0,1]
	s_waitcnt vmcnt(0)
	v_pk_fma_f32 v[94:95], v[164:165], s[0:1], v[94:95] op_sel_hi:[1,0,1]
	v_pk_fma_f32 v[92:93], v[162:163], s[0:1], v[92:93] op_sel_hi:[1,0,1]
	v_cndmask_b32_e32 v149, v149, v172, vcc
	global_load_dwordx4 v[134:137], v[140:141], off
	global_load_dwordx4 v[154:157], v[140:141], off offset:64
	global_load_dwordx4 v[158:161], v[140:141], off offset:512
	global_load_dwordx4 v[162:165], v[140:141], off offset:576
	v_lshlrev_b32_e32 v149, 2, v149
	v_cmp_gt_u32_e32 vcc, 16, v150
	s_waitcnt vmcnt(3)
	v_pk_fma_f32 v[98:99], v[136:137], s[0:1], v[98:99] op_sel_hi:[1,0,1]
	v_pk_fma_f32 v[96:97], v[134:135], s[0:1], v[96:97] op_sel_hi:[1,0,1]
	s_waitcnt vmcnt(2)
	v_pk_fma_f32 v[90:91], v[156:157], s[0:1], v[90:91] op_sel_hi:[1,0,1]
	v_pk_fma_f32 v[88:89], v[154:155], s[0:1], v[88:89] op_sel_hi:[1,0,1]
	s_waitcnt vmcnt(1)
	v_pk_fma_f32 v[86:87], v[160:161], s[0:1], v[86:87] op_sel_hi:[1,0,1]
	v_pk_fma_f32 v[84:85], v[158:159], s[0:1], v[84:85] op_sel_hi:[1,0,1]
	s_waitcnt vmcnt(0)
	v_pk_fma_f32 v[78:79], v[164:165], s[0:1], v[78:79] op_sel_hi:[1,0,1]
	v_pk_fma_f32 v[76:77], v[162:163], s[0:1], v[76:77] op_sel_hi:[1,0,1]
	v_lshl_add_u64 v[136:137], v[130:131], 0, v[146:147]
	global_load_dwordx4 v[154:157], v[138:139], off
	global_load_dwordx4 v[158:161], v[138:139], off offset:64
	global_load_dwordx4 v[162:165], v[138:139], off offset:512
	global_load_dwordx4 v[166:169], v[138:139], off offset:576
	v_add_u32_e32 v130, 0x90, v132
	v_ashrrev_i32_e32 v131, 31, v130
	v_lshlrev_b64 v[130:131], 12, v[130:131]
	v_lshl_add_u64 v[130:131], s[90:91], 0, v[130:131]
	v_lshl_add_u64 v[134:135], v[130:131], 0, v[146:147]
	v_add_u32_e32 v130, 0xa0, v132
	v_ashrrev_i32_e32 v131, 31, v130
	v_lshlrev_b64 v[130:131], 12, v[130:131]
	v_lshl_add_u64 v[130:131], s[90:91], 0, v[130:131]
	v_lshl_add_u64 v[130:131], v[130:131], 0, v[146:147]
	v_add_u32_e32 v132, 0xb0, v132
	v_ashrrev_i32_e32 v133, 31, v132
	v_lshlrev_b64 v[132:133], 12, v[132:133]
	v_lshl_add_u64 v[132:133], s[90:91], 0, v[132:133]
	v_lshl_add_u64 v[132:133], v[132:133], 0, v[146:147]
	s_waitcnt vmcnt(3)
;     DI void fused(f32x4 (&acc)[2][2][4][2], const Unit& u, int wr, int wc, int fr_, int fq_, LAS unsigned char* lds, int wid, int lane_) const {
;     ...
;             for (int m = 0; m < 4; ++m) { const int r = u.pm * BM + ai * HALF + wr * 64 + m * 16 + fr; const size_t ro = (size_t)r * ldc + col0;
; #pragma unroll
;                 for (int bj = 0; bj < 2; ++bj)
; #pragma unroll
;                     for (int n = 0; n < 2; ++n) { const f32x4 h = *(const f32x4*)(Hin + ro + bj * HALF + n * 16); acc[ai][bj][m][n] = h * alpha + acc[ai][bj][m][n] * s; }
;                 asm volatile("" : "+v"(acc[ai][0][m][0]), "+v"(acc[ai][0][m][1]), "+v"(acc[ai][1][m][0]), "+v"(acc[ai][1][m][1]));
;                 asm volatile("" ::: "memory"); }
; #pragma unroll
;         for (int ai = 0; ai < 2; ++ai)
; #pragma unroll
;             for (int m = 0; m < 4; ++m) {
;                 float sm = 0.f;
; #pragma unroll
;                 for (int bj = 0; bj < 2; ++bj)
; #pragma unroll
;                     for (int n = 0; n < 2; ++n) { const f32x4 x = acc[ai][bj][m][n]; sm += (x[0] + x[1]) + (x[2] + x[3]); }
;                 sm += __shfl_xor(sm, 16); sm += __shfl_xor(sm, 32);
;                 const float mw = sm * (1.0f / 64.0f); float q = 0.f;
; #pragma unroll
;                 for (int bj = 0; bj < 2; ++bj)
; #pragma unroll
;                     for (int n = 0; n < 2; ++n) { const f32x4 d = acc[ai][bj][m][n] - mw; q += (d[0] * d[0] + d[1] * d[1]) + (d[2] * d[2] + d[3] * d[3]); }
;                 q += __shfl_xor(q, 16); q += __shfl_xor(q, 32);
;                 if (fq == 0) P[(ai * HALF + wr * 64 + m * 16 + fr) * 4 + wc] = (f32x2){mw, q};
	v_pk_fma_f32 v[82:83], v[156:157], s[0:1], v[82:83] op_sel_hi:[1,0,1]
	v_pk_fma_f32 v[80:81], v[154:155], s[0:1], v[80:81] op_sel_hi:[1,0,1]
	s_waitcnt vmcnt(2)
	v_pk_fma_f32 v[74:75], v[160:161], s[0:1], v[74:75] op_sel_hi:[1,0,1]
	v_pk_fma_f32 v[72:73], v[158:159], s[0:1], v[72:73] op_sel_hi:[1,0,1]
	s_waitcnt vmcnt(1)
	v_pk_fma_f32 v[70:71], v[164:165], s[0:1], v[70:71] op_sel_hi:[1,0,1]
	v_pk_fma_f32 v[68:69], v[162:163], s[0:1], v[68:69] op_sel_hi:[1,0,1]
	s_waitcnt vmcnt(0)
	v_pk_fma_f32 v[66:67], v[168:169], s[0:1], v[66:67] op_sel_hi:[1,0,1]
	v_pk_fma_f32 v[64:65], v[166:167], s[0:1], v[64:65] op_sel_hi:[1,0,1]
	s_nop 0
	global_load_dwordx4 v[154:157], v[136:137], off
	global_load_dwordx4 v[158:161], v[136:137], off offset:64
	global_load_dwordx4 v[162:165], v[136:137], off offset:512
	global_load_dwordx4 v[166:169], v[136:137], off offset:576
	s_waitcnt vmcnt(3)
	v_pk_fma_f32 v[62:63], v[156:157], s[0:1], v[62:63] op_sel_hi:[1,0,1]
	v_pk_fma_f32 v[60:61], v[154:155], s[0:1], v[60:61] op_sel_hi:[1,0,1]
	s_waitcnt vmcnt(2)
	v_pk_fma_f32 v[58:59], v[160:161], s[0:1], v[58:59] op_sel_hi:[1,0,1]
	v_pk_fma_f32 v[56:57], v[158:159], s[0:1], v[56:57] op_sel_hi:[1,0,1]
	s_waitcnt vmcnt(1)
	v_pk_fma_f32 v[54:55], v[164:165], s[0:1], v[54:55] op_sel_hi:[1,0,1]
	v_pk_fma_f32 v[52:53], v[162:163], s[0:1], v[52:53] op_sel_hi:[1,0,1]
	s_waitcnt vmcnt(0)
	v_pk_fma_f32 v[50:51], v[168:169], s[0:1], v[50:51] op_sel_hi:[1,0,1]
	v_pk_fma_f32 v[48:49], v[166:167], s[0:1], v[48:49] op_sel_hi:[1,0,1]
	s_nop 0
	global_load_dwordx4 v[154:157], v[134:135], off
	global_load_dwordx4 v[158:161], v[134:135], off offset:64
	global_load_dwordx4 v[162:165], v[134:135], off offset:512
	global_load_dwordx4 v[166:169], v[134:135], off offset:576
	s_waitcnt vmcnt(3)
	v_pk_fma_f32 v[46:47], v[156:157], s[0:1], v[46:47] op_sel_hi:[1,0,1]
	v_pk_fma_f32 v[44:45], v[154:155], s[0:1], v[44:45] op_sel_hi:[1,0,1]
	s_waitcnt vmcnt(2)
	v_pk_fma_f32 v[42:43], v[160:161], s[0:1], v[42:43] op_sel_hi:[1,0,1]
	v_pk_fma_f32 v[40:41], v[158:159], s[0:1], v[40:41] op_sel_hi:[1,0,1]
	s_waitcnt vmcnt(1)
	v_pk_fma_f32 v[38:39], v[164:165], s[0:1], v[38:39] op_sel_hi:[1,0,1]
	v_pk_fma_f32 v[36:37], v[162:163], s[0:1], v[36:37] op_sel_hi:[1,0,1]
	s_waitcnt vmcnt(0)
	v_pk_fma_f32 v[34:35], v[168:169], s[0:1], v[34:35] op_sel_hi:[1,0,1]
	v_pk_fma_f32 v[32:33], v[166:167], s[0:1], v[32:33] op_sel_hi:[1,0,1]
	s_nop 0
	global_load_dwordx4 v[154:157], v[130:131], off
	global_load_dwordx4 v[158:161], v[130:131], off offset:64
	global_load_dwordx4 v[162:165], v[130:131], off offset:512
	global_load_dwordx4 v[166:169], v[130:131], off offset:576
	s_waitcnt vmcnt(3)
	v_pk_fma_f32 v[30:31], v[156:157], s[0:1], v[30:31] op_sel_hi:[1,0,1]
	v_pk_fma_f32 v[28:29], v[154:155], s[0:1], v[28:29] op_sel_hi:[1,0,1]
	s_waitcnt vmcnt(2)
	v_pk_fma_f32 v[26:27], v[160:161], s[0:1], v[26:27] op_sel_hi:[1,0,1]
	v_pk_fma_f32 v[24:25], v[158:159], s[0:1], v[24:25] op_sel_hi:[1,0,1]
	s_waitcnt vmcnt(1)
	v_pk_fma_f32 v[22:23], v[164:165], s[0:1], v[22:23] op_sel_hi:[1,0,1]
	v_pk_fma_f32 v[20:21], v[162:163], s[0:1], v[20:21] op_sel_hi:[1,0,1]
	s_waitcnt vmcnt(0)
	v_pk_fma_f32 v[18:19], v[168:169], s[0:1], v[18:19] op_sel_hi:[1,0,1]
	v_pk_fma_f32 v[16:17], v[166:167], s[0:1], v[16:17] op_sel_hi:[1,0,1]
	v_mov_b32_e32 v154, v120
	global_load_dwordx4 v[156:159], v[132:133], off
	global_load_dwordx4 v[160:163], v[132:133], off offset:64
	global_load_dwordx4 v[164:167], v[132:133], off offset:512
	global_load_dwordx4 v[168:171], v[132:133], off offset:576
	v_mov_b32_e32 v155, v123
	v_pk_add_f32 v[154:155], v[176:177], v[154:155]
	s_waitcnt vmcnt(3)
	v_pk_fma_f32 v[14:15], v[158:159], s[0:1], v[14:15] op_sel_hi:[1,0,1]
	v_pk_add_f32 v[154:155], v[154:155], v[154:155] op_sel_hi:[0,1]
	v_mov_b32_e32 v154, v110
	v_pk_add_f32 v[154:155], v[154:155], v[182:183]
	v_pk_fma_f32 v[12:13], v[156:157], s[0:1], v[12:13] op_sel_hi:[1,0,1]
	v_pk_add_f32 v[154:155], v[174:175], v[154:155]
	s_waitcnt vmcnt(2)
	v_pk_fma_f32 v[10:11], v[162:163], s[0:1], v[10:11] op_sel_hi:[1,0,1]
	v_add_f32_e32 v154, v154, v155
	v_mov_b32_e32 v155, v154
	s_nop 1
	v_permlane16_swap_b32_e32 v154, v155
	v_pk_fma_f32 v[8:9], v[160:161], s[0:1], v[8:9] op_sel_hi:[1,0,1]
	s_waitcnt vmcnt(1)
	v_pk_fma_f32 v[6:7], v[166:167], s[0:1], v[6:7] op_sel_hi:[1,0,1]
	v_pk_fma_f32 v[4:5], v[164:165], s[0:1], v[4:5] op_sel_hi:[1,0,1]
	s_waitcnt vmcnt(0)
	v_pk_fma_f32 v[2:3], v[170:171], s[0:1], v[2:3] op_sel_hi:[1,0,1]
	s_waitcnt lgkmcnt(0)
	v_add_f32_e32 v151, v154, v155
	v_mov_b32_e32 v154, v151
	s_nop 1
	v_permlane32_swap_b32_e32 v151, v154
	v_pk_fma_f32 v[0:1], v[168:169], s[0:1], v[0:1] op_sel_hi:[1,0,1]
	s_lshl_b32 s0, s28, 3
	s_waitcnt lgkmcnt(0)
	v_add_f32_e32 v151, v151, v154
	v_fmamk_f32 v155, v151, 0xbc800000, v127
	v_fmamk_f32 v173, v151, 0xbc800000, v125
	v_fmamk_f32 v175, v151, 0xbc800000, v123
	v_fmamk_f32 v177, v151, 0xbc800000, v121
	v_fmamk_f32 v154, v151, 0xbc800000, v126
	v_fmamk_f32 v172, v151, 0xbc800000, v124
	v_fmamk_f32 v174, v151, 0xbc800000, v122
	v_fmamk_f32 v176, v151, 0xbc800000, v120
	v_fmamk_f32 v179, v151, 0xbc800000, v119
	v_fmamk_f32 v181, v151, 0xbc800000, v117
	v_mul_f32_e32 v173, v173, v173
	v_mul_f32_e32 v155, v155, v155
	v_mul_f32_e32 v177, v177, v177
	v_mul_f32_e32 v175, v175, v175
	v_fmamk_f32 v178, v151, 0xbc800000, v118
	v_fmamk_f32 v180, v151, 0xbc800000, v116
	v_fmamk_f32 v183, v151, 0xbc800000, v111
	v_fmamk_f32 v185, v151, 0xbc800000, v109
	v_mul_f32_e32 v181, v181, v181
	v_mul_f32_e32 v179, v179, v179
	v_fmac_f32_e32 v173, v172, v172
	v_fmac_f32_e32 v155, v154, v154
	v_fmac_f32_e32 v177, v176, v176
	v_fmac_f32_e32 v175, v174, v174
	v_fmamk_f32 v182, v151, 0xbc800000, v110
	v_fmamk_f32 v184, v151, 0xbc800000, v108
	v_mul_f32_e32 v185, v185, v185
	v_mul_f32_e32 v183, v183, v183
	v_fmac_f32_e32 v181, v180, v180
	v_fmac_f32_e32 v179, v178, v178
	v_add_f32_e32 v154, v173, v155
	v_add_f32_e32 v155, v177, v175
	v_fmac_f32_e32 v185, v184, v184
	v_fmac_f32_e32 v183, v182, v182
	v_add_f32_e32 v172, v181, v179
	v_add_f32_e32 v154, v154, v155
	v_add_f32_e32 v173, v185, v183
	v_add_f32_e32 v154, v172, v154
	v_add_f32_e32 v154, v173, v154
	v_mov_b32_e32 v155, v154
	s_nop 1
	v_permlane16_swap_b32_e32 v154, v155
	s_add_i32 s4, s0, 0x100
	s_waitcnt lgkmcnt(0)
	v_add_f32_e32 v154, v154, v155
	v_mov_b32_e32 v155, v154
	s_nop 1
	v_permlane32_swap_b32_e32 v154, v155
	s_and_saveexec_b64 s[0:1], vcc
	s_cbranch_execz .LBB0_2324
	s_lshl_b32 s5, s27, 11
	s_add_i32 s5, s4, s5
	v_mul_f32_e32 v156, 0x3c800000, v151
	v_lshl_add_u32 v151, v150, 5, s5
	s_waitcnt lgkmcnt(0)
	v_add_f32_e32 v157, v154, v155
	ds_write_b64 v151, v[156:157]
;     DI void fused(f32x4 (&acc)[2][2][4][2], const Unit& u, int wr, int wc, int fr_, int fq_, LAS unsigned char* lds, int wid, int lane_) const {
;     ...
;         for (int ai = 0; ai < 2; ++ai)
; #pragma unroll
;             for (int m = 0; m < 4; ++m) {
;                 float sm = 0.f;
; #pragma unroll
;                 for (int bj = 0; bj < 2; ++bj)
; #pragma unroll
;                     for (int n = 0; n < 2; ++n) { const f32x4 x = acc[ai][bj][m][n]; sm += (x[0] + x[1]) + (x[2] + x[3]); }
;                 sm += __shfl_xor(sm, 16); sm += __shfl_xor(sm, 32);
;                 const float mw = sm * (1.0f / 64.0f); float q = 0.f;
; #pragma unroll
;                 for (int bj = 0; bj < 2; ++bj)
; #pragma unroll
;                     for (int n = 0; n < 2; ++n) { const f32x4 d = acc[ai][bj][m][n] - mw; q += (d[0] * d[0] + d[1] * d[1]) + (d[2] * d[2] + d[3] * d[3]); }
;                 q += __shfl_xor(q, 16); q += __shfl_xor(q, 32);
;                 if (fq == 0) P[(ai * HALF + wr * 64 + m * 16 + fr) * 4 + wc] = (f32x2){mw, q};
.LBB0_2324:
	s_or_b64 exec, exec, s[0:1]
	v_mov_b32_e32 v154, v113
	s_waitcnt lgkmcnt(0)
	v_mov_b32_e32 v155, v114
	v_mov_b32_e32 v156, v112
	v_mov_b32_e32 v157, v115
	v_pk_add_f32 v[154:155], v[154:155], v[156:157]
	v_mov_b32_e32 v156, v105
	v_mov_b32_e32 v157, v106
	v_mov_b32_e32 v158, v104
	v_mov_b32_e32 v159, v107
	v_pk_add_f32 v[156:157], v[156:157], v[158:159]
	v_add_f32_e32 v151, v154, v155
	v_pk_add_f32 v[156:157], v[156:157], v[156:157] op_sel_hi:[0,1]
	v_add_f32_e32 v155, 0, v151
	v_add_f32_e32 v159, v100, v101
	v_add_f32_e32 v161, v102, v103
	v_mov_b32_e32 v158, v92
	v_mov_b32_e32 v160, v93
	v_mov_b32_e32 v156, v94
	v_mov_b32_e32 v154, v95
	v_pk_add_f32 v[158:159], v[158:159], v[160:161]
	v_pk_add_f32 v[154:155], v[156:157], v[154:155]
	s_nop 0
	v_pk_add_f32 v[154:155], v[158:159], v[154:155]
	s_nop 0
	v_add_f32_e32 v151, v154, v155
	v_mov_b32_e32 v154, v151
	s_nop 1
	v_permlane16_swap_b32_e32 v151, v154
	s_waitcnt lgkmcnt(0)
	v_add_f32_e32 v151, v151, v154
	v_mov_b32_e32 v154, v151
	s_nop 1
	v_permlane32_swap_b32_e32 v151, v154
	s_waitcnt lgkmcnt(0)
	v_add_f32_e32 v151, v151, v154
	v_fmamk_f32 v155, v151, 0xbc800000, v115
	v_fmamk_f32 v157, v151, 0xbc800000, v113
	v_fmamk_f32 v154, v151, 0xbc800000, v114
	v_fmamk_f32 v156, v151, 0xbc800000, v112
	v_mul_f32_e32 v157, v157, v157
	v_mul_f32_e32 v155, v155, v155
	v_fmac_f32_e32 v157, v156, v156
	v_fmac_f32_e32 v155, v154, v154
	v_fmamk_f32 v156, v151, 0xbc800000, v107
	v_fmamk_f32 v158, v151, 0xbc800000, v105
	v_add_f32_e32 v154, v157, v155
	v_fmamk_f32 v155, v151, 0xbc800000, v106
	v_fmamk_f32 v157, v151, 0xbc800000, v104
	v_mul_f32_e32 v158, v158, v158
	v_mul_f32_e32 v156, v156, v156
	v_fmac_f32_e32 v158, v157, v157
	v_fmac_f32_e32 v156, v155, v155
	v_add_f32_e32 v155, v158, v156
	v_fmamk_f32 v156, v151, 0xbc800000, v103
	v_fmamk_f32 v158, v151, 0xbc800000, v101
	v_add_f32_e32 v154, v154, v155
	v_fmamk_f32 v155, v151, 0xbc800000, v102
	v_fmamk_f32 v157, v151, 0xbc800000, v100
	v_mul_f32_e32 v158, v158, v158
	v_mul_f32_e32 v156, v156, v156
	v_fmac_f32_e32 v158, v157, v157
	v_fmac_f32_e32 v156, v155, v155
	v_add_f32_e32 v155, v158, v156
	v_fmamk_f32 v156, v151, 0xbc800000, v95
	v_fmamk_f32 v158, v151, 0xbc800000, v93
	v_add_f32_e32 v154, v155, v154
	v_fmamk_f32 v155, v151, 0xbc800000, v94
	v_fmamk_f32 v157, v151, 0xbc800000, v92
	v_mul_f32_e32 v158, v158, v158
	v_mul_f32_e32 v156, v156, v156
	v_fmac_f32_e32 v158, v157, v157
	v_fmac_f32_e32 v156, v155, v155
	v_add_f32_e32 v155, v158, v156
	v_add_f32_e32 v154, v155, v154
	v_mov_b32_e32 v155, v154
	s_nop 1
	v_permlane16_swap_b32_e32 v154, v155
	s_waitcnt lgkmcnt(0)
	v_add_f32_e32 v154, v154, v155
	v_mov_b32_e32 v155, v154
	s_nop 1
	v_permlane32_swap_b32_e32 v154, v155
	s_and_saveexec_b64 s[0:1], vcc
	s_cbranch_execz .LBB0_2326
	s_lshl_b32 s5, s27, 11
	s_add_i32 s5, s4, s5
	v_mul_f32_e32 v156, 0x3c800000, v151
	v_lshl_add_u32 v151, v150, 5, s5
	s_waitcnt lgkmcnt(0)
	v_add_f32_e32 v157, v154, v155
	ds_write_b64 v151, v[156:157] offset:512
.LBB0_2326:
	s_or_b64 exec, exec, s[0:1]
	v_mov_b32_e32 v154, v97
	s_waitcnt lgkmcnt(0)
	v_mov_b32_e32 v155, v98
	v_mov_b32_e32 v156, v96
	v_mov_b32_e32 v157, v99
	v_pk_add_f32 v[154:155], v[154:155], v[156:157]
	v_mov_b32_e32 v156, v89
	v_mov_b32_e32 v157, v90
	v_mov_b32_e32 v158, v88
	v_mov_b32_e32 v159, v91
	v_pk_add_f32 v[156:157], v[156:157], v[158:159]
	v_add_f32_e32 v151, v154, v155
	v_pk_add_f32 v[156:157], v[156:157], v[156:157] op_sel_hi:[0,1]
	v_add_f32_e32 v155, 0, v151
	v_add_f32_e32 v159, v84, v85
	v_add_f32_e32 v161, v86, v87
	v_mov_b32_e32 v158, v76
	v_mov_b32_e32 v160, v77
	v_mov_b32_e32 v156, v78
	v_mov_b32_e32 v154, v79
	v_pk_add_f32 v[158:159], v[158:159], v[160:161]
	v_pk_add_f32 v[154:155], v[156:157], v[154:155]
	s_nop 0
	v_pk_add_f32 v[154:155], v[158:159], v[154:155]
	s_nop 0
	v_add_f32_e32 v151, v154, v155
	v_mov_b32_e32 v154, v151
	s_nop 1
	v_permlane16_swap_b32_e32 v151, v154
	s_waitcnt lgkmcnt(0)
	v_add_f32_e32 v151, v151, v154
	v_mov_b32_e32 v154, v151
	s_nop 1
	v_permlane32_swap_b32_e32 v151, v154
	s_waitcnt lgkmcnt(0)
	v_add_f32_e32 v151, v151, v154
	v_fmamk_f32 v155, v151, 0xbc800000, v99
	v_fmamk_f32 v157, v151, 0xbc800000, v97
	v_fmamk_f32 v154, v151, 0xbc800000, v98
	v_fmamk_f32 v156, v151, 0xbc800000, v96
	v_mul_f32_e32 v157, v157, v157
	v_mul_f32_e32 v155, v155, v155
	v_fmac_f32_e32 v157, v156, v156
	v_fmac_f32_e32 v155, v154, v154
	v_fmamk_f32 v156, v151, 0xbc800000, v91
	v_fmamk_f32 v158, v151, 0xbc800000, v89
	v_add_f32_e32 v154, v157, v155
	v_fmamk_f32 v155, v151, 0xbc800000, v90
	v_fmamk_f32 v157, v151, 0xbc800000, v88
	v_mul_f32_e32 v158, v158, v158
	v_mul_f32_e32 v156, v156, v156
	v_fmac_f32_e32 v158, v157, v157
	v_fmac_f32_e32 v156, v155, v155
	v_add_f32_e32 v155, v158, v156
	v_fmamk_f32 v156, v151, 0xbc800000, v87
	v_fmamk_f32 v158, v151, 0xbc800000, v85
	v_add_f32_e32 v154, v154, v155
	v_fmamk_f32 v155, v151, 0xbc800000, v86
	v_fmamk_f32 v157, v151, 0xbc800000, v84
	v_mul_f32_e32 v158, v158, v158
	v_mul_f32_e32 v156, v156, v156
	v_fmac_f32_e32 v158, v157, v157
	v_fmac_f32_e32 v156, v155, v155
	v_add_f32_e32 v155, v158, v156
	v_fmamk_f32 v156, v151, 0xbc800000, v79
	v_fmamk_f32 v158, v151, 0xbc800000, v77
	v_add_f32_e32 v154, v155, v154
	v_fmamk_f32 v155, v151, 0xbc800000, v78
	v_fmamk_f32 v157, v151, 0xbc800000, v76
	v_mul_f32_e32 v158, v158, v158
	v_mul_f32_e32 v156, v156, v156
	v_fmac_f32_e32 v158, v157, v157
	v_fmac_f32_e32 v156, v155, v155
	v_add_f32_e32 v155, v158, v156
	v_add_f32_e32 v154, v155, v154
	v_mov_b32_e32 v155, v154
	s_nop 1
	v_permlane16_swap_b32_e32 v154, v155
	s_waitcnt lgkmcnt(0)
	v_add_f32_e32 v154, v154, v155
	v_mov_b32_e32 v155, v154
	s_nop 1
	v_permlane32_swap_b32_e32 v154, v155
	s_and_saveexec_b64 s[0:1], vcc
	s_cbranch_execz .LBB0_2328
	s_lshl_b32 s5, s27, 11
	s_add_i32 s5, s4, s5
	v_mul_f32_e32 v156, 0x3c800000, v151
	v_lshl_add_u32 v151, v150, 5, s5
	s_waitcnt lgkmcnt(0)
	v_add_f32_e32 v157, v154, v155
	ds_write_b64 v151, v[156:157] offset:1024
;     DI void fused(f32x4 (&acc)[2][2][4][2], const Unit& u, int wr, int wc, int fr_, int fq_, LAS unsigned char* lds, int wid, int lane_) const {
;     ...
;         for (int ai = 0; ai < 2; ++ai)
; #pragma unroll
;             for (int m = 0; m < 4; ++m) {
;                 float sm = 0.f;
; #pragma unroll
;                 for (int bj = 0; bj < 2; ++bj)
; #pragma unroll
;                     for (int n = 0; n < 2; ++n) { const f32x4 x = acc[ai][bj][m][n]; sm += (x[0] + x[1]) + (x[2] + x[3]); }
;                 sm += __shfl_xor(sm, 16); sm += __shfl_xor(sm, 32);
;                 const float mw = sm * (1.0f / 64.0f); float q = 0.f;
; #pragma unroll
;                 for (int bj = 0; bj < 2; ++bj)
; #pragma unroll
;                     for (int n = 0; n < 2; ++n) { const f32x4 d = acc[ai][bj][m][n] - mw; q += (d[0] * d[0] + d[1] * d[1]) + (d[2] * d[2] + d[3] * d[3]); }
;                 q += __shfl_xor(q, 16); q += __shfl_xor(q, 32);
;                 if (fq == 0) P[(ai * HALF + wr * 64 + m * 16 + fr) * 4 + wc] = (f32x2){mw, q};
.LBB0_2328:
	s_or_b64 exec, exec, s[0:1]
	v_mov_b32_e32 v154, v81
	s_waitcnt lgkmcnt(0)
	v_mov_b32_e32 v155, v82
	v_mov_b32_e32 v156, v80
	v_mov_b32_e32 v157, v83
	v_pk_add_f32 v[154:155], v[154:155], v[156:157]
	v_mov_b32_e32 v156, v73
	v_mov_b32_e32 v157, v74
	v_mov_b32_e32 v158, v72
	v_mov_b32_e32 v159, v75
	v_pk_add_f32 v[156:157], v[156:157], v[158:159]
	v_add_f32_e32 v151, v154, v155
	v_pk_add_f32 v[156:157], v[156:157], v[156:157] op_sel_hi:[0,1]
	v_add_f32_e32 v155, 0, v151
	v_add_f32_e32 v159, v68, v69
	v_add_f32_e32 v161, v70, v71
	v_mov_b32_e32 v158, v64
	v_mov_b32_e32 v160, v65
	v_mov_b32_e32 v156, v66
	v_mov_b32_e32 v154, v67
	v_pk_add_f32 v[158:159], v[158:159], v[160:161]
	v_pk_add_f32 v[154:155], v[156:157], v[154:155]
	s_nop 0
	v_pk_add_f32 v[154:155], v[158:159], v[154:155]
	s_nop 0
	v_add_f32_e32 v151, v154, v155
	v_mov_b32_e32 v154, v151
	s_nop 1
	v_permlane16_swap_b32_e32 v151, v154
	s_waitcnt lgkmcnt(0)
	v_add_f32_e32 v151, v151, v154
	v_mov_b32_e32 v154, v151
	s_nop 1
	v_permlane32_swap_b32_e32 v151, v154
	s_waitcnt lgkmcnt(0)
	v_add_f32_e32 v151, v151, v154
	v_fmamk_f32 v155, v151, 0xbc800000, v83
	v_fmamk_f32 v157, v151, 0xbc800000, v81
	v_fmamk_f32 v154, v151, 0xbc800000, v82
	v_fmamk_f32 v156, v151, 0xbc800000, v80
	v_mul_f32_e32 v157, v157, v157
	v_mul_f32_e32 v155, v155, v155
	v_fmac_f32_e32 v157, v156, v156
	v_fmac_f32_e32 v155, v154, v154
	v_fmamk_f32 v156, v151, 0xbc800000, v75
	v_fmamk_f32 v158, v151, 0xbc800000, v73
	v_add_f32_e32 v154, v157, v155
	v_fmamk_f32 v155, v151, 0xbc800000, v74
	v_fmamk_f32 v157, v151, 0xbc800000, v72
	v_mul_f32_e32 v158, v158, v158
	v_mul_f32_e32 v156, v156, v156
	v_fmac_f32_e32 v158, v157, v157
	v_fmac_f32_e32 v156, v155, v155
	v_add_f32_e32 v155, v158, v156
	v_fmamk_f32 v156, v151, 0xbc800000, v71
	v_fmamk_f32 v158, v151, 0xbc800000, v69
	v_add_f32_e32 v154, v154, v155
	v_fmamk_f32 v155, v151, 0xbc800000, v70
	v_fmamk_f32 v157, v151, 0xbc800000, v68
	v_mul_f32_e32 v158, v158, v158
	v_mul_f32_e32 v156, v156, v156
	v_fmac_f32_e32 v158, v157, v157
	v_fmac_f32_e32 v156, v155, v155
	v_add_f32_e32 v155, v158, v156
	v_fmamk_f32 v156, v151, 0xbc800000, v67
	v_fmamk_f32 v158, v151, 0xbc800000, v65
	v_add_f32_e32 v154, v155, v154
	v_fmamk_f32 v155, v151, 0xbc800000, v66
	v_fmamk_f32 v157, v151, 0xbc800000, v64
	v_mul_f32_e32 v158, v158, v158
	v_mul_f32_e32 v156, v156, v156
	v_fmac_f32_e32 v158, v157, v157
	v_fmac_f32_e32 v156, v155, v155
	v_add_f32_e32 v155, v158, v156
	v_add_f32_e32 v154, v155, v154
	v_mov_b32_e32 v155, v154
	s_nop 1
	v_permlane16_swap_b32_e32 v154, v155
	s_waitcnt lgkmcnt(0)
	v_add_f32_e32 v154, v154, v155
	v_mov_b32_e32 v155, v154
	s_nop 1
	v_permlane32_swap_b32_e32 v154, v155
	s_and_saveexec_b64 s[0:1], vcc
	s_cbranch_execz .LBB0_2330
	s_lshl_b32 s5, s27, 11
	s_add_i32 s5, s4, s5
	v_mul_f32_e32 v156, 0x3c800000, v151
	v_lshl_add_u32 v151, v150, 5, s5
	s_waitcnt lgkmcnt(0)
	v_add_f32_e32 v157, v154, v155
	ds_write_b64 v151, v[156:157] offset:1536
.LBB0_2330:
	s_or_b64 exec, exec, s[0:1]
	v_mov_b32_e32 v154, v61
	s_waitcnt lgkmcnt(0)
	v_mov_b32_e32 v155, v62
	v_mov_b32_e32 v156, v60
	v_mov_b32_e32 v157, v63
	v_pk_add_f32 v[154:155], v[154:155], v[156:157]
	v_mov_b32_e32 v156, v57
	v_mov_b32_e32 v157, v58
	v_mov_b32_e32 v158, v56
	v_mov_b32_e32 v159, v59
	v_pk_add_f32 v[156:157], v[156:157], v[158:159]
	v_add_f32_e32 v151, v154, v155
	v_pk_add_f32 v[156:157], v[156:157], v[156:157] op_sel_hi:[0,1]
	v_add_f32_e32 v155, 0, v151
	v_add_f32_e32 v159, v52, v53
	v_add_f32_e32 v161, v54, v55
	v_mov_b32_e32 v158, v48
	v_mov_b32_e32 v160, v49
	v_mov_b32_e32 v156, v50
	v_mov_b32_e32 v154, v51
	v_pk_add_f32 v[158:159], v[158:159], v[160:161]
	v_pk_add_f32 v[154:155], v[156:157], v[154:155]
	s_nop 0
	v_pk_add_f32 v[154:155], v[158:159], v[154:155]
	s_nop 0
	v_add_f32_e32 v151, v154, v155
	v_mov_b32_e32 v154, v151
	s_nop 1
	v_permlane16_swap_b32_e32 v151, v154
	s_waitcnt lgkmcnt(0)
	v_add_f32_e32 v151, v151, v154
	v_mov_b32_e32 v154, v151
	s_nop 1
	v_permlane32_swap_b32_e32 v151, v154
	s_waitcnt lgkmcnt(0)
	v_add_f32_e32 v151, v151, v154
	v_fmamk_f32 v155, v151, 0xbc800000, v63
	v_fmamk_f32 v157, v151, 0xbc800000, v61
	v_fmamk_f32 v154, v151, 0xbc800000, v62
	v_fmamk_f32 v156, v151, 0xbc800000, v60
	v_mul_f32_e32 v157, v157, v157
	v_mul_f32_e32 v155, v155, v155
	v_fmac_f32_e32 v157, v156, v156
	v_fmac_f32_e32 v155, v154, v154
	v_fmamk_f32 v156, v151, 0xbc800000, v59
	v_fmamk_f32 v158, v151, 0xbc800000, v57
	v_add_f32_e32 v154, v157, v155
	v_fmamk_f32 v155, v151, 0xbc800000, v58
	v_fmamk_f32 v157, v151, 0xbc800000, v56
	v_mul_f32_e32 v158, v158, v158
	v_mul_f32_e32 v156, v156, v156
	v_fmac_f32_e32 v158, v157, v157
	v_fmac_f32_e32 v156, v155, v155
	v_add_f32_e32 v155, v158, v156
	v_fmamk_f32 v156, v151, 0xbc800000, v55
	v_fmamk_f32 v158, v151, 0xbc800000, v53
	v_add_f32_e32 v154, v154, v155
	v_fmamk_f32 v155, v151, 0xbc800000, v54
	v_fmamk_f32 v157, v151, 0xbc800000, v52
	v_mul_f32_e32 v158, v158, v158
	v_mul_f32_e32 v156, v156, v156
	v_fmac_f32_e32 v158, v157, v157
	v_fmac_f32_e32 v156, v155, v155
	v_add_f32_e32 v155, v158, v156
	v_fmamk_f32 v156, v151, 0xbc800000, v51
	v_fmamk_f32 v158, v151, 0xbc800000, v49
	v_add_f32_e32 v154, v155, v154
	v_fmamk_f32 v155, v151, 0xbc800000, v50
	v_fmamk_f32 v157, v151, 0xbc800000, v48
	v_mul_f32_e32 v158, v158, v158
	v_mul_f32_e32 v156, v156, v156
	v_fmac_f32_e32 v158, v157, v157
	v_fmac_f32_e32 v156, v155, v155
	v_add_f32_e32 v155, v158, v156
	v_add_f32_e32 v154, v155, v154
	v_mov_b32_e32 v155, v154
	s_nop 1
	v_permlane16_swap_b32_e32 v154, v155
	s_waitcnt lgkmcnt(0)
	v_add_f32_e32 v154, v154, v155
	v_mov_b32_e32 v155, v154
	s_nop 1
	v_permlane32_swap_b32_e32 v154, v155
	s_and_saveexec_b64 s[0:1], vcc
	s_cbranch_execz .LBB0_2332
	s_lshl_b32 s5, s27, 11
	s_add_i32 s5, s4, s5
	v_mul_f32_e32 v156, 0x3c800000, v151
	v_lshl_add_u32 v151, v150, 5, s5
	s_waitcnt lgkmcnt(0)
	v_add_f32_e32 v157, v154, v155
	ds_write_b64 v151, v[156:157] offset:4096
;     DI void fused(f32x4 (&acc)[2][2][4][2], const Unit& u, int wr, int wc, int fr_, int fq_, LAS unsigned char* lds, int wid, int lane_) const {
;     ...
;         for (int ai = 0; ai < 2; ++ai)
; #pragma unroll
;             for (int m = 0; m < 4; ++m) {
;                 float sm = 0.f;
; #pragma unroll
;                 for (int bj = 0; bj < 2; ++bj)
; #pragma unroll
;                     for (int n = 0; n < 2; ++n) { const f32x4 x = acc[ai][bj][m][n]; sm += (x[0] + x[1]) + (x[2] + x[3]); }
;                 sm += __shfl_xor(sm, 16); sm += __shfl_xor(sm, 32);
;                 const float mw = sm * (1.0f / 64.0f); float q = 0.f;
; #pragma unroll
;                 for (int bj = 0; bj < 2; ++bj)
; #pragma unroll
;                     for (int n = 0; n < 2; ++n) { const f32x4 d = acc[ai][bj][m][n] - mw; q += (d[0] * d[0] + d[1] * d[1]) + (d[2] * d[2] + d[3] * d[3]); }
;                 q += __shfl_xor(q, 16); q += __shfl_xor(q, 32);
;                 if (fq == 0) P[(ai * HALF + wr * 64 + m * 16 + fr) * 4 + wc] = (f32x2){mw, q};
.LBB0_2332:
	s_or_b64 exec, exec, s[0:1]
	v_mov_b32_e32 v154, v45
	s_waitcnt lgkmcnt(0)
	v_mov_b32_e32 v155, v46
	v_mov_b32_e32 v156, v44
	v_mov_b32_e32 v157, v47
	v_pk_add_f32 v[154:155], v[154:155], v[156:157]
	v_mov_b32_e32 v156, v41
	v_mov_b32_e32 v157, v42
	v_mov_b32_e32 v158, v40
	v_mov_b32_e32 v159, v43
	v_pk_add_f32 v[156:157], v[156:157], v[158:159]
	v_add_f32_e32 v151, v154, v155
	v_pk_add_f32 v[156:157], v[156:157], v[156:157] op_sel_hi:[0,1]
	v_add_f32_e32 v155, 0, v151
	v_add_f32_e32 v159, v36, v37
	v_add_f32_e32 v161, v38, v39
	v_mov_b32_e32 v158, v32
	v_mov_b32_e32 v160, v33
	v_mov_b32_e32 v156, v34
	v_mov_b32_e32 v154, v35
	v_pk_add_f32 v[158:159], v[158:159], v[160:161]
	v_pk_add_f32 v[154:155], v[156:157], v[154:155]
	s_nop 0
	v_pk_add_f32 v[154:155], v[158:159], v[154:155]
	s_nop 0
	v_add_f32_e32 v151, v154, v155
	v_mov_b32_e32 v154, v151
	s_nop 1
	v_permlane16_swap_b32_e32 v151, v154
	s_waitcnt lgkmcnt(0)
	v_add_f32_e32 v151, v151, v154
	v_mov_b32_e32 v154, v151
	s_nop 1
	v_permlane32_swap_b32_e32 v151, v154
	s_waitcnt lgkmcnt(0)
	v_add_f32_e32 v151, v151, v154
	v_fmamk_f32 v155, v151, 0xbc800000, v47
	v_fmamk_f32 v157, v151, 0xbc800000, v45
	v_fmamk_f32 v154, v151, 0xbc800000, v46
	v_fmamk_f32 v156, v151, 0xbc800000, v44
	v_mul_f32_e32 v157, v157, v157
	v_mul_f32_e32 v155, v155, v155
	v_fmac_f32_e32 v157, v156, v156
	v_fmac_f32_e32 v155, v154, v154
	v_fmamk_f32 v156, v151, 0xbc800000, v43
	v_fmamk_f32 v158, v151, 0xbc800000, v41
	v_add_f32_e32 v154, v157, v155
	v_fmamk_f32 v155, v151, 0xbc800000, v42
	v_fmamk_f32 v157, v151, 0xbc800000, v40
	v_mul_f32_e32 v158, v158, v158
	v_mul_f32_e32 v156, v156, v156
	v_fmac_f32_e32 v158, v157, v157
	v_fmac_f32_e32 v156, v155, v155
	v_add_f32_e32 v155, v158, v156
	v_fmamk_f32 v156, v151, 0xbc800000, v39
	v_fmamk_f32 v158, v151, 0xbc800000, v37
	v_add_f32_e32 v154, v154, v155
	v_fmamk_f32 v155, v151, 0xbc800000, v38
	v_fmamk_f32 v157, v151, 0xbc800000, v36
	v_mul_f32_e32 v158, v158, v158
	v_mul_f32_e32 v156, v156, v156
	v_fmac_f32_e32 v158, v157, v157
	v_fmac_f32_e32 v156, v155, v155
	v_add_f32_e32 v155, v158, v156
	v_fmamk_f32 v156, v151, 0xbc800000, v35
	v_fmamk_f32 v158, v151, 0xbc800000, v33
	v_add_f32_e32 v154, v155, v154
	v_fmamk_f32 v155, v151, 0xbc800000, v34
	v_fmamk_f32 v157, v151, 0xbc800000, v32
	v_mul_f32_e32 v158, v158, v158
	v_mul_f32_e32 v156, v156, v156
	v_fmac_f32_e32 v158, v157, v157
	v_fmac_f32_e32 v156, v155, v155
	v_add_f32_e32 v155, v158, v156
	v_add_f32_e32 v154, v155, v154
	v_mov_b32_e32 v155, v154
	s_nop 1
	v_permlane16_swap_b32_e32 v154, v155
	s_waitcnt lgkmcnt(0)
	v_add_f32_e32 v154, v154, v155
	v_mov_b32_e32 v155, v154
	s_nop 1
	v_permlane32_swap_b32_e32 v154, v155
	s_and_saveexec_b64 s[0:1], vcc
	s_cbranch_execz .LBB0_2334
	s_lshl_b32 s5, s27, 11
	s_add_i32 s5, s4, s5
	v_mul_f32_e32 v156, 0x3c800000, v151
	v_lshl_add_u32 v151, v150, 5, s5
	s_waitcnt lgkmcnt(0)
	v_add_f32_e32 v157, v154, v155
	ds_write_b64 v151, v[156:157] offset:4608
;     DI void fused(f32x4 (&acc)[2][2][4][2], const Unit& u, int wr, int wc, int fr_, int fq_, LAS unsigned char* lds, int wid, int lane_) const {
;     ...
;         for (int ai = 0; ai < 2; ++ai)
; #pragma unroll
;             for (int m = 0; m < 4; ++m) {
;                 float sm = 0.f;
; #pragma unroll
;                 for (int bj = 0; bj < 2; ++bj)
; #pragma unroll
;                     for (int n = 0; n < 2; ++n) { const f32x4 x = acc[ai][bj][m][n]; sm += (x[0] + x[1]) + (x[2] + x[3]); }
;                 sm += __shfl_xor(sm, 16); sm += __shfl_xor(sm, 32);
;                 const float mw = sm * (1.0f / 64.0f); float q = 0.f;
; #pragma unroll
;                 for (int bj = 0; bj < 2; ++bj)
; #pragma unroll
;                     for (int n = 0; n < 2; ++n) { const f32x4 d = acc[ai][bj][m][n] - mw; q += (d[0] * d[0] + d[1] * d[1]) + (d[2] * d[2] + d[3] * d[3]); }
;                 q += __shfl_xor(q, 16); q += __shfl_xor(q, 32);
;                 if (fq == 0) P[(ai * HALF + wr * 64 + m * 16 + fr) * 4 + wc] = (f32x2){mw, q};
.LBB0_2334:
	s_or_b64 exec, exec, s[0:1]
	v_mov_b32_e32 v154, v29
	s_waitcnt lgkmcnt(0)
	v_mov_b32_e32 v155, v30
	v_mov_b32_e32 v156, v28
	v_mov_b32_e32 v157, v31
	v_pk_add_f32 v[154:155], v[154:155], v[156:157]
	v_mov_b32_e32 v156, v25
	v_mov_b32_e32 v157, v26
	v_mov_b32_e32 v158, v24
	v_mov_b32_e32 v159, v27
	v_pk_add_f32 v[156:157], v[156:157], v[158:159]
	v_add_f32_e32 v151, v154, v155
	v_pk_add_f32 v[156:157], v[156:157], v[156:157] op_sel_hi:[0,1]
	v_add_f32_e32 v155, 0, v151
	v_add_f32_e32 v159, v20, v21
	v_add_f32_e32 v161, v22, v23
	v_mov_b32_e32 v158, v16
	v_mov_b32_e32 v160, v17
	v_mov_b32_e32 v156, v18
	v_mov_b32_e32 v154, v19
	v_pk_add_f32 v[158:159], v[158:159], v[160:161]
	v_pk_add_f32 v[154:155], v[156:157], v[154:155]
	s_nop 0
	v_pk_add_f32 v[154:155], v[158:159], v[154:155]
	s_nop 0
	v_add_f32_e32 v151, v154, v155
	v_mov_b32_e32 v154, v151
	s_nop 1
	v_permlane16_swap_b32_e32 v151, v154
	s_waitcnt lgkmcnt(0)
	v_add_f32_e32 v151, v151, v154
	v_mov_b32_e32 v154, v151
	s_nop 1
	v_permlane32_swap_b32_e32 v151, v154
	s_waitcnt lgkmcnt(0)
	v_add_f32_e32 v151, v151, v154
	v_fmamk_f32 v155, v151, 0xbc800000, v31
	v_fmamk_f32 v157, v151, 0xbc800000, v29
	v_fmamk_f32 v154, v151, 0xbc800000, v30
	v_fmamk_f32 v156, v151, 0xbc800000, v28
	v_mul_f32_e32 v157, v157, v157
	v_mul_f32_e32 v155, v155, v155
	v_fmac_f32_e32 v157, v156, v156
	v_fmac_f32_e32 v155, v154, v154
	v_fmamk_f32 v156, v151, 0xbc800000, v27
	v_fmamk_f32 v158, v151, 0xbc800000, v25
	v_add_f32_e32 v154, v157, v155
	v_fmamk_f32 v155, v151, 0xbc800000, v26
	v_fmamk_f32 v157, v151, 0xbc800000, v24
	v_mul_f32_e32 v158, v158, v158
	v_mul_f32_e32 v156, v156, v156
	v_fmac_f32_e32 v158, v157, v157
	v_fmac_f32_e32 v156, v155, v155
	v_add_f32_e32 v155, v158, v156
	v_fmamk_f32 v156, v151, 0xbc800000, v23
	v_fmamk_f32 v158, v151, 0xbc800000, v21
	v_add_f32_e32 v154, v154, v155
	v_fmamk_f32 v155, v151, 0xbc800000, v22
	v_fmamk_f32 v157, v151, 0xbc800000, v20
	v_mul_f32_e32 v158, v158, v158
	v_mul_f32_e32 v156, v156, v156
	v_fmac_f32_e32 v158, v157, v157
	v_fmac_f32_e32 v156, v155, v155
	v_add_f32_e32 v155, v158, v156
	v_fmamk_f32 v156, v151, 0xbc800000, v19
	v_fmamk_f32 v158, v151, 0xbc800000, v17
	v_add_f32_e32 v154, v155, v154
	v_fmamk_f32 v155, v151, 0xbc800000, v18
	v_fmamk_f32 v157, v151, 0xbc800000, v16
	v_mul_f32_e32 v158, v158, v158
	v_mul_f32_e32 v156, v156, v156
	v_fmac_f32_e32 v158, v157, v157
	v_fmac_f32_e32 v156, v155, v155
	v_add_f32_e32 v155, v158, v156
	v_add_f32_e32 v154, v155, v154
	v_mov_b32_e32 v155, v154
	s_nop 1
	v_permlane16_swap_b32_e32 v154, v155
	s_waitcnt lgkmcnt(0)
	v_add_f32_e32 v154, v154, v155
	v_mov_b32_e32 v155, v154
	s_nop 1
	v_permlane32_swap_b32_e32 v154, v155
	s_and_saveexec_b64 s[0:1], vcc
	s_cbranch_execz .LBB0_2336
	s_lshl_b32 s5, s27, 11
	s_add_i32 s5, s4, s5
	v_mul_f32_e32 v156, 0x3c800000, v151
	v_lshl_add_u32 v151, v150, 5, s5
	s_waitcnt lgkmcnt(0)
	v_add_f32_e32 v157, v154, v155
	ds_write_b64 v151, v[156:157] offset:5120
.LBB0_2336:
	s_or_b64 exec, exec, s[0:1]
	v_mov_b32_e32 v154, v13
	s_waitcnt lgkmcnt(0)
	v_mov_b32_e32 v155, v14
	v_mov_b32_e32 v156, v12
	v_mov_b32_e32 v157, v15
	v_pk_add_f32 v[154:155], v[154:155], v[156:157]
	v_mov_b32_e32 v156, v9
	v_mov_b32_e32 v157, v10
	v_mov_b32_e32 v158, v8
	v_mov_b32_e32 v159, v11
	v_pk_add_f32 v[156:157], v[156:157], v[158:159]
	v_add_f32_e32 v151, v154, v155
	v_pk_add_f32 v[156:157], v[156:157], v[156:157] op_sel_hi:[0,1]
	v_add_f32_e32 v155, 0, v151
	v_add_f32_e32 v159, v4, v5
	v_add_f32_e32 v161, v6, v7
	v_mov_b32_e32 v158, v0
	v_mov_b32_e32 v160, v1
	v_mov_b32_e32 v156, v2
	v_mov_b32_e32 v154, v3
	v_pk_add_f32 v[158:159], v[158:159], v[160:161]
	v_pk_add_f32 v[154:155], v[156:157], v[154:155]
	s_nop 0
	v_pk_add_f32 v[154:155], v[158:159], v[154:155]
	s_nop 0
	v_add_f32_e32 v151, v154, v155
	v_mov_b32_e32 v154, v151
	s_nop 1
	v_permlane16_swap_b32_e32 v151, v154
	s_waitcnt lgkmcnt(0)
	v_add_f32_e32 v151, v151, v154
	v_mov_b32_e32 v154, v151
	s_nop 1
	v_permlane32_swap_b32_e32 v151, v154
	s_waitcnt lgkmcnt(0)
	v_add_f32_e32 v151, v151, v154
	v_fmamk_f32 v155, v151, 0xbc800000, v15
	v_fmamk_f32 v157, v151, 0xbc800000, v13
	v_fmamk_f32 v154, v151, 0xbc800000, v14
	v_fmamk_f32 v156, v151, 0xbc800000, v12
	v_mul_f32_e32 v157, v157, v157
	v_mul_f32_e32 v155, v155, v155
	v_fmac_f32_e32 v157, v156, v156
	v_fmac_f32_e32 v155, v154, v154
	v_fmamk_f32 v156, v151, 0xbc800000, v11
	v_fmamk_f32 v158, v151, 0xbc800000, v9
	v_add_f32_e32 v154, v157, v155
	v_fmamk_f32 v155, v151, 0xbc800000, v10
	v_fmamk_f32 v157, v151, 0xbc800000, v8
	v_mul_f32_e32 v158, v158, v158
	v_mul_f32_e32 v156, v156, v156
	v_fmac_f32_e32 v158, v157, v157
	v_fmac_f32_e32 v156, v155, v155
	v_add_f32_e32 v155, v158, v156
	v_fmamk_f32 v156, v151, 0xbc800000, v7
	v_fmamk_f32 v158, v151, 0xbc800000, v5
	v_add_f32_e32 v154, v154, v155
	v_fmamk_f32 v155, v151, 0xbc800000, v6
	v_fmamk_f32 v157, v151, 0xbc800000, v4
	v_mul_f32_e32 v158, v158, v158
	v_mul_f32_e32 v156, v156, v156
	v_fmac_f32_e32 v158, v157, v157
	v_fmac_f32_e32 v156, v155, v155
	v_add_f32_e32 v155, v158, v156
	v_fmamk_f32 v156, v151, 0xbc800000, v3
	v_fmamk_f32 v158, v151, 0xbc800000, v1
	v_add_f32_e32 v154, v155, v154
	v_fmamk_f32 v155, v151, 0xbc800000, v2
	v_fmamk_f32 v157, v151, 0xbc800000, v0
	v_mul_f32_e32 v158, v158, v158
	v_mul_f32_e32 v156, v156, v156
	v_fmac_f32_e32 v158, v157, v157
	v_fmac_f32_e32 v156, v155, v155
	v_add_f32_e32 v155, v158, v156
	v_add_f32_e32 v154, v155, v154
	v_mov_b32_e32 v148, v154
	s_nop 1
	v_permlane16_swap_b32_e32 v154, v148
	s_waitcnt lgkmcnt(0)
	v_add_f32_e32 v148, v154, v148
	v_mov_b32_e32 v149, v148
	s_nop 1
	v_permlane32_swap_b32_e32 v148, v149
	s_and_saveexec_b64 s[0:1], vcc
	s_cbranch_execz .LBB0_2338
	s_lshl_b32 s5, s27, 11
	s_add_i32 s4, s4, s5
	v_mul_f32_e32 v154, 0x3c800000, v151
	v_lshl_add_u32 v151, v150, 5, s4
	s_waitcnt lgkmcnt(0)
	v_add_f32_e32 v155, v148, v149
	ds_write_b64 v151, v[154:155] offset:5632

;     DI void fused(f32x4 (&acc)[2][2][4][2], const Unit& u, int wr, int wc, int fr_, int fq_, LAS unsigned char* lds, int wid, int lane_) const {
;     ...
;         const int col0 = u.pn * BM + wc * 32 + 4 * fq;
; #pragma unroll
;         for (int ai = 0; ai < 2; ++ai)
; #pragma unroll
;             for (int m = 0; m < 4; ++m) { const int r = u.pm * BM + ai * HALF + wr * 64 + m * 16 + fr; const size_t ro = (size_t)r * ldc + col0;
; #pragma unroll
;                 for (int bj = 0; bj < 2; ++bj)
; #pragma unroll
;                     for (int n = 0; n < 2; ++n) { const f32x4 h = *(const f32x4*)(Hin + ro + bj * HALF + n * 16); acc[ai][bj][m][n] = h * alpha + acc[ai][bj][m][n] * s; }
;                 asm volatile("" : "+v"(acc[ai][0][m][0]), "+v"(acc[ai][0][m][1]), "+v"(acc[ai][1][m][0]), "+v"(acc[ai][1][m][1]));
;                 asm volatile("" ::: "memory"); }
.LBB0_2555:
	s_lshl_b32 s0, s24, 5
	s_barrier
	s_lshl_b32 s1, s2, 8
	v_ashrrev_i32_e32 v128, 2, v202
	s_or_b32 s0, s1, s0
	v_and_b32_e32 v128, -4, v128
	s_lshl_b32 s8, s22, 8
	v_and_b32_e32 v153, 15, v202
	v_add_u32_e32 v128, s0, v128
	s_add_i32 s0, s8, s20
	v_or_b32_e32 v132, s0, v153
	v_ashrrev_i32_e32 v133, 31, v132
	v_ashrrev_i32_e32 v129, 31, v128
	v_lshlrev_b64 v[130:131], 12, v[132:133]
	v_lshl_add_u64 v[130:131], s[90:91], 0, v[130:131]
	v_lshlrev_b64 v[146:147], 2, v[128:129]
	v_lshl_add_u64 v[144:145], v[130:131], 0, v[146:147]
	global_load_dwordx4 v[134:137], v[144:145], off
	global_load_dwordx4 v[138:141], v[144:145], off offset:64
	global_load_dwordx4 v[148:151], v[144:145], off offset:512
	global_load_dwordx4 v[154:157], v[144:145], off offset:576
	v_or_b32_e32 v130, 16, v132
	v_ashrrev_i32_e32 v131, 31, v130
	v_lshlrev_b64 v[130:131], 12, v[130:131]
	v_pk_mul_f32 v[124:125], v[124:125], 0.5 op_sel_hi:[1,0]
	v_pk_mul_f32 v[126:127], v[126:127], 0.5 op_sel_hi:[1,0]
	s_mov_b32 s0, 0x3fb504f3
	v_pk_mul_f32 v[120:121], v[120:121], 0.5 op_sel_hi:[1,0]
	v_lshl_add_u64 v[130:131], s[90:91], 0, v[130:131]
	v_pk_mul_f32 v[122:123], v[122:123], 0.5 op_sel_hi:[1,0]
	v_lshl_add_u64 v[142:143], v[130:131], 0, v[146:147]
	v_mbcnt_lo_u32_b32 v133, -1, 0
	s_waitcnt vmcnt(0)
	v_pk_fma_f32 v[126:127], v[136:137], s[0:1], v[126:127] op_sel_hi:[1,0,1]
	v_pk_fma_f32 v[124:125], v[134:135], s[0:1], v[124:125] op_sel_hi:[1,0,1]
	v_pk_fma_f32 v[120:121], v[138:139], s[0:1], v[120:121] op_sel_hi:[1,0,1]
	v_pk_mul_f32 v[130:131], v[150:151], s[0:1] op_sel_hi:[1,0]
	v_pk_mul_f32 v[134:135], v[148:149], s[0:1] op_sel_hi:[1,0]
	v_pk_mul_f32 v[136:137], v[156:157], s[0:1] op_sel_hi:[1,0]
	v_pk_mul_f32 v[138:139], v[154:155], s[0:1] op_sel_hi:[1,0]
	v_pk_fma_f32 v[122:123], v[140:141], s[0:1], v[122:123] op_sel_hi:[1,0,1]
	v_pk_fma_f32 v[118:119], v[118:119], 0.5, v[130:131] op_sel_hi:[1,0,1]
	v_pk_fma_f32 v[116:117], v[116:117], 0.5, v[134:135] op_sel_hi:[1,0,1]
	v_pk_fma_f32 v[106:107], v[106:107], 0.5, v[136:137] op_sel_hi:[1,0,1]
	v_pk_fma_f32 v[104:105], v[104:105], 0.5, v[138:139] op_sel_hi:[1,0,1]
	v_or_b32_e32 v130, 32, v132
	global_load_dwordx4 v[134:137], v[142:143], off
	global_load_dwordx4 v[148:151], v[142:143], off offset:64
	global_load_dwordx4 v[154:157], v[142:143], off offset:512
	global_load_dwordx4 v[158:161], v[142:143], off offset:576
	v_ashrrev_i32_e32 v131, 31, v130
	v_lshlrev_b64 v[130:131], 12, v[130:131]
	v_lshl_add_u64 v[130:131], s[90:91], 0, v[130:131]
	v_lshl_add_u64 v[140:141], v[130:131], 0, v[146:147]
	v_mov_b32_e32 v172, v124
	v_mov_b32_e32 v173, v127
	v_mov_b32_e32 v174, v121
	v_mov_b32_e32 v175, v122
	v_add_f32_e32 v177, v116, v117
	v_add_f32_e32 v179, v118, v119
	v_mov_b32_e32 v176, v104
	v_mov_b32_e32 v178, v105
	v_mov_b32_e32 v180, v107
	s_waitcnt vmcnt(3)
	v_pk_mul_f32 v[130:131], v[136:137], s[0:1] op_sel_hi:[1,0]
	v_pk_mul_f32 v[134:135], v[134:135], s[0:1] op_sel_hi:[1,0]
	s_waitcnt vmcnt(2)
	v_pk_mul_f32 v[136:137], v[150:151], s[0:1] op_sel_hi:[1,0]
	v_pk_mul_f32 v[138:139], v[148:149], s[0:1] op_sel_hi:[1,0]
	s_waitcnt vmcnt(1)
	v_pk_mul_f32 v[148:149], v[156:157], s[0:1] op_sel_hi:[1,0]
	v_pk_mul_f32 v[150:151], v[154:155], s[0:1] op_sel_hi:[1,0]
	s_waitcnt vmcnt(0)
	v_pk_mul_f32 v[154:155], v[160:161], s[0:1] op_sel_hi:[1,0]
	v_pk_mul_f32 v[156:157], v[158:159], s[0:1] op_sel_hi:[1,0]
	v_pk_fma_f32 v[114:115], v[114:115], 0.5, v[130:131] op_sel_hi:[1,0,1]
	v_pk_fma_f32 v[112:113], v[112:113], 0.5, v[134:135] op_sel_hi:[1,0,1]
	v_pk_fma_f32 v[110:111], v[110:111], 0.5, v[136:137] op_sel_hi:[1,0,1]
	v_pk_fma_f32 v[108:109], v[108:109], 0.5, v[138:139] op_sel_hi:[1,0,1]
	v_pk_fma_f32 v[102:103], v[102:103], 0.5, v[148:149] op_sel_hi:[1,0,1]
	v_pk_fma_f32 v[100:101], v[100:101], 0.5, v[150:151] op_sel_hi:[1,0,1]
	v_pk_fma_f32 v[90:91], v[90:91], 0.5, v[154:155] op_sel_hi:[1,0,1]
	v_pk_fma_f32 v[88:89], v[88:89], 0.5, v[156:157] op_sel_hi:[1,0,1]
	v_or_b32_e32 v130, 48, v132
	global_load_dwordx4 v[134:137], v[140:141], off
	global_load_dwordx4 v[148:151], v[140:141], off offset:64
	global_load_dwordx4 v[154:157], v[140:141], off offset:512
	global_load_dwordx4 v[158:161], v[140:141], off offset:576
	v_ashrrev_i32_e32 v131, 31, v130
	v_lshlrev_b64 v[130:131], 12, v[130:131]
	v_lshl_add_u64 v[130:131], s[90:91], 0, v[130:131]
	v_lshl_add_u64 v[138:139], v[130:131], 0, v[146:147]
	s_waitcnt vmcnt(3)
	v_pk_mul_f32 v[130:131], v[136:137], s[0:1] op_sel_hi:[1,0]
	v_pk_mul_f32 v[134:135], v[134:135], s[0:1] op_sel_hi:[1,0]
	s_waitcnt vmcnt(2)
	v_pk_mul_f32 v[136:137], v[150:151], s[0:1] op_sel_hi:[1,0]
	v_pk_mul_f32 v[148:149], v[148:149], s[0:1] op_sel_hi:[1,0]
	s_waitcnt vmcnt(1)
	v_pk_mul_f32 v[150:151], v[156:157], s[0:1] op_sel_hi:[1,0]
	v_pk_mul_f32 v[154:155], v[154:155], s[0:1] op_sel_hi:[1,0]
	s_waitcnt vmcnt(0)
	v_pk_mul_f32 v[156:157], v[160:161], s[0:1] op_sel_hi:[1,0]
	v_pk_mul_f32 v[158:159], v[158:159], s[0:1] op_sel_hi:[1,0]
	v_pk_fma_f32 v[98:99], v[98:99], 0.5, v[130:131] op_sel_hi:[1,0,1]
	v_pk_fma_f32 v[96:97], v[96:97], 0.5, v[134:135] op_sel_hi:[1,0,1]
	v_pk_fma_f32 v[94:95], v[94:95], 0.5, v[136:137] op_sel_hi:[1,0,1]
	v_pk_fma_f32 v[92:93], v[92:93], 0.5, v[148:149] op_sel_hi:[1,0,1]
	v_pk_fma_f32 v[86:87], v[86:87], 0.5, v[150:151] op_sel_hi:[1,0,1]
	v_pk_fma_f32 v[84:85], v[84:85], 0.5, v[154:155] op_sel_hi:[1,0,1]
	v_pk_fma_f32 v[74:75], v[74:75], 0.5, v[156:157] op_sel_hi:[1,0,1]
	v_pk_fma_f32 v[72:73], v[72:73], 0.5, v[158:159] op_sel_hi:[1,0,1]
	v_add_u32_e32 v130, 0x80, v132
	global_load_dwordx4 v[148:151], v[138:139], off
	global_load_dwordx4 v[154:157], v[138:139], off offset:64
	global_load_dwordx4 v[158:161], v[138:139], off offset:512
	global_load_dwordx4 v[162:165], v[138:139], off offset:576
	v_ashrrev_i32_e32 v131, 31, v130
	v_lshlrev_b64 v[130:131], 12, v[130:131]
	v_lshl_add_u64 v[130:131], s[90:91], 0, v[130:131]
	v_lshl_add_u64 v[136:137], v[130:131], 0, v[146:147]
	s_waitcnt vmcnt(3)
;     DI void fused(f32x4 (&acc)[2][2][4][2], const Unit& u, int wr, int wc, int fr_, int fq_, LAS unsigned char* lds, int wid, int lane_) const {
;     ...
;             for (int m = 0; m < 4; ++m) { const int r = u.pm * BM + ai * HALF + wr * 64 + m * 16 + fr; const size_t ro = (size_t)r * ldc + col0;
; #pragma unroll
;                 for (int bj = 0; bj < 2; ++bj)
; #pragma unroll
;                     for (int n = 0; n < 2; ++n) { const f32x4 h = *(const f32x4*)(Hin + ro + bj * HALF + n * 16); acc[ai][bj][m][n] = h * alpha + acc[ai][bj][m][n] * s; }
;                 asm volatile("" : "+v"(acc[ai][0][m][0]), "+v"(acc[ai][0][m][1]), "+v"(acc[ai][1][m][0]), "+v"(acc[ai][1][m][1]));
;                 asm volatile("" ::: "memory"); }
	v_pk_mul_f32 v[130:131], v[150:151], s[0:1] op_sel_hi:[1,0]
	v_pk_mul_f32 v[134:135], v[148:149], s[0:1] op_sel_hi:[1,0]
	s_waitcnt vmcnt(2)
	v_pk_mul_f32 v[148:149], v[156:157], s[0:1] op_sel_hi:[1,0]
	v_pk_mul_f32 v[150:151], v[154:155], s[0:1] op_sel_hi:[1,0]
	s_waitcnt vmcnt(1)
	v_pk_mul_f32 v[154:155], v[160:161], s[0:1] op_sel_hi:[1,0]
	v_pk_mul_f32 v[156:157], v[158:159], s[0:1] op_sel_hi:[1,0]
	s_waitcnt vmcnt(0)
	v_pk_mul_f32 v[158:159], v[164:165], s[0:1] op_sel_hi:[1,0]
	v_pk_mul_f32 v[160:161], v[162:163], s[0:1] op_sel_hi:[1,0]
	v_pk_fma_f32 v[82:83], v[82:83], 0.5, v[130:131] op_sel_hi:[1,0,1]
	v_pk_fma_f32 v[80:81], v[80:81], 0.5, v[134:135] op_sel_hi:[1,0,1]
	v_pk_fma_f32 v[78:79], v[78:79], 0.5, v[148:149] op_sel_hi:[1,0,1]
	v_pk_fma_f32 v[76:77], v[76:77], 0.5, v[150:151] op_sel_hi:[1,0,1]
	v_pk_fma_f32 v[70:71], v[70:71], 0.5, v[154:155] op_sel_hi:[1,0,1]
	v_pk_fma_f32 v[68:69], v[68:69], 0.5, v[156:157] op_sel_hi:[1,0,1]
	v_pk_fma_f32 v[66:67], v[66:67], 0.5, v[158:159] op_sel_hi:[1,0,1]
	v_pk_fma_f32 v[64:65], v[64:65], 0.5, v[160:161] op_sel_hi:[1,0,1]
	v_add_u32_e32 v130, 0x90, v132
	global_load_dwordx4 v[148:151], v[136:137], off
	global_load_dwordx4 v[154:157], v[136:137], off offset:64
	global_load_dwordx4 v[158:161], v[136:137], off offset:512
	global_load_dwordx4 v[162:165], v[136:137], off offset:576
	v_ashrrev_i32_e32 v131, 31, v130
	v_lshlrev_b64 v[130:131], 12, v[130:131]
	v_lshl_add_u64 v[130:131], s[90:91], 0, v[130:131]
	v_lshl_add_u64 v[134:135], v[130:131], 0, v[146:147]
	s_waitcnt vmcnt(3)
	v_pk_mul_f32 v[130:131], v[150:151], s[0:1] op_sel_hi:[1,0]
	v_pk_mul_f32 v[148:149], v[148:149], s[0:1] op_sel_hi:[1,0]
	s_waitcnt vmcnt(2)
	v_pk_mul_f32 v[150:151], v[156:157], s[0:1] op_sel_hi:[1,0]
	v_pk_mul_f32 v[154:155], v[154:155], s[0:1] op_sel_hi:[1,0]
	s_waitcnt vmcnt(1)
	v_pk_mul_f32 v[156:157], v[160:161], s[0:1] op_sel_hi:[1,0]
	v_pk_mul_f32 v[158:159], v[158:159], s[0:1] op_sel_hi:[1,0]
	s_waitcnt vmcnt(0)
	v_pk_mul_f32 v[160:161], v[164:165], s[0:1] op_sel_hi:[1,0]
	v_pk_mul_f32 v[162:163], v[162:163], s[0:1] op_sel_hi:[1,0]
	v_pk_fma_f32 v[62:63], v[62:63], 0.5, v[130:131] op_sel_hi:[1,0,1]
	v_pk_fma_f32 v[60:61], v[60:61], 0.5, v[148:149] op_sel_hi:[1,0,1]
	v_pk_fma_f32 v[58:59], v[58:59], 0.5, v[150:151] op_sel_hi:[1,0,1]
	v_pk_fma_f32 v[56:57], v[56:57], 0.5, v[154:155] op_sel_hi:[1,0,1]
	v_pk_fma_f32 v[54:55], v[54:55], 0.5, v[156:157] op_sel_hi:[1,0,1]
	v_pk_fma_f32 v[52:53], v[52:53], 0.5, v[158:159] op_sel_hi:[1,0,1]
	v_pk_fma_f32 v[50:51], v[50:51], 0.5, v[160:161] op_sel_hi:[1,0,1]
	v_pk_fma_f32 v[48:49], v[48:49], 0.5, v[162:163] op_sel_hi:[1,0,1]
	v_add_u32_e32 v130, 0xa0, v132
	global_load_dwordx4 v[148:151], v[134:135], off
	global_load_dwordx4 v[154:157], v[134:135], off offset:64
	global_load_dwordx4 v[158:161], v[134:135], off offset:512
	global_load_dwordx4 v[162:165], v[134:135], off offset:576
	v_ashrrev_i32_e32 v131, 31, v130
	v_lshlrev_b64 v[130:131], 12, v[130:131]
	v_lshl_add_u64 v[130:131], s[90:91], 0, v[130:131]
	v_lshl_add_u64 v[130:131], v[130:131], 0, v[146:147]
	v_add_u32_e32 v132, 0xb0, v132
	s_waitcnt vmcnt(3)
	v_pk_mul_f32 v[150:151], v[150:151], s[0:1] op_sel_hi:[1,0]
	v_pk_mul_f32 v[148:149], v[148:149], s[0:1] op_sel_hi:[1,0]
	s_waitcnt vmcnt(2)
	v_pk_mul_f32 v[156:157], v[156:157], s[0:1] op_sel_hi:[1,0]
	v_pk_mul_f32 v[154:155], v[154:155], s[0:1] op_sel_hi:[1,0]
	s_waitcnt vmcnt(1)
	v_pk_mul_f32 v[160:161], v[160:161], s[0:1] op_sel_hi:[1,0]
	v_pk_mul_f32 v[158:159], v[158:159], s[0:1] op_sel_hi:[1,0]
	s_waitcnt vmcnt(0)
	v_pk_mul_f32 v[164:165], v[164:165], s[0:1] op_sel_hi:[1,0]
	v_pk_mul_f32 v[162:163], v[162:163], s[0:1] op_sel_hi:[1,0]
	v_pk_fma_f32 v[46:47], v[46:47], 0.5, v[150:151] op_sel_hi:[1,0,1]
	v_pk_fma_f32 v[44:45], v[44:45], 0.5, v[148:149] op_sel_hi:[1,0,1]
	v_pk_fma_f32 v[42:43], v[42:43], 0.5, v[156:157] op_sel_hi:[1,0,1]
	v_pk_fma_f32 v[40:41], v[40:41], 0.5, v[154:155] op_sel_hi:[1,0,1]
	v_pk_fma_f32 v[38:39], v[38:39], 0.5, v[160:161] op_sel_hi:[1,0,1]
	v_pk_fma_f32 v[36:37], v[36:37], 0.5, v[158:159] op_sel_hi:[1,0,1]
	v_pk_fma_f32 v[34:35], v[34:35], 0.5, v[164:165] op_sel_hi:[1,0,1]
	v_pk_fma_f32 v[32:33], v[32:33], 0.5, v[162:163] op_sel_hi:[1,0,1]
	v_mbcnt_hi_u32_b32 v149, -1, v133
	global_load_dwordx4 v[154:157], v[130:131], off
	global_load_dwordx4 v[158:161], v[130:131], off offset:64
	global_load_dwordx4 v[162:165], v[130:131], off offset:512
	global_load_dwordx4 v[166:169], v[130:131], off offset:576
	v_and_b32_e32 v133, 64, v149
	v_add_u32_e32 v182, 64, v133
	v_ashrrev_i32_e32 v133, 31, v132
	v_lshlrev_b64 v[132:133], 12, v[132:133]
	v_lshl_add_u64 v[132:133], s[90:91], 0, v[132:133]
	v_lshl_add_u64 v[132:133], v[132:133], 0, v[146:147]
	v_mov_b32_e32 v150, v125
	v_mov_b32_e32 v151, v126
	v_pk_add_f32 v[150:151], v[150:151], v[172:173]
	v_xor_b32_e32 v148, 16, v149
	v_cmp_lt_i32_e32 vcc, v148, v182
	v_pk_add_f32 v[172:173], v[176:177], v[178:179]
	s_waitcnt vmcnt(3)
	v_pk_mul_f32 v[156:157], v[156:157], s[0:1] op_sel_hi:[1,0]
	v_pk_mul_f32 v[154:155], v[154:155], s[0:1] op_sel_hi:[1,0]
	s_waitcnt vmcnt(2)
	v_pk_mul_f32 v[160:161], v[160:161], s[0:1] op_sel_hi:[1,0]
	v_pk_mul_f32 v[158:159], v[158:159], s[0:1] op_sel_hi:[1,0]
	s_waitcnt vmcnt(1)
	v_pk_mul_f32 v[164:165], v[164:165], s[0:1] op_sel_hi:[1,0]
	v_pk_mul_f32 v[162:163], v[162:163], s[0:1] op_sel_hi:[1,0]
	s_waitcnt vmcnt(0)
;     DI void fused(f32x4 (&acc)[2][2][4][2], const Unit& u, int wr, int wc, int fr_, int fq_, LAS unsigned char* lds, int wid, int lane_) const {
;     ...
;             for (int m = 0; m < 4; ++m) { const int r = u.pm * BM + ai * HALF + wr * 64 + m * 16 + fr; const size_t ro = (size_t)r * ldc + col0;
; #pragma unroll
;                 for (int bj = 0; bj < 2; ++bj)
; #pragma unroll
;                     for (int n = 0; n < 2; ++n) { const f32x4 h = *(const f32x4*)(Hin + ro + bj * HALF + n * 16); acc[ai][bj][m][n] = h * alpha + acc[ai][bj][m][n] * s; }
;                 asm volatile("" : "+v"(acc[ai][0][m][0]), "+v"(acc[ai][0][m][1]), "+v"(acc[ai][1][m][0]), "+v"(acc[ai][1][m][1]));
;                 asm volatile("" ::: "memory"); }
; #pragma unroll
;         for (int ai = 0; ai < 2; ++ai)
; #pragma unroll
;             for (int m = 0; m < 4; ++m) {
;                 float sm = 0.f;
; #pragma unroll
;                 for (int bj = 0; bj < 2; ++bj)
; #pragma unroll
;                     for (int n = 0; n < 2; ++n) { const f32x4 x = acc[ai][bj][m][n]; sm += (x[0] + x[1]) + (x[2] + x[3]); }
;                 sm += __shfl_xor(sm, 16); sm += __shfl_xor(sm, 32);
;                 const float mw = sm * (1.0f / 64.0f); float q = 0.f;
; #pragma unroll
;                 for (int bj = 0; bj < 2; ++bj)
; #pragma unroll
;                     for (int n = 0; n < 2; ++n) { const f32x4 d = acc[ai][bj][m][n] - mw; q += (d[0] * d[0] + d[1] * d[1]) + (d[2] * d[2] + d[3] * d[3]); }
;                 q += __shfl_xor(q, 16); q += __shfl_xor(q, 32);
;                 if (fq == 0) P[(ai * HALF + wr * 64 + m * 16 + fr) * 4 + wc] = (f32x2){mw, q};
	v_pk_mul_f32 v[168:169], v[168:169], s[0:1] op_sel_hi:[1,0]
	v_pk_mul_f32 v[166:167], v[166:167], s[0:1] op_sel_hi:[1,0]
	v_pk_fma_f32 v[30:31], v[30:31], 0.5, v[156:157] op_sel_hi:[1,0,1]
	v_pk_fma_f32 v[28:29], v[28:29], 0.5, v[154:155] op_sel_hi:[1,0,1]
	v_pk_fma_f32 v[26:27], v[26:27], 0.5, v[160:161] op_sel_hi:[1,0,1]
	v_pk_fma_f32 v[24:25], v[24:25], 0.5, v[158:159] op_sel_hi:[1,0,1]
	v_pk_fma_f32 v[22:23], v[22:23], 0.5, v[164:165] op_sel_hi:[1,0,1]
	v_pk_fma_f32 v[20:21], v[20:21], 0.5, v[162:163] op_sel_hi:[1,0,1]
	v_pk_fma_f32 v[18:19], v[18:19], 0.5, v[168:169] op_sel_hi:[1,0,1]
	v_pk_fma_f32 v[16:17], v[16:17], 0.5, v[166:167] op_sel_hi:[1,0,1]
	v_mov_b32_e32 v154, v120
	global_load_dwordx4 v[156:159], v[132:133], off
	global_load_dwordx4 v[160:163], v[132:133], off offset:64
	global_load_dwordx4 v[164:167], v[132:133], off offset:512
	global_load_dwordx4 v[168:171], v[132:133], off offset:576
	v_mov_b32_e32 v155, v123
	v_pk_add_f32 v[154:155], v[174:175], v[154:155]
	v_add_f32_e32 v174, v150, v151
	v_pk_add_f32 v[150:151], v[154:155], v[154:155] op_sel_hi:[0,1]
	v_add_f32_e32 v181, 0, v174
	v_mov_b32_e32 v150, v106
	v_pk_add_f32 v[150:151], v[150:151], v[180:181]
	v_cndmask_b32_e32 v148, v149, v148, vcc
	v_pk_add_f32 v[150:151], v[172:173], v[150:151]
	v_lshlrev_b32_e32 v148, 2, v148
	v_add_f32_e32 v150, v150, v151
	v_mov_b32_e32 v151, v150
	s_nop 1
	v_permlane16_swap_b32_e32 v150, v151
	v_xor_b32_e32 v154, 32, v149
	v_cmp_lt_i32_e32 vcc, v154, v182
	s_waitcnt lgkmcnt(0)
	v_add_f32_e32 v150, v150, v151
	v_cndmask_b32_e32 v149, v149, v154, vcc
	v_lshlrev_b32_e32 v149, 2, v149
	v_mov_b32_e32 v151, v150
	s_nop 1
	v_permlane32_swap_b32_e32 v150, v151
	v_cmp_gt_u32_e32 vcc, 16, v202
	s_waitcnt lgkmcnt(0)
	v_add_f32_e32 v150, v150, v151
	v_fmamk_f32 v154, v150, 0xbc800000, v127
	v_fmamk_f32 v172, v150, 0xbc800000, v125
	v_fmamk_f32 v174, v150, 0xbc800000, v123
	v_fmamk_f32 v176, v150, 0xbc800000, v121
	v_fmamk_f32 v151, v150, 0xbc800000, v126
	v_fmamk_f32 v155, v150, 0xbc800000, v124
	v_fmamk_f32 v173, v150, 0xbc800000, v122
	v_fmamk_f32 v175, v150, 0xbc800000, v120
	v_fmamk_f32 v178, v150, 0xbc800000, v119
	v_fmamk_f32 v180, v150, 0xbc800000, v117
	v_mul_f32_e32 v172, v172, v172
	v_mul_f32_e32 v154, v154, v154
	v_mul_f32_e32 v176, v176, v176
	v_mul_f32_e32 v174, v174, v174
	v_fmamk_f32 v177, v150, 0xbc800000, v118
	v_fmamk_f32 v179, v150, 0xbc800000, v116
	v_fmamk_f32 v182, v150, 0xbc800000, v107
	v_fmamk_f32 v184, v150, 0xbc800000, v105
	v_mul_f32_e32 v180, v180, v180
	v_mul_f32_e32 v178, v178, v178
	v_fmac_f32_e32 v172, v155, v155
	v_fmac_f32_e32 v154, v151, v151
	v_fmac_f32_e32 v176, v175, v175
	v_fmac_f32_e32 v174, v173, v173
	v_fmamk_f32 v181, v150, 0xbc800000, v106
	v_fmamk_f32 v183, v150, 0xbc800000, v104
	v_mul_f32_e32 v184, v184, v184
	v_mul_f32_e32 v182, v182, v182
	v_fmac_f32_e32 v180, v179, v179
	v_fmac_f32_e32 v178, v177, v177
	v_add_f32_e32 v151, v172, v154
	v_add_f32_e32 v154, v176, v174
	v_fmac_f32_e32 v184, v183, v183
	v_fmac_f32_e32 v182, v181, v181
	v_add_f32_e32 v155, v180, v178
	v_add_f32_e32 v151, v151, v154
	v_add_f32_e32 v172, v184, v182
	v_add_f32_e32 v151, v155, v151
	v_add_f32_e32 v151, v172, v151
	v_mov_b32_e32 v154, v151
	s_nop 1
	v_permlane16_swap_b32_e32 v151, v154
	s_waitcnt lgkmcnt(0)
	v_add_f32_e32 v151, v151, v154
	v_mov_b32_e32 v154, v151
	s_nop 1
	v_permlane32_swap_b32_e32 v151, v154
	s_waitcnt vmcnt(3)
	v_pk_mul_f32 v[158:159], v[158:159], s[0:1] op_sel_hi:[1,0]
	v_pk_mul_f32 v[156:157], v[156:157], s[0:1] op_sel_hi:[1,0]
	s_waitcnt vmcnt(2)
	v_pk_mul_f32 v[162:163], v[162:163], s[0:1] op_sel_hi:[1,0]
	v_pk_mul_f32 v[160:161], v[160:161], s[0:1] op_sel_hi:[1,0]
	s_waitcnt vmcnt(1)
	v_pk_mul_f32 v[166:167], v[166:167], s[0:1] op_sel_hi:[1,0]
	v_pk_mul_f32 v[164:165], v[164:165], s[0:1] op_sel_hi:[1,0]
	s_waitcnt vmcnt(0)
	v_pk_mul_f32 v[170:171], v[170:171], s[0:1] op_sel_hi:[1,0]
	v_pk_mul_f32 v[168:169], v[168:169], s[0:1] op_sel_hi:[1,0]
	v_pk_fma_f32 v[14:15], v[14:15], 0.5, v[158:159] op_sel_hi:[1,0,1]
	v_pk_fma_f32 v[12:13], v[12:13], 0.5, v[156:157] op_sel_hi:[1,0,1]
	v_pk_fma_f32 v[10:11], v[10:11], 0.5, v[162:163] op_sel_hi:[1,0,1]
	v_pk_fma_f32 v[8:9], v[8:9], 0.5, v[160:161] op_sel_hi:[1,0,1]
	v_pk_fma_f32 v[6:7], v[6:7], 0.5, v[166:167] op_sel_hi:[1,0,1]
	v_pk_fma_f32 v[4:5], v[4:5], 0.5, v[164:165] op_sel_hi:[1,0,1]
	v_pk_fma_f32 v[2:3], v[2:3], 0.5, v[170:171] op_sel_hi:[1,0,1]
	v_pk_fma_f32 v[0:1], v[0:1], 0.5, v[168:169] op_sel_hi:[1,0,1]
	s_lshl_b32 s0, s24, 3
	s_add_i32 s4, s0, 0x100
	s_and_saveexec_b64 s[0:1], vcc
	s_cbranch_execz .LBB0_2557
	s_lshl_b32 s5, s23, 11
	s_add_i32 s5, s4, s5
	v_mul_f32_e32 v150, 0x3c800000, v150
	v_lshl_add_u32 v155, v202, 5, s5
	s_waitcnt lgkmcnt(0)
	v_add_f32_e32 v151, v151, v154
	ds_write_b64 v155, v[150:151]
;     DI void fused(f32x4 (&acc)[2][2][4][2], const Unit& u, int wr, int wc, int fr_, int fq_, LAS unsigned char* lds, int wid, int lane_) const {
;     ...
;         for (int ai = 0; ai < 2; ++ai)
; #pragma unroll
;             for (int m = 0; m < 4; ++m) {
;                 float sm = 0.f;
; #pragma unroll
;                 for (int bj = 0; bj < 2; ++bj)
; #pragma unroll
;                     for (int n = 0; n < 2; ++n) { const f32x4 x = acc[ai][bj][m][n]; sm += (x[0] + x[1]) + (x[2] + x[3]); }
;                 sm += __shfl_xor(sm, 16); sm += __shfl_xor(sm, 32);
;                 const float mw = sm * (1.0f / 64.0f); float q = 0.f;
; #pragma unroll
;                 for (int bj = 0; bj < 2; ++bj)
; #pragma unroll
;                     for (int n = 0; n < 2; ++n) { const f32x4 d = acc[ai][bj][m][n] - mw; q += (d[0] * d[0] + d[1] * d[1]) + (d[2] * d[2] + d[3] * d[3]); }
;                 q += __shfl_xor(q, 16); q += __shfl_xor(q, 32);
;                 if (fq == 0) P[(ai * HALF + wr * 64 + m * 16 + fr) * 4 + wc] = (f32x2){mw, q};
.LBB0_2557:
	s_or_b64 exec, exec, s[0:1]
	v_mov_b32_e32 v150, v113
	v_mov_b32_e32 v151, v114
	s_waitcnt lgkmcnt(0)
	v_mov_b32_e32 v154, v112
	v_mov_b32_e32 v155, v115
	v_pk_add_f32 v[150:151], v[150:151], v[154:155]
	v_mov_b32_e32 v154, v109
	v_mov_b32_e32 v155, v110
	v_mov_b32_e32 v156, v108
	v_mov_b32_e32 v157, v111
	v_pk_add_f32 v[154:155], v[154:155], v[156:157]
	v_add_f32_e32 v150, v150, v151
	v_pk_add_f32 v[154:155], v[154:155], v[154:155] op_sel_hi:[0,1]
	v_add_f32_e32 v151, 0, v150
	v_add_f32_e32 v157, v100, v101
	v_add_f32_e32 v159, v102, v103
	v_mov_b32_e32 v156, v88
	v_mov_b32_e32 v158, v89
	v_mov_b32_e32 v154, v90
	v_mov_b32_e32 v150, v91
	v_pk_add_f32 v[156:157], v[156:157], v[158:159]
	v_pk_add_f32 v[150:151], v[154:155], v[150:151]
	s_nop 0
	v_pk_add_f32 v[150:151], v[156:157], v[150:151]
	s_nop 0
	v_add_f32_e32 v150, v150, v151
	v_mov_b32_e32 v151, v150
	s_nop 1
	v_permlane16_swap_b32_e32 v150, v151
	s_waitcnt lgkmcnt(0)
	v_add_f32_e32 v150, v150, v151
	v_mov_b32_e32 v151, v150
	s_nop 1
	v_permlane32_swap_b32_e32 v150, v151
	s_waitcnt lgkmcnt(0)
	v_add_f32_e32 v150, v150, v151
	v_fmamk_f32 v154, v150, 0xbc800000, v115
	v_fmamk_f32 v156, v150, 0xbc800000, v113
	v_fmamk_f32 v151, v150, 0xbc800000, v114
	v_fmamk_f32 v155, v150, 0xbc800000, v112
	v_mul_f32_e32 v156, v156, v156
	v_mul_f32_e32 v154, v154, v154
	v_fmac_f32_e32 v156, v155, v155
	v_fmac_f32_e32 v154, v151, v151
	v_fmamk_f32 v155, v150, 0xbc800000, v111
	v_fmamk_f32 v157, v150, 0xbc800000, v109
	v_add_f32_e32 v151, v156, v154
	v_fmamk_f32 v154, v150, 0xbc800000, v110
	v_fmamk_f32 v156, v150, 0xbc800000, v108
	v_mul_f32_e32 v157, v157, v157
	v_mul_f32_e32 v155, v155, v155
	v_fmac_f32_e32 v157, v156, v156
	v_fmac_f32_e32 v155, v154, v154
	v_add_f32_e32 v154, v157, v155
	v_fmamk_f32 v155, v150, 0xbc800000, v103
	v_fmamk_f32 v157, v150, 0xbc800000, v101
	v_add_f32_e32 v151, v151, v154
	v_fmamk_f32 v154, v150, 0xbc800000, v102
	v_fmamk_f32 v156, v150, 0xbc800000, v100
	v_mul_f32_e32 v157, v157, v157
	v_mul_f32_e32 v155, v155, v155
	v_fmac_f32_e32 v157, v156, v156
	v_fmac_f32_e32 v155, v154, v154
	v_add_f32_e32 v154, v157, v155
	v_fmamk_f32 v155, v150, 0xbc800000, v91
	v_fmamk_f32 v157, v150, 0xbc800000, v89
	v_add_f32_e32 v151, v154, v151
	v_fmamk_f32 v154, v150, 0xbc800000, v90
	v_fmamk_f32 v156, v150, 0xbc800000, v88
	v_mul_f32_e32 v157, v157, v157
	v_mul_f32_e32 v155, v155, v155
	v_fmac_f32_e32 v157, v156, v156
	v_fmac_f32_e32 v155, v154, v154
	v_add_f32_e32 v154, v157, v155
	v_add_f32_e32 v151, v154, v151
	v_mov_b32_e32 v154, v151
	s_nop 1
	v_permlane16_swap_b32_e32 v151, v154
	s_waitcnt lgkmcnt(0)
	v_add_f32_e32 v151, v151, v154
	v_mov_b32_e32 v154, v151
	s_nop 1
	v_permlane32_swap_b32_e32 v151, v154
	s_and_saveexec_b64 s[0:1], vcc
	s_cbranch_execz .LBB0_2559
	s_lshl_b32 s5, s23, 11
	s_add_i32 s5, s4, s5
	v_mul_f32_e32 v150, 0x3c800000, v150
	v_lshl_add_u32 v155, v202, 5, s5
	s_waitcnt lgkmcnt(0)
	v_add_f32_e32 v151, v151, v154
	ds_write_b64 v155, v[150:151] offset:512
.LBB0_2559:
	s_or_b64 exec, exec, s[0:1]
	v_mov_b32_e32 v150, v97
	v_mov_b32_e32 v151, v98
	s_waitcnt lgkmcnt(0)
	v_mov_b32_e32 v154, v96
	v_mov_b32_e32 v155, v99
	v_pk_add_f32 v[150:151], v[150:151], v[154:155]
	v_mov_b32_e32 v154, v93
	v_mov_b32_e32 v155, v94
	v_mov_b32_e32 v156, v92
	v_mov_b32_e32 v157, v95
	v_pk_add_f32 v[154:155], v[154:155], v[156:157]
	v_add_f32_e32 v150, v150, v151
	v_pk_add_f32 v[154:155], v[154:155], v[154:155] op_sel_hi:[0,1]
	v_add_f32_e32 v151, 0, v150
	v_add_f32_e32 v157, v84, v85
	v_add_f32_e32 v159, v86, v87
	v_mov_b32_e32 v156, v72
	v_mov_b32_e32 v158, v73
	v_mov_b32_e32 v154, v74
	v_mov_b32_e32 v150, v75
	v_pk_add_f32 v[156:157], v[156:157], v[158:159]
	v_pk_add_f32 v[150:151], v[154:155], v[150:151]
	s_nop 0
	v_pk_add_f32 v[150:151], v[156:157], v[150:151]
	s_nop 0
	v_add_f32_e32 v150, v150, v151
	v_mov_b32_e32 v151, v150
	s_nop 1
	v_permlane16_swap_b32_e32 v150, v151
	s_waitcnt lgkmcnt(0)
	v_add_f32_e32 v150, v150, v151
	v_mov_b32_e32 v151, v150
	s_nop 1
	v_permlane32_swap_b32_e32 v150, v151
	s_waitcnt lgkmcnt(0)
	v_add_f32_e32 v150, v150, v151
	v_fmamk_f32 v154, v150, 0xbc800000, v99
	v_fmamk_f32 v156, v150, 0xbc800000, v97
	v_fmamk_f32 v151, v150, 0xbc800000, v98
	v_fmamk_f32 v155, v150, 0xbc800000, v96
	v_mul_f32_e32 v156, v156, v156
	v_mul_f32_e32 v154, v154, v154
	v_fmac_f32_e32 v156, v155, v155
	v_fmac_f32_e32 v154, v151, v151
	v_fmamk_f32 v155, v150, 0xbc800000, v95
	v_fmamk_f32 v157, v150, 0xbc800000, v93
	v_add_f32_e32 v151, v156, v154
	v_fmamk_f32 v154, v150, 0xbc800000, v94
	v_fmamk_f32 v156, v150, 0xbc800000, v92
	v_mul_f32_e32 v157, v157, v157
	v_mul_f32_e32 v155, v155, v155
	v_fmac_f32_e32 v157, v156, v156
	v_fmac_f32_e32 v155, v154, v154
	v_add_f32_e32 v154, v157, v155
	v_fmamk_f32 v155, v150, 0xbc800000, v87
	v_fmamk_f32 v157, v150, 0xbc800000, v85
	v_add_f32_e32 v151, v151, v154
	v_fmamk_f32 v154, v150, 0xbc800000, v86
	v_fmamk_f32 v156, v150, 0xbc800000, v84
	v_mul_f32_e32 v157, v157, v157
	v_mul_f32_e32 v155, v155, v155
	v_fmac_f32_e32 v157, v156, v156
	v_fmac_f32_e32 v155, v154, v154
	v_add_f32_e32 v154, v157, v155
	v_fmamk_f32 v155, v150, 0xbc800000, v75
	v_fmamk_f32 v157, v150, 0xbc800000, v73
	v_add_f32_e32 v151, v154, v151
	v_fmamk_f32 v154, v150, 0xbc800000, v74
	v_fmamk_f32 v156, v150, 0xbc800000, v72
	v_mul_f32_e32 v157, v157, v157
	v_mul_f32_e32 v155, v155, v155
	v_fmac_f32_e32 v157, v156, v156
	v_fmac_f32_e32 v155, v154, v154
	v_add_f32_e32 v154, v157, v155
	v_add_f32_e32 v151, v154, v151
	v_mov_b32_e32 v154, v151
	s_nop 1
	v_permlane16_swap_b32_e32 v151, v154
	s_waitcnt lgkmcnt(0)
	v_add_f32_e32 v151, v151, v154
	v_mov_b32_e32 v154, v151
	s_nop 1
	v_permlane32_swap_b32_e32 v151, v154
	s_and_saveexec_b64 s[0:1], vcc
	s_cbranch_execz .LBB0_2561
	s_lshl_b32 s5, s23, 11
	s_add_i32 s5, s4, s5
	v_mul_f32_e32 v150, 0x3c800000, v150
	v_lshl_add_u32 v155, v202, 5, s5
	s_waitcnt lgkmcnt(0)
	v_add_f32_e32 v151, v151, v154
	ds_write_b64 v155, v[150:151] offset:1024
;     DI void fused(f32x4 (&acc)[2][2][4][2], const Unit& u, int wr, int wc, int fr_, int fq_, LAS unsigned char* lds, int wid, int lane_) const {
;     ...
;         for (int ai = 0; ai < 2; ++ai)
; #pragma unroll
;             for (int m = 0; m < 4; ++m) {
;                 float sm = 0.f;
; #pragma unroll
;                 for (int bj = 0; bj < 2; ++bj)
; #pragma unroll
;                     for (int n = 0; n < 2; ++n) { const f32x4 x = acc[ai][bj][m][n]; sm += (x[0] + x[1]) + (x[2] + x[3]); }
;                 sm += __shfl_xor(sm, 16); sm += __shfl_xor(sm, 32);
;                 const float mw = sm * (1.0f / 64.0f); float q = 0.f;
; #pragma unroll
;                 for (int bj = 0; bj < 2; ++bj)
; #pragma unroll
;                     for (int n = 0; n < 2; ++n) { const f32x4 d = acc[ai][bj][m][n] - mw; q += (d[0] * d[0] + d[1] * d[1]) + (d[2] * d[2] + d[3] * d[3]); }
;                 q += __shfl_xor(q, 16); q += __shfl_xor(q, 32);
;                 if (fq == 0) P[(ai * HALF + wr * 64 + m * 16 + fr) * 4 + wc] = (f32x2){mw, q};
.LBB0_2561:
	s_or_b64 exec, exec, s[0:1]
	v_mov_b32_e32 v150, v81
	v_mov_b32_e32 v151, v82
	s_waitcnt lgkmcnt(0)
	v_mov_b32_e32 v154, v80
	v_mov_b32_e32 v155, v83
	v_pk_add_f32 v[150:151], v[150:151], v[154:155]
	v_mov_b32_e32 v154, v77
	v_mov_b32_e32 v155, v78
	v_mov_b32_e32 v156, v76
	v_mov_b32_e32 v157, v79
	v_pk_add_f32 v[154:155], v[154:155], v[156:157]
	v_add_f32_e32 v150, v150, v151
	v_pk_add_f32 v[154:155], v[154:155], v[154:155] op_sel_hi:[0,1]
	v_add_f32_e32 v151, 0, v150
	v_add_f32_e32 v157, v68, v69
	v_add_f32_e32 v159, v70, v71
	v_mov_b32_e32 v156, v64
	v_mov_b32_e32 v158, v65
	v_mov_b32_e32 v154, v66
	v_mov_b32_e32 v150, v67
	v_pk_add_f32 v[156:157], v[156:157], v[158:159]
	v_pk_add_f32 v[150:151], v[154:155], v[150:151]
	s_nop 0
	v_pk_add_f32 v[150:151], v[156:157], v[150:151]
	s_nop 0
	v_add_f32_e32 v150, v150, v151
	v_mov_b32_e32 v151, v150
	s_nop 1
	v_permlane16_swap_b32_e32 v150, v151
	s_waitcnt lgkmcnt(0)
	v_add_f32_e32 v150, v150, v151
	v_mov_b32_e32 v151, v150
	s_nop 1
	v_permlane32_swap_b32_e32 v150, v151
	s_waitcnt lgkmcnt(0)
	v_add_f32_e32 v150, v150, v151
	v_fmamk_f32 v154, v150, 0xbc800000, v83
	v_fmamk_f32 v156, v150, 0xbc800000, v81
	v_fmamk_f32 v151, v150, 0xbc800000, v82
	v_fmamk_f32 v155, v150, 0xbc800000, v80
	v_mul_f32_e32 v156, v156, v156
	v_mul_f32_e32 v154, v154, v154
	v_fmac_f32_e32 v156, v155, v155
	v_fmac_f32_e32 v154, v151, v151
	v_fmamk_f32 v155, v150, 0xbc800000, v79
	v_fmamk_f32 v157, v150, 0xbc800000, v77
	v_add_f32_e32 v151, v156, v154
	v_fmamk_f32 v154, v150, 0xbc800000, v78
	v_fmamk_f32 v156, v150, 0xbc800000, v76
	v_mul_f32_e32 v157, v157, v157
	v_mul_f32_e32 v155, v155, v155
	v_fmac_f32_e32 v157, v156, v156
	v_fmac_f32_e32 v155, v154, v154
	v_add_f32_e32 v154, v157, v155
	v_fmamk_f32 v155, v150, 0xbc800000, v71
	v_fmamk_f32 v157, v150, 0xbc800000, v69
	v_add_f32_e32 v151, v151, v154
	v_fmamk_f32 v154, v150, 0xbc800000, v70
	v_fmamk_f32 v156, v150, 0xbc800000, v68
	v_mul_f32_e32 v157, v157, v157
	v_mul_f32_e32 v155, v155, v155
	v_fmac_f32_e32 v157, v156, v156
	v_fmac_f32_e32 v155, v154, v154
	v_add_f32_e32 v154, v157, v155
	v_fmamk_f32 v155, v150, 0xbc800000, v67
	v_fmamk_f32 v157, v150, 0xbc800000, v65
	v_add_f32_e32 v151, v154, v151
	v_fmamk_f32 v154, v150, 0xbc800000, v66
	v_fmamk_f32 v156, v150, 0xbc800000, v64
	v_mul_f32_e32 v157, v157, v157
	v_mul_f32_e32 v155, v155, v155
	v_fmac_f32_e32 v157, v156, v156
	v_fmac_f32_e32 v155, v154, v154
	v_add_f32_e32 v154, v157, v155
	v_add_f32_e32 v151, v154, v151
	v_mov_b32_e32 v154, v151
	s_nop 1
	v_permlane16_swap_b32_e32 v151, v154
	s_waitcnt lgkmcnt(0)
	v_add_f32_e32 v151, v151, v154
	v_mov_b32_e32 v154, v151
	s_nop 1
	v_permlane32_swap_b32_e32 v151, v154
	s_and_saveexec_b64 s[0:1], vcc
	s_cbranch_execz .LBB0_2563
	s_lshl_b32 s5, s23, 11
	s_add_i32 s5, s4, s5
	v_mul_f32_e32 v150, 0x3c800000, v150
	v_lshl_add_u32 v155, v202, 5, s5
	s_waitcnt lgkmcnt(0)
	v_add_f32_e32 v151, v151, v154
	ds_write_b64 v155, v[150:151] offset:1536
.LBB0_2563:
	s_or_b64 exec, exec, s[0:1]
	v_mov_b32_e32 v150, v61
	v_mov_b32_e32 v151, v62
	s_waitcnt lgkmcnt(0)
	v_mov_b32_e32 v154, v60
	v_mov_b32_e32 v155, v63
	v_pk_add_f32 v[150:151], v[150:151], v[154:155]
	v_mov_b32_e32 v154, v57
	v_mov_b32_e32 v155, v58
	v_mov_b32_e32 v156, v56
	v_mov_b32_e32 v157, v59
	v_pk_add_f32 v[154:155], v[154:155], v[156:157]
	v_add_f32_e32 v150, v150, v151
	v_pk_add_f32 v[154:155], v[154:155], v[154:155] op_sel_hi:[0,1]
	v_add_f32_e32 v151, 0, v150
	v_add_f32_e32 v157, v52, v53
	v_add_f32_e32 v159, v54, v55
	v_mov_b32_e32 v156, v48
	v_mov_b32_e32 v158, v49
	v_mov_b32_e32 v154, v50
	v_mov_b32_e32 v150, v51
	v_pk_add_f32 v[156:157], v[156:157], v[158:159]
	v_pk_add_f32 v[150:151], v[154:155], v[150:151]
	s_nop 0
	v_pk_add_f32 v[150:151], v[156:157], v[150:151]
	s_nop 0
	v_add_f32_e32 v150, v150, v151
	v_mov_b32_e32 v151, v150
	s_nop 1
	v_permlane16_swap_b32_e32 v150, v151
	s_waitcnt lgkmcnt(0)
	v_add_f32_e32 v150, v150, v151
	v_mov_b32_e32 v151, v150
	s_nop 1
	v_permlane32_swap_b32_e32 v150, v151
	s_waitcnt lgkmcnt(0)
	v_add_f32_e32 v150, v150, v151
	v_fmamk_f32 v154, v150, 0xbc800000, v63
	v_fmamk_f32 v156, v150, 0xbc800000, v61
	v_fmamk_f32 v151, v150, 0xbc800000, v62
	v_fmamk_f32 v155, v150, 0xbc800000, v60
	v_mul_f32_e32 v156, v156, v156
	v_mul_f32_e32 v154, v154, v154
	v_fmac_f32_e32 v156, v155, v155
	v_fmac_f32_e32 v154, v151, v151
	v_fmamk_f32 v155, v150, 0xbc800000, v59
	v_fmamk_f32 v157, v150, 0xbc800000, v57
	v_add_f32_e32 v151, v156, v154
	v_fmamk_f32 v154, v150, 0xbc800000, v58
	v_fmamk_f32 v156, v150, 0xbc800000, v56
	v_mul_f32_e32 v157, v157, v157
	v_mul_f32_e32 v155, v155, v155
	v_fmac_f32_e32 v157, v156, v156
	v_fmac_f32_e32 v155, v154, v154
	v_add_f32_e32 v154, v157, v155
	v_fmamk_f32 v155, v150, 0xbc800000, v55
	v_fmamk_f32 v157, v150, 0xbc800000, v53
	v_add_f32_e32 v151, v151, v154
	v_fmamk_f32 v154, v150, 0xbc800000, v54
	v_fmamk_f32 v156, v150, 0xbc800000, v52
	v_mul_f32_e32 v157, v157, v157
	v_mul_f32_e32 v155, v155, v155
	v_fmac_f32_e32 v157, v156, v156
	v_fmac_f32_e32 v155, v154, v154
	v_add_f32_e32 v154, v157, v155
	v_fmamk_f32 v155, v150, 0xbc800000, v51
	v_fmamk_f32 v157, v150, 0xbc800000, v49
	v_add_f32_e32 v151, v154, v151
	v_fmamk_f32 v154, v150, 0xbc800000, v50
	v_fmamk_f32 v156, v150, 0xbc800000, v48
	v_mul_f32_e32 v157, v157, v157
	v_mul_f32_e32 v155, v155, v155
	v_fmac_f32_e32 v157, v156, v156
	v_fmac_f32_e32 v155, v154, v154
	v_add_f32_e32 v154, v157, v155
	v_add_f32_e32 v151, v154, v151
	v_mov_b32_e32 v154, v151
	s_nop 1
	v_permlane16_swap_b32_e32 v151, v154
	s_waitcnt lgkmcnt(0)
	v_add_f32_e32 v151, v151, v154
	v_mov_b32_e32 v154, v151
	s_nop 1
	v_permlane32_swap_b32_e32 v151, v154
	s_and_saveexec_b64 s[0:1], vcc
	s_cbranch_execz .LBB0_2565
	s_lshl_b32 s5, s23, 11
	s_add_i32 s5, s4, s5
	v_mul_f32_e32 v150, 0x3c800000, v150
	v_lshl_add_u32 v155, v202, 5, s5
	s_waitcnt lgkmcnt(0)
	v_add_f32_e32 v151, v151, v154
	ds_write_b64 v155, v[150:151] offset:4096
;     DI void fused(f32x4 (&acc)[2][2][4][2], const Unit& u, int wr, int wc, int fr_, int fq_, LAS unsigned char* lds, int wid, int lane_) const {
;     ...
;         for (int ai = 0; ai < 2; ++ai)
; #pragma unroll
;             for (int m = 0; m < 4; ++m) {
;                 float sm = 0.f;
; #pragma unroll
;                 for (int bj = 0; bj < 2; ++bj)
; #pragma unroll
;                     for (int n = 0; n < 2; ++n) { const f32x4 x = acc[ai][bj][m][n]; sm += (x[0] + x[1]) + (x[2] + x[3]); }
;                 sm += __shfl_xor(sm, 16); sm += __shfl_xor(sm, 32);
;                 const float mw = sm * (1.0f / 64.0f); float q = 0.f;
; #pragma unroll
;                 for (int bj = 0; bj < 2; ++bj)
; #pragma unroll
;                     for (int n = 0; n < 2; ++n) { const f32x4 d = acc[ai][bj][m][n] - mw; q += (d[0] * d[0] + d[1] * d[1]) + (d[2] * d[2] + d[3] * d[3]); }
;                 q += __shfl_xor(q, 16); q += __shfl_xor(q, 32);
;                 if (fq == 0) P[(ai * HALF + wr * 64 + m * 16 + fr) * 4 + wc] = (f32x2){mw, q};
.LBB0_2565:
	s_or_b64 exec, exec, s[0:1]
	v_mov_b32_e32 v150, v45
	v_mov_b32_e32 v151, v46
	s_waitcnt lgkmcnt(0)
	v_mov_b32_e32 v154, v44
	v_mov_b32_e32 v155, v47
	v_pk_add_f32 v[150:151], v[150:151], v[154:155]
	v_mov_b32_e32 v154, v41
	v_mov_b32_e32 v155, v42
	v_mov_b32_e32 v156, v40
	v_mov_b32_e32 v157, v43
	v_pk_add_f32 v[154:155], v[154:155], v[156:157]
	v_add_f32_e32 v150, v150, v151
	v_pk_add_f32 v[154:155], v[154:155], v[154:155] op_sel_hi:[0,1]
	v_add_f32_e32 v151, 0, v150
	v_add_f32_e32 v157, v36, v37
	v_add_f32_e32 v159, v38, v39
	v_mov_b32_e32 v156, v32
	v_mov_b32_e32 v158, v33
	v_mov_b32_e32 v154, v34
	v_mov_b32_e32 v150, v35
	v_pk_add_f32 v[156:157], v[156:157], v[158:159]
	v_pk_add_f32 v[150:151], v[154:155], v[150:151]
	s_nop 0
	v_pk_add_f32 v[150:151], v[156:157], v[150:151]
	s_nop 0
	v_add_f32_e32 v150, v150, v151
	v_mov_b32_e32 v151, v150
	s_nop 1
	v_permlane16_swap_b32_e32 v150, v151
	s_waitcnt lgkmcnt(0)
	v_add_f32_e32 v150, v150, v151
	v_mov_b32_e32 v151, v150
	s_nop 1
	v_permlane32_swap_b32_e32 v150, v151
	s_waitcnt lgkmcnt(0)
	v_add_f32_e32 v150, v150, v151
	v_fmamk_f32 v154, v150, 0xbc800000, v47
	v_fmamk_f32 v156, v150, 0xbc800000, v45
	v_fmamk_f32 v151, v150, 0xbc800000, v46
	v_fmamk_f32 v155, v150, 0xbc800000, v44
	v_mul_f32_e32 v156, v156, v156
	v_mul_f32_e32 v154, v154, v154
	v_fmac_f32_e32 v156, v155, v155
	v_fmac_f32_e32 v154, v151, v151
	v_fmamk_f32 v155, v150, 0xbc800000, v43
	v_fmamk_f32 v157, v150, 0xbc800000, v41
	v_add_f32_e32 v151, v156, v154
	v_fmamk_f32 v154, v150, 0xbc800000, v42
	v_fmamk_f32 v156, v150, 0xbc800000, v40
	v_mul_f32_e32 v157, v157, v157
	v_mul_f32_e32 v155, v155, v155
	v_fmac_f32_e32 v157, v156, v156
	v_fmac_f32_e32 v155, v154, v154
	v_add_f32_e32 v154, v157, v155
	v_fmamk_f32 v155, v150, 0xbc800000, v39
	v_fmamk_f32 v157, v150, 0xbc800000, v37
	v_add_f32_e32 v151, v151, v154
	v_fmamk_f32 v154, v150, 0xbc800000, v38
	v_fmamk_f32 v156, v150, 0xbc800000, v36
	v_mul_f32_e32 v157, v157, v157
	v_mul_f32_e32 v155, v155, v155
	v_fmac_f32_e32 v157, v156, v156
	v_fmac_f32_e32 v155, v154, v154
	v_add_f32_e32 v154, v157, v155
	v_fmamk_f32 v155, v150, 0xbc800000, v35
	v_fmamk_f32 v157, v150, 0xbc800000, v33
	v_add_f32_e32 v151, v154, v151
	v_fmamk_f32 v154, v150, 0xbc800000, v34
	v_fmamk_f32 v156, v150, 0xbc800000, v32
	v_mul_f32_e32 v157, v157, v157
	v_mul_f32_e32 v155, v155, v155
	v_fmac_f32_e32 v157, v156, v156
	v_fmac_f32_e32 v155, v154, v154
	v_add_f32_e32 v154, v157, v155
	v_add_f32_e32 v151, v154, v151
	v_mov_b32_e32 v154, v151
	s_nop 1
	v_permlane16_swap_b32_e32 v151, v154
	s_waitcnt lgkmcnt(0)
	v_add_f32_e32 v151, v151, v154
	v_mov_b32_e32 v154, v151
	s_nop 1
	v_permlane32_swap_b32_e32 v151, v154
	s_and_saveexec_b64 s[0:1], vcc
	s_cbranch_execz .LBB0_2567
	s_lshl_b32 s5, s23, 11
	s_add_i32 s5, s4, s5
	v_mul_f32_e32 v150, 0x3c800000, v150
	v_lshl_add_u32 v155, v202, 5, s5
	s_waitcnt lgkmcnt(0)
	v_add_f32_e32 v151, v151, v154
	ds_write_b64 v155, v[150:151] offset:4608
;     DI void fused(f32x4 (&acc)[2][2][4][2], const Unit& u, int wr, int wc, int fr_, int fq_, LAS unsigned char* lds, int wid, int lane_) const {
;     ...
;         for (int ai = 0; ai < 2; ++ai)
; #pragma unroll
;             for (int m = 0; m < 4; ++m) {
;                 float sm = 0.f;
; #pragma unroll
;                 for (int bj = 0; bj < 2; ++bj)
; #pragma unroll
;                     for (int n = 0; n < 2; ++n) { const f32x4 x = acc[ai][bj][m][n]; sm += (x[0] + x[1]) + (x[2] + x[3]); }
;                 sm += __shfl_xor(sm, 16); sm += __shfl_xor(sm, 32);
;                 const float mw = sm * (1.0f / 64.0f); float q = 0.f;
; #pragma unroll
;                 for (int bj = 0; bj < 2; ++bj)
; #pragma unroll
;                     for (int n = 0; n < 2; ++n) { const f32x4 d = acc[ai][bj][m][n] - mw; q += (d[0] * d[0] + d[1] * d[1]) + (d[2] * d[2] + d[3] * d[3]); }
;                 q += __shfl_xor(q, 16); q += __shfl_xor(q, 32);
;                 if (fq == 0) P[(ai * HALF + wr * 64 + m * 16 + fr) * 4 + wc] = (f32x2){mw, q};
.LBB0_2567:
	s_or_b64 exec, exec, s[0:1]
	v_mov_b32_e32 v150, v29
	v_mov_b32_e32 v151, v30
	s_waitcnt lgkmcnt(0)
	v_mov_b32_e32 v154, v28
	v_mov_b32_e32 v155, v31
	v_pk_add_f32 v[150:151], v[150:151], v[154:155]
	v_mov_b32_e32 v154, v25
	v_mov_b32_e32 v155, v26
	v_mov_b32_e32 v156, v24
	v_mov_b32_e32 v157, v27
	v_pk_add_f32 v[154:155], v[154:155], v[156:157]
	v_add_f32_e32 v150, v150, v151
	v_pk_add_f32 v[154:155], v[154:155], v[154:155] op_sel_hi:[0,1]
	v_add_f32_e32 v151, 0, v150
	v_add_f32_e32 v157, v20, v21
	v_add_f32_e32 v159, v22, v23
	v_mov_b32_e32 v156, v16
	v_mov_b32_e32 v158, v17
	v_mov_b32_e32 v154, v18
	v_mov_b32_e32 v150, v19
	v_pk_add_f32 v[156:157], v[156:157], v[158:159]
	v_pk_add_f32 v[150:151], v[154:155], v[150:151]
	s_nop 0
	v_pk_add_f32 v[150:151], v[156:157], v[150:151]
	s_nop 0
	v_add_f32_e32 v150, v150, v151
	v_mov_b32_e32 v151, v150
	s_nop 1
	v_permlane16_swap_b32_e32 v150, v151
	s_waitcnt lgkmcnt(0)
	v_add_f32_e32 v150, v150, v151
	v_mov_b32_e32 v151, v150
	s_nop 1
	v_permlane32_swap_b32_e32 v150, v151
	s_waitcnt lgkmcnt(0)
	v_add_f32_e32 v150, v150, v151
	v_fmamk_f32 v154, v150, 0xbc800000, v31
	v_fmamk_f32 v156, v150, 0xbc800000, v29
	v_fmamk_f32 v151, v150, 0xbc800000, v30
	v_fmamk_f32 v155, v150, 0xbc800000, v28
	v_mul_f32_e32 v156, v156, v156
	v_mul_f32_e32 v154, v154, v154
	v_fmac_f32_e32 v156, v155, v155
	v_fmac_f32_e32 v154, v151, v151
	v_fmamk_f32 v155, v150, 0xbc800000, v27
	v_fmamk_f32 v157, v150, 0xbc800000, v25
	v_add_f32_e32 v151, v156, v154
	v_fmamk_f32 v154, v150, 0xbc800000, v26
	v_fmamk_f32 v156, v150, 0xbc800000, v24
	v_mul_f32_e32 v157, v157, v157
	v_mul_f32_e32 v155, v155, v155
	v_fmac_f32_e32 v157, v156, v156
	v_fmac_f32_e32 v155, v154, v154
	v_add_f32_e32 v154, v157, v155
	v_fmamk_f32 v155, v150, 0xbc800000, v23
	v_fmamk_f32 v157, v150, 0xbc800000, v21
	v_add_f32_e32 v151, v151, v154
	v_fmamk_f32 v154, v150, 0xbc800000, v22
	v_fmamk_f32 v156, v150, 0xbc800000, v20
	v_mul_f32_e32 v157, v157, v157
	v_mul_f32_e32 v155, v155, v155
	v_fmac_f32_e32 v157, v156, v156
	v_fmac_f32_e32 v155, v154, v154
	v_add_f32_e32 v154, v157, v155
	v_fmamk_f32 v155, v150, 0xbc800000, v19
	v_fmamk_f32 v157, v150, 0xbc800000, v17
	v_add_f32_e32 v151, v154, v151
	v_fmamk_f32 v154, v150, 0xbc800000, v18
	v_fmamk_f32 v156, v150, 0xbc800000, v16
	v_mul_f32_e32 v157, v157, v157
	v_mul_f32_e32 v155, v155, v155
	v_fmac_f32_e32 v157, v156, v156
	v_fmac_f32_e32 v155, v154, v154
	v_add_f32_e32 v154, v157, v155
	v_add_f32_e32 v151, v154, v151
	v_mov_b32_e32 v154, v151
	s_nop 1
	v_permlane16_swap_b32_e32 v151, v154
	s_waitcnt lgkmcnt(0)
	v_add_f32_e32 v151, v151, v154
	v_mov_b32_e32 v154, v151
	s_nop 1
	v_permlane32_swap_b32_e32 v151, v154
	s_and_saveexec_b64 s[0:1], vcc
	s_cbranch_execz .LBB0_2569
	s_lshl_b32 s5, s23, 11
	s_add_i32 s5, s4, s5
	v_mul_f32_e32 v150, 0x3c800000, v150
	v_lshl_add_u32 v155, v202, 5, s5
	s_waitcnt lgkmcnt(0)
	v_add_f32_e32 v151, v151, v154
	ds_write_b64 v155, v[150:151] offset:5120
.LBB0_2569:
	s_or_b64 exec, exec, s[0:1]
	v_mov_b32_e32 v150, v13
	v_mov_b32_e32 v151, v14
	s_waitcnt lgkmcnt(0)
	v_mov_b32_e32 v154, v12
	v_mov_b32_e32 v155, v15
	v_pk_add_f32 v[150:151], v[150:151], v[154:155]
	v_mov_b32_e32 v154, v9
	v_mov_b32_e32 v155, v10
	v_mov_b32_e32 v156, v8
	v_mov_b32_e32 v157, v11
	v_pk_add_f32 v[154:155], v[154:155], v[156:157]
	v_add_f32_e32 v150, v150, v151
	v_pk_add_f32 v[154:155], v[154:155], v[154:155] op_sel_hi:[0,1]
	v_add_f32_e32 v151, 0, v150
	v_add_f32_e32 v157, v4, v5
	v_add_f32_e32 v159, v6, v7
	v_mov_b32_e32 v156, v0
	v_mov_b32_e32 v158, v1
	v_mov_b32_e32 v154, v2
	v_mov_b32_e32 v150, v3
	v_pk_add_f32 v[156:157], v[156:157], v[158:159]
	v_pk_add_f32 v[150:151], v[154:155], v[150:151]
	s_nop 0
	v_pk_add_f32 v[150:151], v[156:157], v[150:151]
	s_nop 0
	v_add_f32_e32 v150, v150, v151
	v_mov_b32_e32 v151, v150
	s_nop 1
	v_permlane16_swap_b32_e32 v150, v151
	s_waitcnt lgkmcnt(0)
	v_add_f32_e32 v150, v150, v151
	v_mov_b32_e32 v151, v150
	s_nop 1
	v_permlane32_swap_b32_e32 v150, v151
	s_waitcnt lgkmcnt(0)
	v_add_f32_e32 v150, v150, v151
	v_fmamk_f32 v154, v150, 0xbc800000, v15
	v_fmamk_f32 v156, v150, 0xbc800000, v13
	v_fmamk_f32 v151, v150, 0xbc800000, v14
	v_fmamk_f32 v155, v150, 0xbc800000, v12
	v_mul_f32_e32 v156, v156, v156
	v_mul_f32_e32 v154, v154, v154
	v_fmac_f32_e32 v156, v155, v155
	v_fmac_f32_e32 v154, v151, v151
	v_fmamk_f32 v155, v150, 0xbc800000, v11
	v_fmamk_f32 v157, v150, 0xbc800000, v9
	v_add_f32_e32 v151, v156, v154
	v_fmamk_f32 v154, v150, 0xbc800000, v10
	v_fmamk_f32 v156, v150, 0xbc800000, v8
	v_mul_f32_e32 v157, v157, v157
	v_mul_f32_e32 v155, v155, v155
	v_fmac_f32_e32 v157, v156, v156
	v_fmac_f32_e32 v155, v154, v154
	v_add_f32_e32 v154, v157, v155
	v_fmamk_f32 v155, v150, 0xbc800000, v7
	v_fmamk_f32 v157, v150, 0xbc800000, v5
	v_add_f32_e32 v151, v151, v154
	v_fmamk_f32 v154, v150, 0xbc800000, v6
	v_fmamk_f32 v156, v150, 0xbc800000, v4
	v_mul_f32_e32 v157, v157, v157
	v_mul_f32_e32 v155, v155, v155
	v_fmac_f32_e32 v157, v156, v156
	v_fmac_f32_e32 v155, v154, v154
	v_add_f32_e32 v154, v157, v155
	v_fmamk_f32 v155, v150, 0xbc800000, v3
	v_fmamk_f32 v157, v150, 0xbc800000, v1
	v_add_f32_e32 v151, v154, v151
	v_fmamk_f32 v154, v150, 0xbc800000, v2
	v_fmamk_f32 v156, v150, 0xbc800000, v0
	v_mul_f32_e32 v157, v157, v157
	v_mul_f32_e32 v155, v155, v155
	v_fmac_f32_e32 v157, v156, v156
	v_fmac_f32_e32 v155, v154, v154
	v_add_f32_e32 v154, v157, v155
	v_add_f32_e32 v151, v154, v151
	v_mov_b32_e32 v148, v151
	s_nop 1
	v_permlane16_swap_b32_e32 v151, v148
	s_waitcnt lgkmcnt(0)
	v_add_f32_e32 v148, v151, v148
	v_mov_b32_e32 v149, v148
	s_nop 1
	v_permlane32_swap_b32_e32 v148, v149
	s_and_saveexec_b64 s[0:1], vcc
	s_cbranch_execz .LBB0_2571
	s_lshl_b32 s5, s23, 11
	s_add_i32 s4, s4, s5
	v_mul_f32_e32 v150, 0x3c800000, v150
	v_lshl_add_u32 v154, v202, 5, s4
	s_waitcnt lgkmcnt(0)
	v_add_f32_e32 v151, v148, v149
	ds_write_b64 v154, v[150:151] offset:5632
